# as previous + K-loops: the 4 per-iteration VALU adds forming the A-fragment LDS read base replaced by one pre-loop VGPR and immediate ds_read offsets (K-loops now VALU-free except MFMA)
# speedup vs baseline: 1.0159x; 1.0004x over previous
; #define PG8_STAGE(bufoff, gbase, voff) do { _Pragma("unroll") for (int _i = 0; _i < 2; ++_i) \
;         __builtin_amdgcn_global_load_lds((const unsigned*)((const char*)(gbase) + (voff)[_i]), (LAS unsigned*)(lds + (bufoff) + ldsw + _i * 8192), 16, 0, 0); } while (0)
; #define PG8_LDA(dst, b, h) do { _Pragma("unroll") for (int m = 0; m < 4; ++m) _Pragma("unroll") for (int k = 0; k < 2; ++k) dst[m][k] = *(const LAS bf16x8*)(lds + PG8_SA(b, h) + aoff + m * 2048 + k * 1024); } while (0)
; #define PG8_LDB(dst, b, h) do { _Pragma("unroll") for (int n = 0; n < 2; ++n) _Pragma("unroll") for (int k = 0; k < 2; ++k) dst[n][k] = *(const LAS bf16x8*)(lds + PG8_SB(b, h) + boff + n * 2048 + k * 1024); } while (0)
; #define PG8_MMA(ai, bj, At, Bt) do { __builtin_amdgcn_s_setprio(1); _Pragma("unroll") for (int m = 0; m < 4; ++m) _Pragma("unroll") for (int n = 0; n < 2; ++n) _Pragma("unroll") for (int k = 0; k < 2; ++k) \
;         acc[ai][bj][m][n] = __builtin_amdgcn_mfma_f32_16x16x32_bf16(Bt[n][k], At[m][k], acc[ai][bj][m][n], 0, 0, 0); __builtin_amdgcn_s_setprio(0); } while (0)
; #define PG8_WAIT_L(n) asm volatile("s_waitcnt lgkmcnt(" #n ")" ::: "memory")
; #define PG8_BAR __builtin_amdgcn_s_barrier()
; #define PG8_SCHED __builtin_amdgcn_sched_barrier(0)
; template <class Epi>
; __device__ __forceinline__ void gemm_phase(LAS unsigned char* lds, const Gemm g, const StaticOrder& S, const Epi& E) {
;     ...
;         const bool has_next = S.next(ui + 1, nxt);
;         const char* nA = has_next ? (const char*)g.A + (size_t)nxt.pm * tstepA + (size_t)(nxt.pn >> 2) * gstepA : cA; const char* nB = has_next ? (const char*)g.Bt + (size_t)nxt.pn * tstepB : cB;
;         for (int t = 0; t < nt; t += 2) {
;             const bool last = (t == nt - 2);
;             const char* a1 = cA + (size_t)(t + 1) * kstepA;
;             const char* a2 = last ? nA : cA + (size_t)(t + 2) * kstepA; const char* b2 = last ? nB : cB + (size_t)(t + 2) * kstep;
;             const char* a3 = a2 + kstepA; const char* b3 = b2 + kstep;
;             PG8_LDB(B0, 0, 0); PG8_SCHED; PG8_LDA(At, 0, 0); PG8_STAGE(PG8_SA(1, 1), a1 + hstepA, voffA);
;             PG8_WAIT_L(8); PG8_BAR; PG8_WAIT_L(0); PG8_MMA(0, 0, At, B0); PG8_BAR; PG8_SCHED;
.LBB0_157:
	s_ashr_i32 s23, s22, 31
	s_lshl_b64 s[24:25], s[22:23], 20
	s_add_u32 s26, s10, s24
	s_addc_u32 s27, s11, s25
	s_and_b64 s[24:25], s[40:41], exec
	s_cselect_b32 s23, s27, s39
	s_cselect_b32 s55, s26, s38
	s_ashr_i32 s21, s20, 31
	s_lshl_b64 s[24:25], s[20:21], 20
	s_add_u32 s36, s35, s24
	s_addc_u32 s37, s44, s25
	s_and_b64 s[24:25], s[40:41], exec
	s_cselect_b32 s21, s37, s5
	s_cselect_b32 s56, s36, s4
	s_add_u32 s57, s4, 0x100
	v_mov_b32_e32 v2, 0
	s_addc_u32 s58, s5, 0
	s_mov_b32 s59, -2
	v_mov_b32_e32 v3, v2
	v_mov_b32_e32 v4, v2
	v_mov_b32_e32 v5, v2
	v_mov_b32_e32 v6, v2
	v_mov_b32_e32 v7, v2
	v_mov_b32_e32 v8, v2
	v_mov_b32_e32 v9, v2
	v_mov_b32_e32 v18, v2
	v_mov_b32_e32 v19, v2
	v_mov_b32_e32 v20, v2
	v_mov_b32_e32 v21, v2
	v_mov_b32_e32 v22, v2
	v_mov_b32_e32 v23, v2
	v_mov_b32_e32 v24, v2
	v_mov_b32_e32 v25, v2
	v_mov_b32_e32 v34, v2
	v_mov_b32_e32 v35, v2
	v_mov_b32_e32 v36, v2
	v_mov_b32_e32 v37, v2
	v_mov_b32_e32 v38, v2
	v_mov_b32_e32 v39, v2
	v_mov_b32_e32 v40, v2
	v_mov_b32_e32 v41, v2
	v_mov_b32_e32 v50, v2
	v_mov_b32_e32 v51, v2
	v_mov_b32_e32 v52, v2
	v_mov_b32_e32 v53, v2
	v_mov_b32_e32 v54, v2
	v_mov_b32_e32 v55, v2
	v_mov_b32_e32 v56, v2
	v_mov_b32_e32 v57, v2
	v_mov_b32_e32 v10, v2
	v_mov_b32_e32 v11, v2
	v_mov_b32_e32 v12, v2
	v_mov_b32_e32 v13, v2
	v_mov_b32_e32 v14, v2
	v_mov_b32_e32 v15, v2
	v_mov_b32_e32 v16, v2
	v_mov_b32_e32 v17, v2
	s_waitcnt vmcnt(0)
	v_mov_b32_e32 v26, v2
	v_mov_b32_e32 v27, v2
	v_mov_b32_e32 v28, v2
	v_mov_b32_e32 v29, v2
	v_mov_b32_e32 v30, v2
	v_mov_b32_e32 v31, v2
	v_mov_b32_e32 v32, v2
	v_mov_b32_e32 v33, v2
	v_mov_b32_e32 v42, v2
	v_mov_b32_e32 v43, v2
	v_mov_b32_e32 v44, v2
	v_mov_b32_e32 v45, v2
	v_mov_b32_e32 v46, v2
	v_mov_b32_e32 v47, v2
	v_mov_b32_e32 v48, v2
	v_mov_b32_e32 v49, v2
	v_mov_b32_e32 v58, v2
	v_mov_b32_e32 v59, v2
	v_mov_b32_e32 v60, v2
	v_mov_b32_e32 v61, v2
	v_mov_b32_e32 v62, v2
	v_mov_b32_e32 v63, v2
	v_mov_b32_e32 v64, v2
	v_mov_b32_e32 v65, v2
	v_mov_b32_e32 v66, v2
	v_mov_b32_e32 v67, v2
	v_mov_b32_e32 v68, v2
	v_mov_b32_e32 v69, v2
	v_mov_b32_e32 v70, v2
	v_mov_b32_e32 v71, v2
	v_mov_b32_e32 v72, v2
	v_mov_b32_e32 v73, v2
	v_mov_b32_e32 v82, v2
	v_mov_b32_e32 v83, v2
	v_mov_b32_e32 v84, v2
	v_mov_b32_e32 v85, v2
	v_mov_b32_e32 v86, v2
	v_mov_b32_e32 v87, v2
	v_mov_b32_e32 v88, v2
	v_mov_b32_e32 v89, v2
	v_mov_b32_e32 v98, v2
	v_mov_b32_e32 v99, v2
	v_mov_b32_e32 v100, v2
	v_mov_b32_e32 v101, v2
	v_mov_b32_e32 v102, v2
	v_mov_b32_e32 v103, v2
	v_mov_b32_e32 v104, v2
	v_mov_b32_e32 v105, v2
	v_mov_b32_e32 v114, v2
	v_mov_b32_e32 v115, v2
	v_mov_b32_e32 v116, v2
	v_mov_b32_e32 v117, v2
	v_mov_b32_e32 v118, v2
	v_mov_b32_e32 v119, v2
	v_mov_b32_e32 v120, v2
	v_mov_b32_e32 v121, v2
	v_mov_b32_e32 v74, v2
	v_mov_b32_e32 v75, v2
	v_mov_b32_e32 v76, v2
	v_mov_b32_e32 v77, v2
	v_mov_b32_e32 v78, v2
	v_mov_b32_e32 v79, v2
	v_mov_b32_e32 v80, v2
	v_mov_b32_e32 v81, v2
	v_mov_b32_e32 v90, v2
	v_mov_b32_e32 v91, v2
	v_mov_b32_e32 v92, v2
	v_mov_b32_e32 v93, v2
	v_mov_b32_e32 v94, v2
	v_mov_b32_e32 v95, v2
	v_mov_b32_e32 v96, v2
	v_mov_b32_e32 v97, v2
	v_mov_b32_e32 v106, v2
	v_mov_b32_e32 v107, v2
	v_mov_b32_e32 v108, v2
	v_mov_b32_e32 v109, v2
	v_mov_b32_e32 v110, v2
	v_mov_b32_e32 v111, v2
	v_mov_b32_e32 v112, v2
	v_mov_b32_e32 v113, v2
	v_mov_b32_e32 v122, v2
	v_mov_b32_e32 v123, v2
	v_mov_b32_e32 v124, v2
	v_mov_b32_e32 v125, v2
	v_mov_b32_e32 v126, v2
	v_mov_b32_e32 v127, v2
	v_mov_b32_e32 v128, v2
	v_mov_b32_e32 v129, v2
	v_add_u32_e32 v250, 0x10000, v152
.LBB0_158:
	s_add_u32 s42, s38, 0x100
	s_addc_u32 s43, s39, 0
	s_add_i32 s60, 0, 0x10000
	ds_read_b128 v[146:149], v250
	ds_read_b128 v[162:165], v250 offset:1024
	ds_read_b128 v[166:169], v250 offset:2048
	ds_read_b128 v[170:173], v250 offset:3072
	s_cmp_eq_u32 s59, 28
	s_cselect_b32 s25, s23, s43
	s_cselect_b32 s24, s55, s42
	s_cselect_b32 s5, s21, s58
	s_cselect_b32 s4, s56, s57
	s_add_i32 m0, s46, 0xc000
	ds_read_b128 v[174:177], v154
	ds_read_b128 v[188:191], v154 offset:1024
	ds_read_b128 v[192:195], v154 offset:2048
	ds_read_b128 v[196:199], v154 offset:3072
	ds_read_b128 v[200:203], v154 offset:4096
	ds_read_b128 v[204:207], v154 offset:5120
	ds_read_b128 v[208:211], v154 offset:6144
	ds_read_b128 v[212:215], v154 offset:7168
	global_load_lds_dwordx4 v140, s[38:39]
	s_add_i32 m0, s46, 0xe000
	s_nop 0
	global_load_lds_dwordx4 v142, s[38:39]
	s_waitcnt lgkmcnt(8)
	s_barrier
	s_waitcnt lgkmcnt(0)
	v_mfma_f32_16x16x32_bf16 v[126:129], v[146:149], v[174:177], v[126:129]
	v_mfma_f32_16x16x32_bf16 v[122:125], v[166:169], v[174:177], v[122:125]
	v_mfma_f32_16x16x32_bf16 v[110:113], v[146:149], v[192:195], v[110:113]
	v_mfma_f32_16x16x32_bf16 v[106:109], v[166:169], v[192:195], v[106:109]
	v_mfma_f32_16x16x32_bf16 v[94:97], v[146:149], v[200:203], v[94:97]
	v_mfma_f32_16x16x32_bf16 v[90:93], v[166:169], v[200:203], v[90:93]
	v_mfma_f32_16x16x32_bf16 v[78:81], v[146:149], v[208:211], v[78:81]
	v_mfma_f32_16x16x32_bf16 v[74:77], v[166:169], v[208:211], v[74:77]
	v_mfma_f32_16x16x32_bf16 v[126:129], v[162:165], v[188:191], v[126:129]
	v_mfma_f32_16x16x32_bf16 v[122:125], v[170:173], v[188:191], v[122:125]
	v_mfma_f32_16x16x32_bf16 v[110:113], v[162:165], v[196:199], v[110:113]
	v_mfma_f32_16x16x32_bf16 v[106:109], v[170:173], v[196:199], v[106:109]
	v_mfma_f32_16x16x32_bf16 v[94:97], v[162:165], v[204:207], v[94:97]
	v_mfma_f32_16x16x32_bf16 v[90:93], v[170:173], v[204:207], v[90:93]
	v_mfma_f32_16x16x32_bf16 v[78:81], v[162:165], v[212:215], v[78:81]
	v_mfma_f32_16x16x32_bf16 v[74:77], v[170:173], v[212:215], v[74:77]
	s_barrier
; #define PG8_STAGE(bufoff, gbase, voff) do { _Pragma("unroll") for (int _i = 0; _i < 2; ++_i) \
;         __builtin_amdgcn_global_load_lds((const unsigned*)((const char*)(gbase) + (voff)[_i]), (LAS unsigned*)(lds + (bufoff) + ldsw + _i * 8192), 16, 0, 0); } while (0)
; #define PG8_LDA(dst, b, h) do { _Pragma("unroll") for (int m = 0; m < 4; ++m) _Pragma("unroll") for (int k = 0; k < 2; ++k) dst[m][k] = *(const LAS bf16x8*)(lds + PG8_SA(b, h) + aoff + m * 2048 + k * 1024); } while (0)
; #define PG8_LDB(dst, b, h) do { _Pragma("unroll") for (int n = 0; n < 2; ++n) _Pragma("unroll") for (int k = 0; k < 2; ++k) dst[n][k] = *(const LAS bf16x8*)(lds + PG8_SB(b, h) + boff + n * 2048 + k * 1024); } while (0)
; #define PG8_MMA(ai, bj, At, Bt) do { __builtin_amdgcn_s_setprio(1); _Pragma("unroll") for (int m = 0; m < 4; ++m) _Pragma("unroll") for (int n = 0; n < 2; ++n) _Pragma("unroll") for (int k = 0; k < 2; ++k) \
;         acc[ai][bj][m][n] = __builtin_amdgcn_mfma_f32_16x16x32_bf16(Bt[n][k], At[m][k], acc[ai][bj][m][n], 0, 0, 0); __builtin_amdgcn_s_setprio(0); } while (0)
; #define PG8_WAIT_V(n) asm volatile("s_waitcnt vmcnt(" #n ")" ::: "memory")
; #define PG8_WAIT_L(n) asm volatile("s_waitcnt lgkmcnt(" #n ")" ::: "memory")
; #define PG8_BAR __builtin_amdgcn_s_barrier()
; #define PG8_SCHED __builtin_amdgcn_sched_barrier(0)
; template <class Epi>
; __device__ __forceinline__ void gemm_phase(LAS unsigned char* lds, const Gemm g, const StaticOrder& S, const Epi& E) {
;     ...
;             PG8_LDB(B1, 0, 1); PG8_STAGE(PG8_SB(0, 0), b2, voffB);
;             PG8_BAR; PG8_WAIT_L(0); PG8_MMA(0, 1, At, B1); PG8_BAR;
;             PG8_LDA(At, 0, 1); PG8_STAGE(PG8_SA(0, 0), a2, voffA);
;             PG8_BAR; PG8_WAIT_L(0); PG8_MMA(1, 0, At, B0); PG8_BAR; PG8_SCHED;
;             PG8_STAGE(PG8_SB(0, 1), b2 + hstepB, voffB);
;             PG8_WAIT_V(6); PG8_BAR; PG8_MMA(1, 1, At, B1); PG8_BAR;
;             PG8_LDB(B0, 1, 0); PG8_SCHED; PG8_LDA(At, 1, 0); PG8_STAGE(PG8_SA(0, 1), a2 + hstepA, voffA);
	s_add_i32 s61, 0, 0x14000
	s_add_i32 s38, s60, s45
	s_add_u32 s100, s4, s6
	s_addc_u32 s101, s5, s7
	s_mov_b32 m0, s38
	ds_read_b128 v[216:219], v250 offset:16384
	ds_read_b128 v[220:223], v250 offset:17408
	ds_read_b128 v[224:227], v250 offset:18432
	ds_read_b128 v[228:231], v250 offset:19456
	global_load_lds_dwordx4 v134, s[4:5]
	s_add_i32 m0, s38, 0x2000
	s_nop 0
	global_load_lds_dwordx4 v130, s[4:5]
	s_barrier
	s_waitcnt lgkmcnt(0)
	v_mfma_f32_16x16x32_bf16 v[118:121], v[216:219], v[174:177], v[118:121]
	v_mfma_f32_16x16x32_bf16 v[114:117], v[224:227], v[174:177], v[114:117]
	v_mfma_f32_16x16x32_bf16 v[102:105], v[216:219], v[192:195], v[102:105]
	v_mfma_f32_16x16x32_bf16 v[98:101], v[224:227], v[192:195], v[98:101]
	v_mfma_f32_16x16x32_bf16 v[86:89], v[216:219], v[200:203], v[86:89]
	v_mfma_f32_16x16x32_bf16 v[82:85], v[224:227], v[200:203], v[82:85]
	v_mfma_f32_16x16x32_bf16 v[70:73], v[216:219], v[208:211], v[70:73]
	v_mfma_f32_16x16x32_bf16 v[66:69], v[224:227], v[208:211], v[66:69]
	v_mfma_f32_16x16x32_bf16 v[118:121], v[220:223], v[188:191], v[118:121]
	v_mfma_f32_16x16x32_bf16 v[114:117], v[228:231], v[188:191], v[114:117]
	v_mfma_f32_16x16x32_bf16 v[102:105], v[220:223], v[196:199], v[102:105]
	v_mfma_f32_16x16x32_bf16 v[98:101], v[228:231], v[196:199], v[98:101]
	v_mfma_f32_16x16x32_bf16 v[86:89], v[220:223], v[204:207], v[86:89]
	v_mfma_f32_16x16x32_bf16 v[82:85], v[228:231], v[204:207], v[82:85]
	v_mfma_f32_16x16x32_bf16 v[70:73], v[220:223], v[212:215], v[70:73]
	v_mfma_f32_16x16x32_bf16 v[66:69], v[228:231], v[212:215], v[66:69]
	s_mov_b32 m0, s46
	s_add_u32 vcc_lo, s24, s6
	s_addc_u32 vcc_hi, s25, s7
	s_barrier
	ds_read_b128 v[174:177], v154 offset:16384
	ds_read_b128 v[188:191], v154 offset:17408
	ds_read_b128 v[192:195], v154 offset:18432
	ds_read_b128 v[196:199], v154 offset:19456
	ds_read_b128 v[200:203], v154 offset:20480
	ds_read_b128 v[204:207], v154 offset:21504
	ds_read_b128 v[208:211], v154 offset:22528
	ds_read_b128 v[212:215], v154 offset:23552
	global_load_lds_dwordx4 v136, s[24:25]
	s_mov_b32 m0, s47
	s_nop 0
	global_load_lds_dwordx4 v132, s[24:25]
	s_barrier
	s_waitcnt lgkmcnt(0)
	v_mfma_f32_16x16x32_bf16 v[62:65], v[146:149], v[174:177], v[62:65]
	v_mfma_f32_16x16x32_bf16 v[58:61], v[166:169], v[174:177], v[58:61]
	v_mfma_f32_16x16x32_bf16 v[46:49], v[146:149], v[192:195], v[46:49]
	v_mfma_f32_16x16x32_bf16 v[42:45], v[166:169], v[192:195], v[42:45]
	v_mfma_f32_16x16x32_bf16 v[30:33], v[146:149], v[200:203], v[30:33]
	v_mfma_f32_16x16x32_bf16 v[26:29], v[166:169], v[200:203], v[26:29]
	v_mfma_f32_16x16x32_bf16 v[14:17], v[146:149], v[208:211], v[14:17]
	v_mfma_f32_16x16x32_bf16 v[10:13], v[166:169], v[208:211], v[10:13]
	v_mfma_f32_16x16x32_bf16 v[62:65], v[162:165], v[188:191], v[62:65]
	v_mfma_f32_16x16x32_bf16 v[58:61], v[170:173], v[188:191], v[58:61]
	v_mfma_f32_16x16x32_bf16 v[46:49], v[162:165], v[196:199], v[46:49]
	v_mfma_f32_16x16x32_bf16 v[42:45], v[170:173], v[196:199], v[42:45]
	v_mfma_f32_16x16x32_bf16 v[30:33], v[162:165], v[204:207], v[30:33]
	v_mfma_f32_16x16x32_bf16 v[26:29], v[170:173], v[204:207], v[26:29]
	v_mfma_f32_16x16x32_bf16 v[14:17], v[162:165], v[212:215], v[14:17]
	v_mfma_f32_16x16x32_bf16 v[10:13], v[170:173], v[212:215], v[10:13]
	s_barrier
	s_add_u32 s38, s4, 0x80000
	s_addc_u32 s39, s5, 0
	s_add_i32 s60, s61, s45
	s_mov_b32 m0, s60
	s_nop 0
	global_load_lds_dwordx4 v134, s[38:39]
	s_add_i32 m0, s60, 0x2000
	s_nop 0
	global_load_lds_dwordx4 v130, s[38:39]
	s_waitcnt vmcnt(6)
	s_barrier
	v_mfma_f32_16x16x32_bf16 v[54:57], v[216:219], v[174:177], v[54:57]
	v_mfma_f32_16x16x32_bf16 v[50:53], v[224:227], v[174:177], v[50:53]
	v_mfma_f32_16x16x32_bf16 v[38:41], v[216:219], v[192:195], v[38:41]
	v_mfma_f32_16x16x32_bf16 v[34:37], v[224:227], v[192:195], v[34:37]
	v_mfma_f32_16x16x32_bf16 v[22:25], v[216:219], v[200:203], v[22:25]
	v_mfma_f32_16x16x32_bf16 v[18:21], v[224:227], v[200:203], v[18:21]
	v_mfma_f32_16x16x32_bf16 v[6:9], v[216:219], v[208:211], v[6:9]
	v_mfma_f32_16x16x32_bf16 v[2:5], v[224:227], v[208:211], v[2:5]
	v_mfma_f32_16x16x32_bf16 v[54:57], v[220:223], v[188:191], v[54:57]
	v_mfma_f32_16x16x32_bf16 v[50:53], v[228:231], v[188:191], v[50:53]
	v_mfma_f32_16x16x32_bf16 v[38:41], v[220:223], v[196:199], v[38:41]
	v_mfma_f32_16x16x32_bf16 v[34:37], v[228:231], v[196:199], v[34:37]
	v_mfma_f32_16x16x32_bf16 v[22:25], v[220:223], v[204:207], v[22:25]
	v_mfma_f32_16x16x32_bf16 v[18:21], v[228:231], v[204:207], v[18:21]
	v_mfma_f32_16x16x32_bf16 v[6:9], v[220:223], v[212:215], v[6:9]
	v_mfma_f32_16x16x32_bf16 v[2:5], v[228:231], v[212:215], v[2:5]
	s_add_i32 s38, 0, 0x18000
	s_barrier
	ds_read_b128 v[146:149], v250 offset:32768
	ds_read_b128 v[162:165], v250 offset:33792
	ds_read_b128 v[166:169], v250 offset:34816
	ds_read_b128 v[170:173], v250 offset:35840
	s_add_u32 s24, s24, 0x80000
	s_addc_u32 s25, s25, 0
	s_mov_b32 m0, s48
	ds_read_b128 v[174:177], v154 offset:32768
	ds_read_b128 v[188:191], v154 offset:33792
	ds_read_b128 v[192:195], v154 offset:34816
	ds_read_b128 v[196:199], v154 offset:35840
	ds_read_b128 v[200:203], v154 offset:36864
	ds_read_b128 v[204:207], v154 offset:37888
	ds_read_b128 v[208:211], v154 offset:38912
	ds_read_b128 v[212:215], v154 offset:39936
	global_load_lds_dwordx4 v136, s[24:25]
	s_mov_b32 m0, s49
	s_nop 0
	global_load_lds_dwordx4 v132, s[24:25]
	s_waitcnt lgkmcnt(8)
	s_barrier
; __device__ __forceinline__ unsigned cvt_pk_bf16(float lo, float hi) { unsigned r; asm volatile("v_cvt_pk_bf16_f32 %0, %1, %2" : "=v"(r) : "v"(lo), "v"(hi)); return r; }
; #define PG8_STAGE(bufoff, gbase, voff) do { _Pragma("unroll") for (int _i = 0; _i < 2; ++_i) \
;         __builtin_amdgcn_global_load_lds((const unsigned*)((const char*)(gbase) + (voff)[_i]), (LAS unsigned*)(lds + (bufoff) + ldsw + _i * 8192), 16, 0, 0); } while (0)
; #define PG8_LDA(dst, b, h) do { _Pragma("unroll") for (int m = 0; m < 4; ++m) _Pragma("unroll") for (int k = 0; k < 2; ++k) dst[m][k] = *(const LAS bf16x8*)(lds + PG8_SA(b, h) + aoff + m * 2048 + k * 1024); } while (0)
; #define PG8_LDB(dst, b, h) do { _Pragma("unroll") for (int n = 0; n < 2; ++n) _Pragma("unroll") for (int k = 0; k < 2; ++k) dst[n][k] = *(const LAS bf16x8*)(lds + PG8_SB(b, h) + boff + n * 2048 + k * 1024); } while (0)
; #define PG8_WAIT_V(n) asm volatile("s_waitcnt vmcnt(" #n ")" ::: "memory")
; template <class Epi>
; __device__ __forceinline__ void gemm_phase(LAS unsigned char* lds, const Gemm g, const StaticOrder& S, const Epi& E) {
;     ...
;             PG8_WAIT_L(8); PG8_BAR; PG8_WAIT_L(0); PG8_MMA(0, 0, At, B0); PG8_BAR; PG8_SCHED;
;             PG8_LDB(B1, 1, 1); PG8_STAGE(PG8_SB(1, 0), b3, voffB);
;             PG8_BAR; PG8_WAIT_L(0); PG8_MMA(0, 1, At, B1); PG8_BAR;
;             PG8_LDA(At, 1, 1); PG8_STAGE(PG8_SA(1, 0), a3, voffA);
;             PG8_BAR; PG8_WAIT_L(0); PG8_MMA(1, 0, At, B0); PG8_BAR; PG8_SCHED;
;             PG8_STAGE(PG8_SB(1, 1), b3 + hstepB, voffB);
;             PG8_WAIT_V(6); PG8_BAR; PG8_MMA(1, 1, At, B1); PG8_BAR;
;     __device__ __forceinline__ void operator()(const f32x4 (&acc)[2][2][4][2], const Unit& u, int wr, int wc, int fr, int fq, const Pre& pp) const {
;     ...
;             for (int m = 0; m < 4; ++m) { const int r = row0 + ai * HALF + m * 16; const float inv = rsqrtf(rs[ai * 4 + m] * (1.0f / DM) + EPS);
; #pragma unroll
;                 for (int bj = 0; bj < 2; ++bj) { const f32x4 v0 = acc[ai][bj][m][0] * inv, v1 = acc[ai][bj][m][1] * inv; const int c = col0 + bj * HALF;
;                     u32x4 w; w.x = cvt_pk_bf16(v0[0], v0[1]); w.y = cvt_pk_bf16(v0[2], v0[3]); w.z = cvt_pk_bf16(v1[0], v1[1]); w.w = cvt_pk_bf16(v1[2], v1[3]);
;                     bf16_t* dst = gm ? UG + (size_t)(c >> 4) * GSTR + r * 16 + (c & 15) : O + (size_t)r * DE2 + c;
	s_waitcnt lgkmcnt(0)
	v_mfma_f32_16x16x32_bf16 v[126:129], v[146:149], v[174:177], v[126:129]
	v_mfma_f32_16x16x32_bf16 v[122:125], v[166:169], v[174:177], v[122:125]
	v_mfma_f32_16x16x32_bf16 v[110:113], v[146:149], v[192:195], v[110:113]
	v_mfma_f32_16x16x32_bf16 v[106:109], v[166:169], v[192:195], v[106:109]
	v_mfma_f32_16x16x32_bf16 v[94:97], v[146:149], v[200:203], v[94:97]
	v_mfma_f32_16x16x32_bf16 v[90:93], v[166:169], v[200:203], v[90:93]
	v_mfma_f32_16x16x32_bf16 v[78:81], v[146:149], v[208:211], v[78:81]
	v_mfma_f32_16x16x32_bf16 v[74:77], v[166:169], v[208:211], v[74:77]
	v_mfma_f32_16x16x32_bf16 v[126:129], v[162:165], v[188:191], v[126:129]
	v_mfma_f32_16x16x32_bf16 v[122:125], v[170:173], v[188:191], v[122:125]
	v_mfma_f32_16x16x32_bf16 v[110:113], v[162:165], v[196:199], v[110:113]
	v_mfma_f32_16x16x32_bf16 v[106:109], v[170:173], v[196:199], v[106:109]
	v_mfma_f32_16x16x32_bf16 v[94:97], v[162:165], v[204:207], v[94:97]
	v_mfma_f32_16x16x32_bf16 v[90:93], v[170:173], v[204:207], v[90:93]
	v_mfma_f32_16x16x32_bf16 v[78:81], v[162:165], v[212:215], v[78:81]
	v_mfma_f32_16x16x32_bf16 v[74:77], v[170:173], v[212:215], v[74:77]
	s_barrier
	s_add_i32 s24, 0, 0x1c000
	s_add_i32 s25, s38, s45
	s_mov_b32 m0, s25
	ds_read_b128 v[216:219], v250 offset:49152
	ds_read_b128 v[220:223], v250 offset:50176
	ds_read_b128 v[224:227], v250 offset:51200
	ds_read_b128 v[228:231], v250 offset:52224
	global_load_lds_dwordx4 v134, s[100:101]
	s_add_i32 m0, s25, 0x2000
	s_nop 0
	global_load_lds_dwordx4 v130, s[100:101]
	s_barrier
	s_waitcnt lgkmcnt(0)
	v_mfma_f32_16x16x32_bf16 v[118:121], v[216:219], v[174:177], v[118:121]
	v_mfma_f32_16x16x32_bf16 v[114:117], v[224:227], v[174:177], v[114:117]
	v_mfma_f32_16x16x32_bf16 v[102:105], v[216:219], v[192:195], v[102:105]
	v_mfma_f32_16x16x32_bf16 v[98:101], v[224:227], v[192:195], v[98:101]
	v_mfma_f32_16x16x32_bf16 v[86:89], v[216:219], v[200:203], v[86:89]
	v_mfma_f32_16x16x32_bf16 v[82:85], v[224:227], v[200:203], v[82:85]
	v_mfma_f32_16x16x32_bf16 v[70:73], v[216:219], v[208:211], v[70:73]
	v_mfma_f32_16x16x32_bf16 v[66:69], v[224:227], v[208:211], v[66:69]
	v_mfma_f32_16x16x32_bf16 v[118:121], v[220:223], v[188:191], v[118:121]
	v_mfma_f32_16x16x32_bf16 v[114:117], v[228:231], v[188:191], v[114:117]
	v_mfma_f32_16x16x32_bf16 v[102:105], v[220:223], v[196:199], v[102:105]
	v_mfma_f32_16x16x32_bf16 v[98:101], v[228:231], v[196:199], v[98:101]
	v_mfma_f32_16x16x32_bf16 v[86:89], v[220:223], v[204:207], v[86:89]
	v_mfma_f32_16x16x32_bf16 v[82:85], v[228:231], v[204:207], v[82:85]
	v_mfma_f32_16x16x32_bf16 v[70:73], v[220:223], v[212:215], v[70:73]
	v_mfma_f32_16x16x32_bf16 v[66:69], v[228:231], v[212:215], v[66:69]
	s_mov_b32 m0, s50
	s_barrier
	ds_read_b128 v[174:177], v154 offset:49152
	ds_read_b128 v[188:191], v154 offset:50176
	ds_read_b128 v[192:195], v154 offset:51200
	ds_read_b128 v[196:199], v154 offset:52224
	ds_read_b128 v[200:203], v154 offset:53248
	ds_read_b128 v[204:207], v154 offset:54272
	ds_read_b128 v[208:211], v154 offset:55296
	ds_read_b128 v[212:215], v154 offset:56320
	global_load_lds_dwordx4 v136, vcc
	s_mov_b32 m0, s51
	s_nop 0
	global_load_lds_dwordx4 v132, vcc
	s_barrier
	s_waitcnt lgkmcnt(0)
	v_mfma_f32_16x16x32_bf16 v[62:65], v[146:149], v[174:177], v[62:65]
	v_mfma_f32_16x16x32_bf16 v[58:61], v[166:169], v[174:177], v[58:61]
	v_mfma_f32_16x16x32_bf16 v[46:49], v[146:149], v[192:195], v[46:49]
	v_mfma_f32_16x16x32_bf16 v[42:45], v[166:169], v[192:195], v[42:45]
	v_mfma_f32_16x16x32_bf16 v[30:33], v[146:149], v[200:203], v[30:33]
	v_mfma_f32_16x16x32_bf16 v[26:29], v[166:169], v[200:203], v[26:29]
	v_mfma_f32_16x16x32_bf16 v[14:17], v[146:149], v[208:211], v[14:17]
	v_mfma_f32_16x16x32_bf16 v[10:13], v[166:169], v[208:211], v[10:13]
	v_mfma_f32_16x16x32_bf16 v[62:65], v[162:165], v[188:191], v[62:65]
	v_mfma_f32_16x16x32_bf16 v[58:61], v[170:173], v[188:191], v[58:61]
	v_mfma_f32_16x16x32_bf16 v[46:49], v[162:165], v[196:199], v[46:49]
	v_mfma_f32_16x16x32_bf16 v[42:45], v[170:173], v[196:199], v[42:45]
	v_mfma_f32_16x16x32_bf16 v[30:33], v[162:165], v[204:207], v[30:33]
	v_mfma_f32_16x16x32_bf16 v[26:29], v[170:173], v[204:207], v[26:29]
	v_mfma_f32_16x16x32_bf16 v[14:17], v[162:165], v[212:215], v[14:17]
	v_mfma_f32_16x16x32_bf16 v[10:13], v[170:173], v[212:215], v[10:13]
	s_barrier
	s_add_u32 s4, s4, 0x80080
	s_addc_u32 s5, s5, 0
	s_add_i32 s24, s24, s45
	s_mov_b32 m0, s24
	s_nop 0
	global_load_lds_dwordx4 v134, s[4:5]
	s_add_i32 m0, s24, 0x2000
	s_nop 0
	global_load_lds_dwordx4 v130, s[4:5]
	s_waitcnt vmcnt(6)
	s_barrier
	v_mfma_f32_16x16x32_bf16 v[54:57], v[216:219], v[174:177], v[54:57]
	v_mfma_f32_16x16x32_bf16 v[50:53], v[224:227], v[174:177], v[50:53]
	v_mfma_f32_16x16x32_bf16 v[38:41], v[216:219], v[192:195], v[38:41]
	v_mfma_f32_16x16x32_bf16 v[34:37], v[224:227], v[192:195], v[34:37]
	v_mfma_f32_16x16x32_bf16 v[22:25], v[216:219], v[200:203], v[22:25]
	v_mfma_f32_16x16x32_bf16 v[18:21], v[224:227], v[200:203], v[18:21]
	v_mfma_f32_16x16x32_bf16 v[6:9], v[216:219], v[208:211], v[6:9]
	v_mfma_f32_16x16x32_bf16 v[2:5], v[224:227], v[208:211], v[2:5]
	v_mfma_f32_16x16x32_bf16 v[54:57], v[220:223], v[188:191], v[54:57]
	v_mfma_f32_16x16x32_bf16 v[50:53], v[228:231], v[188:191], v[50:53]
	v_mfma_f32_16x16x32_bf16 v[38:41], v[220:223], v[196:199], v[38:41]
	v_mfma_f32_16x16x32_bf16 v[34:37], v[228:231], v[196:199], v[34:37]
	v_mfma_f32_16x16x32_bf16 v[22:25], v[220:223], v[204:207], v[22:25]
	v_mfma_f32_16x16x32_bf16 v[18:21], v[228:231], v[204:207], v[18:21]
	v_mfma_f32_16x16x32_bf16 v[6:9], v[220:223], v[212:215], v[6:9]
	v_mfma_f32_16x16x32_bf16 v[2:5], v[228:231], v[212:215], v[2:5]
	s_add_i32 s59, s59, 2
	s_add_u32 s57, s57, 0x100
	s_addc_u32 s58, s58, 0
	s_cmp_gt_u32 s59, 29
	s_mov_b64 s[38:39], s[42:43]
	s_barrier
	s_cbranch_scc0 .LBB0_158
	v_fmamk_f32 v0, v145, 0x3a000000, v233
	v_cmp_gt_f32_e32 vcc, s66, v0
	v_mul_f32_e32 v145, 0x4b800000, v0
	v_readlane_b32 s38, v254, 47
	v_cndmask_b32_e32 v0, v0, v145, vcc
	v_rsq_f32_e32 v0, v0
	v_lshl_add_u32 v146, s54, 8, v139
	s_cmp_gt_i32 s53, 15
	v_readlane_b32 s39, v254, 48
	v_mul_f32_e32 v145, 0x45800000, v0
	s_cselect_b64 s[4:5], -1, 0
	s_xor_b64 s[38:39], s[38:39], -1
	v_cndmask_b32_e32 v148, v0, v145, vcc
	v_ashrrev_i32_e32 v147, 31, v146
	s_or_b64 s[4:5], s[38:39], s[4:5]
	v_lshl_or_b32 v144, s53, 8, v153
	v_lshlrev_b64 v[150:151], 14, v[146:147]
	v_pk_mul_f32 v[128:129], v[148:149], v[128:129] op_sel_hi:[0,1]
	s_mov_b64 s[24:25], -1
	v_pk_mul_f32 v[126:127], v[148:149], v[126:127] op_sel_hi:[0,1]
	v_pk_mul_f32 v[162:163], v[148:149], v[124:125] op_sel_hi:[0,1]
	v_pk_mul_f32 v[124:125], v[148:149], v[122:123] op_sel_hi:[0,1]
	v_cvt_pk_bf16_f32 v122, v126, v127
	v_cvt_pk_bf16_f32 v123, v128, v129
	s_and_b64 vcc, exec, s[4:5]
	v_lshl_add_u64 v[128:129], s[16:17], 0, v[150:151]
	v_ashrrev_i32_e32 v145, 31, v144
	v_cvt_pk_bf16_f32 v124, v124, v125
	v_cvt_pk_bf16_f32 v125, v162, v163
	s_cbranch_vccz .LBB0_161
	v_lshl_add_u64 v[150:151], v[144:145], 1, v[128:129]
	s_mov_b64 s[24:25], 0

; #define PG8_STAGE(bufoff, gbase, voff) do { _Pragma("unroll") for (int _i = 0; _i < 2; ++_i) \
;         __builtin_amdgcn_global_load_lds((const unsigned*)((const char*)(gbase) + (voff)[_i]), (LAS unsigned*)(lds + (bufoff) + ldsw + _i * 8192), 16, 0, 0); } while (0)
; #define PG8_LDA(dst, b, h) do { _Pragma("unroll") for (int m = 0; m < 4; ++m) _Pragma("unroll") for (int k = 0; k < 2; ++k) dst[m][k] = *(const LAS bf16x8*)(lds + PG8_SA(b, h) + aoff + m * 2048 + k * 1024); } while (0)
; #define PG8_LDB(dst, b, h) do { _Pragma("unroll") for (int n = 0; n < 2; ++n) _Pragma("unroll") for (int k = 0; k < 2; ++k) dst[n][k] = *(const LAS bf16x8*)(lds + PG8_SB(b, h) + boff + n * 2048 + k * 1024); } while (0)
; #define PG8_MMA(ai, bj, At, Bt) do { __builtin_amdgcn_s_setprio(1); _Pragma("unroll") for (int m = 0; m < 4; ++m) _Pragma("unroll") for (int n = 0; n < 2; ++n) _Pragma("unroll") for (int k = 0; k < 2; ++k) \
;         acc[ai][bj][m][n] = __builtin_amdgcn_mfma_f32_16x16x32_bf16(Bt[n][k], At[m][k], acc[ai][bj][m][n], 0, 0, 0); __builtin_amdgcn_s_setprio(0); } while (0)
; #define PG8_WAIT_L(n) asm volatile("s_waitcnt lgkmcnt(" #n ")" ::: "memory")
; #define PG8_BAR __builtin_amdgcn_s_barrier()
; #define PG8_SCHED __builtin_amdgcn_sched_barrier(0)
; template <class Epi>
; __device__ __forceinline__ void gemm_phase(LAS unsigned char* lds, const Gemm g, const StaticOrder& S, const Epi& E) {
;     ...
;         const bool has_next = S.next(ui + 1, nxt);
;         const char* nA = has_next ? (const char*)g.A + (size_t)nxt.pm * tstepA + (size_t)(nxt.pn >> 2) * gstepA : cA; const char* nB = has_next ? (const char*)g.Bt + (size_t)nxt.pn * tstepB : cB;
;         for (int t = 0; t < nt; t += 2) {
;             const bool last = (t == nt - 2);
;             const char* a1 = cA + (size_t)(t + 1) * kstepA;
;             const char* a2 = last ? nA : cA + (size_t)(t + 2) * kstepA; const char* b2 = last ? nB : cB + (size_t)(t + 2) * kstep;
;             const char* a3 = a2 + kstepA; const char* b3 = b2 + kstep;
;             PG8_LDB(B0, 0, 0); PG8_SCHED; PG8_LDA(At, 0, 0); PG8_STAGE(PG8_SA(1, 1), a1 + hstepA, voffA);
;             PG8_WAIT_L(8); PG8_BAR; PG8_WAIT_L(0); PG8_MMA(0, 0, At, B0); PG8_BAR; PG8_SCHED;
.LBB0_358:
	v_mov_b64_e32 v[2:3], 0x100
	s_ashr_i32 s17, s16, 31
	v_cmp_lt_i64_e32 vcc, s[18:19], v[2:3]
	s_lshl_b64 s[18:19], s[16:17], 21
	s_add_u32 s18, s38, s18
	s_addc_u32 s19, s39, s19
	s_and_b64 s[20:21], vcc, exec
	s_cselect_b32 s17, s19, s23
	s_cselect_b32 s60, s18, s22
	s_ashr_i32 s15, s14, 31
	s_lshl_b64 s[20:21], s[14:15], 21
	s_add_u32 s20, s46, s20
	s_addc_u32 s21, s47, s21
	s_and_b64 s[24:25], vcc, exec
	s_cselect_b32 s15, s21, s27
	s_cselect_b32 s61, s20, s26
	s_add_u32 s62, s26, 0x100
	v_mov_b32_e32 v2, 0
	s_addc_u32 s63, s27, 0
	s_mov_b32 s64, -2
	v_mov_b32_e32 v3, v2
	v_mov_b32_e32 v4, v2
	v_mov_b32_e32 v5, v2
	v_mov_b32_e32 v6, v2
	v_mov_b32_e32 v7, v2
	v_mov_b32_e32 v8, v2
	v_mov_b32_e32 v9, v2
	v_mov_b32_e32 v18, v2
	v_mov_b32_e32 v19, v2
	v_mov_b32_e32 v20, v2
	v_mov_b32_e32 v21, v2
	v_mov_b32_e32 v22, v2
	v_mov_b32_e32 v23, v2
	v_mov_b32_e32 v24, v2
	v_mov_b32_e32 v25, v2
	v_mov_b32_e32 v34, v2
	v_mov_b32_e32 v35, v2
	v_mov_b32_e32 v36, v2
	v_mov_b32_e32 v37, v2
	v_mov_b32_e32 v38, v2
	v_mov_b32_e32 v39, v2
	v_mov_b32_e32 v40, v2
	v_mov_b32_e32 v41, v2
	v_mov_b32_e32 v50, v2
	v_mov_b32_e32 v51, v2
	v_mov_b32_e32 v52, v2
	v_mov_b32_e32 v53, v2
	v_mov_b32_e32 v54, v2
	v_mov_b32_e32 v55, v2
	v_mov_b32_e32 v56, v2
	v_mov_b32_e32 v57, v2
	v_mov_b32_e32 v10, v2
	v_mov_b32_e32 v11, v2
	v_mov_b32_e32 v12, v2
	v_mov_b32_e32 v13, v2
	v_mov_b32_e32 v14, v2
	v_mov_b32_e32 v15, v2
	v_mov_b32_e32 v16, v2
	v_mov_b32_e32 v17, v2
	v_mov_b32_e32 v26, v2
	v_mov_b32_e32 v27, v2
	v_mov_b32_e32 v28, v2
	v_mov_b32_e32 v29, v2
	v_mov_b32_e32 v30, v2
	v_mov_b32_e32 v31, v2
	v_mov_b32_e32 v32, v2
	v_mov_b32_e32 v33, v2
	v_mov_b32_e32 v42, v2
	v_mov_b32_e32 v43, v2
	v_mov_b32_e32 v44, v2
	v_mov_b32_e32 v45, v2
	v_mov_b32_e32 v46, v2
	v_mov_b32_e32 v47, v2
	v_mov_b32_e32 v48, v2
	v_mov_b32_e32 v49, v2
	v_mov_b32_e32 v58, v2
	v_mov_b32_e32 v59, v2
	v_mov_b32_e32 v60, v2
	v_mov_b32_e32 v61, v2
	v_mov_b32_e32 v62, v2
	v_mov_b32_e32 v63, v2
	v_mov_b32_e32 v64, v2
	v_mov_b32_e32 v65, v2
	v_mov_b32_e32 v66, v2
	v_mov_b32_e32 v67, v2
	v_mov_b32_e32 v68, v2
	v_mov_b32_e32 v69, v2
	v_mov_b32_e32 v78, v2
	v_mov_b32_e32 v79, v2
	v_mov_b32_e32 v80, v2
	v_mov_b32_e32 v81, v2
	v_mov_b32_e32 v98, v2
	v_mov_b32_e32 v99, v2
	v_mov_b32_e32 v100, v2
	v_mov_b32_e32 v101, v2
	v_mov_b32_e32 v102, v2
	v_mov_b32_e32 v103, v2
	v_mov_b32_e32 v104, v2
	v_mov_b32_e32 v105, v2
	v_mov_b32_e32 v114, v2
	v_mov_b32_e32 v115, v2
	v_mov_b32_e32 v116, v2
	v_mov_b32_e32 v117, v2
	v_mov_b32_e32 v118, v2
	v_mov_b32_e32 v119, v2
	v_mov_b32_e32 v120, v2
	v_mov_b32_e32 v121, v2
	v_mov_b32_e32 v130, v2
	v_mov_b32_e32 v131, v2
	v_mov_b32_e32 v132, v2
	v_mov_b32_e32 v133, v2
	v_mov_b32_e32 v134, v2
	v_mov_b32_e32 v135, v2
	v_mov_b32_e32 v136, v2
	v_mov_b32_e32 v137, v2
	v_mov_b32_e32 v90, v2
	v_mov_b32_e32 v91, v2
	v_mov_b32_e32 v92, v2
	v_mov_b32_e32 v93, v2
	v_mov_b32_e32 v94, v2
	v_mov_b32_e32 v95, v2
	v_mov_b32_e32 v96, v2
	v_mov_b32_e32 v97, v2
	v_mov_b32_e32 v106, v2
	v_mov_b32_e32 v107, v2
	v_mov_b32_e32 v108, v2
	v_mov_b32_e32 v109, v2
	v_mov_b32_e32 v110, v2
	v_mov_b32_e32 v111, v2
	v_mov_b32_e32 v112, v2
	v_mov_b32_e32 v113, v2
	v_mov_b32_e32 v122, v2
	v_mov_b32_e32 v123, v2
	v_mov_b32_e32 v124, v2
	v_mov_b32_e32 v125, v2
	v_mov_b32_e32 v126, v2
	v_mov_b32_e32 v127, v2
	v_mov_b32_e32 v128, v2
	v_mov_b32_e32 v129, v2
	v_mov_b32_e32 v138, v2
	v_mov_b32_e32 v139, v2
	v_mov_b32_e32 v140, v2
	v_mov_b32_e32 v141, v2
	v_mov_b32_e32 v142, v2
	v_mov_b32_e32 v143, v2
	v_mov_b32_e32 v144, v2
	v_mov_b32_e32 v145, v2
	v_add_u32_e32 v250, 0x10000, v209
.LBB0_359:
	s_add_u32 s26, s22, 0x100
	s_addc_u32 s27, s23, 0
	s_add_i32 s65, 0, 0x10000
	ds_read_b128 v[70:73], v250
	ds_read_b128 v[74:77], v250 offset:1024
	ds_read_b128 v[82:85], v250 offset:2048
	ds_read_b128 v[86:89], v250 offset:3072
	s_cmp_eq_u32 s64, 60
	s_cselect_b32 s25, s17, s27
	s_cselect_b32 s24, s60, s26
	s_cselect_b32 s37, s15, s63
	s_cselect_b32 s36, s61, s62
	s_add_i32 m0, s53, 0xc000
	ds_read_b128 v[146:149], v211
	ds_read_b128 v[150:153], v211 offset:1024
	ds_read_b128 v[154:157], v211 offset:2048
	ds_read_b128 v[158:161], v211 offset:3072
	ds_read_b128 v[162:165], v211 offset:4096
	ds_read_b128 v[166:169], v211 offset:5120
	ds_read_b128 v[170:173], v211 offset:6144
	ds_read_b128 v[184:187], v211 offset:7168
	global_load_lds_dwordx4 v190, s[22:23]
	s_add_i32 m0, s53, 0xe000
	s_nop 0
	global_load_lds_dwordx4 v192, s[22:23]
	s_waitcnt lgkmcnt(8)
	s_barrier
	s_waitcnt lgkmcnt(0)
	v_mfma_f32_16x16x32_bf16 v[142:145], v[70:73], v[146:149], v[142:145]
	v_mfma_f32_16x16x32_bf16 v[138:141], v[82:85], v[146:149], v[138:141]
	v_mfma_f32_16x16x32_bf16 v[126:129], v[70:73], v[154:157], v[126:129]
	v_mfma_f32_16x16x32_bf16 v[122:125], v[82:85], v[154:157], v[122:125]
	v_mfma_f32_16x16x32_bf16 v[110:113], v[70:73], v[162:165], v[110:113]
	v_mfma_f32_16x16x32_bf16 v[106:109], v[82:85], v[162:165], v[106:109]
	v_mfma_f32_16x16x32_bf16 v[94:97], v[70:73], v[170:173], v[94:97]
	v_mfma_f32_16x16x32_bf16 v[90:93], v[82:85], v[170:173], v[90:93]
	v_mfma_f32_16x16x32_bf16 v[142:145], v[74:77], v[150:153], v[142:145]
	v_mfma_f32_16x16x32_bf16 v[138:141], v[86:89], v[150:153], v[138:141]
	v_mfma_f32_16x16x32_bf16 v[126:129], v[74:77], v[158:161], v[126:129]
	v_mfma_f32_16x16x32_bf16 v[122:125], v[86:89], v[158:161], v[122:125]
	v_mfma_f32_16x16x32_bf16 v[110:113], v[74:77], v[166:169], v[110:113]
	v_mfma_f32_16x16x32_bf16 v[106:109], v[86:89], v[166:169], v[106:109]
	v_mfma_f32_16x16x32_bf16 v[94:97], v[74:77], v[184:187], v[94:97]
	v_mfma_f32_16x16x32_bf16 v[90:93], v[86:89], v[184:187], v[90:93]
	s_barrier
; #define PG8_STAGE(bufoff, gbase, voff) do { _Pragma("unroll") for (int _i = 0; _i < 2; ++_i) \
;         __builtin_amdgcn_global_load_lds((const unsigned*)((const char*)(gbase) + (voff)[_i]), (LAS unsigned*)(lds + (bufoff) + ldsw + _i * 8192), 16, 0, 0); } while (0)
; #define PG8_LDA(dst, b, h) do { _Pragma("unroll") for (int m = 0; m < 4; ++m) _Pragma("unroll") for (int k = 0; k < 2; ++k) dst[m][k] = *(const LAS bf16x8*)(lds + PG8_SA(b, h) + aoff + m * 2048 + k * 1024); } while (0)
; #define PG8_LDB(dst, b, h) do { _Pragma("unroll") for (int n = 0; n < 2; ++n) _Pragma("unroll") for (int k = 0; k < 2; ++k) dst[n][k] = *(const LAS bf16x8*)(lds + PG8_SB(b, h) + boff + n * 2048 + k * 1024); } while (0)
; #define PG8_MMA(ai, bj, At, Bt) do { __builtin_amdgcn_s_setprio(1); _Pragma("unroll") for (int m = 0; m < 4; ++m) _Pragma("unroll") for (int n = 0; n < 2; ++n) _Pragma("unroll") for (int k = 0; k < 2; ++k) \
;         acc[ai][bj][m][n] = __builtin_amdgcn_mfma_f32_16x16x32_bf16(Bt[n][k], At[m][k], acc[ai][bj][m][n], 0, 0, 0); __builtin_amdgcn_s_setprio(0); } while (0)
; #define PG8_WAIT_V(n) asm volatile("s_waitcnt vmcnt(" #n ")" ::: "memory")
; #define PG8_WAIT_L(n) asm volatile("s_waitcnt lgkmcnt(" #n ")" ::: "memory")
; #define PG8_BAR __builtin_amdgcn_s_barrier()
; #define PG8_SCHED __builtin_amdgcn_sched_barrier(0)
; template <class Epi>
; __device__ __forceinline__ void gemm_phase(LAS unsigned char* lds, const Gemm g, const StaticOrder& S, const Epi& E) {
;     ...
;             PG8_LDB(B1, 0, 1); PG8_STAGE(PG8_SB(0, 0), b2, voffB);
;             PG8_BAR; PG8_WAIT_L(0); PG8_MMA(0, 1, At, B1); PG8_BAR;
;             PG8_LDA(At, 0, 1); PG8_STAGE(PG8_SA(0, 0), a2, voffA);
;             PG8_BAR; PG8_WAIT_L(0); PG8_MMA(1, 0, At, B0); PG8_BAR; PG8_SCHED;
;             PG8_STAGE(PG8_SB(0, 1), b2 + hstepB, voffB);
;             PG8_WAIT_V(6); PG8_BAR; PG8_MMA(1, 1, At, B1); PG8_BAR;
;             PG8_LDB(B0, 1, 0); PG8_SCHED; PG8_LDA(At, 1, 0); PG8_STAGE(PG8_SA(0, 1), a2 + hstepA, voffA);
	s_add_i32 s66, 0, 0x14000
	s_add_i32 s22, s65, s52
	ds_read_b128 v[194:197], v250 offset:16384
	ds_read_b128 v[198:201], v250 offset:17408
	ds_read_b128 v[202:205], v250 offset:18432
	ds_read_b128 v[212:215], v250 offset:19456
	s_add_u32 s100, s36, s6
	s_addc_u32 s101, s37, s7
	s_mov_b32 m0, s22
	s_nop 0
	global_load_lds_dwordx4 v0, s[36:37]
	s_add_i32 m0, s22, 0x2000
	s_nop 0
	global_load_lds_dwordx4 v174, s[36:37]
	s_barrier
	s_waitcnt lgkmcnt(0)
	v_mfma_f32_16x16x32_bf16 v[134:137], v[194:197], v[146:149], v[134:137]
	v_mfma_f32_16x16x32_bf16 v[130:133], v[202:205], v[146:149], v[130:133]
	v_mfma_f32_16x16x32_bf16 v[118:121], v[194:197], v[154:157], v[118:121]
	v_mfma_f32_16x16x32_bf16 v[114:117], v[202:205], v[154:157], v[114:117]
	v_mfma_f32_16x16x32_bf16 v[102:105], v[194:197], v[162:165], v[102:105]
	v_mfma_f32_16x16x32_bf16 v[98:101], v[202:205], v[162:165], v[98:101]
	v_mfma_f32_16x16x32_bf16 v[78:81], v[194:197], v[170:173], v[78:81]
	v_mfma_f32_16x16x32_bf16 v[66:69], v[202:205], v[170:173], v[66:69]
	v_mfma_f32_16x16x32_bf16 v[134:137], v[198:201], v[150:153], v[134:137]
	v_mfma_f32_16x16x32_bf16 v[130:133], v[212:215], v[150:153], v[130:133]
	v_mfma_f32_16x16x32_bf16 v[118:121], v[198:201], v[158:161], v[118:121]
	v_mfma_f32_16x16x32_bf16 v[114:117], v[212:215], v[158:161], v[114:117]
	v_mfma_f32_16x16x32_bf16 v[102:105], v[198:201], v[166:169], v[102:105]
	v_mfma_f32_16x16x32_bf16 v[98:101], v[212:215], v[166:169], v[98:101]
	v_mfma_f32_16x16x32_bf16 v[78:81], v[198:201], v[184:187], v[78:81]
	v_mfma_f32_16x16x32_bf16 v[66:69], v[212:215], v[184:187], v[66:69]
	s_mov_b32 m0, s53
	s_add_u32 vcc_lo, s24, s6
	s_addc_u32 vcc_hi, s25, s7
	s_barrier
	ds_read_b128 v[146:149], v211 offset:16384
	ds_read_b128 v[150:153], v211 offset:17408
	ds_read_b128 v[154:157], v211 offset:18432
	ds_read_b128 v[158:161], v211 offset:19456
	ds_read_b128 v[162:165], v211 offset:20480
	ds_read_b128 v[166:169], v211 offset:21504
	ds_read_b128 v[170:173], v211 offset:22528
	ds_read_b128 v[184:187], v211 offset:23552
	global_load_lds_dwordx4 v188, s[24:25]
	s_mov_b32 m0, s54
	s_nop 0
	global_load_lds_dwordx4 v176, s[24:25]
	s_barrier
	s_waitcnt lgkmcnt(0)
	v_mfma_f32_16x16x32_bf16 v[62:65], v[70:73], v[146:149], v[62:65]
	v_mfma_f32_16x16x32_bf16 v[58:61], v[82:85], v[146:149], v[58:61]
	v_mfma_f32_16x16x32_bf16 v[46:49], v[70:73], v[154:157], v[46:49]
	v_mfma_f32_16x16x32_bf16 v[42:45], v[82:85], v[154:157], v[42:45]
	v_mfma_f32_16x16x32_bf16 v[30:33], v[70:73], v[162:165], v[30:33]
	v_mfma_f32_16x16x32_bf16 v[26:29], v[82:85], v[162:165], v[26:29]
	v_mfma_f32_16x16x32_bf16 v[14:17], v[70:73], v[170:173], v[14:17]
	v_mfma_f32_16x16x32_bf16 v[10:13], v[82:85], v[170:173], v[10:13]
	v_mfma_f32_16x16x32_bf16 v[62:65], v[74:77], v[150:153], v[62:65]
	v_mfma_f32_16x16x32_bf16 v[58:61], v[86:89], v[150:153], v[58:61]
	v_mfma_f32_16x16x32_bf16 v[46:49], v[74:77], v[158:161], v[46:49]
	v_mfma_f32_16x16x32_bf16 v[42:45], v[86:89], v[158:161], v[42:45]
	v_mfma_f32_16x16x32_bf16 v[30:33], v[74:77], v[166:169], v[30:33]
	v_mfma_f32_16x16x32_bf16 v[26:29], v[86:89], v[166:169], v[26:29]
	v_mfma_f32_16x16x32_bf16 v[14:17], v[74:77], v[184:187], v[14:17]
	v_mfma_f32_16x16x32_bf16 v[10:13], v[86:89], v[184:187], v[10:13]
	s_barrier
	s_add_u32 s22, s36, 0x100000
	s_addc_u32 s23, s37, 0
	s_add_i32 s65, s66, s52
	s_mov_b32 m0, s65
	s_nop 0
	global_load_lds_dwordx4 v0, s[22:23]
	s_add_i32 m0, s65, 0x2000
	s_nop 0
	global_load_lds_dwordx4 v174, s[22:23]
	s_waitcnt vmcnt(6)
	s_barrier
	v_mfma_f32_16x16x32_bf16 v[54:57], v[194:197], v[146:149], v[54:57]
	v_mfma_f32_16x16x32_bf16 v[50:53], v[202:205], v[146:149], v[50:53]
	v_mfma_f32_16x16x32_bf16 v[38:41], v[194:197], v[154:157], v[38:41]
	v_mfma_f32_16x16x32_bf16 v[34:37], v[202:205], v[154:157], v[34:37]
	v_mfma_f32_16x16x32_bf16 v[22:25], v[194:197], v[162:165], v[22:25]
	v_mfma_f32_16x16x32_bf16 v[18:21], v[202:205], v[162:165], v[18:21]
	v_mfma_f32_16x16x32_bf16 v[6:9], v[194:197], v[170:173], v[6:9]
	v_mfma_f32_16x16x32_bf16 v[2:5], v[202:205], v[170:173], v[2:5]
	v_mfma_f32_16x16x32_bf16 v[54:57], v[198:201], v[150:153], v[54:57]
	v_mfma_f32_16x16x32_bf16 v[50:53], v[212:215], v[150:153], v[50:53]
	v_mfma_f32_16x16x32_bf16 v[38:41], v[198:201], v[158:161], v[38:41]
	v_mfma_f32_16x16x32_bf16 v[34:37], v[212:215], v[158:161], v[34:37]
	v_mfma_f32_16x16x32_bf16 v[22:25], v[198:201], v[166:169], v[22:25]
	v_mfma_f32_16x16x32_bf16 v[18:21], v[212:215], v[166:169], v[18:21]
	v_mfma_f32_16x16x32_bf16 v[6:9], v[198:201], v[184:187], v[6:9]
	v_mfma_f32_16x16x32_bf16 v[2:5], v[212:215], v[184:187], v[2:5]
	s_add_i32 s65, 0, 0x18000
	s_barrier
	ds_read_b128 v[70:73], v250 offset:32768
	ds_read_b128 v[74:77], v250 offset:33792
	ds_read_b128 v[82:85], v250 offset:34816
	ds_read_b128 v[86:89], v250 offset:35840
	s_add_u32 s22, s24, 0x100000
	s_addc_u32 s23, s25, 0
	s_mov_b32 m0, s55
	ds_read_b128 v[146:149], v211 offset:32768
	ds_read_b128 v[150:153], v211 offset:33792
	ds_read_b128 v[154:157], v211 offset:34816
	ds_read_b128 v[158:161], v211 offset:35840
	ds_read_b128 v[162:165], v211 offset:36864
	ds_read_b128 v[166:169], v211 offset:37888
	ds_read_b128 v[170:173], v211 offset:38912
	ds_read_b128 v[184:187], v211 offset:39936
	global_load_lds_dwordx4 v188, s[22:23]
	s_mov_b32 m0, s56
	s_nop 0
	global_load_lds_dwordx4 v176, s[22:23]
	s_waitcnt lgkmcnt(8)
	s_barrier
; #define PG8_STAGE(bufoff, gbase, voff) do { _Pragma("unroll") for (int _i = 0; _i < 2; ++_i) \
;         __builtin_amdgcn_global_load_lds((const unsigned*)((const char*)(gbase) + (voff)[_i]), (LAS unsigned*)(lds + (bufoff) + ldsw + _i * 8192), 16, 0, 0); } while (0)
; #define PG8_LDA(dst, b, h) do { _Pragma("unroll") for (int m = 0; m < 4; ++m) _Pragma("unroll") for (int k = 0; k < 2; ++k) dst[m][k] = *(const LAS bf16x8*)(lds + PG8_SA(b, h) + aoff + m * 2048 + k * 1024); } while (0)
; #define PG8_LDB(dst, b, h) do { _Pragma("unroll") for (int n = 0; n < 2; ++n) _Pragma("unroll") for (int k = 0; k < 2; ++k) dst[n][k] = *(const LAS bf16x8*)(lds + PG8_SB(b, h) + boff + n * 2048 + k * 1024); } while (0)
; #define PG8_MMA(ai, bj, At, Bt) do { __builtin_amdgcn_s_setprio(1); _Pragma("unroll") for (int m = 0; m < 4; ++m) _Pragma("unroll") for (int n = 0; n < 2; ++n) _Pragma("unroll") for (int k = 0; k < 2; ++k) \
;         acc[ai][bj][m][n] = __builtin_amdgcn_mfma_f32_16x16x32_bf16(Bt[n][k], At[m][k], acc[ai][bj][m][n], 0, 0, 0); __builtin_amdgcn_s_setprio(0); } while (0)
; #define PG8_WAIT_L(n) asm volatile("s_waitcnt lgkmcnt(" #n ")" ::: "memory")
; #define PG8_BAR __builtin_amdgcn_s_barrier()
; #define PG8_SCHED __builtin_amdgcn_sched_barrier(0)
; template <class Epi>
; __device__ __forceinline__ void gemm_phase(LAS unsigned char* lds, const Gemm g, const StaticOrder& S, const Epi& E) {
;     ...
;             PG8_WAIT_L(8); PG8_BAR; PG8_WAIT_L(0); PG8_MMA(0, 0, At, B0); PG8_BAR; PG8_SCHED;
;             PG8_LDB(B1, 1, 1); PG8_STAGE(PG8_SB(1, 0), b3, voffB);
;             PG8_BAR; PG8_WAIT_L(0); PG8_MMA(0, 1, At, B1); PG8_BAR;
;             PG8_LDA(At, 1, 1); PG8_STAGE(PG8_SA(1, 0), a3, voffA);
;             PG8_BAR; PG8_WAIT_L(0); PG8_MMA(1, 0, At, B0); PG8_BAR; PG8_SCHED;
	s_waitcnt lgkmcnt(0)
	v_mfma_f32_16x16x32_bf16 v[142:145], v[70:73], v[146:149], v[142:145]
	v_mfma_f32_16x16x32_bf16 v[138:141], v[82:85], v[146:149], v[138:141]
	v_mfma_f32_16x16x32_bf16 v[126:129], v[70:73], v[154:157], v[126:129]
	v_mfma_f32_16x16x32_bf16 v[122:125], v[82:85], v[154:157], v[122:125]
	v_mfma_f32_16x16x32_bf16 v[110:113], v[70:73], v[162:165], v[110:113]
	v_mfma_f32_16x16x32_bf16 v[106:109], v[82:85], v[162:165], v[106:109]
	v_mfma_f32_16x16x32_bf16 v[94:97], v[70:73], v[170:173], v[94:97]
	v_mfma_f32_16x16x32_bf16 v[90:93], v[82:85], v[170:173], v[90:93]
	v_mfma_f32_16x16x32_bf16 v[142:145], v[74:77], v[150:153], v[142:145]
	v_mfma_f32_16x16x32_bf16 v[138:141], v[86:89], v[150:153], v[138:141]
	v_mfma_f32_16x16x32_bf16 v[126:129], v[74:77], v[158:161], v[126:129]
	v_mfma_f32_16x16x32_bf16 v[122:125], v[86:89], v[158:161], v[122:125]
	v_mfma_f32_16x16x32_bf16 v[110:113], v[74:77], v[166:169], v[110:113]
	v_mfma_f32_16x16x32_bf16 v[106:109], v[86:89], v[166:169], v[106:109]
	v_mfma_f32_16x16x32_bf16 v[94:97], v[74:77], v[184:187], v[94:97]
	v_mfma_f32_16x16x32_bf16 v[90:93], v[86:89], v[184:187], v[90:93]
	s_barrier
	s_add_i32 s24, 0, 0x1c000
	s_add_i32 s22, s65, s52
	s_mov_b32 m0, s22
	ds_read_b128 v[194:197], v250 offset:49152
	ds_read_b128 v[198:201], v250 offset:50176
	ds_read_b128 v[202:205], v250 offset:51200
	ds_read_b128 v[212:215], v250 offset:52224
	global_load_lds_dwordx4 v0, s[100:101]
	s_add_i32 m0, s22, 0x2000
	s_nop 0
	global_load_lds_dwordx4 v174, s[100:101]
	s_barrier
	s_waitcnt lgkmcnt(0)
	v_mfma_f32_16x16x32_bf16 v[134:137], v[194:197], v[146:149], v[134:137]
	v_mfma_f32_16x16x32_bf16 v[130:133], v[202:205], v[146:149], v[130:133]
	v_mfma_f32_16x16x32_bf16 v[118:121], v[194:197], v[154:157], v[118:121]
	v_mfma_f32_16x16x32_bf16 v[114:117], v[202:205], v[154:157], v[114:117]
	v_mfma_f32_16x16x32_bf16 v[102:105], v[194:197], v[162:165], v[102:105]
	v_mfma_f32_16x16x32_bf16 v[98:101], v[202:205], v[162:165], v[98:101]
	v_mfma_f32_16x16x32_bf16 v[78:81], v[194:197], v[170:173], v[78:81]
	v_mfma_f32_16x16x32_bf16 v[66:69], v[202:205], v[170:173], v[66:69]
	v_mfma_f32_16x16x32_bf16 v[134:137], v[198:201], v[150:153], v[134:137]
	v_mfma_f32_16x16x32_bf16 v[130:133], v[212:215], v[150:153], v[130:133]
	v_mfma_f32_16x16x32_bf16 v[118:121], v[198:201], v[158:161], v[118:121]
	v_mfma_f32_16x16x32_bf16 v[114:117], v[212:215], v[158:161], v[114:117]
	v_mfma_f32_16x16x32_bf16 v[102:105], v[198:201], v[166:169], v[102:105]
	v_mfma_f32_16x16x32_bf16 v[98:101], v[212:215], v[166:169], v[98:101]
	v_mfma_f32_16x16x32_bf16 v[78:81], v[198:201], v[184:187], v[78:81]
	v_mfma_f32_16x16x32_bf16 v[66:69], v[212:215], v[184:187], v[66:69]
	s_mov_b32 m0, s58
	s_barrier
	ds_read_b128 v[146:149], v211 offset:49152
	ds_read_b128 v[150:153], v211 offset:50176
	ds_read_b128 v[154:157], v211 offset:51200
	ds_read_b128 v[158:161], v211 offset:52224
	ds_read_b128 v[162:165], v211 offset:53248
	ds_read_b128 v[166:169], v211 offset:54272
	ds_read_b128 v[170:173], v211 offset:55296
	ds_read_b128 v[184:187], v211 offset:56320
	global_load_lds_dwordx4 v188, vcc
	s_mov_b32 m0, s59
	s_nop 0
	global_load_lds_dwordx4 v176, vcc
	s_barrier
	s_waitcnt lgkmcnt(0)
	v_mfma_f32_16x16x32_bf16 v[62:65], v[70:73], v[146:149], v[62:65]
	v_mfma_f32_16x16x32_bf16 v[58:61], v[82:85], v[146:149], v[58:61]
	v_mfma_f32_16x16x32_bf16 v[46:49], v[70:73], v[154:157], v[46:49]
	v_mfma_f32_16x16x32_bf16 v[42:45], v[82:85], v[154:157], v[42:45]
	v_mfma_f32_16x16x32_bf16 v[30:33], v[70:73], v[162:165], v[30:33]
	v_mfma_f32_16x16x32_bf16 v[26:29], v[82:85], v[162:165], v[26:29]
	v_mfma_f32_16x16x32_bf16 v[14:17], v[70:73], v[170:173], v[14:17]
	v_mfma_f32_16x16x32_bf16 v[10:13], v[82:85], v[170:173], v[10:13]
	v_mfma_f32_16x16x32_bf16 v[62:65], v[74:77], v[150:153], v[62:65]
	v_mfma_f32_16x16x32_bf16 v[58:61], v[86:89], v[150:153], v[58:61]
	v_mfma_f32_16x16x32_bf16 v[46:49], v[74:77], v[158:161], v[46:49]
	v_mfma_f32_16x16x32_bf16 v[42:45], v[86:89], v[158:161], v[42:45]
	v_mfma_f32_16x16x32_bf16 v[30:33], v[74:77], v[166:169], v[30:33]
	v_mfma_f32_16x16x32_bf16 v[26:29], v[86:89], v[166:169], v[26:29]
	v_mfma_f32_16x16x32_bf16 v[14:17], v[74:77], v[184:187], v[14:17]
	v_mfma_f32_16x16x32_bf16 v[10:13], v[86:89], v[184:187], v[10:13]
	s_barrier
; __device__ __forceinline__ unsigned cvt_pk_bf16(float lo, float hi) { unsigned r; asm volatile("v_cvt_pk_bf16_f32 %0, %1, %2" : "=v"(r) : "v"(lo), "v"(hi)); return r; }
; #define PG8_WAIT_V(n) asm volatile("s_waitcnt vmcnt(" #n ")" ::: "memory")
; #define PG8_BAR __builtin_amdgcn_s_barrier()
; template <class Epi>
; __device__ __forceinline__ void gemm_phase(LAS unsigned char* lds, const Gemm g, const StaticOrder& S, const Epi& E) {
;     ...
;             PG8_STAGE(PG8_SB(1, 1), b3 + hstepB, voffB);
;             PG8_WAIT_V(6); PG8_BAR; PG8_MMA(1, 1, At, B1); PG8_BAR;
;     __device__ __forceinline__ void operator()(const f32x4 (&acc)[2][2][4][2], const Unit& u, int wr, int wc, int fr, int fq, const Pre&) const {
;         const int row0 = u.pm * BM + wr * 64 + fr, col0 = u.pn * BM + wc * 32 + 4 * fq;
;         f32x4 gv[2][2];
; #pragma unroll
;         for (int bj = 0; bj < 2; ++bj)
; #pragma unroll
;             for (int n = 0; n < 2; ++n) gv[bj][n] = *(const f32x4*)(gnext + col0 + bj * HALF + n * 16);
;         f32x4 xb[2][2][2];
; #pragma unroll
;         for (int bj = 0; bj < 2; ++bj)
; #pragma unroll
;             for (int n = 0; n < 2; ++n) xb[0][bj][n] = *(const f32x4*)(Xin + (size_t)row0 * DM + col0 + bj * HALF + n * 16);
; #pragma unroll
;         for (int grp = 0; grp < 8; ++grp) { const int ai = grp >> 2, m = grp & 3, cur = grp & 1; const int r = row0 + ai * HALF + m * 16; float ss = 0.f;
;             if (grp < 7) { const int rn = row0 + ((grp + 1) >> 2) * HALF + ((grp + 1) & 3) * 16;
; #pragma unroll
;                 for (int bj = 0; bj < 2; ++bj)
; #pragma unroll
;                     for (int n = 0; n < 2; ++n) xb[cur ^ 1][bj][n] = *(const f32x4*)(Xin + (size_t)rn * DM + col0 + bj * HALF + n * 16); }
; #pragma unroll
;             for (int bj = 0; bj < 2; ++bj)
; #pragma unroll
;                 for (int n = 0; n < 2; ++n) { const int c = col0 + bj * HALF + n * 16;
;                     const f32x4 xv = xb[cur][bj][n] + acc[ai][bj][m][n]; *(f32x4*)(X + (size_t)r * DM + c) = xv;
;                     ss += (xv[0] * xv[0] + xv[1] * xv[1]) + (xv[2] * xv[2] + xv[3] * xv[3]);
;                     if (H) { const f32x4 hv = xv * gv[bj][n]; u32x2 w; w.x = cvt_pk_bf16(hv[0], hv[1]); w.y = cvt_pk_bf16(hv[2], hv[3]);
;                         *(u32x2*)(H + (size_t)r * DM + c) = w; } }
	s_add_u32 s22, s36, 0x100080
	s_addc_u32 s23, s37, 0
	s_add_i32 s24, s24, s52
	s_mov_b32 m0, s24
	s_nop 0
	global_load_lds_dwordx4 v0, s[22:23]
	s_add_i32 m0, s24, 0x2000
	s_nop 0
	global_load_lds_dwordx4 v174, s[22:23]
	s_waitcnt vmcnt(6)
	s_barrier
	v_mfma_f32_16x16x32_bf16 v[54:57], v[194:197], v[146:149], v[54:57]
	v_mfma_f32_16x16x32_bf16 v[50:53], v[202:205], v[146:149], v[50:53]
	v_mfma_f32_16x16x32_bf16 v[38:41], v[194:197], v[154:157], v[38:41]
	v_mfma_f32_16x16x32_bf16 v[34:37], v[202:205], v[154:157], v[34:37]
	v_mfma_f32_16x16x32_bf16 v[22:25], v[194:197], v[162:165], v[22:25]
	v_mfma_f32_16x16x32_bf16 v[18:21], v[202:205], v[162:165], v[18:21]
	v_mfma_f32_16x16x32_bf16 v[6:9], v[194:197], v[170:173], v[6:9]
	v_mfma_f32_16x16x32_bf16 v[2:5], v[202:205], v[170:173], v[2:5]
	v_mfma_f32_16x16x32_bf16 v[54:57], v[198:201], v[150:153], v[54:57]
	v_mfma_f32_16x16x32_bf16 v[50:53], v[212:215], v[150:153], v[50:53]
	v_mfma_f32_16x16x32_bf16 v[38:41], v[198:201], v[158:161], v[38:41]
	v_mfma_f32_16x16x32_bf16 v[34:37], v[212:215], v[158:161], v[34:37]
	v_mfma_f32_16x16x32_bf16 v[22:25], v[198:201], v[166:169], v[22:25]
	v_mfma_f32_16x16x32_bf16 v[18:21], v[212:215], v[166:169], v[18:21]
	v_mfma_f32_16x16x32_bf16 v[6:9], v[198:201], v[184:187], v[6:9]
	v_mfma_f32_16x16x32_bf16 v[2:5], v[212:215], v[184:187], v[2:5]
	s_add_i32 s64, s64, 2
	s_add_u32 s62, s62, 0x100
	s_addc_u32 s63, s63, 0
	s_cmp_gt_u32 s64, 61
	s_mov_b64 s[22:23], s[26:27]
	s_barrier
	s_cbranch_scc0 .LBB0_359
	v_lshl_add_u32 v198, s44, 8, v208
	v_lshl_or_b32 v194, s45, 8, v210
	v_ashrrev_i32_e32 v199, 31, v198
	v_ashrrev_i32_e32 v195, 31, v194
	v_lshlrev_b64 v[204:205], 13, v[198:199]
	v_or_b32_e32 v202, 16, v198
	v_lshlrev_b64 v[196:197], 2, v[194:195]
	v_lshl_add_u64 v[146:147], s[0:1], 0, v[204:205]
	v_ashrrev_i32_e32 v203, 31, v202
	v_lshl_add_u64 v[70:71], s[4:5], 0, v[196:197]
	v_lshl_add_u64 v[146:147], v[146:147], 0, v[196:197]
	v_lshlrev_b64 v[200:201], 13, v[202:203]
	global_load_dwordx4 v[86:89], v[70:71], off
	global_load_dwordx4 v[82:85], v[70:71], off offset:64
	global_load_dwordx4 v[74:77], v[70:71], off offset:512
	s_nop 0
	global_load_dwordx4 v[70:73], v[70:71], off offset:576
	s_nop 0
	global_load_dwordx4 v[184:187], v[146:147], off
	global_load_dwordx4 v[170:173], v[146:147], off offset:64
	global_load_dwordx4 v[166:169], v[146:147], off offset:512
	global_load_dwordx4 v[162:165], v[146:147], off offset:576
	v_lshl_add_u64 v[146:147], s[0:1], 0, v[200:201]
	v_lshl_add_u64 v[146:147], v[146:147], 0, v[196:197]
	global_load_dwordx4 v[158:161], v[146:147], off
	global_load_dwordx4 v[154:157], v[146:147], off offset:64
	global_load_dwordx4 v[150:153], v[146:147], off offset:512
	s_nop 0
	global_load_dwordx4 v[146:149], v[146:147], off offset:576
	v_cndmask_b32_e64 v206, 0, 1, s[10:11]
	v_lshlrev_b64 v[212:213], 11, v[198:199]
	v_lshl_add_u64 v[204:205], s[48:49], 0, v[204:205]
	v_cmp_ne_u32_e64 s[44:45], 1, v206
	s_andn2_b64 vcc, exec, s[10:11]
	v_lshl_add_u64 v[206:207], v[204:205], 0, v[196:197]
	v_lshl_add_u64 v[204:205], v[212:213], 1, s[50:51]
	s_waitcnt vmcnt(0)
	v_pk_add_f32 v[144:145], v[144:145], v[186:187]
	v_pk_add_f32 v[142:143], v[142:143], v[184:185]
	global_store_dwordx4 v[206:207], v[142:145], off
	s_cbranch_vccnz .LBB0_362
	v_pk_mul_f32 v[184:185], v[88:89], v[144:145]
	v_pk_mul_f32 v[186:187], v[86:87], v[142:143]
	s_nop 0
	v_cvt_pk_bf16_f32 v186, v186, v187
	v_cvt_pk_bf16_f32 v187, v184, v185
	v_lshl_add_u64 v[184:185], v[194:195], 1, v[204:205]
	global_store_dwordx2 v[184:185], v[186:187], off

; #define PG8_STAGE(bufoff, gbase, voff) do { _Pragma("unroll") for (int _i = 0; _i < 2; ++_i) \
;         __builtin_amdgcn_global_load_lds((const unsigned*)((const char*)(gbase) + (voff)[_i]), (LAS unsigned*)(lds + (bufoff) + ldsw + _i * 8192), 16, 0, 0); } while (0)
; #define PG8_LDA(dst, b, h) do { _Pragma("unroll") for (int m = 0; m < 4; ++m) _Pragma("unroll") for (int k = 0; k < 2; ++k) dst[m][k] = *(const LAS bf16x8*)(lds + PG8_SA(b, h) + aoff + m * 2048 + k * 1024); } while (0)
; #define PG8_LDB(dst, b, h) do { _Pragma("unroll") for (int n = 0; n < 2; ++n) _Pragma("unroll") for (int k = 0; k < 2; ++k) dst[n][k] = *(const LAS bf16x8*)(lds + PG8_SB(b, h) + boff + n * 2048 + k * 1024); } while (0)
; #define PG8_MMA(ai, bj, At, Bt) do { __builtin_amdgcn_s_setprio(1); _Pragma("unroll") for (int m = 0; m < 4; ++m) _Pragma("unroll") for (int n = 0; n < 2; ++n) _Pragma("unroll") for (int k = 0; k < 2; ++k) \
;         acc[ai][bj][m][n] = __builtin_amdgcn_mfma_f32_16x16x32_bf16(Bt[n][k], At[m][k], acc[ai][bj][m][n], 0, 0, 0); __builtin_amdgcn_s_setprio(0); } while (0)
; #define PG8_WAIT_L(n) asm volatile("s_waitcnt lgkmcnt(" #n ")" ::: "memory")
; #define PG8_BAR __builtin_amdgcn_s_barrier()
; #define PG8_SCHED __builtin_amdgcn_sched_barrier(0)
; template <class Epi>
; __device__ __forceinline__ void gemm_phase(LAS unsigned char* lds, const Gemm g, const StaticOrder& S, const Epi& E) {
;     ...
;         const char* nA = has_next ? (const char*)g.A + (size_t)nxt.pm * tstepA + (size_t)(nxt.pn >> 2) * gstepA : cA; const char* nB = has_next ? (const char*)g.Bt + (size_t)nxt.pn * tstepB : cB;
;         for (int t = 0; t < nt; t += 2) {
;             const bool last = (t == nt - 2);
;             const char* a1 = cA + (size_t)(t + 1) * kstepA;
;             const char* a2 = last ? nA : cA + (size_t)(t + 2) * kstepA; const char* b2 = last ? nB : cB + (size_t)(t + 2) * kstep;
;             const char* a3 = a2 + kstepA; const char* b3 = b2 + kstep;
;             PG8_LDB(B0, 0, 0); PG8_SCHED; PG8_LDA(At, 0, 0); PG8_STAGE(PG8_SA(1, 1), a1 + hstepA, voffA);
;             PG8_WAIT_L(8); PG8_BAR; PG8_WAIT_L(0); PG8_MMA(0, 0, At, B0); PG8_BAR; PG8_SCHED;
;             PG8_LDB(B1, 0, 1); PG8_STAGE(PG8_SB(0, 0), b2, voffB);
;             PG8_BAR; PG8_WAIT_L(0); PG8_MMA(0, 1, At, B1); PG8_BAR;
;             PG8_LDA(At, 0, 1); PG8_STAGE(PG8_SA(0, 0), a2, voffA);
.LBB0_471:
	s_add_u32 s17, s20, 0x100
	s_addc_u32 s58, s21, 0
	s_ashr_i32 s11, s10, 31
	s_lshl_b64 s[14:15], s[10:11], 21
	s_add_u32 s18, s35, s14
	s_addc_u32 s19, s36, s15
	s_and_b64 s[14:15], s[42:43], exec
	s_cselect_b32 s11, s19, s5
	s_cselect_b32 s59, s18, s4
	s_ashr_i32 s9, s8, 31
	s_lshl_b64 s[14:15], s[8:9], 21
	s_add_u32 s14, s37, s14
	s_addc_u32 s15, s38, s15
	s_and_b64 s[22:23], s[42:43], exec
	s_cselect_b32 s9, s15, s21
	s_cselect_b32 s60, s14, s20
	s_add_u32 s20, s4, 0x100080
	s_addc_u32 s21, s5, 0
	v_lshl_add_u64 v[140:141], s[20:21], 0, v[136:137]
	v_lshl_add_u64 v[142:143], s[20:21], 0, v[138:139]
	s_mov_b32 s61, -2
	s_mov_b64 s[20:21], 0
	v_add_u32_e32 v250, 0x10000, v146
.LBB0_472:
	s_add_u32 s22, s4, s20
	s_addc_u32 s23, s5, s21
	s_add_u32 s22, s22, 0x100
	s_addc_u32 s23, s23, 0
	s_add_u32 s62, s17, s20
	s_addc_u32 s63, s58, s21
	s_add_i32 s64, 0, 0x10000
	ds_read_b128 v[148:151], v250
	ds_read_b128 v[152:155], v250 offset:1024
	ds_read_b128 v[156:159], v250 offset:2048
	ds_read_b128 v[160:163], v250 offset:3072
	s_cmpk_eq_i32 s20, 0x1f00
	s_cselect_b32 s25, s11, s23
	s_cselect_b32 s24, s59, s22
	s_cselect_b32 s23, s9, s63
	s_cselect_b32 s22, s60, s62
	v_lshl_add_u64 v[176:177], v[140:141], 0, s[20:21]
	s_add_i32 m0, s48, 0xc000
	ds_read_b128 v[164:167], v147
	ds_read_b128 v[168:171], v147 offset:1024
	ds_read_b128 v[172:175], v147 offset:2048
	ds_read_b128 v[184:187], v147 offset:3072
	ds_read_b128 v[188:191], v147 offset:4096
	ds_read_b128 v[192:195], v147 offset:5120
	ds_read_b128 v[196:199], v147 offset:6144
	ds_read_b128 v[200:203], v147 offset:7168
	global_load_lds_dwordx4 v[176:177], off
	v_lshl_add_u64 v[176:177], v[142:143], 0, s[20:21]
	s_add_i32 m0, s48, 0xe000
	s_nop 0
	global_load_lds_dwordx4 v[176:177], off
	s_waitcnt lgkmcnt(8)
	s_barrier
	s_waitcnt lgkmcnt(0)
	v_mfma_f32_16x16x32_bf16 v[126:129], v[148:151], v[164:167], v[126:129]
	v_mfma_f32_16x16x32_bf16 v[122:125], v[156:159], v[164:167], v[122:125]
	v_mfma_f32_16x16x32_bf16 v[110:113], v[148:151], v[172:175], v[110:113]
	v_mfma_f32_16x16x32_bf16 v[106:109], v[156:159], v[172:175], v[106:109]
	v_mfma_f32_16x16x32_bf16 v[94:97], v[148:151], v[188:191], v[94:97]
	v_mfma_f32_16x16x32_bf16 v[90:93], v[156:159], v[188:191], v[90:93]
	v_mfma_f32_16x16x32_bf16 v[78:81], v[148:151], v[196:199], v[78:81]
	v_mfma_f32_16x16x32_bf16 v[74:77], v[156:159], v[196:199], v[74:77]
	v_mfma_f32_16x16x32_bf16 v[126:129], v[152:155], v[168:171], v[126:129]
	v_mfma_f32_16x16x32_bf16 v[122:125], v[160:163], v[168:171], v[122:125]
	v_mfma_f32_16x16x32_bf16 v[110:113], v[152:155], v[184:187], v[110:113]
	v_mfma_f32_16x16x32_bf16 v[106:109], v[160:163], v[184:187], v[106:109]
	v_mfma_f32_16x16x32_bf16 v[94:97], v[152:155], v[192:195], v[94:97]
	v_mfma_f32_16x16x32_bf16 v[90:93], v[160:163], v[192:195], v[90:93]
	v_mfma_f32_16x16x32_bf16 v[78:81], v[152:155], v[200:203], v[78:81]
	v_mfma_f32_16x16x32_bf16 v[74:77], v[160:163], v[200:203], v[74:77]
	s_barrier
	s_add_i32 s65, 0, 0x14000
	s_add_i32 s62, s64, s39
	ds_read_b128 v[204:207], v250 offset:16384
	ds_read_b128 v[208:211], v250 offset:17408
	ds_read_b128 v[212:215], v250 offset:18432
	ds_read_b128 v[216:219], v250 offset:19456
	s_add_u32 s100, s22, s6
	s_addc_u32 s101, s23, s7
	s_mov_b32 m0, s62
	s_nop 0
	global_load_lds_dwordx4 v0, s[22:23]
	s_add_i32 m0, s62, 0x2000
	s_nop 0
	global_load_lds_dwordx4 v130, s[22:23]
	s_barrier
	s_waitcnt lgkmcnt(0)
	v_mfma_f32_16x16x32_bf16 v[118:121], v[204:207], v[164:167], v[118:121]
	v_mfma_f32_16x16x32_bf16 v[114:117], v[212:215], v[164:167], v[114:117]
	v_mfma_f32_16x16x32_bf16 v[102:105], v[204:207], v[172:175], v[102:105]
	v_mfma_f32_16x16x32_bf16 v[98:101], v[212:215], v[172:175], v[98:101]
	v_mfma_f32_16x16x32_bf16 v[86:89], v[204:207], v[188:191], v[86:89]
	v_mfma_f32_16x16x32_bf16 v[82:85], v[212:215], v[188:191], v[82:85]
	v_mfma_f32_16x16x32_bf16 v[70:73], v[204:207], v[196:199], v[70:73]
	v_mfma_f32_16x16x32_bf16 v[66:69], v[212:215], v[196:199], v[66:69]
	v_mfma_f32_16x16x32_bf16 v[118:121], v[208:211], v[168:171], v[118:121]
	v_mfma_f32_16x16x32_bf16 v[114:117], v[216:219], v[168:171], v[114:117]
	v_mfma_f32_16x16x32_bf16 v[102:105], v[208:211], v[184:187], v[102:105]
	v_mfma_f32_16x16x32_bf16 v[98:101], v[216:219], v[184:187], v[98:101]
	v_mfma_f32_16x16x32_bf16 v[86:89], v[208:211], v[192:195], v[86:89]
	v_mfma_f32_16x16x32_bf16 v[82:85], v[216:219], v[192:195], v[82:85]
	v_mfma_f32_16x16x32_bf16 v[70:73], v[208:211], v[200:203], v[70:73]
	v_mfma_f32_16x16x32_bf16 v[66:69], v[216:219], v[200:203], v[66:69]
	s_mov_b32 m0, s48
	s_add_u32 vcc_lo, s24, s6
	s_addc_u32 vcc_hi, s25, s7
	s_barrier
	ds_read_b128 v[164:167], v147 offset:16384
	ds_read_b128 v[168:171], v147 offset:17408
	ds_read_b128 v[172:175], v147 offset:18432
	ds_read_b128 v[184:187], v147 offset:19456
	ds_read_b128 v[188:191], v147 offset:20480
	ds_read_b128 v[192:195], v147 offset:21504
	ds_read_b128 v[196:199], v147 offset:22528
	ds_read_b128 v[200:203], v147 offset:23552
	global_load_lds_dwordx4 v134, s[24:25]
	s_mov_b32 m0, s49
	s_nop 0
	global_load_lds_dwordx4 v132, s[24:25]
	s_barrier
; #define PG8_STAGE(bufoff, gbase, voff) do { _Pragma("unroll") for (int _i = 0; _i < 2; ++_i) \
;         __builtin_amdgcn_global_load_lds((const unsigned*)((const char*)(gbase) + (voff)[_i]), (LAS unsigned*)(lds + (bufoff) + ldsw + _i * 8192), 16, 0, 0); } while (0)
; #define PG8_LDA(dst, b, h) do { _Pragma("unroll") for (int m = 0; m < 4; ++m) _Pragma("unroll") for (int k = 0; k < 2; ++k) dst[m][k] = *(const LAS bf16x8*)(lds + PG8_SA(b, h) + aoff + m * 2048 + k * 1024); } while (0)
; #define PG8_LDB(dst, b, h) do { _Pragma("unroll") for (int n = 0; n < 2; ++n) _Pragma("unroll") for (int k = 0; k < 2; ++k) dst[n][k] = *(const LAS bf16x8*)(lds + PG8_SB(b, h) + boff + n * 2048 + k * 1024); } while (0)
; #define PG8_MMA(ai, bj, At, Bt) do { __builtin_amdgcn_s_setprio(1); _Pragma("unroll") for (int m = 0; m < 4; ++m) _Pragma("unroll") for (int n = 0; n < 2; ++n) _Pragma("unroll") for (int k = 0; k < 2; ++k) \
;         acc[ai][bj][m][n] = __builtin_amdgcn_mfma_f32_16x16x32_bf16(Bt[n][k], At[m][k], acc[ai][bj][m][n], 0, 0, 0); __builtin_amdgcn_s_setprio(0); } while (0)
; #define PG8_WAIT_V(n) asm volatile("s_waitcnt vmcnt(" #n ")" ::: "memory")
; #define PG8_WAIT_L(n) asm volatile("s_waitcnt lgkmcnt(" #n ")" ::: "memory")
; #define PG8_BAR __builtin_amdgcn_s_barrier()
; #define PG8_SCHED __builtin_amdgcn_sched_barrier(0)
; template <class Epi>
; __device__ __forceinline__ void gemm_phase(LAS unsigned char* lds, const Gemm g, const StaticOrder& S, const Epi& E) {
;     ...
;             PG8_BAR; PG8_WAIT_L(0); PG8_MMA(1, 0, At, B0); PG8_BAR; PG8_SCHED;
;             PG8_STAGE(PG8_SB(0, 1), b2 + hstepB, voffB);
;             PG8_WAIT_V(6); PG8_BAR; PG8_MMA(1, 1, At, B1); PG8_BAR;
;             PG8_LDB(B0, 1, 0); PG8_SCHED; PG8_LDA(At, 1, 0); PG8_STAGE(PG8_SA(0, 1), a2 + hstepA, voffA);
;             PG8_WAIT_L(8); PG8_BAR; PG8_WAIT_L(0); PG8_MMA(0, 0, At, B0); PG8_BAR; PG8_SCHED;
;             PG8_LDB(B1, 1, 1); PG8_STAGE(PG8_SB(1, 0), b3, voffB);
;             PG8_BAR; PG8_WAIT_L(0); PG8_MMA(0, 1, At, B1); PG8_BAR;
	s_waitcnt lgkmcnt(0)
	v_mfma_f32_16x16x32_bf16 v[62:65], v[148:151], v[164:167], v[62:65]
	v_mfma_f32_16x16x32_bf16 v[58:61], v[156:159], v[164:167], v[58:61]
	v_mfma_f32_16x16x32_bf16 v[46:49], v[148:151], v[172:175], v[46:49]
	v_mfma_f32_16x16x32_bf16 v[42:45], v[156:159], v[172:175], v[42:45]
	v_mfma_f32_16x16x32_bf16 v[30:33], v[148:151], v[188:191], v[30:33]
	v_mfma_f32_16x16x32_bf16 v[26:29], v[156:159], v[188:191], v[26:29]
	v_mfma_f32_16x16x32_bf16 v[18:21], v[148:151], v[196:199], v[18:21]
	v_mfma_f32_16x16x32_bf16 v[10:13], v[156:159], v[196:199], v[10:13]
	v_mfma_f32_16x16x32_bf16 v[62:65], v[152:155], v[168:171], v[62:65]
	v_mfma_f32_16x16x32_bf16 v[58:61], v[160:163], v[168:171], v[58:61]
	v_mfma_f32_16x16x32_bf16 v[46:49], v[152:155], v[184:187], v[46:49]
	v_mfma_f32_16x16x32_bf16 v[42:45], v[160:163], v[184:187], v[42:45]
	v_mfma_f32_16x16x32_bf16 v[30:33], v[152:155], v[192:195], v[30:33]
	v_mfma_f32_16x16x32_bf16 v[26:29], v[160:163], v[192:195], v[26:29]
	v_mfma_f32_16x16x32_bf16 v[18:21], v[152:155], v[200:203], v[18:21]
	v_mfma_f32_16x16x32_bf16 v[10:13], v[160:163], v[200:203], v[10:13]
	s_barrier
	s_add_u32 s62, s22, 0x100000
	s_addc_u32 s63, s23, 0
	s_add_i32 s64, s65, s39
	s_mov_b32 m0, s64
	s_nop 0
	global_load_lds_dwordx4 v0, s[62:63]
	s_add_i32 m0, s64, 0x2000
	s_nop 0
	global_load_lds_dwordx4 v130, s[62:63]
	s_waitcnt vmcnt(6)
	s_barrier
	v_mfma_f32_16x16x32_bf16 v[54:57], v[204:207], v[164:167], v[54:57]
	v_mfma_f32_16x16x32_bf16 v[50:53], v[212:215], v[164:167], v[50:53]
	v_mfma_f32_16x16x32_bf16 v[38:41], v[204:207], v[172:175], v[38:41]
	v_mfma_f32_16x16x32_bf16 v[34:37], v[212:215], v[172:175], v[34:37]
	v_mfma_f32_16x16x32_bf16 v[22:25], v[204:207], v[188:191], v[22:25]
	v_mfma_f32_16x16x32_bf16 v[14:17], v[212:215], v[188:191], v[14:17]
	v_mfma_f32_16x16x32_bf16 v[6:9], v[204:207], v[196:199], v[6:9]
	v_mfma_f32_16x16x32_bf16 v[2:5], v[212:215], v[196:199], v[2:5]
	v_mfma_f32_16x16x32_bf16 v[54:57], v[208:211], v[168:171], v[54:57]
	v_mfma_f32_16x16x32_bf16 v[50:53], v[216:219], v[168:171], v[50:53]
	v_mfma_f32_16x16x32_bf16 v[38:41], v[208:211], v[184:187], v[38:41]
	v_mfma_f32_16x16x32_bf16 v[34:37], v[216:219], v[184:187], v[34:37]
	v_mfma_f32_16x16x32_bf16 v[22:25], v[208:211], v[192:195], v[22:25]
	v_mfma_f32_16x16x32_bf16 v[14:17], v[216:219], v[192:195], v[14:17]
	v_mfma_f32_16x16x32_bf16 v[6:9], v[208:211], v[200:203], v[6:9]
	v_mfma_f32_16x16x32_bf16 v[2:5], v[216:219], v[200:203], v[2:5]
	s_add_i32 s62, 0, 0x18000
	s_barrier
	ds_read_b128 v[148:151], v250 offset:32768
	ds_read_b128 v[152:155], v250 offset:33792
	ds_read_b128 v[156:159], v250 offset:34816
	ds_read_b128 v[160:163], v250 offset:35840
	s_add_u32 s24, s24, 0x100000
	s_addc_u32 s25, s25, 0
	s_mov_b32 m0, s50
	ds_read_b128 v[164:167], v147 offset:32768
	ds_read_b128 v[168:171], v147 offset:33792
	ds_read_b128 v[172:175], v147 offset:34816
	ds_read_b128 v[184:187], v147 offset:35840
	ds_read_b128 v[188:191], v147 offset:36864
	ds_read_b128 v[192:195], v147 offset:37888
	ds_read_b128 v[196:199], v147 offset:38912
	ds_read_b128 v[200:203], v147 offset:39936
	global_load_lds_dwordx4 v134, s[24:25]
	s_mov_b32 m0, s51
	s_nop 0
	global_load_lds_dwordx4 v132, s[24:25]
	s_waitcnt lgkmcnt(8)
	s_barrier
	s_waitcnt lgkmcnt(0)
	v_mfma_f32_16x16x32_bf16 v[126:129], v[148:151], v[164:167], v[126:129]
	v_mfma_f32_16x16x32_bf16 v[122:125], v[156:159], v[164:167], v[122:125]
	v_mfma_f32_16x16x32_bf16 v[110:113], v[148:151], v[172:175], v[110:113]
	v_mfma_f32_16x16x32_bf16 v[106:109], v[156:159], v[172:175], v[106:109]
	v_mfma_f32_16x16x32_bf16 v[94:97], v[148:151], v[188:191], v[94:97]
	v_mfma_f32_16x16x32_bf16 v[90:93], v[156:159], v[188:191], v[90:93]
	v_mfma_f32_16x16x32_bf16 v[78:81], v[148:151], v[196:199], v[78:81]
	v_mfma_f32_16x16x32_bf16 v[74:77], v[156:159], v[196:199], v[74:77]
	v_mfma_f32_16x16x32_bf16 v[126:129], v[152:155], v[168:171], v[126:129]
	v_mfma_f32_16x16x32_bf16 v[122:125], v[160:163], v[168:171], v[122:125]
	v_mfma_f32_16x16x32_bf16 v[110:113], v[152:155], v[184:187], v[110:113]
	v_mfma_f32_16x16x32_bf16 v[106:109], v[160:163], v[184:187], v[106:109]
	v_mfma_f32_16x16x32_bf16 v[94:97], v[152:155], v[192:195], v[94:97]
	v_mfma_f32_16x16x32_bf16 v[90:93], v[160:163], v[192:195], v[90:93]
	v_mfma_f32_16x16x32_bf16 v[78:81], v[152:155], v[200:203], v[78:81]
	v_mfma_f32_16x16x32_bf16 v[74:77], v[160:163], v[200:203], v[74:77]
	s_barrier
	s_add_i32 s24, 0, 0x1c000
	s_add_i32 s25, s62, s39
	s_mov_b32 m0, s25
	ds_read_b128 v[204:207], v250 offset:49152
	ds_read_b128 v[208:211], v250 offset:50176
	ds_read_b128 v[212:215], v250 offset:51200
	ds_read_b128 v[216:219], v250 offset:52224
	global_load_lds_dwordx4 v0, s[100:101]
	s_add_i32 m0, s25, 0x2000
	s_nop 0
	global_load_lds_dwordx4 v130, s[100:101]
	s_barrier
	s_waitcnt lgkmcnt(0)
	v_mfma_f32_16x16x32_bf16 v[118:121], v[204:207], v[164:167], v[118:121]
	v_mfma_f32_16x16x32_bf16 v[114:117], v[212:215], v[164:167], v[114:117]
	v_mfma_f32_16x16x32_bf16 v[102:105], v[204:207], v[172:175], v[102:105]
	v_mfma_f32_16x16x32_bf16 v[98:101], v[212:215], v[172:175], v[98:101]
	v_mfma_f32_16x16x32_bf16 v[86:89], v[204:207], v[188:191], v[86:89]
	v_mfma_f32_16x16x32_bf16 v[82:85], v[212:215], v[188:191], v[82:85]
	v_mfma_f32_16x16x32_bf16 v[70:73], v[204:207], v[196:199], v[70:73]
	v_mfma_f32_16x16x32_bf16 v[66:69], v[212:215], v[196:199], v[66:69]
	v_mfma_f32_16x16x32_bf16 v[118:121], v[208:211], v[168:171], v[118:121]
	v_mfma_f32_16x16x32_bf16 v[114:117], v[216:219], v[168:171], v[114:117]
	v_mfma_f32_16x16x32_bf16 v[102:105], v[208:211], v[184:187], v[102:105]
	v_mfma_f32_16x16x32_bf16 v[98:101], v[216:219], v[184:187], v[98:101]
	v_mfma_f32_16x16x32_bf16 v[86:89], v[208:211], v[192:195], v[86:89]
	v_mfma_f32_16x16x32_bf16 v[82:85], v[216:219], v[192:195], v[82:85]
	v_mfma_f32_16x16x32_bf16 v[70:73], v[208:211], v[200:203], v[70:73]
	v_mfma_f32_16x16x32_bf16 v[66:69], v[216:219], v[200:203], v[66:69]
	s_mov_b32 m0, s54
	s_barrier
; #define PG8_STAGE(bufoff, gbase, voff) do { _Pragma("unroll") for (int _i = 0; _i < 2; ++_i) \
;         __builtin_amdgcn_global_load_lds((const unsigned*)((const char*)(gbase) + (voff)[_i]), (LAS unsigned*)(lds + (bufoff) + ldsw + _i * 8192), 16, 0, 0); } while (0)
; #define PG8_LDA(dst, b, h) do { _Pragma("unroll") for (int m = 0; m < 4; ++m) _Pragma("unroll") for (int k = 0; k < 2; ++k) dst[m][k] = *(const LAS bf16x8*)(lds + PG8_SA(b, h) + aoff + m * 2048 + k * 1024); } while (0)
; #define PG8_MMA(ai, bj, At, Bt) do { __builtin_amdgcn_s_setprio(1); _Pragma("unroll") for (int m = 0; m < 4; ++m) _Pragma("unroll") for (int n = 0; n < 2; ++n) _Pragma("unroll") for (int k = 0; k < 2; ++k) \
;         acc[ai][bj][m][n] = __builtin_amdgcn_mfma_f32_16x16x32_bf16(Bt[n][k], At[m][k], acc[ai][bj][m][n], 0, 0, 0); __builtin_amdgcn_s_setprio(0); } while (0)
; #define PG8_WAIT_V(n) asm volatile("s_waitcnt vmcnt(" #n ")" ::: "memory")
; #define PG8_WAIT_L(n) asm volatile("s_waitcnt lgkmcnt(" #n ")" ::: "memory")
; #define PG8_BAR __builtin_amdgcn_s_barrier()
; #define PG8_SCHED __builtin_amdgcn_sched_barrier(0)
; template <class Epi>
; __device__ __forceinline__ void gemm_phase(LAS unsigned char* lds, const Gemm g, const StaticOrder& S, const Epi& E) {
;     ...
;             PG8_LDA(At, 1, 1); PG8_STAGE(PG8_SA(1, 0), a3, voffA);
;             PG8_BAR; PG8_WAIT_L(0); PG8_MMA(1, 0, At, B0); PG8_BAR; PG8_SCHED;
;             PG8_STAGE(PG8_SB(1, 1), b3 + hstepB, voffB);
;             PG8_WAIT_V(6); PG8_BAR; PG8_MMA(1, 1, At, B1); PG8_BAR;
;         }
;         if constexpr (!Epi::AFTER_DRAIN) E(acc, cur, wr, wc, fr, fq, pre);
;         if (!has_next) break;
; #pragma unroll
;         for (int a = 0; a < 2; ++a)
; #pragma unroll
;             for (int b = 0; b < 2; ++b)
; #pragma unroll
;                 for (int m = 0; m < 4; ++m)
; #pragma unroll
;                     for (int n = 0; n < 2; ++n) acc[a][b][m][n] = (f32x4){0.f, 0.f, 0.f, 0.f};
;         cur = nxt; cA = nA; cB = nB; ++ui;
	ds_read_b128 v[164:167], v147 offset:49152
	ds_read_b128 v[168:171], v147 offset:50176
	ds_read_b128 v[172:175], v147 offset:51200
	ds_read_b128 v[184:187], v147 offset:52224
	ds_read_b128 v[188:191], v147 offset:53248
	ds_read_b128 v[192:195], v147 offset:54272
	ds_read_b128 v[196:199], v147 offset:55296
	ds_read_b128 v[200:203], v147 offset:56320
	global_load_lds_dwordx4 v134, vcc
	s_mov_b32 m0, s55
	s_nop 0
	global_load_lds_dwordx4 v132, vcc
	s_barrier
	s_waitcnt lgkmcnt(0)
	v_mfma_f32_16x16x32_bf16 v[62:65], v[148:151], v[164:167], v[62:65]
	v_mfma_f32_16x16x32_bf16 v[58:61], v[156:159], v[164:167], v[58:61]
	v_mfma_f32_16x16x32_bf16 v[46:49], v[148:151], v[172:175], v[46:49]
	v_mfma_f32_16x16x32_bf16 v[42:45], v[156:159], v[172:175], v[42:45]
	v_mfma_f32_16x16x32_bf16 v[30:33], v[148:151], v[188:191], v[30:33]
	v_mfma_f32_16x16x32_bf16 v[26:29], v[156:159], v[188:191], v[26:29]
	v_mfma_f32_16x16x32_bf16 v[18:21], v[148:151], v[196:199], v[18:21]
	v_mfma_f32_16x16x32_bf16 v[10:13], v[156:159], v[196:199], v[10:13]
	v_mfma_f32_16x16x32_bf16 v[62:65], v[152:155], v[168:171], v[62:65]
	v_mfma_f32_16x16x32_bf16 v[58:61], v[160:163], v[168:171], v[58:61]
	v_mfma_f32_16x16x32_bf16 v[46:49], v[152:155], v[184:187], v[46:49]
	v_mfma_f32_16x16x32_bf16 v[42:45], v[160:163], v[184:187], v[42:45]
	v_mfma_f32_16x16x32_bf16 v[30:33], v[152:155], v[192:195], v[30:33]
	v_mfma_f32_16x16x32_bf16 v[26:29], v[160:163], v[192:195], v[26:29]
	v_mfma_f32_16x16x32_bf16 v[18:21], v[152:155], v[200:203], v[18:21]
	v_mfma_f32_16x16x32_bf16 v[10:13], v[160:163], v[200:203], v[10:13]
	s_barrier
	s_add_u32 s22, s22, 0x100080
	s_addc_u32 s23, s23, 0
	s_add_i32 s24, s24, s39
	s_mov_b32 m0, s24
	s_nop 0
	global_load_lds_dwordx4 v0, s[22:23]
	s_add_i32 m0, s24, 0x2000
	s_nop 0
	global_load_lds_dwordx4 v130, s[22:23]
	s_waitcnt vmcnt(6)
	s_barrier
	v_mfma_f32_16x16x32_bf16 v[54:57], v[204:207], v[164:167], v[54:57]
	v_mfma_f32_16x16x32_bf16 v[50:53], v[212:215], v[164:167], v[50:53]
	v_mfma_f32_16x16x32_bf16 v[38:41], v[204:207], v[172:175], v[38:41]
	v_mfma_f32_16x16x32_bf16 v[34:37], v[212:215], v[172:175], v[34:37]
	v_mfma_f32_16x16x32_bf16 v[22:25], v[204:207], v[188:191], v[22:25]
	v_mfma_f32_16x16x32_bf16 v[14:17], v[212:215], v[188:191], v[14:17]
	v_mfma_f32_16x16x32_bf16 v[6:9], v[204:207], v[196:199], v[6:9]
	v_mfma_f32_16x16x32_bf16 v[2:5], v[212:215], v[196:199], v[2:5]
	v_mfma_f32_16x16x32_bf16 v[54:57], v[208:211], v[168:171], v[54:57]
	v_mfma_f32_16x16x32_bf16 v[50:53], v[216:219], v[168:171], v[50:53]
	v_mfma_f32_16x16x32_bf16 v[38:41], v[208:211], v[184:187], v[38:41]
	v_mfma_f32_16x16x32_bf16 v[34:37], v[216:219], v[184:187], v[34:37]
	v_mfma_f32_16x16x32_bf16 v[22:25], v[208:211], v[192:195], v[22:25]
	v_mfma_f32_16x16x32_bf16 v[14:17], v[216:219], v[192:195], v[14:17]
	v_mfma_f32_16x16x32_bf16 v[6:9], v[208:211], v[200:203], v[6:9]
	v_mfma_f32_16x16x32_bf16 v[2:5], v[216:219], v[200:203], v[2:5]
	s_add_i32 s61, s61, 2
	s_add_u32 s20, s20, 0x100
	s_addc_u32 s21, s21, 0
	s_cmp_gt_u32 s61, 61
	s_barrier
	s_cbranch_scc0 .LBB0_472
	s_add_u32 s20, s17, 0xffffff00
	s_addc_u32 s21, s58, -1
	s_andn2_b64 vcc, exec, s[42:43]
	s_cbranch_vccnz .LBB0_463
	v_mov_b32_e32 v2, 0
	s_mov_b32 s57, s8
	s_mov_b32 s26, s10
	s_mov_b64 s[4:5], s[18:19]
	s_mov_b32 s56, s16
	v_mov_b32_e32 v3, v2
	v_mov_b32_e32 v4, v2
	v_mov_b32_e32 v5, v2
	v_mov_b32_e32 v6, v2
	v_mov_b32_e32 v7, v2
	v_mov_b32_e32 v8, v2
	v_mov_b32_e32 v9, v2
	v_mov_b32_e32 v14, v2
	v_mov_b32_e32 v15, v2
	v_mov_b32_e32 v16, v2
	v_mov_b32_e32 v17, v2
	v_mov_b32_e32 v22, v2
	v_mov_b32_e32 v23, v2
	v_mov_b32_e32 v24, v2
	v_mov_b32_e32 v25, v2
	v_mov_b32_e32 v34, v2
	v_mov_b32_e32 v35, v2
	v_mov_b32_e32 v36, v2
	v_mov_b32_e32 v37, v2
	v_mov_b32_e32 v38, v2
	v_mov_b32_e32 v39, v2
	v_mov_b32_e32 v40, v2
	v_mov_b32_e32 v41, v2
	v_mov_b32_e32 v50, v2
	v_mov_b32_e32 v51, v2
	v_mov_b32_e32 v52, v2
	v_mov_b32_e32 v53, v2
	v_mov_b32_e32 v54, v2
	v_mov_b32_e32 v55, v2
	v_mov_b32_e32 v56, v2
	v_mov_b32_e32 v57, v2
	v_mov_b32_e32 v10, v2
	v_mov_b32_e32 v11, v2
	v_mov_b32_e32 v12, v2
	v_mov_b32_e32 v13, v2
	v_mov_b32_e32 v18, v2
	v_mov_b32_e32 v19, v2
	v_mov_b32_e32 v20, v2
	v_mov_b32_e32 v21, v2
	v_mov_b32_e32 v26, v2
	v_mov_b32_e32 v27, v2
	v_mov_b32_e32 v28, v2
	v_mov_b32_e32 v29, v2
	v_mov_b32_e32 v30, v2
	v_mov_b32_e32 v31, v2
	v_mov_b32_e32 v32, v2
	v_mov_b32_e32 v33, v2
	v_mov_b32_e32 v42, v2
	v_mov_b32_e32 v43, v2
	v_mov_b32_e32 v44, v2
	v_mov_b32_e32 v45, v2
	v_mov_b32_e32 v46, v2
	v_mov_b32_e32 v47, v2
	v_mov_b32_e32 v48, v2
	v_mov_b32_e32 v49, v2
	v_mov_b32_e32 v58, v2
	v_mov_b32_e32 v59, v2
	v_mov_b32_e32 v60, v2
	v_mov_b32_e32 v61, v2
	v_mov_b32_e32 v62, v2
	v_mov_b32_e32 v63, v2
	v_mov_b32_e32 v64, v2
	v_mov_b32_e32 v65, v2
	v_mov_b32_e32 v66, v2
	v_mov_b32_e32 v67, v2
	v_mov_b32_e32 v68, v2
	v_mov_b32_e32 v69, v2
	v_mov_b32_e32 v70, v2
	v_mov_b32_e32 v71, v2
	v_mov_b32_e32 v72, v2
	v_mov_b32_e32 v73, v2
	v_mov_b32_e32 v82, v2
	v_mov_b32_e32 v83, v2
	v_mov_b32_e32 v84, v2
	v_mov_b32_e32 v85, v2
	v_mov_b32_e32 v86, v2
	v_mov_b32_e32 v87, v2
	v_mov_b32_e32 v88, v2
	v_mov_b32_e32 v89, v2
	v_mov_b32_e32 v98, v2
	v_mov_b32_e32 v99, v2
	v_mov_b32_e32 v100, v2
	v_mov_b32_e32 v101, v2
	v_mov_b32_e32 v102, v2
	v_mov_b32_e32 v103, v2
	v_mov_b32_e32 v104, v2
	v_mov_b32_e32 v105, v2
	v_mov_b32_e32 v114, v2
	v_mov_b32_e32 v115, v2
	v_mov_b32_e32 v116, v2
	v_mov_b32_e32 v117, v2
	v_mov_b32_e32 v118, v2
	v_mov_b32_e32 v119, v2
	v_mov_b32_e32 v120, v2
	v_mov_b32_e32 v121, v2
	v_mov_b32_e32 v74, v2
	v_mov_b32_e32 v75, v2
	v_mov_b32_e32 v76, v2
	v_mov_b32_e32 v77, v2
	v_mov_b32_e32 v78, v2
	v_mov_b32_e32 v79, v2
	v_mov_b32_e32 v80, v2
	v_mov_b32_e32 v81, v2
	v_mov_b32_e32 v90, v2
	v_mov_b32_e32 v91, v2
	v_mov_b32_e32 v92, v2
	v_mov_b32_e32 v93, v2
	v_mov_b32_e32 v94, v2
	v_mov_b32_e32 v95, v2
	v_mov_b32_e32 v96, v2
	v_mov_b32_e32 v97, v2
	v_mov_b32_e32 v106, v2
	v_mov_b32_e32 v107, v2
	v_mov_b32_e32 v108, v2
	v_mov_b32_e32 v109, v2
	v_mov_b32_e32 v110, v2
	v_mov_b32_e32 v111, v2
	v_mov_b32_e32 v112, v2
	v_mov_b32_e32 v113, v2
	v_mov_b32_e32 v122, v2
	v_mov_b32_e32 v123, v2
	v_mov_b32_e32 v124, v2
	v_mov_b32_e32 v125, v2
	v_mov_b32_e32 v126, v2
	v_mov_b32_e32 v127, v2
	v_mov_b32_e32 v128, v2
	v_mov_b32_e32 v129, v2
	s_andn2_b64 vcc, exec, s[40:41]
	s_cbranch_vccnz .LBB0_464

; #define PG8_STAGE(bufoff, gbase, voff) do { _Pragma("unroll") for (int _i = 0; _i < 2; ++_i) \
;         __builtin_amdgcn_global_load_lds((const unsigned*)((const char*)(gbase) + (voff)[_i]), (LAS unsigned*)(lds + (bufoff) + ldsw + _i * 8192), 16, 0, 0); } while (0)
; #define PG8_LDA(dst, b, h) do { _Pragma("unroll") for (int m = 0; m < 4; ++m) _Pragma("unroll") for (int k = 0; k < 2; ++k) dst[m][k] = *(const LAS bf16x8*)(lds + PG8_SA(b, h) + aoff + m * 2048 + k * 1024); } while (0)
; #define PG8_LDB(dst, b, h) do { _Pragma("unroll") for (int n = 0; n < 2; ++n) _Pragma("unroll") for (int k = 0; k < 2; ++k) dst[n][k] = *(const LAS bf16x8*)(lds + PG8_SB(b, h) + boff + n * 2048 + k * 1024); } while (0)
; #define PG8_MMA(ai, bj, At, Bt) do { __builtin_amdgcn_s_setprio(1); _Pragma("unroll") for (int m = 0; m < 4; ++m) _Pragma("unroll") for (int n = 0; n < 2; ++n) _Pragma("unroll") for (int k = 0; k < 2; ++k) \
;         acc[ai][bj][m][n] = __builtin_amdgcn_mfma_f32_16x16x32_bf16(Bt[n][k], At[m][k], acc[ai][bj][m][n], 0, 0, 0); __builtin_amdgcn_s_setprio(0); } while (0)
; #define PG8_WAIT_L(n) asm volatile("s_waitcnt lgkmcnt(" #n ")" ::: "memory")
; #define PG8_BAR __builtin_amdgcn_s_barrier()
; #define PG8_SCHED __builtin_amdgcn_sched_barrier(0)
; template <class Epi>
; __device__ __forceinline__ void gemm_phase(LAS unsigned char* lds, const Gemm g, const StaticOrder& S, const Epi& E) {
;     ...
;         const bool has_next = S.next(ui + 1, nxt);
;         const char* nA = has_next ? (const char*)g.A + (size_t)nxt.pm * tstepA + (size_t)(nxt.pn >> 2) * gstepA : cA; const char* nB = has_next ? (const char*)g.Bt + (size_t)nxt.pn * tstepB : cB;
;         for (int t = 0; t < nt; t += 2) {
;             const bool last = (t == nt - 2);
;             const char* a1 = cA + (size_t)(t + 1) * kstepA;
;             const char* a2 = last ? nA : cA + (size_t)(t + 2) * kstepA; const char* b2 = last ? nB : cB + (size_t)(t + 2) * kstep;
;             const char* a3 = a2 + kstepA; const char* b3 = b2 + kstep;
;             PG8_LDB(B0, 0, 0); PG8_SCHED; PG8_LDA(At, 0, 0); PG8_STAGE(PG8_SA(1, 1), a1 + hstepA, voffA);
;             PG8_WAIT_L(8); PG8_BAR; PG8_WAIT_L(0); PG8_MMA(0, 0, At, B0); PG8_BAR; PG8_SCHED;
.LBB0_602:
	s_ashr_i32 s53, s52, 31
	v_cmp_lt_i64_e32 vcc, s[4:5], v[182:183]
	s_lshl_b64 s[4:5], s[52:53], 21
	s_add_u32 s10, s15, s4
	s_addc_u32 s11, s16, s5
	s_ashr_i32 s4, s50, 2
	s_ashr_i32 s5, s4, 31
	s_lshl_b64 s[4:5], s[4:5], 11
	s_add_u32 s54, s10, s4
	s_addc_u32 s55, s11, s5
	s_and_b64 s[4:5], vcc, exec
	s_cselect_b32 s35, s55, s1
	s_cselect_b32 s36, s54, s0
	s_ashr_i32 s51, s50, 31
	s_lshl_b64 s[4:5], s[50:51], 19
	s_add_u32 s56, s17, s4
	s_addc_u32 s57, s18, s5
	s_and_b64 s[4:5], vcc, exec
	s_cselect_b32 s37, s57, s9
	s_cselect_b32 s51, s56, s8
	s_add_u32 s53, s8, 0x100
	v_mov_b32_e32 v2, 0
	s_addc_u32 s58, s9, 0
	s_mov_b32 s59, -2
	v_mov_b32_e32 v3, v2
	v_mov_b32_e32 v4, v2
	v_mov_b32_e32 v5, v2
	v_mov_b32_e32 v6, v2
	v_mov_b32_e32 v7, v2
	v_mov_b32_e32 v8, v2
	v_mov_b32_e32 v9, v2
	v_mov_b32_e32 v10, v2
	v_mov_b32_e32 v11, v2
	v_mov_b32_e32 v12, v2
	v_mov_b32_e32 v13, v2
	v_mov_b32_e32 v14, v2
	v_mov_b32_e32 v15, v2
	v_mov_b32_e32 v16, v2
	v_mov_b32_e32 v17, v2
	v_mov_b32_e32 v18, v2
	v_mov_b32_e32 v19, v2
	v_mov_b32_e32 v20, v2
	v_mov_b32_e32 v21, v2
	v_mov_b32_e32 v22, v2
	v_mov_b32_e32 v23, v2
	v_mov_b32_e32 v24, v2
	v_mov_b32_e32 v25, v2
	v_mov_b32_e32 v26, v2
	v_mov_b32_e32 v27, v2
	v_mov_b32_e32 v28, v2
	v_mov_b32_e32 v29, v2
	v_mov_b32_e32 v30, v2
	v_mov_b32_e32 v31, v2
	v_mov_b32_e32 v32, v2
	v_mov_b32_e32 v33, v2
	v_mov_b32_e32 v74, v2
	v_mov_b32_e32 v75, v2
	v_mov_b32_e32 v76, v2
	v_mov_b32_e32 v77, v2
	v_mov_b32_e32 v78, v2
	v_mov_b32_e32 v79, v2
	v_mov_b32_e32 v80, v2
	v_mov_b32_e32 v81, v2
	v_mov_b32_e32 v82, v2
	v_mov_b32_e32 v83, v2
	v_mov_b32_e32 v84, v2
	v_mov_b32_e32 v85, v2
	v_mov_b32_e32 v86, v2
	v_mov_b32_e32 v87, v2
	v_mov_b32_e32 v88, v2
	v_mov_b32_e32 v89, v2
	v_mov_b32_e32 v90, v2
	v_mov_b32_e32 v91, v2
	v_mov_b32_e32 v92, v2
	v_mov_b32_e32 v93, v2
	v_mov_b32_e32 v94, v2
	v_mov_b32_e32 v95, v2
	v_mov_b32_e32 v96, v2
	v_mov_b32_e32 v97, v2
	v_mov_b32_e32 v110, v2
	v_mov_b32_e32 v111, v2
	v_mov_b32_e32 v112, v2
	v_mov_b32_e32 v113, v2
	v_mov_b32_e32 v114, v2
	v_mov_b32_e32 v115, v2
	v_mov_b32_e32 v116, v2
	v_mov_b32_e32 v117, v2
	v_mov_b32_e32 v42, v2
	v_mov_b32_e32 v43, v2
	v_mov_b32_e32 v44, v2
	v_mov_b32_e32 v45, v2
	v_mov_b32_e32 v46, v2
	v_mov_b32_e32 v47, v2
	v_mov_b32_e32 v48, v2
	v_mov_b32_e32 v49, v2
	v_mov_b32_e32 v50, v2
	v_mov_b32_e32 v51, v2
	v_mov_b32_e32 v52, v2
	v_mov_b32_e32 v53, v2
	v_mov_b32_e32 v54, v2
	v_mov_b32_e32 v55, v2
	v_mov_b32_e32 v56, v2
	v_mov_b32_e32 v57, v2
	v_mov_b32_e32 v58, v2
	v_mov_b32_e32 v59, v2
	v_mov_b32_e32 v60, v2
	v_mov_b32_e32 v61, v2
	v_mov_b32_e32 v62, v2
	v_mov_b32_e32 v63, v2
	v_mov_b32_e32 v64, v2
	v_mov_b32_e32 v65, v2
	v_mov_b32_e32 v66, v2
	v_mov_b32_e32 v67, v2
	v_mov_b32_e32 v68, v2
	v_mov_b32_e32 v69, v2
	v_mov_b32_e32 v70, v2
	v_mov_b32_e32 v71, v2
	v_mov_b32_e32 v72, v2
	v_mov_b32_e32 v73, v2
	v_mov_b32_e32 v122, v2
	v_mov_b32_e32 v123, v2
	v_mov_b32_e32 v124, v2
	v_mov_b32_e32 v125, v2
	v_mov_b32_e32 v126, v2
	v_mov_b32_e32 v127, v2
	v_mov_b32_e32 v128, v2
	v_mov_b32_e32 v129, v2
	v_mov_b32_e32 v134, v2
	v_mov_b32_e32 v135, v2
	v_mov_b32_e32 v136, v2
	v_mov_b32_e32 v137, v2
	v_mov_b32_e32 v138, v2
	v_mov_b32_e32 v139, v2
	v_mov_b32_e32 v140, v2
	v_mov_b32_e32 v141, v2
	v_mov_b32_e32 v146, v2
	v_mov_b32_e32 v147, v2
	v_mov_b32_e32 v148, v2
	v_mov_b32_e32 v149, v2
	v_mov_b32_e32 v150, v2
	v_mov_b32_e32 v151, v2
	v_mov_b32_e32 v152, v2
	v_mov_b32_e32 v153, v2
	v_mov_b32_e32 v162, v2
	v_mov_b32_e32 v163, v2
	v_mov_b32_e32 v164, v2
	v_mov_b32_e32 v165, v2
	v_mov_b32_e32 v166, v2
	v_mov_b32_e32 v167, v2
	v_mov_b32_e32 v168, v2
	v_mov_b32_e32 v169, v2
	v_add_u32_e32 v250, 0x10000, v229
.LBB0_603:
	s_add_u32 s8, s0, 0x100
	s_addc_u32 s9, s1, 0
	s_add_i32 s60, 0, 0x10000
	ds_read_b128 v[34:37], v250
	ds_read_b128 v[38:41], v250 offset:1024
	ds_read_b128 v[98:101], v250 offset:2048
	ds_read_b128 v[102:105], v250 offset:3072
	s_cmp_eq_u32 s59, 12
	s_cselect_b32 s11, s35, s9
	s_cselect_b32 s10, s36, s8
	s_cselect_b32 s5, s37, s58
	s_cselect_b32 s4, s51, s53
	s_add_i32 m0, s20, 0xc000
	ds_read_b128 v[106:109], v231
	ds_read_b128 v[118:121], v231 offset:1024
	ds_read_b128 v[130:133], v231 offset:2048
	ds_read_b128 v[142:145], v231 offset:3072
	ds_read_b128 v[154:157], v231 offset:4096
	ds_read_b128 v[158:161], v231 offset:5120
	ds_read_b128 v[170:173], v231 offset:6144
	ds_read_b128 v[174:177], v231 offset:7168
	global_load_lds_dwordx4 v194, s[0:1]
	s_add_i32 m0, s20, 0xe000
	s_nop 0
	global_load_lds_dwordx4 v196, s[0:1]
	s_waitcnt lgkmcnt(8)
	s_barrier
	s_waitcnt lgkmcnt(0)
	v_mfma_f32_16x16x32_bf16 v[166:169], v[34:37], v[106:109], v[166:169]
	v_mfma_f32_16x16x32_bf16 v[162:165], v[98:101], v[106:109], v[162:165]
	v_mfma_f32_16x16x32_bf16 v[150:153], v[34:37], v[130:133], v[150:153]
	v_mfma_f32_16x16x32_bf16 v[146:149], v[98:101], v[130:133], v[146:149]
	v_mfma_f32_16x16x32_bf16 v[138:141], v[34:37], v[154:157], v[138:141]
	v_mfma_f32_16x16x32_bf16 v[134:137], v[98:101], v[154:157], v[134:137]
	v_mfma_f32_16x16x32_bf16 v[126:129], v[34:37], v[170:173], v[126:129]
	v_mfma_f32_16x16x32_bf16 v[122:125], v[98:101], v[170:173], v[122:125]
	v_mfma_f32_16x16x32_bf16 v[166:169], v[38:41], v[118:121], v[166:169]
	v_mfma_f32_16x16x32_bf16 v[162:165], v[102:105], v[118:121], v[162:165]
	v_mfma_f32_16x16x32_bf16 v[150:153], v[38:41], v[142:145], v[150:153]
	v_mfma_f32_16x16x32_bf16 v[146:149], v[102:105], v[142:145], v[146:149]
	v_mfma_f32_16x16x32_bf16 v[138:141], v[38:41], v[158:161], v[138:141]
	v_mfma_f32_16x16x32_bf16 v[134:137], v[102:105], v[158:161], v[134:137]
	v_mfma_f32_16x16x32_bf16 v[126:129], v[38:41], v[174:177], v[126:129]
	v_mfma_f32_16x16x32_bf16 v[122:125], v[102:105], v[174:177], v[122:125]
	s_barrier
; #define PG8_STAGE(bufoff, gbase, voff) do { _Pragma("unroll") for (int _i = 0; _i < 2; ++_i) \
;         __builtin_amdgcn_global_load_lds((const unsigned*)((const char*)(gbase) + (voff)[_i]), (LAS unsigned*)(lds + (bufoff) + ldsw + _i * 8192), 16, 0, 0); } while (0)
; #define PG8_LDA(dst, b, h) do { _Pragma("unroll") for (int m = 0; m < 4; ++m) _Pragma("unroll") for (int k = 0; k < 2; ++k) dst[m][k] = *(const LAS bf16x8*)(lds + PG8_SA(b, h) + aoff + m * 2048 + k * 1024); } while (0)
; #define PG8_LDB(dst, b, h) do { _Pragma("unroll") for (int n = 0; n < 2; ++n) _Pragma("unroll") for (int k = 0; k < 2; ++k) dst[n][k] = *(const LAS bf16x8*)(lds + PG8_SB(b, h) + boff + n * 2048 + k * 1024); } while (0)
; #define PG8_MMA(ai, bj, At, Bt) do { __builtin_amdgcn_s_setprio(1); _Pragma("unroll") for (int m = 0; m < 4; ++m) _Pragma("unroll") for (int n = 0; n < 2; ++n) _Pragma("unroll") for (int k = 0; k < 2; ++k) \
;         acc[ai][bj][m][n] = __builtin_amdgcn_mfma_f32_16x16x32_bf16(Bt[n][k], At[m][k], acc[ai][bj][m][n], 0, 0, 0); __builtin_amdgcn_s_setprio(0); } while (0)
; #define PG8_WAIT_V(n) asm volatile("s_waitcnt vmcnt(" #n ")" ::: "memory")
; #define PG8_WAIT_L(n) asm volatile("s_waitcnt lgkmcnt(" #n ")" ::: "memory")
; #define PG8_BAR __builtin_amdgcn_s_barrier()
; #define PG8_SCHED __builtin_amdgcn_sched_barrier(0)
; template <class Epi>
; __device__ __forceinline__ void gemm_phase(LAS unsigned char* lds, const Gemm g, const StaticOrder& S, const Epi& E) {
;     ...
;             PG8_LDB(B1, 0, 1); PG8_STAGE(PG8_SB(0, 0), b2, voffB);
;             PG8_BAR; PG8_WAIT_L(0); PG8_MMA(0, 1, At, B1); PG8_BAR;
;             PG8_LDA(At, 0, 1); PG8_STAGE(PG8_SA(0, 0), a2, voffA);
;             PG8_BAR; PG8_WAIT_L(0); PG8_MMA(1, 0, At, B0); PG8_BAR; PG8_SCHED;
;             PG8_STAGE(PG8_SB(0, 1), b2 + hstepB, voffB);
;             PG8_WAIT_V(6); PG8_BAR; PG8_MMA(1, 1, At, B1); PG8_BAR;
;             PG8_LDB(B0, 1, 0); PG8_SCHED; PG8_LDA(At, 1, 0); PG8_STAGE(PG8_SA(0, 1), a2 + hstepA, voffA);
	s_add_i32 s61, 0, 0x14000
	s_add_i32 s0, s60, s19
	ds_read_b128 v[198:201], v250 offset:16384
	ds_read_b128 v[202:205], v250 offset:17408
	ds_read_b128 v[206:209], v250 offset:18432
	ds_read_b128 v[210:213], v250 offset:19456
	s_add_u32 s100, s4, s6
	s_addc_u32 s101, s5, s7
	s_mov_b32 m0, s0
	s_nop 0
	global_load_lds_dwordx4 v0, s[4:5]
	s_add_i32 m0, s0, 0x2000
	s_nop 0
	global_load_lds_dwordx4 v188, s[4:5]
	s_barrier
	s_waitcnt lgkmcnt(0)
	v_mfma_f32_16x16x32_bf16 v[70:73], v[198:201], v[106:109], v[70:73]
	v_mfma_f32_16x16x32_bf16 v[66:69], v[206:209], v[106:109], v[66:69]
	v_mfma_f32_16x16x32_bf16 v[62:65], v[198:201], v[130:133], v[62:65]
	v_mfma_f32_16x16x32_bf16 v[58:61], v[206:209], v[130:133], v[58:61]
	v_mfma_f32_16x16x32_bf16 v[54:57], v[198:201], v[154:157], v[54:57]
	v_mfma_f32_16x16x32_bf16 v[50:53], v[206:209], v[154:157], v[50:53]
	v_mfma_f32_16x16x32_bf16 v[46:49], v[198:201], v[170:173], v[46:49]
	v_mfma_f32_16x16x32_bf16 v[42:45], v[206:209], v[170:173], v[42:45]
	v_mfma_f32_16x16x32_bf16 v[70:73], v[202:205], v[118:121], v[70:73]
	v_mfma_f32_16x16x32_bf16 v[66:69], v[210:213], v[118:121], v[66:69]
	v_mfma_f32_16x16x32_bf16 v[62:65], v[202:205], v[142:145], v[62:65]
	v_mfma_f32_16x16x32_bf16 v[58:61], v[210:213], v[142:145], v[58:61]
	v_mfma_f32_16x16x32_bf16 v[54:57], v[202:205], v[158:161], v[54:57]
	v_mfma_f32_16x16x32_bf16 v[50:53], v[210:213], v[158:161], v[50:53]
	v_mfma_f32_16x16x32_bf16 v[46:49], v[202:205], v[174:177], v[46:49]
	v_mfma_f32_16x16x32_bf16 v[42:45], v[210:213], v[174:177], v[42:45]
	s_mov_b32 m0, s20
	s_add_u32 vcc_lo, s10, s6
	s_addc_u32 vcc_hi, s11, s7
	s_barrier
	ds_read_b128 v[106:109], v231 offset:16384
	ds_read_b128 v[118:121], v231 offset:17408
	ds_read_b128 v[130:133], v231 offset:18432
	ds_read_b128 v[142:145], v231 offset:19456
	ds_read_b128 v[154:157], v231 offset:20480
	ds_read_b128 v[158:161], v231 offset:21504
	ds_read_b128 v[170:173], v231 offset:22528
	ds_read_b128 v[174:177], v231 offset:23552
	global_load_lds_dwordx4 v192, s[10:11]
	s_mov_b32 m0, s21
	s_nop 0
	global_load_lds_dwordx4 v190, s[10:11]
	s_barrier
	s_waitcnt lgkmcnt(0)
	v_mfma_f32_16x16x32_bf16 v[114:117], v[34:37], v[106:109], v[114:117]
	v_mfma_f32_16x16x32_bf16 v[110:113], v[98:101], v[106:109], v[110:113]
	v_mfma_f32_16x16x32_bf16 v[94:97], v[34:37], v[130:133], v[94:97]
	v_mfma_f32_16x16x32_bf16 v[90:93], v[98:101], v[130:133], v[90:93]
	v_mfma_f32_16x16x32_bf16 v[86:89], v[34:37], v[154:157], v[86:89]
	v_mfma_f32_16x16x32_bf16 v[82:85], v[98:101], v[154:157], v[82:85]
	v_mfma_f32_16x16x32_bf16 v[34:37], v[34:37], v[170:173], v[78:81]
	v_mfma_f32_16x16x32_bf16 v[114:117], v[38:41], v[118:121], v[114:117]
	v_mfma_f32_16x16x32_bf16 v[110:113], v[102:105], v[118:121], v[110:113]
	v_mfma_f32_16x16x32_bf16 v[94:97], v[38:41], v[142:145], v[94:97]
	v_mfma_f32_16x16x32_bf16 v[90:93], v[102:105], v[142:145], v[90:93]
	v_mfma_f32_16x16x32_bf16 v[86:89], v[38:41], v[158:161], v[86:89]
	v_mfma_f32_16x16x32_bf16 v[82:85], v[102:105], v[158:161], v[82:85]
	v_mfma_f32_16x16x32_bf16 v[34:37], v[38:41], v[174:177], v[34:37]
	v_mfma_f32_16x16x32_bf16 v[38:41], v[98:101], v[170:173], v[74:77]
	v_mfma_f32_16x16x32_bf16 v[38:41], v[102:105], v[174:177], v[38:41]
	s_barrier
	s_add_u32 s0, s4, 0x40000
	s_addc_u32 s1, s5, 0
	s_add_i32 s60, s61, s19
	s_mov_b32 m0, s60
	s_nop 0
	global_load_lds_dwordx4 v0, s[0:1]
	s_add_i32 m0, s60, 0x2000
	s_nop 0
	global_load_lds_dwordx4 v188, s[0:1]
	s_waitcnt vmcnt(6)
	s_barrier
	v_mfma_f32_16x16x32_bf16 v[30:33], v[198:201], v[106:109], v[30:33]
	v_mfma_f32_16x16x32_bf16 v[26:29], v[206:209], v[106:109], v[26:29]
	v_mfma_f32_16x16x32_bf16 v[22:25], v[198:201], v[130:133], v[22:25]
	v_mfma_f32_16x16x32_bf16 v[18:21], v[206:209], v[130:133], v[18:21]
	v_mfma_f32_16x16x32_bf16 v[14:17], v[198:201], v[154:157], v[14:17]
	v_mfma_f32_16x16x32_bf16 v[10:13], v[206:209], v[154:157], v[10:13]
	v_mfma_f32_16x16x32_bf16 v[6:9], v[198:201], v[170:173], v[6:9]
	v_mfma_f32_16x16x32_bf16 v[2:5], v[206:209], v[170:173], v[2:5]
	v_mfma_f32_16x16x32_bf16 v[30:33], v[202:205], v[118:121], v[30:33]
	v_mfma_f32_16x16x32_bf16 v[26:29], v[210:213], v[118:121], v[26:29]
	v_mfma_f32_16x16x32_bf16 v[22:25], v[202:205], v[142:145], v[22:25]
	v_mfma_f32_16x16x32_bf16 v[18:21], v[210:213], v[142:145], v[18:21]
	v_mfma_f32_16x16x32_bf16 v[14:17], v[202:205], v[158:161], v[14:17]
	v_mfma_f32_16x16x32_bf16 v[10:13], v[210:213], v[158:161], v[10:13]
	v_mfma_f32_16x16x32_bf16 v[6:9], v[202:205], v[174:177], v[6:9]
	v_mfma_f32_16x16x32_bf16 v[2:5], v[210:213], v[174:177], v[2:5]
	s_add_i32 s60, 0, 0x18000
	s_barrier
	ds_read_b128 v[74:77], v250 offset:32768
	ds_read_b128 v[78:81], v250 offset:33792
	ds_read_b128 v[98:101], v250 offset:34816
	ds_read_b128 v[102:105], v250 offset:35840
	s_add_u32 s0, s10, 0x100000
	s_addc_u32 s1, s11, 0
	s_mov_b32 m0, s22
	ds_read_b128 v[106:109], v231 offset:32768
	ds_read_b128 v[118:121], v231 offset:33792
	ds_read_b128 v[130:133], v231 offset:34816
	ds_read_b128 v[142:145], v231 offset:35840
	ds_read_b128 v[154:157], v231 offset:36864
	ds_read_b128 v[158:161], v231 offset:37888
	ds_read_b128 v[170:173], v231 offset:38912
	ds_read_b128 v[174:177], v231 offset:39936
	global_load_lds_dwordx4 v192, s[0:1]
	s_mov_b32 m0, s23
	s_nop 0
	global_load_lds_dwordx4 v190, s[0:1]
	s_waitcnt lgkmcnt(8)
	s_barrier
; #define PG8_STAGE(bufoff, gbase, voff) do { _Pragma("unroll") for (int _i = 0; _i < 2; ++_i) \
;         __builtin_amdgcn_global_load_lds((const unsigned*)((const char*)(gbase) + (voff)[_i]), (LAS unsigned*)(lds + (bufoff) + ldsw + _i * 8192), 16, 0, 0); } while (0)
; #define PG8_LDA(dst, b, h) do { _Pragma("unroll") for (int m = 0; m < 4; ++m) _Pragma("unroll") for (int k = 0; k < 2; ++k) dst[m][k] = *(const LAS bf16x8*)(lds + PG8_SA(b, h) + aoff + m * 2048 + k * 1024); } while (0)
; #define PG8_LDB(dst, b, h) do { _Pragma("unroll") for (int n = 0; n < 2; ++n) _Pragma("unroll") for (int k = 0; k < 2; ++k) dst[n][k] = *(const LAS bf16x8*)(lds + PG8_SB(b, h) + boff + n * 2048 + k * 1024); } while (0)
; #define PG8_MMA(ai, bj, At, Bt) do { __builtin_amdgcn_s_setprio(1); _Pragma("unroll") for (int m = 0; m < 4; ++m) _Pragma("unroll") for (int n = 0; n < 2; ++n) _Pragma("unroll") for (int k = 0; k < 2; ++k) \
;         acc[ai][bj][m][n] = __builtin_amdgcn_mfma_f32_16x16x32_bf16(Bt[n][k], At[m][k], acc[ai][bj][m][n], 0, 0, 0); __builtin_amdgcn_s_setprio(0); } while (0)
; #define PG8_WAIT_V(n) asm volatile("s_waitcnt vmcnt(" #n ")" ::: "memory")
; #define PG8_WAIT_L(n) asm volatile("s_waitcnt lgkmcnt(" #n ")" ::: "memory")
; #define PG8_BAR __builtin_amdgcn_s_barrier()
; #define PG8_SCHED __builtin_amdgcn_sched_barrier(0)
; template <class Epi>
; __device__ __forceinline__ void gemm_phase(LAS unsigned char* lds, const Gemm g, const StaticOrder& S, const Epi& E) {
;     ...
;             PG8_WAIT_L(8); PG8_BAR; PG8_WAIT_L(0); PG8_MMA(0, 0, At, B0); PG8_BAR; PG8_SCHED;
;             PG8_LDB(B1, 1, 1); PG8_STAGE(PG8_SB(1, 0), b3, voffB);
;             PG8_BAR; PG8_WAIT_L(0); PG8_MMA(0, 1, At, B1); PG8_BAR;
;             PG8_LDA(At, 1, 1); PG8_STAGE(PG8_SA(1, 0), a3, voffA);
;             PG8_BAR; PG8_WAIT_L(0); PG8_MMA(1, 0, At, B0); PG8_BAR; PG8_SCHED;
;             PG8_STAGE(PG8_SB(1, 1), b3 + hstepB, voffB);
;             PG8_WAIT_V(6); PG8_BAR; PG8_MMA(1, 1, At, B1); PG8_BAR;
	s_waitcnt lgkmcnt(0)
	v_mfma_f32_16x16x32_bf16 v[166:169], v[74:77], v[106:109], v[166:169]
	v_mfma_f32_16x16x32_bf16 v[162:165], v[98:101], v[106:109], v[162:165]
	v_mfma_f32_16x16x32_bf16 v[150:153], v[74:77], v[130:133], v[150:153]
	v_mfma_f32_16x16x32_bf16 v[146:149], v[98:101], v[130:133], v[146:149]
	v_mfma_f32_16x16x32_bf16 v[138:141], v[74:77], v[154:157], v[138:141]
	v_mfma_f32_16x16x32_bf16 v[134:137], v[98:101], v[154:157], v[134:137]
	v_mfma_f32_16x16x32_bf16 v[126:129], v[74:77], v[170:173], v[126:129]
	v_mfma_f32_16x16x32_bf16 v[122:125], v[98:101], v[170:173], v[122:125]
	v_mfma_f32_16x16x32_bf16 v[166:169], v[78:81], v[118:121], v[166:169]
	v_mfma_f32_16x16x32_bf16 v[162:165], v[102:105], v[118:121], v[162:165]
	v_mfma_f32_16x16x32_bf16 v[150:153], v[78:81], v[142:145], v[150:153]
	v_mfma_f32_16x16x32_bf16 v[146:149], v[102:105], v[142:145], v[146:149]
	v_mfma_f32_16x16x32_bf16 v[138:141], v[78:81], v[158:161], v[138:141]
	v_mfma_f32_16x16x32_bf16 v[134:137], v[102:105], v[158:161], v[134:137]
	v_mfma_f32_16x16x32_bf16 v[126:129], v[78:81], v[174:177], v[126:129]
	v_mfma_f32_16x16x32_bf16 v[122:125], v[102:105], v[174:177], v[122:125]
	s_barrier
	s_add_i32 s10, 0, 0x1c000
	s_add_i32 s0, s60, s19
	s_mov_b32 m0, s0
	ds_read_b128 v[198:201], v250 offset:49152
	ds_read_b128 v[202:205], v250 offset:50176
	ds_read_b128 v[206:209], v250 offset:51200
	ds_read_b128 v[210:213], v250 offset:52224
	global_load_lds_dwordx4 v0, s[100:101]
	s_add_i32 m0, s0, 0x2000
	s_nop 0
	global_load_lds_dwordx4 v188, s[100:101]
	s_barrier
	s_waitcnt lgkmcnt(0)
	v_mfma_f32_16x16x32_bf16 v[70:73], v[198:201], v[106:109], v[70:73]
	v_mfma_f32_16x16x32_bf16 v[66:69], v[206:209], v[106:109], v[66:69]
	v_mfma_f32_16x16x32_bf16 v[62:65], v[198:201], v[130:133], v[62:65]
	v_mfma_f32_16x16x32_bf16 v[58:61], v[206:209], v[130:133], v[58:61]
	v_mfma_f32_16x16x32_bf16 v[54:57], v[198:201], v[154:157], v[54:57]
	v_mfma_f32_16x16x32_bf16 v[50:53], v[206:209], v[154:157], v[50:53]
	v_mfma_f32_16x16x32_bf16 v[46:49], v[198:201], v[170:173], v[46:49]
	v_mfma_f32_16x16x32_bf16 v[42:45], v[206:209], v[170:173], v[42:45]
	v_mfma_f32_16x16x32_bf16 v[70:73], v[202:205], v[118:121], v[70:73]
	v_mfma_f32_16x16x32_bf16 v[66:69], v[210:213], v[118:121], v[66:69]
	v_mfma_f32_16x16x32_bf16 v[62:65], v[202:205], v[142:145], v[62:65]
	v_mfma_f32_16x16x32_bf16 v[58:61], v[210:213], v[142:145], v[58:61]
	v_mfma_f32_16x16x32_bf16 v[54:57], v[202:205], v[158:161], v[54:57]
	v_mfma_f32_16x16x32_bf16 v[50:53], v[210:213], v[158:161], v[50:53]
	v_mfma_f32_16x16x32_bf16 v[46:49], v[202:205], v[174:177], v[46:49]
	v_mfma_f32_16x16x32_bf16 v[42:45], v[210:213], v[174:177], v[42:45]
	s_mov_b32 m0, s24
	s_barrier
	ds_read_b128 v[106:109], v231 offset:49152
	ds_read_b128 v[118:121], v231 offset:50176
	ds_read_b128 v[130:133], v231 offset:51200
	ds_read_b128 v[142:145], v231 offset:52224
	ds_read_b128 v[154:157], v231 offset:53248
	ds_read_b128 v[158:161], v231 offset:54272
	ds_read_b128 v[170:173], v231 offset:55296
	ds_read_b128 v[174:177], v231 offset:56320
	global_load_lds_dwordx4 v192, vcc
	s_mov_b32 m0, s25
	s_nop 0
	global_load_lds_dwordx4 v190, vcc
	s_barrier
	s_waitcnt lgkmcnt(0)
	v_mfma_f32_16x16x32_bf16 v[114:117], v[74:77], v[106:109], v[114:117]
	v_mfma_f32_16x16x32_bf16 v[94:97], v[74:77], v[130:133], v[94:97]
	v_mfma_f32_16x16x32_bf16 v[86:89], v[74:77], v[154:157], v[86:89]
	v_mfma_f32_16x16x32_bf16 v[34:37], v[74:77], v[170:173], v[34:37]
	v_mfma_f32_16x16x32_bf16 v[114:117], v[78:81], v[118:121], v[114:117]
	v_mfma_f32_16x16x32_bf16 v[110:113], v[98:101], v[106:109], v[110:113]
	v_mfma_f32_16x16x32_bf16 v[94:97], v[78:81], v[142:145], v[94:97]
	v_mfma_f32_16x16x32_bf16 v[90:93], v[98:101], v[130:133], v[90:93]
	v_mfma_f32_16x16x32_bf16 v[86:89], v[78:81], v[158:161], v[86:89]
	v_mfma_f32_16x16x32_bf16 v[82:85], v[98:101], v[154:157], v[82:85]
	v_mfma_f32_16x16x32_bf16 v[78:81], v[78:81], v[174:177], v[34:37]
	v_mfma_f32_16x16x32_bf16 v[34:37], v[98:101], v[170:173], v[38:41]
	v_mfma_f32_16x16x32_bf16 v[110:113], v[102:105], v[118:121], v[110:113]
	v_mfma_f32_16x16x32_bf16 v[90:93], v[102:105], v[142:145], v[90:93]
	v_mfma_f32_16x16x32_bf16 v[82:85], v[102:105], v[158:161], v[82:85]
	v_mfma_f32_16x16x32_bf16 v[74:77], v[102:105], v[174:177], v[34:37]
	s_barrier
	s_add_u32 s0, s4, 0x40080
	s_addc_u32 s1, s5, 0
	s_add_i32 s4, s10, s19
	s_mov_b32 m0, s4
	s_nop 0
	global_load_lds_dwordx4 v0, s[0:1]
	s_add_i32 m0, s4, 0x2000
	s_nop 0
	global_load_lds_dwordx4 v188, s[0:1]
	s_waitcnt vmcnt(6)
	s_barrier
	v_mfma_f32_16x16x32_bf16 v[30:33], v[198:201], v[106:109], v[30:33]
	v_mfma_f32_16x16x32_bf16 v[26:29], v[206:209], v[106:109], v[26:29]
	v_mfma_f32_16x16x32_bf16 v[22:25], v[198:201], v[130:133], v[22:25]
	v_mfma_f32_16x16x32_bf16 v[18:21], v[206:209], v[130:133], v[18:21]
	v_mfma_f32_16x16x32_bf16 v[14:17], v[198:201], v[154:157], v[14:17]
	v_mfma_f32_16x16x32_bf16 v[10:13], v[206:209], v[154:157], v[10:13]
	v_mfma_f32_16x16x32_bf16 v[6:9], v[198:201], v[170:173], v[6:9]
	v_mfma_f32_16x16x32_bf16 v[2:5], v[206:209], v[170:173], v[2:5]
	v_mfma_f32_16x16x32_bf16 v[30:33], v[202:205], v[118:121], v[30:33]
	v_mfma_f32_16x16x32_bf16 v[26:29], v[210:213], v[118:121], v[26:29]
	v_mfma_f32_16x16x32_bf16 v[22:25], v[202:205], v[142:145], v[22:25]
	v_mfma_f32_16x16x32_bf16 v[18:21], v[210:213], v[142:145], v[18:21]
	v_mfma_f32_16x16x32_bf16 v[14:17], v[202:205], v[158:161], v[14:17]
	v_mfma_f32_16x16x32_bf16 v[10:13], v[210:213], v[158:161], v[10:13]
	v_mfma_f32_16x16x32_bf16 v[6:9], v[202:205], v[174:177], v[6:9]
	v_mfma_f32_16x16x32_bf16 v[2:5], v[210:213], v[174:177], v[2:5]
	s_add_i32 s59, s59, 2
	s_add_u32 s53, s53, 0x100
	s_addc_u32 s58, s58, 0
	s_cmp_gt_u32 s59, 13
	s_mov_b64 s[0:1], s[8:9]
	s_barrier
; __device__ __forceinline__ unsigned cvt_pk_bf16(float lo, float hi) { unsigned r; asm volatile("v_cvt_pk_bf16_f32 %0, %1, %2" : "=v"(r) : "v"(lo), "v"(hi)); return r; }
; __device__ __forceinline__ float bf_lo(unsigned w) { return __uint_as_float(w << 16); }
; __device__ __forceinline__ float bf_hi(unsigned w) { return __uint_as_float(w & 0xffff0000u); }
; __device__ __forceinline__ float silu_f(float z) { return z * fast_rcp(1.0f + __builtin_amdgcn_exp2f(z * -1.44269504f)); }
;     __device__ __forceinline__ void operator()(const f32x4 (&acc)[2][2][4][2], const Unit& u, int wr, int wc, int fr, int fq, const Pre&) const {
;         const int row0 = u.pm * BM + wr * 64 + fr, col0 = u.pn * BM + wc * 32 + 8 * fq;
;         f32x4 sc[2][2];
; #pragma unroll
;         for (int bj = 0; bj < 2; ++bj) { sc[bj][0] = *(const f32x4*)(scale + col0 + bj * HALF); sc[bj][1] = *(const f32x4*)(scale + col0 + bj * HALF + 4); }
; #pragma unroll
;         for (int bj = 0; bj < 2; ++bj) { const int c = col0 + bj * HALF;
;             u32x4 zv[8];
; #pragma unroll
;             for (int g8 = 0; g8 < 8; ++g8) zv[g8] = *(const u32x4*)(Z + (size_t)(row0 + (g8 >> 2) * HALF + (g8 & 3) * 16) * DE2 + c);
; #pragma unroll
;             for (int ai = 0; ai < 2; ++ai)
; #pragma unroll
;                 for (int m = 0; m < 4; ++m) { const int r = row0 + ai * HALF + m * 16;
;                     const u32x4 zw = zv[ai * 4 + m];
;                     const f32x4 a0 = acc[ai][bj][m][0] * sc[bj][0], a1 = acc[ai][bj][m][1] * sc[bj][1];
;                     u32x4 w;
;                     w.x = cvt_pk_bf16(a0[0] * silu_f(bf_lo(zw.x)), a0[1] * silu_f(bf_hi(zw.x)));
;                     w.y = cvt_pk_bf16(a0[2] * silu_f(bf_lo(zw.y)), a0[3] * silu_f(bf_hi(zw.y)));
;                     w.z = cvt_pk_bf16(a1[0] * silu_f(bf_lo(zw.z)), a1[1] * silu_f(bf_hi(zw.z)));
;                     w.w = cvt_pk_bf16(a1[2] * silu_f(bf_lo(zw.w)), a1[3] * silu_f(bf_hi(zw.w)));
	s_cbranch_scc0 .LBB0_603
	v_lshl_or_b32 v200, s34, 8, v230
	v_ashrrev_i32_e32 v201, 31, v200
	v_lshl_add_u32 v226, s27, 8, v228
	v_lshlrev_b64 v[216:217], 1, v[200:201]
	v_ashrrev_i32_e32 v227, 31, v226
	v_lshl_add_u64 v[106:107], s[46:47], 0, v[216:217]
	v_lshlrev_b64 v[204:205], 14, v[226:227]
	v_lshl_add_u64 v[38:39], v[200:201], 2, s[48:49]
	v_lshl_add_u64 v[108:109], v[106:107], 0, v[204:205]
	global_load_dwordx4 v[98:101], v[38:39], off offset:16
	global_load_dwordx4 v[102:105], v[38:39], off
	global_load_dwordx4 v[34:37], v[38:39], off offset:528
	s_nop 0
	global_load_dwordx4 v[38:41], v[38:39], off offset:512
	v_or_b32_e32 v224, 16, v226
	global_load_dwordx4 v[174:177], v[108:109], off
	v_ashrrev_i32_e32 v225, 31, v224
	v_or_b32_e32 v222, 32, v226
	v_lshlrev_b64 v[198:199], 14, v[224:225]
	v_ashrrev_i32_e32 v223, 31, v222
	v_or_b32_e32 v220, 48, v226
	v_lshl_add_u64 v[108:109], v[106:107], 0, v[198:199]
	v_lshlrev_b64 v[202:203], 14, v[222:223]
	v_ashrrev_i32_e32 v221, 31, v220
	v_add_u32_e32 v218, 0x80, v226
	global_load_dwordx4 v[170:173], v[108:109], off
	v_lshl_add_u64 v[108:109], v[106:107], 0, v[202:203]
	v_lshlrev_b64 v[206:207], 14, v[220:221]
	v_ashrrev_i32_e32 v219, 31, v218
	global_load_dwordx4 v[158:161], v[108:109], off
	v_lshl_add_u64 v[108:109], v[106:107], 0, v[206:207]
	v_lshlrev_b64 v[208:209], 14, v[218:219]
	global_load_dwordx4 v[154:157], v[108:109], off
	v_lshl_add_u64 v[108:109], v[106:107], 0, v[208:209]
	global_load_dwordx4 v[142:145], v[108:109], off
	v_add_u32_e32 v108, 0x90, v226
	v_ashrrev_i32_e32 v109, 31, v108
	v_lshlrev_b64 v[210:211], 14, v[108:109]
	v_lshl_add_u64 v[108:109], v[106:107], 0, v[210:211]
	global_load_dwordx4 v[130:133], v[108:109], off
	v_add_u32_e32 v108, 0xa0, v226
	v_ashrrev_i32_e32 v109, 31, v108
	v_lshlrev_b64 v[212:213], 14, v[108:109]
	v_lshl_add_u64 v[108:109], v[106:107], 0, v[212:213]
	global_load_dwordx4 v[118:121], v[108:109], off
	v_add_u32_e32 v108, 0xb0, v226
	v_ashrrev_i32_e32 v109, 31, v108
	v_lshlrev_b64 v[214:215], 14, v[108:109]
	v_lshl_add_u64 v[106:107], v[106:107], 0, v[214:215]
	global_load_dwordx4 v[106:109], v[106:107], off
	s_mov_b64 s[0:1], 0x120000
	s_mov_b32 s27, s52
	s_mov_b32 s34, s50
	s_mov_b64 s[8:9], s[56:57]
	s_waitcnt vmcnt(0)
	v_pk_mul_f32 v[146:147], v[146:147], v[98:99]
	v_pk_mul_f32 v[184:185], v[166:167], v[102:103]
	v_pk_mul_f32 v[166:167], v[164:165], v[100:101]
	v_pk_mul_f32 v[164:165], v[162:163], v[98:99]
	v_pk_mul_f32 v[168:169], v[168:169], v[104:105]
	v_lshlrev_b32_e32 v162, 16, v174
	v_mul_f32_e32 v163, 0xbfb8aa3b, v162
	v_exp_f32_e32 v163, v163
	v_pk_mul_f32 v[150:151], v[150:151], v[102:103]
	v_pk_mul_f32 v[152:153], v[152:153], v[104:105]
	v_pk_mul_f32 v[148:149], v[148:149], v[100:101]
	v_add_f32_e32 v163, 1.0, v163
	v_rcp_f32_e32 v163, v163
	v_pk_mul_f32 v[138:139], v[138:139], v[102:103]
	v_pk_mul_f32 v[140:141], v[140:141], v[104:105]
	v_pk_mul_f32 v[134:135], v[134:135], v[98:99]
	v_mul_f32_e32 v162, v163, v162
	v_and_b32_e32 v163, 0xffff0000, v174
	v_mul_f32_e32 v174, 0xbfb8aa3b, v163
	v_exp_f32_e32 v174, v174
	v_mul_f32_e32 v162, v184, v162
	v_pk_mul_f32 v[136:137], v[136:137], v[100:101]
	v_pk_mul_f32 v[126:127], v[126:127], v[102:103]
	v_add_f32_e32 v174, 1.0, v174
	v_rcp_f32_e32 v174, v174
	v_pk_mul_f32 v[128:129], v[128:129], v[104:105]
	v_pk_mul_f32 v[122:123], v[122:123], v[98:99]
	v_pk_mul_f32 v[124:125], v[124:125], v[100:101]
	v_mul_f32_e32 v163, v174, v163
	v_mul_f32_e32 v163, v185, v163
	v_cvt_pk_bf16_f32 v162, v162, v163
	v_lshlrev_b32_e32 v163, 16, v175
	v_mul_f32_e32 v174, 0xbfb8aa3b, v163
	v_exp_f32_e32 v174, v174
	v_pk_mul_f32 v[114:115], v[114:115], v[102:103]
	v_pk_mul_f32 v[116:117], v[116:117], v[104:105]
	v_pk_mul_f32 v[110:111], v[110:111], v[98:99]
	v_add_f32_e32 v174, 1.0, v174
	v_rcp_f32_e32 v174, v174
	v_pk_mul_f32 v[112:113], v[112:113], v[100:101]
	v_pk_mul_f32 v[94:95], v[94:95], v[102:103]
	v_pk_mul_f32 v[96:97], v[96:97], v[104:105]
	v_mul_f32_e32 v163, v174, v163
	v_mul_f32_e32 v163, v168, v163
	v_and_b32_e32 v168, 0xffff0000, v175
	v_mul_f32_e32 v174, 0xbfb8aa3b, v168
	v_exp_f32_e32 v174, v174
	v_pk_mul_f32 v[90:91], v[90:91], v[98:99]
	v_pk_mul_f32 v[92:93], v[92:93], v[100:101]
	v_pk_mul_f32 v[86:87], v[86:87], v[102:103]
	v_add_f32_e32 v174, 1.0, v174
	v_rcp_f32_e32 v174, v174
	v_pk_mul_f32 v[88:89], v[88:89], v[104:105]
	v_pk_mul_f32 v[82:83], v[82:83], v[98:99]
	v_pk_mul_f32 v[84:85], v[84:85], v[100:101]
	v_mul_f32_e32 v168, v174, v168
	v_mul_f32_e32 v168, v169, v168
	v_cvt_pk_bf16_f32 v163, v163, v168
	v_lshlrev_b32_e32 v168, 16, v176
	v_mul_f32_e32 v169, 0xbfb8aa3b, v168
	v_exp_f32_e32 v169, v169
	v_pk_mul_f32 v[78:79], v[78:79], v[102:103]
	v_pk_mul_f32 v[80:81], v[80:81], v[104:105]
	v_pk_mul_f32 v[74:75], v[74:75], v[98:99]
	v_add_f32_e32 v169, 1.0, v169
	v_rcp_f32_e32 v169, v169
	v_pk_mul_f32 v[76:77], v[76:77], v[100:101]
	v_pk_mul_f32 v[70:71], v[70:71], v[38:39]
	v_pk_mul_f32 v[72:73], v[72:73], v[40:41]
	v_mul_f32_e32 v168, v169, v168
	v_mul_f32_e32 v164, v164, v168
	v_and_b32_e32 v168, 0xffff0000, v176
	v_mul_f32_e32 v169, 0xbfb8aa3b, v168
	v_exp_f32_e32 v169, v169
	v_pk_mul_f32 v[66:67], v[66:67], v[34:35]
	v_pk_mul_f32 v[68:69], v[68:69], v[36:37]
	v_pk_mul_f32 v[62:63], v[62:63], v[38:39]
	v_add_f32_e32 v169, 1.0, v169
	v_rcp_f32_e32 v169, v169
	v_pk_mul_f32 v[64:65], v[64:65], v[40:41]
	v_pk_mul_f32 v[58:59], v[58:59], v[34:35]
	v_pk_mul_f32 v[60:61], v[60:61], v[36:37]
	v_mul_f32_e32 v168, v169, v168
	v_mul_f32_e32 v165, v165, v168
	v_cvt_pk_bf16_f32 v164, v164, v165
	v_lshlrev_b32_e32 v165, 16, v177
	v_mul_f32_e32 v168, 0xbfb8aa3b, v165
	v_exp_f32_e32 v168, v168
; __device__ __forceinline__ unsigned cvt_pk_bf16(float lo, float hi) { unsigned r; asm volatile("v_cvt_pk_bf16_f32 %0, %1, %2" : "=v"(r) : "v"(lo), "v"(hi)); return r; }
; __device__ __forceinline__ float bf_lo(unsigned w) { return __uint_as_float(w << 16); }
; __device__ __forceinline__ float bf_hi(unsigned w) { return __uint_as_float(w & 0xffff0000u); }
; __device__ __forceinline__ float silu_f(float z) { return z * fast_rcp(1.0f + __builtin_amdgcn_exp2f(z * -1.44269504f)); }
;     __device__ __forceinline__ void operator()(const f32x4 (&acc)[2][2][4][2], const Unit& u, int wr, int wc, int fr, int fq, const Pre&) const {
;     ...
;                 for (int m = 0; m < 4; ++m) { const int r = row0 + ai * HALF + m * 16;
;                     const u32x4 zw = zv[ai * 4 + m];
;                     const f32x4 a0 = acc[ai][bj][m][0] * sc[bj][0], a1 = acc[ai][bj][m][1] * sc[bj][1];
;                     u32x4 w;
;                     w.x = cvt_pk_bf16(a0[0] * silu_f(bf_lo(zw.x)), a0[1] * silu_f(bf_hi(zw.x)));
;                     w.y = cvt_pk_bf16(a0[2] * silu_f(bf_lo(zw.y)), a0[3] * silu_f(bf_hi(zw.y)));
;                     w.z = cvt_pk_bf16(a1[0] * silu_f(bf_lo(zw.z)), a1[1] * silu_f(bf_hi(zw.z)));
;                     w.w = cvt_pk_bf16(a1[2] * silu_f(bf_lo(zw.w)), a1[3] * silu_f(bf_hi(zw.w)));
;                     *(u32x4*)(O + (size_t)r * DE + c) = w; } }
	v_pk_mul_f32 v[54:55], v[54:55], v[38:39]
	v_pk_mul_f32 v[56:57], v[56:57], v[40:41]
	v_pk_mul_f32 v[50:51], v[50:51], v[34:35]
	v_add_f32_e32 v168, 1.0, v168
	v_rcp_f32_e32 v168, v168
	v_pk_mul_f32 v[52:53], v[52:53], v[36:37]
	v_pk_mul_f32 v[46:47], v[46:47], v[38:39]
	v_pk_mul_f32 v[48:49], v[48:49], v[40:41]
	v_mul_f32_e32 v165, v168, v165
	v_mul_f32_e32 v165, v166, v165
	v_and_b32_e32 v166, 0xffff0000, v177
	v_mul_f32_e32 v168, 0xbfb8aa3b, v166
	v_exp_f32_e32 v168, v168
	v_pk_mul_f32 v[42:43], v[42:43], v[34:35]
	v_pk_mul_f32 v[44:45], v[44:45], v[36:37]
	v_pk_mul_f32 v[30:31], v[30:31], v[38:39]
	v_add_f32_e32 v168, 1.0, v168
	v_rcp_f32_e32 v168, v168
	v_pk_mul_f32 v[32:33], v[32:33], v[40:41]
	v_pk_mul_f32 v[26:27], v[26:27], v[34:35]
	v_pk_mul_f32 v[28:29], v[28:29], v[36:37]
	v_mul_f32_e32 v166, v168, v166
	v_mul_f32_e32 v166, v167, v166
	v_cvt_pk_bf16_f32 v165, v165, v166
	v_lshlrev_b64 v[166:167], 13, v[226:227]
	v_lshl_add_u64 v[166:167], s[44:45], 0, v[166:167]
	v_lshl_add_u64 v[166:167], v[166:167], 0, v[216:217]
	global_store_dwordx4 v[166:167], v[162:165], off
	v_pk_mul_f32 v[22:23], v[22:23], v[38:39]
	v_pk_mul_f32 v[24:25], v[24:25], v[40:41]
	v_lshlrev_b32_e32 v162, 16, v170
	v_mul_f32_e32 v163, 0xbfb8aa3b, v162
	v_exp_f32_e32 v163, v163
	v_pk_mul_f32 v[18:19], v[18:19], v[34:35]
	v_pk_mul_f32 v[20:21], v[20:21], v[36:37]
	v_pk_mul_f32 v[14:15], v[14:15], v[38:39]
	v_add_f32_e32 v163, 1.0, v163
	v_rcp_f32_e32 v163, v163
	v_pk_mul_f32 v[16:17], v[16:17], v[40:41]
	v_pk_mul_f32 v[10:11], v[10:11], v[34:35]
	v_pk_mul_f32 v[12:13], v[12:13], v[36:37]
	v_mul_f32_e32 v162, v163, v162
	v_mul_f32_e32 v150, v150, v162
	v_and_b32_e32 v162, 0xffff0000, v170
	v_mul_f32_e32 v163, 0xbfb8aa3b, v162
	v_exp_f32_e32 v163, v163
	v_pk_mul_f32 v[6:7], v[6:7], v[38:39]
	v_pk_mul_f32 v[8:9], v[8:9], v[40:41]
	v_pk_mul_f32 v[2:3], v[2:3], v[34:35]
	v_add_f32_e32 v163, 1.0, v163
	v_rcp_f32_e32 v163, v163
	v_pk_mul_f32 v[4:5], v[4:5], v[36:37]
	v_mul_f32_e32 v162, v163, v162
	v_mul_f32_e32 v151, v151, v162
	v_cvt_pk_bf16_f32 v150, v150, v151
	v_lshlrev_b32_e32 v151, 16, v171
	v_mul_f32_e32 v162, 0xbfb8aa3b, v151
	v_exp_f32_e32 v162, v162
	s_nop 0
	v_add_f32_e32 v162, 1.0, v162
	v_rcp_f32_e32 v162, v162
	s_nop 0
	v_mul_f32_e32 v151, v162, v151
	v_mul_f32_e32 v151, v152, v151
	v_and_b32_e32 v152, 0xffff0000, v171
	v_mul_f32_e32 v162, 0xbfb8aa3b, v152
	v_exp_f32_e32 v162, v162
	s_nop 0
	v_add_f32_e32 v162, 1.0, v162
	v_rcp_f32_e32 v162, v162
	s_nop 0
	v_mul_f32_e32 v152, v162, v152
	v_mul_f32_e32 v152, v153, v152
	v_cvt_pk_bf16_f32 v151, v151, v152
	v_lshlrev_b32_e32 v152, 16, v172
	v_mul_f32_e32 v153, 0xbfb8aa3b, v152
	v_exp_f32_e32 v153, v153
	s_nop 0
	v_add_f32_e32 v153, 1.0, v153
	v_rcp_f32_e32 v153, v153
	s_nop 0
	v_mul_f32_e32 v152, v153, v152
	v_mul_f32_e32 v146, v146, v152
	v_and_b32_e32 v152, 0xffff0000, v172
	v_mul_f32_e32 v153, 0xbfb8aa3b, v152
	v_exp_f32_e32 v153, v153
	s_nop 0
	v_add_f32_e32 v153, 1.0, v153
	v_rcp_f32_e32 v153, v153
	s_nop 0
	v_mul_f32_e32 v152, v153, v152
	v_mul_f32_e32 v147, v147, v152
	v_cvt_pk_bf16_f32 v152, v146, v147
	v_lshlrev_b32_e32 v146, 16, v173
	v_mul_f32_e32 v147, 0xbfb8aa3b, v146
	v_exp_f32_e32 v147, v147
	s_nop 0
	v_add_f32_e32 v147, 1.0, v147
	v_rcp_f32_e32 v147, v147
	s_nop 0
	v_mul_f32_e32 v146, v147, v146
	v_and_b32_e32 v147, 0xffff0000, v173
	v_mul_f32_e32 v146, v148, v146
	v_mul_f32_e32 v148, 0xbfb8aa3b, v147
	v_exp_f32_e32 v148, v148
	s_nop 0
	v_add_f32_e32 v148, 1.0, v148
	v_rcp_f32_e32 v148, v148
	s_nop 0
	v_mul_f32_e32 v147, v148, v147
	v_lshlrev_b32_e32 v148, 16, v158
	v_mul_f32_e32 v147, v149, v147
	v_mul_f32_e32 v149, 0xbfb8aa3b, v148
	v_exp_f32_e32 v149, v149
	v_cvt_pk_bf16_f32 v153, v146, v147
	v_lshlrev_b64 v[146:147], 13, v[224:225]
	v_lshl_add_u64 v[146:147], s[44:45], 0, v[146:147]
	v_add_f32_e32 v149, 1.0, v149
	v_rcp_f32_e32 v149, v149
	v_lshl_add_u64 v[146:147], v[146:147], 0, v[216:217]
	global_store_dwordx4 v[146:147], v[150:153], off
	v_mul_f32_e32 v148, v149, v148
	v_mul_f32_e32 v138, v138, v148
	v_and_b32_e32 v148, 0xffff0000, v158
	v_mul_f32_e32 v149, 0xbfb8aa3b, v148
	v_exp_f32_e32 v149, v149
	s_nop 0
	v_add_f32_e32 v149, 1.0, v149
	v_rcp_f32_e32 v149, v149
	s_nop 0
	v_mul_f32_e32 v148, v149, v148
	v_mul_f32_e32 v139, v139, v148
	v_cvt_pk_bf16_f32 v138, v138, v139
	v_lshlrev_b32_e32 v139, 16, v159
	v_mul_f32_e32 v148, 0xbfb8aa3b, v139
	v_exp_f32_e32 v148, v148
	s_nop 0
	v_add_f32_e32 v148, 1.0, v148
	v_rcp_f32_e32 v148, v148
	s_nop 0
	v_mul_f32_e32 v139, v148, v139
	v_mul_f32_e32 v139, v140, v139
	v_and_b32_e32 v140, 0xffff0000, v159
	v_mul_f32_e32 v148, 0xbfb8aa3b, v140
	v_exp_f32_e32 v148, v148
	s_nop 0
	v_add_f32_e32 v148, 1.0, v148
	v_rcp_f32_e32 v148, v148
	s_nop 0
	v_mul_f32_e32 v140, v148, v140
	v_mul_f32_e32 v140, v141, v140
	v_cvt_pk_bf16_f32 v139, v139, v140
	v_lshlrev_b32_e32 v140, 16, v160
	v_mul_f32_e32 v141, 0xbfb8aa3b, v140
	v_exp_f32_e32 v141, v141
	s_nop 0
	v_add_f32_e32 v141, 1.0, v141
	v_rcp_f32_e32 v141, v141
	s_nop 0
	v_mul_f32_e32 v140, v141, v140
	v_mul_f32_e32 v134, v134, v140
	v_and_b32_e32 v140, 0xffff0000, v160
	v_mul_f32_e32 v141, 0xbfb8aa3b, v140
	v_exp_f32_e32 v141, v141
	s_nop 0
	v_add_f32_e32 v141, 1.0, v141
	v_rcp_f32_e32 v141, v141
	s_nop 0
	v_mul_f32_e32 v140, v141, v140
	v_mul_f32_e32 v135, v135, v140
	v_cvt_pk_bf16_f32 v140, v134, v135
	v_lshlrev_b32_e32 v134, 16, v161
	v_mul_f32_e32 v135, 0xbfb8aa3b, v134
	v_exp_f32_e32 v135, v135
	s_nop 0
	v_add_f32_e32 v135, 1.0, v135
	v_rcp_f32_e32 v135, v135
	s_nop 0
	v_mul_f32_e32 v134, v135, v134
	v_and_b32_e32 v135, 0xffff0000, v161
	v_mul_f32_e32 v134, v136, v134
	v_mul_f32_e32 v136, 0xbfb8aa3b, v135
; __device__ __forceinline__ unsigned cvt_pk_bf16(float lo, float hi) { unsigned r; asm volatile("v_cvt_pk_bf16_f32 %0, %1, %2" : "=v"(r) : "v"(lo), "v"(hi)); return r; }
; __device__ __forceinline__ float bf_lo(unsigned w) { return __uint_as_float(w << 16); }
; __device__ __forceinline__ float bf_hi(unsigned w) { return __uint_as_float(w & 0xffff0000u); }
; __device__ __forceinline__ float silu_f(float z) { return z * fast_rcp(1.0f + __builtin_amdgcn_exp2f(z * -1.44269504f)); }
;     __device__ __forceinline__ void operator()(const f32x4 (&acc)[2][2][4][2], const Unit& u, int wr, int wc, int fr, int fq, const Pre&) const {
;     ...
;                 for (int m = 0; m < 4; ++m) { const int r = row0 + ai * HALF + m * 16;
;                     const u32x4 zw = zv[ai * 4 + m];
;                     const f32x4 a0 = acc[ai][bj][m][0] * sc[bj][0], a1 = acc[ai][bj][m][1] * sc[bj][1];
;                     u32x4 w;
;                     w.x = cvt_pk_bf16(a0[0] * silu_f(bf_lo(zw.x)), a0[1] * silu_f(bf_hi(zw.x)));
;                     w.y = cvt_pk_bf16(a0[2] * silu_f(bf_lo(zw.y)), a0[3] * silu_f(bf_hi(zw.y)));
;                     w.z = cvt_pk_bf16(a1[0] * silu_f(bf_lo(zw.z)), a1[1] * silu_f(bf_hi(zw.z)));
;                     w.w = cvt_pk_bf16(a1[2] * silu_f(bf_lo(zw.w)), a1[3] * silu_f(bf_hi(zw.w)));
;                     *(u32x4*)(O + (size_t)r * DE + c) = w; } }
	v_exp_f32_e32 v136, v136
	s_nop 0
	v_add_f32_e32 v136, 1.0, v136
	v_rcp_f32_e32 v136, v136
	s_nop 0
	v_mul_f32_e32 v135, v136, v135
	v_lshlrev_b32_e32 v136, 16, v154
	v_mul_f32_e32 v135, v137, v135
	v_mul_f32_e32 v137, 0xbfb8aa3b, v136
	v_exp_f32_e32 v137, v137
	v_cvt_pk_bf16_f32 v141, v134, v135
	v_lshlrev_b64 v[134:135], 13, v[222:223]
	v_lshl_add_u64 v[134:135], s[44:45], 0, v[134:135]
	v_add_f32_e32 v137, 1.0, v137
	v_rcp_f32_e32 v137, v137
	v_lshl_add_u64 v[134:135], v[134:135], 0, v[216:217]
	global_store_dwordx4 v[134:135], v[138:141], off
	v_mul_f32_e32 v136, v137, v136
	v_mul_f32_e32 v126, v126, v136
	v_and_b32_e32 v136, 0xffff0000, v154
	v_mul_f32_e32 v137, 0xbfb8aa3b, v136
	v_exp_f32_e32 v137, v137
	s_nop 0
	v_add_f32_e32 v137, 1.0, v137
	v_rcp_f32_e32 v137, v137
	s_nop 0
	v_mul_f32_e32 v136, v137, v136
	v_mul_f32_e32 v127, v127, v136
	v_cvt_pk_bf16_f32 v126, v126, v127
	v_lshlrev_b32_e32 v127, 16, v155
	v_mul_f32_e32 v136, 0xbfb8aa3b, v127
	v_exp_f32_e32 v136, v136
	s_nop 0
	v_add_f32_e32 v136, 1.0, v136
	v_rcp_f32_e32 v136, v136
	s_nop 0
	v_mul_f32_e32 v127, v136, v127
	v_mul_f32_e32 v127, v128, v127
	v_and_b32_e32 v128, 0xffff0000, v155
	v_mul_f32_e32 v136, 0xbfb8aa3b, v128
	v_exp_f32_e32 v136, v136
	s_nop 0
	v_add_f32_e32 v136, 1.0, v136
	v_rcp_f32_e32 v136, v136
	s_nop 0
	v_mul_f32_e32 v128, v136, v128
	v_mul_f32_e32 v128, v129, v128
	v_cvt_pk_bf16_f32 v127, v127, v128
	v_lshlrev_b32_e32 v128, 16, v156
	v_mul_f32_e32 v129, 0xbfb8aa3b, v128
	v_exp_f32_e32 v129, v129
	s_nop 0
	v_add_f32_e32 v129, 1.0, v129
	v_rcp_f32_e32 v129, v129
	s_nop 0
	v_mul_f32_e32 v128, v129, v128
	v_mul_f32_e32 v122, v122, v128
	v_and_b32_e32 v128, 0xffff0000, v156
	v_mul_f32_e32 v129, 0xbfb8aa3b, v128
	v_exp_f32_e32 v129, v129
	s_nop 0
	v_add_f32_e32 v129, 1.0, v129
	v_rcp_f32_e32 v129, v129
	s_nop 0
	v_mul_f32_e32 v128, v129, v128
	v_mul_f32_e32 v123, v123, v128
	v_cvt_pk_bf16_f32 v128, v122, v123
	v_lshlrev_b32_e32 v122, 16, v157
	v_mul_f32_e32 v123, 0xbfb8aa3b, v122
	v_exp_f32_e32 v123, v123
	s_nop 0
	v_add_f32_e32 v123, 1.0, v123
	v_rcp_f32_e32 v123, v123
	s_nop 0
	v_mul_f32_e32 v122, v123, v122
	v_and_b32_e32 v123, 0xffff0000, v157
	v_mul_f32_e32 v122, v124, v122
	v_mul_f32_e32 v124, 0xbfb8aa3b, v123
	v_exp_f32_e32 v124, v124
	s_nop 0
	v_add_f32_e32 v124, 1.0, v124
	v_rcp_f32_e32 v124, v124
	s_nop 0
	v_mul_f32_e32 v123, v124, v123
	v_lshlrev_b32_e32 v124, 16, v142
	v_mul_f32_e32 v123, v125, v123
	v_mul_f32_e32 v125, 0xbfb8aa3b, v124
	v_exp_f32_e32 v125, v125
	v_cvt_pk_bf16_f32 v129, v122, v123
	v_lshlrev_b64 v[122:123], 13, v[220:221]
	v_lshl_add_u64 v[122:123], s[44:45], 0, v[122:123]
	v_add_f32_e32 v125, 1.0, v125
	v_rcp_f32_e32 v125, v125
	v_lshl_add_u64 v[122:123], v[122:123], 0, v[216:217]
	global_store_dwordx4 v[122:123], v[126:129], off
	v_mul_f32_e32 v124, v125, v124
	v_mul_f32_e32 v114, v114, v124
	v_and_b32_e32 v124, 0xffff0000, v142
	v_mul_f32_e32 v125, 0xbfb8aa3b, v124
	v_exp_f32_e32 v125, v125
	s_nop 0
	v_add_f32_e32 v125, 1.0, v125
	v_rcp_f32_e32 v125, v125
	s_nop 0
	v_mul_f32_e32 v124, v125, v124
	v_mul_f32_e32 v115, v115, v124
	v_cvt_pk_bf16_f32 v114, v114, v115
	v_lshlrev_b32_e32 v115, 16, v143
	v_mul_f32_e32 v124, 0xbfb8aa3b, v115
	v_exp_f32_e32 v124, v124
	s_nop 0
	v_add_f32_e32 v124, 1.0, v124
	v_rcp_f32_e32 v124, v124
	s_nop 0
	v_mul_f32_e32 v115, v124, v115
	v_mul_f32_e32 v115, v116, v115
	v_and_b32_e32 v116, 0xffff0000, v143
	v_mul_f32_e32 v124, 0xbfb8aa3b, v116
	v_exp_f32_e32 v124, v124
	s_nop 0
	v_add_f32_e32 v124, 1.0, v124
	v_rcp_f32_e32 v124, v124
	s_nop 0
	v_mul_f32_e32 v116, v124, v116
	v_mul_f32_e32 v116, v117, v116
	v_cvt_pk_bf16_f32 v115, v115, v116
	v_lshlrev_b32_e32 v116, 16, v144
	v_mul_f32_e32 v117, 0xbfb8aa3b, v116
	v_exp_f32_e32 v117, v117
	s_nop 0
	v_add_f32_e32 v117, 1.0, v117
	v_rcp_f32_e32 v117, v117
	s_nop 0
	v_mul_f32_e32 v116, v117, v116
	v_mul_f32_e32 v110, v110, v116
	v_and_b32_e32 v116, 0xffff0000, v144
	v_mul_f32_e32 v117, 0xbfb8aa3b, v116
	v_exp_f32_e32 v117, v117
	s_nop 0
	v_add_f32_e32 v117, 1.0, v117
	v_rcp_f32_e32 v117, v117
	s_nop 0
	v_mul_f32_e32 v116, v117, v116
	v_mul_f32_e32 v111, v111, v116
	v_cvt_pk_bf16_f32 v116, v110, v111
	v_lshlrev_b32_e32 v110, 16, v145
	v_mul_f32_e32 v111, 0xbfb8aa3b, v110
	v_exp_f32_e32 v111, v111
	s_nop 0
	v_add_f32_e32 v111, 1.0, v111
	v_rcp_f32_e32 v111, v111
	s_nop 0
	v_mul_f32_e32 v110, v111, v110
	v_and_b32_e32 v111, 0xffff0000, v145
	v_mul_f32_e32 v110, v112, v110
	v_mul_f32_e32 v112, 0xbfb8aa3b, v111
	v_exp_f32_e32 v112, v112
	s_nop 0
	v_add_f32_e32 v112, 1.0, v112
	v_rcp_f32_e32 v112, v112
	s_nop 0
	v_mul_f32_e32 v111, v112, v111
	v_mul_f32_e32 v111, v113, v111
	v_cvt_pk_bf16_f32 v117, v110, v111
	v_lshlrev_b64 v[110:111], 13, v[218:219]
	v_lshl_add_u64 v[110:111], s[44:45], 0, v[110:111]
	v_lshl_add_u64 v[112:113], v[110:111], 0, v[216:217]
	v_lshlrev_b32_e32 v110, 16, v130
	v_mul_f32_e32 v111, 0xbfb8aa3b, v110
	v_exp_f32_e32 v111, v111
	global_store_dwordx4 v[112:113], v[114:117], off
	v_add_f32_e32 v111, 1.0, v111
	v_rcp_f32_e32 v111, v111
	s_nop 0
	v_mul_f32_e32 v110, v111, v110
	v_mul_f32_e32 v94, v94, v110
	v_and_b32_e32 v110, 0xffff0000, v130
	v_mul_f32_e32 v111, 0xbfb8aa3b, v110
	v_exp_f32_e32 v111, v111
	s_nop 0
	v_add_f32_e32 v111, 1.0, v111
	v_rcp_f32_e32 v111, v111
	s_nop 0
	v_mul_f32_e32 v110, v111, v110
	v_mul_f32_e32 v95, v95, v110
	v_cvt_pk_bf16_f32 v94, v94, v95
	v_lshlrev_b32_e32 v95, 16, v131
	v_mul_f32_e32 v110, 0xbfb8aa3b, v95
	v_exp_f32_e32 v110, v110
	s_nop 0
	v_add_f32_e32 v110, 1.0, v110
	v_rcp_f32_e32 v110, v110
	s_nop 0
	v_mul_f32_e32 v95, v110, v95
	v_mul_f32_e32 v95, v96, v95
	v_and_b32_e32 v96, 0xffff0000, v131
; __device__ __forceinline__ unsigned cvt_pk_bf16(float lo, float hi) { unsigned r; asm volatile("v_cvt_pk_bf16_f32 %0, %1, %2" : "=v"(r) : "v"(lo), "v"(hi)); return r; }
; __device__ __forceinline__ float bf_lo(unsigned w) { return __uint_as_float(w << 16); }
; __device__ __forceinline__ float bf_hi(unsigned w) { return __uint_as_float(w & 0xffff0000u); }
; __device__ __forceinline__ float silu_f(float z) { return z * fast_rcp(1.0f + __builtin_amdgcn_exp2f(z * -1.44269504f)); }
;     __device__ __forceinline__ void operator()(const f32x4 (&acc)[2][2][4][2], const Unit& u, int wr, int wc, int fr, int fq, const Pre&) const {
;     ...
;         for (int bj = 0; bj < 2; ++bj) { const int c = col0 + bj * HALF;
;             u32x4 zv[8];
; #pragma unroll
;             for (int g8 = 0; g8 < 8; ++g8) zv[g8] = *(const u32x4*)(Z + (size_t)(row0 + (g8 >> 2) * HALF + (g8 & 3) * 16) * DE2 + c);
; #pragma unroll
;             for (int ai = 0; ai < 2; ++ai)
; #pragma unroll
;                 for (int m = 0; m < 4; ++m) { const int r = row0 + ai * HALF + m * 16;
;                     const u32x4 zw = zv[ai * 4 + m];
;                     const f32x4 a0 = acc[ai][bj][m][0] * sc[bj][0], a1 = acc[ai][bj][m][1] * sc[bj][1];
;                     u32x4 w;
;                     w.x = cvt_pk_bf16(a0[0] * silu_f(bf_lo(zw.x)), a0[1] * silu_f(bf_hi(zw.x)));
;                     w.y = cvt_pk_bf16(a0[2] * silu_f(bf_lo(zw.y)), a0[3] * silu_f(bf_hi(zw.y)));
;                     w.z = cvt_pk_bf16(a1[0] * silu_f(bf_lo(zw.z)), a1[1] * silu_f(bf_hi(zw.z)));
;                     w.w = cvt_pk_bf16(a1[2] * silu_f(bf_lo(zw.w)), a1[3] * silu_f(bf_hi(zw.w)));
;                     *(u32x4*)(O + (size_t)r * DE + c) = w; } }
	v_mul_f32_e32 v110, 0xbfb8aa3b, v96
	v_exp_f32_e32 v110, v110
	s_nop 0
	v_add_f32_e32 v110, 1.0, v110
	v_rcp_f32_e32 v110, v110
	s_nop 0
	v_mul_f32_e32 v96, v110, v96
	v_mul_f32_e32 v96, v97, v96
	v_cvt_pk_bf16_f32 v95, v95, v96
	v_lshlrev_b32_e32 v96, 16, v132
	v_mul_f32_e32 v97, 0xbfb8aa3b, v96
	v_exp_f32_e32 v97, v97
	v_lshl_add_u64 v[110:111], v[166:167], 0, s[0:1]
	s_mov_b64 s[0:1], 0x140000
	v_lshl_add_u64 v[114:115], v[166:167], 0, s[0:1]
	v_add_f32_e32 v97, 1.0, v97
	v_rcp_f32_e32 v97, v97
	s_mov_b64 s[0:1], 0x160000
	v_mul_f32_e32 v96, v97, v96
	v_mul_f32_e32 v90, v90, v96
	v_and_b32_e32 v96, 0xffff0000, v132
	v_mul_f32_e32 v97, 0xbfb8aa3b, v96
	v_exp_f32_e32 v97, v97
	s_nop 0
	v_add_f32_e32 v97, 1.0, v97
	v_rcp_f32_e32 v97, v97
	s_nop 0
	v_mul_f32_e32 v96, v97, v96
	v_mul_f32_e32 v91, v91, v96
	v_cvt_pk_bf16_f32 v96, v90, v91
	v_lshlrev_b32_e32 v90, 16, v133
	v_mul_f32_e32 v91, 0xbfb8aa3b, v90
	v_exp_f32_e32 v91, v91
	s_nop 0
	v_add_f32_e32 v91, 1.0, v91
	v_rcp_f32_e32 v91, v91
	s_nop 0
	v_mul_f32_e32 v90, v91, v90
	v_and_b32_e32 v91, 0xffff0000, v133
	v_mul_f32_e32 v90, v92, v90
	v_mul_f32_e32 v92, 0xbfb8aa3b, v91
	v_exp_f32_e32 v92, v92
	s_nop 0
	v_add_f32_e32 v92, 1.0, v92
	v_rcp_f32_e32 v92, v92
	s_nop 0
	v_mul_f32_e32 v91, v92, v91
	v_mul_f32_e32 v91, v93, v91
	v_cvt_pk_bf16_f32 v97, v90, v91
	v_add_co_u32_e32 v90, vcc, s41, v166
	s_nop 1
	v_addc_co_u32_e32 v91, vcc, 0, v167, vcc
	global_store_dwordx4 v[90:91], v[94:97], off
	v_lshlrev_b32_e32 v90, 16, v118
	v_mul_f32_e32 v91, 0xbfb8aa3b, v90
	v_exp_f32_e32 v91, v91
	s_nop 0
	v_add_f32_e32 v91, 1.0, v91
	v_rcp_f32_e32 v91, v91
	s_nop 0
	v_mul_f32_e32 v90, v91, v90
	v_mul_f32_e32 v86, v86, v90
	v_and_b32_e32 v90, 0xffff0000, v118
	v_mul_f32_e32 v91, 0xbfb8aa3b, v90
	v_exp_f32_e32 v91, v91
	s_nop 0
	v_add_f32_e32 v91, 1.0, v91
	v_rcp_f32_e32 v91, v91
	s_nop 0
	v_mul_f32_e32 v90, v91, v90
	v_mul_f32_e32 v87, v87, v90
	v_cvt_pk_bf16_f32 v86, v86, v87
	v_lshlrev_b32_e32 v87, 16, v119
	v_mul_f32_e32 v90, 0xbfb8aa3b, v87
	v_exp_f32_e32 v90, v90
	s_nop 0
	v_add_f32_e32 v90, 1.0, v90
	v_rcp_f32_e32 v90, v90
	s_nop 0
	v_mul_f32_e32 v87, v90, v87
	v_mul_f32_e32 v87, v88, v87
	v_and_b32_e32 v88, 0xffff0000, v119
	v_mul_f32_e32 v90, 0xbfb8aa3b, v88
	v_exp_f32_e32 v90, v90
	s_nop 0
	v_add_f32_e32 v90, 1.0, v90
	v_rcp_f32_e32 v90, v90
	s_nop 0
	v_mul_f32_e32 v88, v90, v88
	v_mul_f32_e32 v88, v89, v88
	v_cvt_pk_bf16_f32 v87, v87, v88
	v_lshlrev_b32_e32 v88, 16, v120
	v_mul_f32_e32 v89, 0xbfb8aa3b, v88
	v_exp_f32_e32 v89, v89
	s_nop 0
	v_add_f32_e32 v89, 1.0, v89
	v_rcp_f32_e32 v89, v89
	s_nop 0
	v_mul_f32_e32 v88, v89, v88
	v_mul_f32_e32 v82, v82, v88
	v_and_b32_e32 v88, 0xffff0000, v120
	v_mul_f32_e32 v89, 0xbfb8aa3b, v88
	v_exp_f32_e32 v89, v89
	s_nop 0
	v_add_f32_e32 v89, 1.0, v89
	v_rcp_f32_e32 v89, v89
	s_nop 0
	v_mul_f32_e32 v88, v89, v88
	v_mul_f32_e32 v83, v83, v88
	v_cvt_pk_bf16_f32 v88, v82, v83
	v_lshlrev_b32_e32 v82, 16, v121
	v_mul_f32_e32 v83, 0xbfb8aa3b, v82
	v_exp_f32_e32 v83, v83
	s_nop 0
	v_add_f32_e32 v83, 1.0, v83
	v_rcp_f32_e32 v83, v83
	s_nop 0
	v_mul_f32_e32 v82, v83, v82
	v_and_b32_e32 v83, 0xffff0000, v121
	v_mul_f32_e32 v82, v84, v82
	v_mul_f32_e32 v84, 0xbfb8aa3b, v83
	v_exp_f32_e32 v84, v84
	s_nop 0
	v_add_f32_e32 v84, 1.0, v84
	v_rcp_f32_e32 v84, v84
	s_nop 0
	v_mul_f32_e32 v83, v84, v83
	v_mul_f32_e32 v83, v85, v83
	v_cvt_pk_bf16_f32 v89, v82, v83
	v_add_co_u32_e32 v82, vcc, s65, v166
	s_nop 1
	v_addc_co_u32_e32 v83, vcc, 0, v167, vcc
	global_store_dwordx4 v[82:83], v[86:89], off
	v_lshlrev_b32_e32 v82, 16, v106
	v_mul_f32_e32 v83, 0xbfb8aa3b, v82
	v_exp_f32_e32 v83, v83
	s_nop 0
	v_add_f32_e32 v83, 1.0, v83
	v_rcp_f32_e32 v83, v83
	s_nop 0
	v_mul_f32_e32 v82, v83, v82
	v_mul_f32_e32 v78, v78, v82
	v_and_b32_e32 v82, 0xffff0000, v106
	v_mul_f32_e32 v83, 0xbfb8aa3b, v82
	v_exp_f32_e32 v83, v83
	s_nop 0
	v_add_f32_e32 v83, 1.0, v83
	v_rcp_f32_e32 v83, v83
	s_nop 0
	v_mul_f32_e32 v82, v83, v82
	v_mul_f32_e32 v79, v79, v82
	v_cvt_pk_bf16_f32 v78, v78, v79
	v_lshlrev_b32_e32 v79, 16, v107
	v_mul_f32_e32 v82, 0xbfb8aa3b, v79
	v_exp_f32_e32 v82, v82
	s_nop 0
	v_add_f32_e32 v82, 1.0, v82
	v_rcp_f32_e32 v82, v82
	s_nop 0
	v_mul_f32_e32 v79, v82, v79
	v_mul_f32_e32 v79, v80, v79
	v_and_b32_e32 v80, 0xffff0000, v107
	v_mul_f32_e32 v82, 0xbfb8aa3b, v80
	v_exp_f32_e32 v82, v82
	v_lshl_add_u64 v[106:107], v[166:167], 0, s[0:1]
	s_mov_b64 s[0:1], s[54:55]
	v_add_f32_e32 v82, 1.0, v82
	v_rcp_f32_e32 v82, v82
	s_nop 0
	v_mul_f32_e32 v80, v82, v80
	v_mul_f32_e32 v80, v81, v80
	v_cvt_pk_bf16_f32 v79, v79, v80
	v_lshlrev_b32_e32 v80, 16, v108
	v_mul_f32_e32 v81, 0xbfb8aa3b, v80
	v_exp_f32_e32 v81, v81
	s_nop 0
	v_add_f32_e32 v81, 1.0, v81
	v_rcp_f32_e32 v81, v81
	s_nop 0
	v_mul_f32_e32 v80, v81, v80
	v_mul_f32_e32 v74, v74, v80
	v_and_b32_e32 v80, 0xffff0000, v108
	v_mul_f32_e32 v81, 0xbfb8aa3b, v80
	v_exp_f32_e32 v81, v81
	s_nop 0
	v_add_f32_e32 v81, 1.0, v81
	v_rcp_f32_e32 v81, v81
	s_nop 0
	v_mul_f32_e32 v80, v81, v80
	v_mul_f32_e32 v75, v75, v80
	v_cvt_pk_bf16_f32 v80, v74, v75
	v_lshlrev_b32_e32 v74, 16, v109
	v_mul_f32_e32 v75, 0xbfb8aa3b, v74
	v_exp_f32_e32 v75, v75
	s_nop 0
	v_add_f32_e32 v75, 1.0, v75
	v_rcp_f32_e32 v75, v75
	s_nop 0
	v_mul_f32_e32 v74, v75, v74
	v_and_b32_e32 v75, 0xffff0000, v109
	v_mul_f32_e32 v74, v76, v74
	v_mul_f32_e32 v76, 0xbfb8aa3b, v75
	v_exp_f32_e32 v76, v76
	s_nop 0
	v_add_f32_e32 v76, 1.0, v76
	v_rcp_f32_e32 v76, v76
	s_nop 0
	v_mul_f32_e32 v75, v76, v75
	v_mul_f32_e32 v75, v77, v75
	v_cvt_pk_bf16_f32 v81, v74, v75
	v_add_co_u32_e32 v74, vcc, s70, v166
	v_lshl_add_u64 v[76:77], s[46:47], 0, v[204:205]
	s_nop 0
	v_addc_co_u32_e32 v75, vcc, 0, v167, vcc
	global_store_dwordx4 v[74:75], v[78:81], off
	v_or_b32_e32 v74, 0x80, v200
	v_ashrrev_i32_e32 v75, 31, v74
	v_lshlrev_b64 v[74:75], 1, v[74:75]
	v_lshl_add_u64 v[76:77], v[76:77], 0, v[74:75]
	global_load_dwordx4 v[102:105], v[76:77], off
	v_lshl_add_u64 v[76:77], s[46:47], 0, v[198:199]
	v_lshl_add_u64 v[76:77], v[76:77], 0, v[74:75]
	global_load_dwordx4 v[98:101], v[76:77], off
	v_lshl_add_u64 v[76:77], s[46:47], 0, v[202:203]
	v_lshl_add_u64 v[76:77], v[76:77], 0, v[74:75]
	global_load_dwordx4 v[94:97], v[76:77], off
	v_lshl_add_u64 v[76:77], s[46:47], 0, v[206:207]
	v_lshl_add_u64 v[76:77], v[76:77], 0, v[74:75]
	global_load_dwordx4 v[90:93], v[76:77], off
	v_lshl_add_u64 v[76:77], s[46:47], 0, v[208:209]
	v_lshl_add_u64 v[76:77], v[76:77], 0, v[74:75]
	global_load_dwordx4 v[86:89], v[76:77], off
	v_lshl_add_u64 v[76:77], s[46:47], 0, v[210:211]
	v_lshl_add_u64 v[76:77], v[76:77], 0, v[74:75]
	global_load_dwordx4 v[82:85], v[76:77], off
	v_lshl_add_u64 v[76:77], s[46:47], 0, v[212:213]
	v_lshl_add_u64 v[76:77], v[76:77], 0, v[74:75]
	global_load_dwordx4 v[78:81], v[76:77], off
	v_lshl_add_u64 v[76:77], s[46:47], 0, v[214:215]
	v_lshl_add_u64 v[74:75], v[76:77], 0, v[74:75]
	global_load_dwordx4 v[74:77], v[74:75], off
	s_and_b64 vcc, exec, s[42:43]
	s_waitcnt vmcnt(0)
; __device__ __forceinline__ unsigned cvt_pk_bf16(float lo, float hi) { unsigned r; asm volatile("v_cvt_pk_bf16_f32 %0, %1, %2" : "=v"(r) : "v"(lo), "v"(hi)); return r; }
; __device__ __forceinline__ float bf_lo(unsigned w) { return __uint_as_float(w << 16); }
; __device__ __forceinline__ float bf_hi(unsigned w) { return __uint_as_float(w & 0xffff0000u); }
; __device__ __forceinline__ float silu_f(float z) { return z * fast_rcp(1.0f + __builtin_amdgcn_exp2f(z * -1.44269504f)); }
;     __device__ __forceinline__ void operator()(const f32x4 (&acc)[2][2][4][2], const Unit& u, int wr, int wc, int fr, int fq, const Pre&) const {
;     ...
;                 for (int m = 0; m < 4; ++m) { const int r = row0 + ai * HALF + m * 16;
;                     const u32x4 zw = zv[ai * 4 + m];
;                     const f32x4 a0 = acc[ai][bj][m][0] * sc[bj][0], a1 = acc[ai][bj][m][1] * sc[bj][1];
;                     u32x4 w;
;                     w.x = cvt_pk_bf16(a0[0] * silu_f(bf_lo(zw.x)), a0[1] * silu_f(bf_hi(zw.x)));
;                     w.y = cvt_pk_bf16(a0[2] * silu_f(bf_lo(zw.y)), a0[3] * silu_f(bf_hi(zw.y)));
;                     w.z = cvt_pk_bf16(a1[0] * silu_f(bf_lo(zw.z)), a1[1] * silu_f(bf_hi(zw.z)));
;                     w.w = cvt_pk_bf16(a1[2] * silu_f(bf_lo(zw.w)), a1[3] * silu_f(bf_hi(zw.w)));
;                     *(u32x4*)(O + (size_t)r * DE + c) = w; } }
	v_lshlrev_b32_e32 v108, 16, v102
	v_mul_f32_e32 v109, 0xbfb8aa3b, v108
	v_exp_f32_e32 v109, v109
	v_and_b32_e32 v102, 0xffff0000, v102
	v_add_f32_e32 v109, 1.0, v109
	v_rcp_f32_e32 v109, v109
	s_nop 0
	v_mul_f32_e32 v108, v109, v108
	v_mul_f32_e32 v70, v70, v108
	v_mul_f32_e32 v108, 0xbfb8aa3b, v102
	v_exp_f32_e32 v108, v108
	s_nop 0
	v_add_f32_e32 v108, 1.0, v108
	v_rcp_f32_e32 v108, v108
	s_nop 0
	v_mul_f32_e32 v102, v108, v102
	v_mul_f32_e32 v71, v71, v102
	v_cvt_pk_bf16_f32 v70, v70, v71
	v_lshlrev_b32_e32 v71, 16, v103
	v_mul_f32_e32 v102, 0xbfb8aa3b, v71
	v_exp_f32_e32 v102, v102
	s_nop 0
	v_add_f32_e32 v102, 1.0, v102
	v_rcp_f32_e32 v102, v102
	s_nop 0
	v_mul_f32_e32 v71, v102, v71
	v_mul_f32_e32 v71, v72, v71
	v_and_b32_e32 v72, 0xffff0000, v103
	v_mul_f32_e32 v102, 0xbfb8aa3b, v72
	v_exp_f32_e32 v102, v102
	s_nop 0
	v_add_f32_e32 v102, 1.0, v102
	v_rcp_f32_e32 v102, v102
	s_nop 0
	v_mul_f32_e32 v72, v102, v72
	v_mul_f32_e32 v72, v73, v72
	v_cvt_pk_bf16_f32 v71, v71, v72
	v_lshlrev_b32_e32 v72, 16, v104
	v_mul_f32_e32 v73, 0xbfb8aa3b, v72
	v_exp_f32_e32 v73, v73
	s_nop 0
	v_add_f32_e32 v73, 1.0, v73
	v_rcp_f32_e32 v73, v73
	s_nop 0
	v_mul_f32_e32 v72, v73, v72
	v_mul_f32_e32 v66, v66, v72
	v_and_b32_e32 v72, 0xffff0000, v104
	v_mul_f32_e32 v73, 0xbfb8aa3b, v72
	v_exp_f32_e32 v73, v73
	s_nop 0
	v_add_f32_e32 v73, 1.0, v73
	v_rcp_f32_e32 v73, v73
	s_nop 0
	v_mul_f32_e32 v72, v73, v72
	v_mul_f32_e32 v67, v67, v72
	v_cvt_pk_bf16_f32 v72, v66, v67
	v_lshlrev_b32_e32 v66, 16, v105
	v_mul_f32_e32 v67, 0xbfb8aa3b, v66
	v_exp_f32_e32 v67, v67
	s_nop 0
	v_add_f32_e32 v67, 1.0, v67
	v_rcp_f32_e32 v67, v67
	s_nop 0
	v_mul_f32_e32 v66, v67, v66
	v_and_b32_e32 v67, 0xffff0000, v105
	v_mul_f32_e32 v66, v68, v66
	v_mul_f32_e32 v68, 0xbfb8aa3b, v67
	v_exp_f32_e32 v68, v68
	s_nop 0
	v_add_f32_e32 v68, 1.0, v68
	v_rcp_f32_e32 v68, v68
	s_nop 0
	v_mul_f32_e32 v67, v68, v67
	v_mul_f32_e32 v67, v69, v67
	v_cvt_pk_bf16_f32 v73, v66, v67
	v_lshlrev_b32_e32 v66, 16, v98
	v_mul_f32_e32 v67, 0xbfb8aa3b, v66
	v_exp_f32_e32 v67, v67
	global_store_dwordx4 v[166:167], v[70:73], off offset:256
	v_add_f32_e32 v67, 1.0, v67
	v_rcp_f32_e32 v67, v67
	s_nop 0
	v_mul_f32_e32 v66, v67, v66
	v_mul_f32_e32 v62, v62, v66
	v_and_b32_e32 v66, 0xffff0000, v98
	v_mul_f32_e32 v67, 0xbfb8aa3b, v66
	v_exp_f32_e32 v67, v67
	s_nop 0
	v_add_f32_e32 v67, 1.0, v67
	v_rcp_f32_e32 v67, v67
	s_nop 0
	v_mul_f32_e32 v66, v67, v66
	v_mul_f32_e32 v63, v63, v66
	v_cvt_pk_bf16_f32 v62, v62, v63
	v_lshlrev_b32_e32 v63, 16, v99
	v_mul_f32_e32 v66, 0xbfb8aa3b, v63
	v_exp_f32_e32 v66, v66
	s_nop 0
	v_add_f32_e32 v66, 1.0, v66
	v_rcp_f32_e32 v66, v66
	s_nop 0
	v_mul_f32_e32 v63, v66, v63
	v_mul_f32_e32 v63, v64, v63
	v_and_b32_e32 v64, 0xffff0000, v99
	v_mul_f32_e32 v66, 0xbfb8aa3b, v64
	v_exp_f32_e32 v66, v66
	s_nop 0
	v_add_f32_e32 v66, 1.0, v66
	v_rcp_f32_e32 v66, v66
	s_nop 0
	v_mul_f32_e32 v64, v66, v64
	v_mul_f32_e32 v64, v65, v64
	v_cvt_pk_bf16_f32 v63, v63, v64
	v_lshlrev_b32_e32 v64, 16, v100
	v_mul_f32_e32 v65, 0xbfb8aa3b, v64
	v_exp_f32_e32 v65, v65
	s_nop 0
	v_add_f32_e32 v65, 1.0, v65
	v_rcp_f32_e32 v65, v65
	s_nop 0
	v_mul_f32_e32 v64, v65, v64
	v_mul_f32_e32 v58, v58, v64
	v_and_b32_e32 v64, 0xffff0000, v100
	v_mul_f32_e32 v65, 0xbfb8aa3b, v64
	v_exp_f32_e32 v65, v65
	s_nop 0
	v_add_f32_e32 v65, 1.0, v65
	v_rcp_f32_e32 v65, v65
	s_nop 0
	v_mul_f32_e32 v64, v65, v64
	v_mul_f32_e32 v59, v59, v64
	v_cvt_pk_bf16_f32 v64, v58, v59
	v_lshlrev_b32_e32 v58, 16, v101
	v_mul_f32_e32 v59, 0xbfb8aa3b, v58
	v_exp_f32_e32 v59, v59
	s_nop 0
	v_add_f32_e32 v59, 1.0, v59
	v_rcp_f32_e32 v59, v59
	s_nop 0
	v_mul_f32_e32 v58, v59, v58
	v_and_b32_e32 v59, 0xffff0000, v101
	v_mul_f32_e32 v58, v60, v58
	v_mul_f32_e32 v60, 0xbfb8aa3b, v59
	v_exp_f32_e32 v60, v60
	s_nop 0
	v_add_f32_e32 v60, 1.0, v60
	v_rcp_f32_e32 v60, v60
	s_nop 0
	v_mul_f32_e32 v59, v60, v59
	v_mul_f32_e32 v59, v61, v59
	v_cvt_pk_bf16_f32 v65, v58, v59
	v_lshlrev_b32_e32 v58, 16, v94
	v_mul_f32_e32 v59, 0xbfb8aa3b, v58
	v_exp_f32_e32 v59, v59
	global_store_dwordx4 v[146:147], v[62:65], off offset:256
	v_add_f32_e32 v59, 1.0, v59
	v_rcp_f32_e32 v59, v59
	s_nop 0
	v_mul_f32_e32 v58, v59, v58
	v_mul_f32_e32 v54, v54, v58
	v_and_b32_e32 v58, 0xffff0000, v94
	v_mul_f32_e32 v59, 0xbfb8aa3b, v58
	v_exp_f32_e32 v59, v59
	s_nop 0
	v_add_f32_e32 v59, 1.0, v59
	v_rcp_f32_e32 v59, v59
	s_nop 0
	v_mul_f32_e32 v58, v59, v58
	v_mul_f32_e32 v55, v55, v58
	v_cvt_pk_bf16_f32 v54, v54, v55
	v_lshlrev_b32_e32 v55, 16, v95
	v_mul_f32_e32 v58, 0xbfb8aa3b, v55
	v_exp_f32_e32 v58, v58
	s_nop 0
	v_add_f32_e32 v58, 1.0, v58
	v_rcp_f32_e32 v58, v58
	s_nop 0
	v_mul_f32_e32 v55, v58, v55
	v_mul_f32_e32 v55, v56, v55
	v_and_b32_e32 v56, 0xffff0000, v95
	v_mul_f32_e32 v58, 0xbfb8aa3b, v56
	v_exp_f32_e32 v58, v58
	s_nop 0
	v_add_f32_e32 v58, 1.0, v58
	v_rcp_f32_e32 v58, v58
	s_nop 0
	v_mul_f32_e32 v56, v58, v56
	v_mul_f32_e32 v56, v57, v56
	v_cvt_pk_bf16_f32 v55, v55, v56
	v_lshlrev_b32_e32 v56, 16, v96
	v_mul_f32_e32 v57, 0xbfb8aa3b, v56
	v_exp_f32_e32 v57, v57
	s_nop 0
	v_add_f32_e32 v57, 1.0, v57
	v_rcp_f32_e32 v57, v57
	s_nop 0
	v_mul_f32_e32 v56, v57, v56
	v_mul_f32_e32 v50, v50, v56
	v_and_b32_e32 v56, 0xffff0000, v96
	v_mul_f32_e32 v57, 0xbfb8aa3b, v56
	v_exp_f32_e32 v57, v57
	s_nop 0
	v_add_f32_e32 v57, 1.0, v57
	v_rcp_f32_e32 v57, v57
	s_nop 0
	v_mul_f32_e32 v56, v57, v56
	v_mul_f32_e32 v51, v51, v56
	v_cvt_pk_bf16_f32 v56, v50, v51
	v_lshlrev_b32_e32 v50, 16, v97
	v_mul_f32_e32 v51, 0xbfb8aa3b, v50
	v_exp_f32_e32 v51, v51
	s_nop 0
	v_add_f32_e32 v51, 1.0, v51
	v_rcp_f32_e32 v51, v51
	s_nop 0
	v_mul_f32_e32 v50, v51, v50
	v_and_b32_e32 v51, 0xffff0000, v97
; __device__ __forceinline__ unsigned cvt_pk_bf16(float lo, float hi) { unsigned r; asm volatile("v_cvt_pk_bf16_f32 %0, %1, %2" : "=v"(r) : "v"(lo), "v"(hi)); return r; }
; __device__ __forceinline__ float bf_lo(unsigned w) { return __uint_as_float(w << 16); }
; __device__ __forceinline__ float bf_hi(unsigned w) { return __uint_as_float(w & 0xffff0000u); }
; __device__ __forceinline__ float silu_f(float z) { return z * fast_rcp(1.0f + __builtin_amdgcn_exp2f(z * -1.44269504f)); }
;     __device__ __forceinline__ void operator()(const f32x4 (&acc)[2][2][4][2], const Unit& u, int wr, int wc, int fr, int fq, const Pre&) const {
;     ...
;                 for (int m = 0; m < 4; ++m) { const int r = row0 + ai * HALF + m * 16;
;                     const u32x4 zw = zv[ai * 4 + m];
;                     const f32x4 a0 = acc[ai][bj][m][0] * sc[bj][0], a1 = acc[ai][bj][m][1] * sc[bj][1];
;                     u32x4 w;
;                     w.x = cvt_pk_bf16(a0[0] * silu_f(bf_lo(zw.x)), a0[1] * silu_f(bf_hi(zw.x)));
;                     w.y = cvt_pk_bf16(a0[2] * silu_f(bf_lo(zw.y)), a0[3] * silu_f(bf_hi(zw.y)));
;                     w.z = cvt_pk_bf16(a1[0] * silu_f(bf_lo(zw.z)), a1[1] * silu_f(bf_hi(zw.z)));
;                     w.w = cvt_pk_bf16(a1[2] * silu_f(bf_lo(zw.w)), a1[3] * silu_f(bf_hi(zw.w)));
;                     *(u32x4*)(O + (size_t)r * DE + c) = w; } }
	v_mul_f32_e32 v50, v52, v50
	v_mul_f32_e32 v52, 0xbfb8aa3b, v51
	v_exp_f32_e32 v52, v52
	s_nop 0
	v_add_f32_e32 v52, 1.0, v52
	v_rcp_f32_e32 v52, v52
	s_nop 0
	v_mul_f32_e32 v51, v52, v51
	v_mul_f32_e32 v51, v53, v51
	v_cvt_pk_bf16_f32 v57, v50, v51
	v_lshlrev_b32_e32 v50, 16, v90
	v_mul_f32_e32 v51, 0xbfb8aa3b, v50
	v_exp_f32_e32 v51, v51
	global_store_dwordx4 v[134:135], v[54:57], off offset:256
	v_add_f32_e32 v51, 1.0, v51
	v_rcp_f32_e32 v51, v51
	s_nop 0
	v_mul_f32_e32 v50, v51, v50
	v_mul_f32_e32 v46, v46, v50
	v_and_b32_e32 v50, 0xffff0000, v90
	v_mul_f32_e32 v51, 0xbfb8aa3b, v50
	v_exp_f32_e32 v51, v51
	s_nop 0
	v_add_f32_e32 v51, 1.0, v51
	v_rcp_f32_e32 v51, v51
	s_nop 0
	v_mul_f32_e32 v50, v51, v50
	v_mul_f32_e32 v47, v47, v50
	v_cvt_pk_bf16_f32 v46, v46, v47
	v_lshlrev_b32_e32 v47, 16, v91
	v_mul_f32_e32 v50, 0xbfb8aa3b, v47
	v_exp_f32_e32 v50, v50
	s_nop 0
	v_add_f32_e32 v50, 1.0, v50
	v_rcp_f32_e32 v50, v50
	s_nop 0
	v_mul_f32_e32 v47, v50, v47
	v_mul_f32_e32 v47, v48, v47
	v_and_b32_e32 v48, 0xffff0000, v91
	v_mul_f32_e32 v50, 0xbfb8aa3b, v48
	v_exp_f32_e32 v50, v50
	s_nop 0
	v_add_f32_e32 v50, 1.0, v50
	v_rcp_f32_e32 v50, v50
	s_nop 0
	v_mul_f32_e32 v48, v50, v48
	v_mul_f32_e32 v48, v49, v48
	v_cvt_pk_bf16_f32 v47, v47, v48
	v_lshlrev_b32_e32 v48, 16, v92
	v_mul_f32_e32 v49, 0xbfb8aa3b, v48
	v_exp_f32_e32 v49, v49
	s_nop 0
	v_add_f32_e32 v49, 1.0, v49
	v_rcp_f32_e32 v49, v49
	s_nop 0
	v_mul_f32_e32 v48, v49, v48
	v_mul_f32_e32 v42, v42, v48
	v_and_b32_e32 v48, 0xffff0000, v92
	v_mul_f32_e32 v49, 0xbfb8aa3b, v48
	v_exp_f32_e32 v49, v49
	s_nop 0
	v_add_f32_e32 v49, 1.0, v49
	v_rcp_f32_e32 v49, v49
	s_nop 0
	v_mul_f32_e32 v48, v49, v48
	v_mul_f32_e32 v43, v43, v48
	v_cvt_pk_bf16_f32 v48, v42, v43
	v_lshlrev_b32_e32 v42, 16, v93
	v_mul_f32_e32 v43, 0xbfb8aa3b, v42
	v_exp_f32_e32 v43, v43
	s_nop 0
	v_add_f32_e32 v43, 1.0, v43
	v_rcp_f32_e32 v43, v43
	s_nop 0
	v_mul_f32_e32 v42, v43, v42
	v_and_b32_e32 v43, 0xffff0000, v93
	v_mul_f32_e32 v42, v44, v42
	v_mul_f32_e32 v44, 0xbfb8aa3b, v43
	v_exp_f32_e32 v44, v44
	s_nop 0
	v_add_f32_e32 v44, 1.0, v44
	v_rcp_f32_e32 v44, v44
	s_nop 0
	v_mul_f32_e32 v43, v44, v43
	v_mul_f32_e32 v43, v45, v43
	v_cvt_pk_bf16_f32 v49, v42, v43
	v_lshlrev_b32_e32 v42, 16, v86
	v_mul_f32_e32 v43, 0xbfb8aa3b, v42
	v_exp_f32_e32 v43, v43
	global_store_dwordx4 v[122:123], v[46:49], off offset:256
	v_add_f32_e32 v43, 1.0, v43
	v_rcp_f32_e32 v43, v43
	s_nop 0
	v_mul_f32_e32 v42, v43, v42
	v_mul_f32_e32 v30, v30, v42
	v_and_b32_e32 v42, 0xffff0000, v86
	v_mul_f32_e32 v43, 0xbfb8aa3b, v42
	v_exp_f32_e32 v43, v43
	s_nop 0
	v_add_f32_e32 v43, 1.0, v43
	v_rcp_f32_e32 v43, v43
	s_nop 0
	v_mul_f32_e32 v42, v43, v42
	v_mul_f32_e32 v31, v31, v42
	v_cvt_pk_bf16_f32 v30, v30, v31
	v_lshlrev_b32_e32 v31, 16, v87
	v_mul_f32_e32 v42, 0xbfb8aa3b, v31
	v_exp_f32_e32 v42, v42
	s_nop 0
	v_add_f32_e32 v42, 1.0, v42
	v_rcp_f32_e32 v42, v42
	s_nop 0
	v_mul_f32_e32 v31, v42, v31
	v_mul_f32_e32 v31, v32, v31
	v_and_b32_e32 v32, 0xffff0000, v87
	v_mul_f32_e32 v42, 0xbfb8aa3b, v32
	v_exp_f32_e32 v42, v42
	s_nop 0
	v_add_f32_e32 v42, 1.0, v42
	v_rcp_f32_e32 v42, v42
	s_nop 0
	v_mul_f32_e32 v32, v42, v32
	v_mul_f32_e32 v32, v33, v32
	v_cvt_pk_bf16_f32 v31, v31, v32
	v_lshlrev_b32_e32 v32, 16, v88
	v_mul_f32_e32 v33, 0xbfb8aa3b, v32
	v_exp_f32_e32 v33, v33
	s_nop 0
	v_add_f32_e32 v33, 1.0, v33
	v_rcp_f32_e32 v33, v33
	s_nop 0
	v_mul_f32_e32 v32, v33, v32
	v_mul_f32_e32 v26, v26, v32
	v_and_b32_e32 v32, 0xffff0000, v88
	v_mul_f32_e32 v33, 0xbfb8aa3b, v32
	v_exp_f32_e32 v33, v33
	s_nop 0
	v_add_f32_e32 v33, 1.0, v33
	v_rcp_f32_e32 v33, v33
	s_nop 0
	v_mul_f32_e32 v32, v33, v32
	v_mul_f32_e32 v27, v27, v32
	v_cvt_pk_bf16_f32 v32, v26, v27
	v_lshlrev_b32_e32 v26, 16, v89
	v_mul_f32_e32 v27, 0xbfb8aa3b, v26
	v_exp_f32_e32 v27, v27
	s_nop 0
	v_add_f32_e32 v27, 1.0, v27
	v_rcp_f32_e32 v27, v27
	s_nop 0
	v_mul_f32_e32 v26, v27, v26
	v_and_b32_e32 v27, 0xffff0000, v89
	v_mul_f32_e32 v26, v28, v26
	v_mul_f32_e32 v28, 0xbfb8aa3b, v27
	v_exp_f32_e32 v28, v28
	s_nop 0
	v_add_f32_e32 v28, 1.0, v28
	v_rcp_f32_e32 v28, v28
	s_nop 0
	v_mul_f32_e32 v27, v28, v27
	v_mul_f32_e32 v27, v29, v27
	v_cvt_pk_bf16_f32 v33, v26, v27
	v_lshlrev_b32_e32 v26, 16, v82
	v_mul_f32_e32 v27, 0xbfb8aa3b, v26
	v_exp_f32_e32 v27, v27
	global_store_dwordx4 v[112:113], v[30:33], off offset:256
	v_add_f32_e32 v27, 1.0, v27
	v_rcp_f32_e32 v27, v27
	s_nop 0
	v_mul_f32_e32 v26, v27, v26
	v_mul_f32_e32 v22, v22, v26
	v_and_b32_e32 v26, 0xffff0000, v82
	v_mul_f32_e32 v27, 0xbfb8aa3b, v26
	v_exp_f32_e32 v27, v27
	s_nop 0
	v_add_f32_e32 v27, 1.0, v27
	v_rcp_f32_e32 v27, v27
	s_nop 0
	v_mul_f32_e32 v26, v27, v26
	v_mul_f32_e32 v23, v23, v26
	v_cvt_pk_bf16_f32 v22, v22, v23
	v_lshlrev_b32_e32 v23, 16, v83
	v_mul_f32_e32 v26, 0xbfb8aa3b, v23
	v_exp_f32_e32 v26, v26
	s_nop 0
	v_add_f32_e32 v26, 1.0, v26
	v_rcp_f32_e32 v26, v26
	s_nop 0
	v_mul_f32_e32 v23, v26, v23
	v_mul_f32_e32 v23, v24, v23
	v_and_b32_e32 v24, 0xffff0000, v83
	v_mul_f32_e32 v26, 0xbfb8aa3b, v24
	v_exp_f32_e32 v26, v26
	s_nop 0
	v_add_f32_e32 v26, 1.0, v26
	v_rcp_f32_e32 v26, v26
; __device__ __forceinline__ unsigned cvt_pk_bf16(float lo, float hi) { unsigned r; asm volatile("v_cvt_pk_bf16_f32 %0, %1, %2" : "=v"(r) : "v"(lo), "v"(hi)); return r; }
; __device__ __forceinline__ float bf_lo(unsigned w) { return __uint_as_float(w << 16); }
; __device__ __forceinline__ float bf_hi(unsigned w) { return __uint_as_float(w & 0xffff0000u); }
; __device__ __forceinline__ float silu_f(float z) { return z * fast_rcp(1.0f + __builtin_amdgcn_exp2f(z * -1.44269504f)); }
; #define PG8_WAIT_V(n) asm volatile("s_waitcnt vmcnt(" #n ")" ::: "memory")
; #define PG8_BAR __builtin_amdgcn_s_barrier()
; template <class Epi>
; __device__ __forceinline__ void gemm_phase(LAS unsigned char* lds, const Gemm g, const StaticOrder& S, const Epi& E) {
;     ...
;         if (!has_next) break;
; #pragma unroll
;         for (int a = 0; a < 2; ++a)
; #pragma unroll
;             for (int b = 0; b < 2; ++b)
; #pragma unroll
;                 for (int m = 0; m < 4; ++m)
; #pragma unroll
;                     for (int n = 0; n < 2; ++n) acc[a][b][m][n] = (f32x4){0.f, 0.f, 0.f, 0.f};
;         cur = nxt; cA = nA; cB = nB; ++ui;
;         pre = E.pre(cur, wr, fr);
;     }
;     PG8_WAIT_V(0);
;     if (wr == 0) PG8_BAR;
;     __device__ __forceinline__ void operator()(const f32x4 (&acc)[2][2][4][2], const Unit& u, int wr, int wc, int fr, int fq, const Pre&) const {
;     ...
;                 for (int m = 0; m < 4; ++m) { const int r = row0 + ai * HALF + m * 16;
;                     const u32x4 zw = zv[ai * 4 + m];
;                     const f32x4 a0 = acc[ai][bj][m][0] * sc[bj][0], a1 = acc[ai][bj][m][1] * sc[bj][1];
;                     u32x4 w;
;                     w.x = cvt_pk_bf16(a0[0] * silu_f(bf_lo(zw.x)), a0[1] * silu_f(bf_hi(zw.x)));
;                     w.y = cvt_pk_bf16(a0[2] * silu_f(bf_lo(zw.y)), a0[3] * silu_f(bf_hi(zw.y)));
;                     w.z = cvt_pk_bf16(a1[0] * silu_f(bf_lo(zw.z)), a1[1] * silu_f(bf_hi(zw.z)));
;                     w.w = cvt_pk_bf16(a1[2] * silu_f(bf_lo(zw.w)), a1[3] * silu_f(bf_hi(zw.w)));
;                     *(u32x4*)(O + (size_t)r * DE + c) = w; } }
	s_nop 0
	v_mul_f32_e32 v24, v26, v24
	v_mul_f32_e32 v24, v25, v24
	v_cvt_pk_bf16_f32 v23, v23, v24
	v_lshlrev_b32_e32 v24, 16, v84
	v_mul_f32_e32 v25, 0xbfb8aa3b, v24
	v_exp_f32_e32 v25, v25
	s_nop 0
	v_add_f32_e32 v25, 1.0, v25
	v_rcp_f32_e32 v25, v25
	s_nop 0
	v_mul_f32_e32 v24, v25, v24
	v_mul_f32_e32 v18, v18, v24
	v_and_b32_e32 v24, 0xffff0000, v84
	v_mul_f32_e32 v25, 0xbfb8aa3b, v24
	v_exp_f32_e32 v25, v25
	s_nop 0
	v_add_f32_e32 v25, 1.0, v25
	v_rcp_f32_e32 v25, v25
	s_nop 0
	v_mul_f32_e32 v24, v25, v24
	v_mul_f32_e32 v19, v19, v24
	v_cvt_pk_bf16_f32 v24, v18, v19
	v_lshlrev_b32_e32 v18, 16, v85
	v_mul_f32_e32 v19, 0xbfb8aa3b, v18
	v_exp_f32_e32 v19, v19
	s_nop 0
	v_add_f32_e32 v19, 1.0, v19
	v_rcp_f32_e32 v19, v19
	s_nop 0
	v_mul_f32_e32 v18, v19, v18
	v_and_b32_e32 v19, 0xffff0000, v85
	v_mul_f32_e32 v18, v20, v18
	v_mul_f32_e32 v20, 0xbfb8aa3b, v19
	v_exp_f32_e32 v20, v20
	s_nop 0
	v_add_f32_e32 v20, 1.0, v20
	v_rcp_f32_e32 v20, v20
	s_nop 0
	v_mul_f32_e32 v19, v20, v19
	v_mul_f32_e32 v19, v21, v19
	v_cvt_pk_bf16_f32 v25, v18, v19
	v_lshlrev_b32_e32 v18, 16, v78
	v_mul_f32_e32 v19, 0xbfb8aa3b, v18
	v_exp_f32_e32 v19, v19
	global_store_dwordx4 v[110:111], v[22:25], off offset:256
	v_add_f32_e32 v19, 1.0, v19
	v_rcp_f32_e32 v19, v19
	s_nop 0
	v_mul_f32_e32 v18, v19, v18
	v_mul_f32_e32 v14, v14, v18
	v_and_b32_e32 v18, 0xffff0000, v78
	v_mul_f32_e32 v19, 0xbfb8aa3b, v18
	v_exp_f32_e32 v19, v19
	s_nop 0
	v_add_f32_e32 v19, 1.0, v19
	v_rcp_f32_e32 v19, v19
	s_nop 0
	v_mul_f32_e32 v18, v19, v18
	v_mul_f32_e32 v15, v15, v18
	v_cvt_pk_bf16_f32 v14, v14, v15
	v_lshlrev_b32_e32 v15, 16, v79
	v_mul_f32_e32 v18, 0xbfb8aa3b, v15
	v_exp_f32_e32 v18, v18
	s_nop 0
	v_add_f32_e32 v18, 1.0, v18
	v_rcp_f32_e32 v18, v18
	s_nop 0
	v_mul_f32_e32 v15, v18, v15
	v_mul_f32_e32 v15, v16, v15
	v_and_b32_e32 v16, 0xffff0000, v79
	v_mul_f32_e32 v18, 0xbfb8aa3b, v16
	v_exp_f32_e32 v18, v18
	s_nop 0
	v_add_f32_e32 v18, 1.0, v18
	v_rcp_f32_e32 v18, v18
	s_nop 0
	v_mul_f32_e32 v16, v18, v16
	v_mul_f32_e32 v16, v17, v16
	v_cvt_pk_bf16_f32 v15, v15, v16
	v_lshlrev_b32_e32 v16, 16, v80
	v_mul_f32_e32 v17, 0xbfb8aa3b, v16
	v_exp_f32_e32 v17, v17
	s_nop 0
	v_add_f32_e32 v17, 1.0, v17
	v_rcp_f32_e32 v17, v17
	s_nop 0
	v_mul_f32_e32 v16, v17, v16
	v_mul_f32_e32 v10, v10, v16
	v_and_b32_e32 v16, 0xffff0000, v80
	v_mul_f32_e32 v17, 0xbfb8aa3b, v16
	v_exp_f32_e32 v17, v17
	s_nop 0
	v_add_f32_e32 v17, 1.0, v17
	v_rcp_f32_e32 v17, v17
	s_nop 0
	v_mul_f32_e32 v16, v17, v16
	v_mul_f32_e32 v11, v11, v16
	v_cvt_pk_bf16_f32 v16, v10, v11
	v_lshlrev_b32_e32 v10, 16, v81
	v_mul_f32_e32 v11, 0xbfb8aa3b, v10
	v_exp_f32_e32 v11, v11
	s_nop 0
	v_add_f32_e32 v11, 1.0, v11
	v_rcp_f32_e32 v11, v11
	s_nop 0
	v_mul_f32_e32 v10, v11, v10
	v_and_b32_e32 v11, 0xffff0000, v81
	v_mul_f32_e32 v10, v12, v10
	v_mul_f32_e32 v12, 0xbfb8aa3b, v11
	v_exp_f32_e32 v12, v12
	s_nop 0
	v_add_f32_e32 v12, 1.0, v12
	v_rcp_f32_e32 v12, v12
	s_nop 0
	v_mul_f32_e32 v11, v12, v11
	v_mul_f32_e32 v11, v13, v11
	v_cvt_pk_bf16_f32 v17, v10, v11
	v_lshlrev_b32_e32 v10, 16, v74
	v_mul_f32_e32 v11, 0xbfb8aa3b, v10
	v_exp_f32_e32 v11, v11
	global_store_dwordx4 v[114:115], v[14:17], off offset:256
	v_add_f32_e32 v11, 1.0, v11
	v_rcp_f32_e32 v11, v11
	s_nop 0
	v_mul_f32_e32 v10, v11, v10
	v_mul_f32_e32 v6, v6, v10
	v_and_b32_e32 v10, 0xffff0000, v74
	v_mul_f32_e32 v11, 0xbfb8aa3b, v10
	v_exp_f32_e32 v11, v11
	s_nop 0
	v_add_f32_e32 v11, 1.0, v11
	v_rcp_f32_e32 v11, v11
	s_nop 0
	v_mul_f32_e32 v10, v11, v10
	v_mul_f32_e32 v7, v7, v10
	v_cvt_pk_bf16_f32 v6, v6, v7
	v_lshlrev_b32_e32 v7, 16, v75
	v_mul_f32_e32 v10, 0xbfb8aa3b, v7
	v_exp_f32_e32 v10, v10
	s_nop 0
	v_add_f32_e32 v10, 1.0, v10
	v_rcp_f32_e32 v10, v10
	s_nop 0
	v_mul_f32_e32 v7, v10, v7
	v_mul_f32_e32 v7, v8, v7
	v_and_b32_e32 v8, 0xffff0000, v75
	v_mul_f32_e32 v10, 0xbfb8aa3b, v8
	v_exp_f32_e32 v10, v10
	s_nop 0
	v_add_f32_e32 v10, 1.0, v10
	v_rcp_f32_e32 v10, v10
	s_nop 0
	v_mul_f32_e32 v8, v10, v8
	v_mul_f32_e32 v8, v9, v8
	v_cvt_pk_bf16_f32 v7, v7, v8
	v_lshlrev_b32_e32 v8, 16, v76
	v_mul_f32_e32 v9, 0xbfb8aa3b, v8
	v_exp_f32_e32 v9, v9
	s_nop 0
	v_add_f32_e32 v9, 1.0, v9
	v_rcp_f32_e32 v9, v9
	s_nop 0
	v_mul_f32_e32 v8, v9, v8
	v_mul_f32_e32 v2, v2, v8
	v_and_b32_e32 v8, 0xffff0000, v76
	v_mul_f32_e32 v9, 0xbfb8aa3b, v8
	v_exp_f32_e32 v9, v9
	s_nop 0
	v_add_f32_e32 v9, 1.0, v9
	v_rcp_f32_e32 v9, v9
	s_nop 0
	v_mul_f32_e32 v8, v9, v8
	v_mul_f32_e32 v3, v3, v8
	v_cvt_pk_bf16_f32 v8, v2, v3
	v_lshlrev_b32_e32 v2, 16, v77
	v_mul_f32_e32 v3, 0xbfb8aa3b, v2
	v_exp_f32_e32 v3, v3
	s_nop 0
	v_add_f32_e32 v3, 1.0, v3
	v_rcp_f32_e32 v3, v3
	s_nop 0
	v_mul_f32_e32 v2, v3, v2
	v_and_b32_e32 v3, 0xffff0000, v77
	v_mul_f32_e32 v2, v4, v2
	v_mul_f32_e32 v4, 0xbfb8aa3b, v3
	v_exp_f32_e32 v4, v4
	s_nop 0
	v_add_f32_e32 v4, 1.0, v4
	v_rcp_f32_e32 v4, v4
	s_nop 0
	v_mul_f32_e32 v3, v4, v3
	v_mul_f32_e32 v3, v5, v3
	v_cvt_pk_bf16_f32 v9, v2, v3
	global_store_dwordx4 v[106:107], v[6:9], off offset:256
	s_cbranch_vccz .LBB0_596
	s_waitcnt vmcnt(0)
	s_cmpk_gt_u32 s14, 0xff
	s_mov_b64 s[36:37], s[96:97]
	s_cbranch_scc1 .LBB0_607
	s_barrier

; #define PG8_STAGE(bufoff, gbase, voff) do { _Pragma("unroll") for (int _i = 0; _i < 2; ++_i) \
;         __builtin_amdgcn_global_load_lds((const unsigned*)((const char*)(gbase) + (voff)[_i]), (LAS unsigned*)(lds + (bufoff) + ldsw + _i * 8192), 16, 0, 0); } while (0)
; #define PG8_LDA(dst, b, h) do { _Pragma("unroll") for (int m = 0; m < 4; ++m) _Pragma("unroll") for (int k = 0; k < 2; ++k) dst[m][k] = *(const LAS bf16x8*)(lds + PG8_SA(b, h) + aoff + m * 2048 + k * 1024); } while (0)
; #define PG8_LDB(dst, b, h) do { _Pragma("unroll") for (int n = 0; n < 2; ++n) _Pragma("unroll") for (int k = 0; k < 2; ++k) dst[n][k] = *(const LAS bf16x8*)(lds + PG8_SB(b, h) + boff + n * 2048 + k * 1024); } while (0)
; #define PG8_MMA(ai, bj, At, Bt) do { __builtin_amdgcn_s_setprio(1); _Pragma("unroll") for (int m = 0; m < 4; ++m) _Pragma("unroll") for (int n = 0; n < 2; ++n) _Pragma("unroll") for (int k = 0; k < 2; ++k) \
;         acc[ai][bj][m][n] = __builtin_amdgcn_mfma_f32_16x16x32_bf16(Bt[n][k], At[m][k], acc[ai][bj][m][n], 0, 0, 0); __builtin_amdgcn_s_setprio(0); } while (0)
; #define PG8_WAIT_L(n) asm volatile("s_waitcnt lgkmcnt(" #n ")" ::: "memory")
; #define PG8_BAR __builtin_amdgcn_s_barrier()
; #define PG8_SCHED __builtin_amdgcn_sched_barrier(0)
; template <class Epi>
; __device__ __forceinline__ void gemm_phase(LAS unsigned char* lds, const Gemm g, const StaticOrder& S, const Epi& E) {
;     ...
;         const bool has_next = S.next(ui + 1, nxt);
;         const char* nA = has_next ? (const char*)g.A + (size_t)nxt.pm * tstepA + (size_t)(nxt.pn >> 2) * gstepA : cA; const char* nB = has_next ? (const char*)g.Bt + (size_t)nxt.pn * tstepB : cB;
;         for (int t = 0; t < nt; t += 2) {
;             const bool last = (t == nt - 2);
;             const char* a1 = cA + (size_t)(t + 1) * kstepA;
;             const char* a2 = last ? nA : cA + (size_t)(t + 2) * kstepA; const char* b2 = last ? nB : cB + (size_t)(t + 2) * kstep;
;             const char* a3 = a2 + kstepA; const char* b3 = b2 + kstep;
;             PG8_LDB(B0, 0, 0); PG8_SCHED; PG8_LDA(At, 0, 0); PG8_STAGE(PG8_SA(1, 1), a1 + hstepA, voffA);
;             PG8_WAIT_L(8); PG8_BAR; PG8_WAIT_L(0); PG8_MMA(0, 0, At, B0); PG8_BAR; PG8_SCHED;
.LBB0_795:
	s_ashr_i32 s51, s50, 31
	v_cmp_lt_i64_e32 vcc, s[4:5], v[182:183]
	s_lshl_b64 s[4:5], s[50:51], 13
	s_add_u32 s52, s42, s4
	s_addc_u32 s53, s43, s5
	s_and_b64 s[4:5], vcc, exec
	s_cselect_b32 s37, s53, s15
	s_cselect_b32 s38, s52, s14
	s_ashr_i32 s49, s48, 31
	s_lshl_b64 s[4:5], s[48:49], 21
	s_add_u32 s54, s19, s4
	s_addc_u32 s55, s20, s5
	s_and_b64 s[4:5], vcc, exec
	s_cselect_b32 s39, s55, s9
	s_cselect_b32 s49, s54, s8
	s_add_u32 s51, s8, 0x100
	s_addc_u32 s56, s9, 0
	s_add_u32 s8, s14, 0x105400
	v_mov_b32_e32 v2, 0
	s_addc_u32 s9, s15, 0
	s_mov_b32 s57, -2
	v_mov_b32_e32 v3, v2
	v_mov_b32_e32 v4, v2
	v_mov_b32_e32 v5, v2
	v_mov_b32_e32 v6, v2
	v_mov_b32_e32 v7, v2
	v_mov_b32_e32 v8, v2
	v_mov_b32_e32 v9, v2
	v_mov_b32_e32 v10, v2
	v_mov_b32_e32 v11, v2
	v_mov_b32_e32 v12, v2
	v_mov_b32_e32 v13, v2
	v_mov_b32_e32 v14, v2
	v_mov_b32_e32 v15, v2
	v_mov_b32_e32 v16, v2
	v_mov_b32_e32 v17, v2
	v_mov_b32_e32 v18, v2
	v_mov_b32_e32 v19, v2
	v_mov_b32_e32 v20, v2
	v_mov_b32_e32 v21, v2
	v_mov_b32_e32 v22, v2
	v_mov_b32_e32 v23, v2
	v_mov_b32_e32 v24, v2
	v_mov_b32_e32 v25, v2
	v_mov_b32_e32 v34, v2
	v_mov_b32_e32 v35, v2
	v_mov_b32_e32 v36, v2
	v_mov_b32_e32 v37, v2
	v_mov_b32_e32 v38, v2
	v_mov_b32_e32 v39, v2
	v_mov_b32_e32 v40, v2
	v_mov_b32_e32 v41, v2
	v_mov_b32_e32 v74, v2
	v_mov_b32_e32 v75, v2
	v_mov_b32_e32 v76, v2
	v_mov_b32_e32 v77, v2
	v_mov_b32_e32 v78, v2
	v_mov_b32_e32 v79, v2
	v_mov_b32_e32 v80, v2
	v_mov_b32_e32 v81, v2
	v_mov_b32_e32 v82, v2
	v_mov_b32_e32 v83, v2
	v_mov_b32_e32 v84, v2
	v_mov_b32_e32 v85, v2
	v_mov_b32_e32 v86, v2
	v_mov_b32_e32 v87, v2
	v_mov_b32_e32 v88, v2
	v_mov_b32_e32 v89, v2
	v_mov_b32_e32 v90, v2
	v_mov_b32_e32 v91, v2
	v_mov_b32_e32 v92, v2
	v_mov_b32_e32 v93, v2
	v_mov_b32_e32 v94, v2
	v_mov_b32_e32 v95, v2
	v_mov_b32_e32 v96, v2
	v_mov_b32_e32 v97, v2
	v_mov_b32_e32 v106, v2
	v_mov_b32_e32 v107, v2
	v_mov_b32_e32 v108, v2
	v_mov_b32_e32 v109, v2
	v_mov_b32_e32 v110, v2
	v_mov_b32_e32 v111, v2
	v_mov_b32_e32 v112, v2
	v_mov_b32_e32 v113, v2
	v_mov_b32_e32 v42, v2
	v_mov_b32_e32 v43, v2
	v_mov_b32_e32 v44, v2
	v_mov_b32_e32 v45, v2
	v_mov_b32_e32 v46, v2
	v_mov_b32_e32 v47, v2
	v_mov_b32_e32 v48, v2
	v_mov_b32_e32 v49, v2
	v_mov_b32_e32 v50, v2
	v_mov_b32_e32 v51, v2
	v_mov_b32_e32 v52, v2
	v_mov_b32_e32 v53, v2
	v_mov_b32_e32 v54, v2
	v_mov_b32_e32 v55, v2
	v_mov_b32_e32 v56, v2
	v_mov_b32_e32 v57, v2
	v_mov_b32_e32 v58, v2
	v_mov_b32_e32 v59, v2
	v_mov_b32_e32 v60, v2
	v_mov_b32_e32 v61, v2
	v_mov_b32_e32 v62, v2
	v_mov_b32_e32 v63, v2
	v_mov_b32_e32 v64, v2
	v_mov_b32_e32 v65, v2
	v_mov_b32_e32 v66, v2
	v_mov_b32_e32 v67, v2
	v_mov_b32_e32 v68, v2
	v_mov_b32_e32 v69, v2
	v_mov_b32_e32 v70, v2
	v_mov_b32_e32 v71, v2
	v_mov_b32_e32 v72, v2
	v_mov_b32_e32 v73, v2
	v_mov_b32_e32 v114, v2
	v_mov_b32_e32 v115, v2
	v_mov_b32_e32 v116, v2
	v_mov_b32_e32 v117, v2
	v_mov_b32_e32 v118, v2
	v_mov_b32_e32 v119, v2
	v_mov_b32_e32 v120, v2
	v_mov_b32_e32 v121, v2
	v_mov_b32_e32 v122, v2
	v_mov_b32_e32 v123, v2
	v_mov_b32_e32 v124, v2
	v_mov_b32_e32 v125, v2
	v_mov_b32_e32 v126, v2
	v_mov_b32_e32 v127, v2
	v_mov_b32_e32 v128, v2
	v_mov_b32_e32 v129, v2
	v_mov_b32_e32 v134, v2
	v_mov_b32_e32 v135, v2
	v_mov_b32_e32 v136, v2
	v_mov_b32_e32 v137, v2
	v_mov_b32_e32 v138, v2
	v_mov_b32_e32 v139, v2
	v_mov_b32_e32 v140, v2
	v_mov_b32_e32 v141, v2
	v_mov_b32_e32 v158, v2
	v_mov_b32_e32 v159, v2
	v_mov_b32_e32 v160, v2
	v_mov_b32_e32 v161, v2
	v_mov_b32_e32 v162, v2
	v_mov_b32_e32 v163, v2
	v_mov_b32_e32 v164, v2
	v_mov_b32_e32 v165, v2
	v_add_u32_e32 v250, 0x10000, v245
.LBB0_796:
	s_add_u32 s4, s8, 0x103400
	s_addc_u32 s5, s9, 0
	s_cmp_eq_u32 s57, 60
	s_cselect_b32 s16, s38, s4
	s_cselect_b32 s17, s37, s5
	s_cselect_b32 s4, s49, s51
	s_cselect_b32 s5, s39, s56
	s_add_u32 s14, s16, 0x104400
	s_addc_u32 s15, s17, 0
	s_add_i32 s58, 0, 0x10000
	ds_read_b128 v[26:29], v250
	ds_read_b128 v[30:33], v250 offset:1024
	ds_read_b128 v[98:101], v250 offset:2048
	ds_read_b128 v[102:105], v250 offset:3072
	s_add_i32 m0, s22, 0xc000
	ds_read_b128 v[130:133], v247
	ds_read_b128 v[142:145], v247 offset:1024
	ds_read_b128 v[146:149], v247 offset:2048
	ds_read_b128 v[150:153], v247 offset:3072
	ds_read_b128 v[154:157], v247 offset:4096
	ds_read_b128 v[166:169], v247 offset:5120
	ds_read_b128 v[170:173], v247 offset:6144
	ds_read_b128 v[174:177], v247 offset:7168
	global_load_lds_dwordx4 v196, s[8:9]
	s_add_i32 m0, s22, 0xe000
	s_nop 0
	global_load_lds_dwordx4 v198, s[8:9]
	s_waitcnt lgkmcnt(8)
	s_barrier
	s_waitcnt lgkmcnt(0)
	v_mfma_f32_16x16x32_bf16 v[162:165], v[26:29], v[130:133], v[162:165]
	v_mfma_f32_16x16x32_bf16 v[158:161], v[98:101], v[130:133], v[158:161]
	v_mfma_f32_16x16x32_bf16 v[138:141], v[26:29], v[146:149], v[138:141]
	v_mfma_f32_16x16x32_bf16 v[134:137], v[98:101], v[146:149], v[134:137]
	v_mfma_f32_16x16x32_bf16 v[126:129], v[26:29], v[154:157], v[126:129]
	v_mfma_f32_16x16x32_bf16 v[122:125], v[98:101], v[154:157], v[122:125]
	v_mfma_f32_16x16x32_bf16 v[118:121], v[26:29], v[170:173], v[118:121]
	v_mfma_f32_16x16x32_bf16 v[114:117], v[98:101], v[170:173], v[114:117]
	v_mfma_f32_16x16x32_bf16 v[162:165], v[30:33], v[142:145], v[162:165]
	v_mfma_f32_16x16x32_bf16 v[158:161], v[102:105], v[142:145], v[158:161]
	v_mfma_f32_16x16x32_bf16 v[138:141], v[30:33], v[150:153], v[138:141]
	v_mfma_f32_16x16x32_bf16 v[134:137], v[102:105], v[150:153], v[134:137]
	v_mfma_f32_16x16x32_bf16 v[126:129], v[30:33], v[166:169], v[126:129]
	v_mfma_f32_16x16x32_bf16 v[122:125], v[102:105], v[166:169], v[122:125]
	v_mfma_f32_16x16x32_bf16 v[118:121], v[30:33], v[174:177], v[118:121]
	v_mfma_f32_16x16x32_bf16 v[114:117], v[102:105], v[174:177], v[114:117]
	s_barrier
; #define PG8_STAGE(bufoff, gbase, voff) do { _Pragma("unroll") for (int _i = 0; _i < 2; ++_i) \
;         __builtin_amdgcn_global_load_lds((const unsigned*)((const char*)(gbase) + (voff)[_i]), (LAS unsigned*)(lds + (bufoff) + ldsw + _i * 8192), 16, 0, 0); } while (0)
; #define PG8_LDA(dst, b, h) do { _Pragma("unroll") for (int m = 0; m < 4; ++m) _Pragma("unroll") for (int k = 0; k < 2; ++k) dst[m][k] = *(const LAS bf16x8*)(lds + PG8_SA(b, h) + aoff + m * 2048 + k * 1024); } while (0)
; #define PG8_LDB(dst, b, h) do { _Pragma("unroll") for (int n = 0; n < 2; ++n) _Pragma("unroll") for (int k = 0; k < 2; ++k) dst[n][k] = *(const LAS bf16x8*)(lds + PG8_SB(b, h) + boff + n * 2048 + k * 1024); } while (0)
; #define PG8_MMA(ai, bj, At, Bt) do { __builtin_amdgcn_s_setprio(1); _Pragma("unroll") for (int m = 0; m < 4; ++m) _Pragma("unroll") for (int n = 0; n < 2; ++n) _Pragma("unroll") for (int k = 0; k < 2; ++k) \
;         acc[ai][bj][m][n] = __builtin_amdgcn_mfma_f32_16x16x32_bf16(Bt[n][k], At[m][k], acc[ai][bj][m][n], 0, 0, 0); __builtin_amdgcn_s_setprio(0); } while (0)
; #define PG8_WAIT_V(n) asm volatile("s_waitcnt vmcnt(" #n ")" ::: "memory")
; #define PG8_WAIT_L(n) asm volatile("s_waitcnt lgkmcnt(" #n ")" ::: "memory")
; #define PG8_BAR __builtin_amdgcn_s_barrier()
; #define PG8_SCHED __builtin_amdgcn_sched_barrier(0)
; template <class Epi>
; __device__ __forceinline__ void gemm_phase(LAS unsigned char* lds, const Gemm g, const StaticOrder& S, const Epi& E) {
;     ...
;             PG8_LDB(B1, 0, 1); PG8_STAGE(PG8_SB(0, 0), b2, voffB);
;             PG8_BAR; PG8_WAIT_L(0); PG8_MMA(0, 1, At, B1); PG8_BAR;
;             PG8_LDA(At, 0, 1); PG8_STAGE(PG8_SA(0, 0), a2, voffA);
;             PG8_BAR; PG8_WAIT_L(0); PG8_MMA(1, 0, At, B0); PG8_BAR; PG8_SCHED;
;             PG8_STAGE(PG8_SB(0, 1), b2 + hstepB, voffB);
;             PG8_WAIT_V(6); PG8_BAR; PG8_MMA(1, 1, At, B1); PG8_BAR;
;             PG8_LDB(B0, 1, 0); PG8_SCHED; PG8_LDA(At, 1, 0); PG8_STAGE(PG8_SA(0, 1), a2 + hstepA, voffA);
	s_add_i32 s60, 0, 0x14000
	s_add_i32 s58, s58, s21
	s_add_u32 s100, s4, s6
	s_addc_u32 s101, s5, s7
	s_mov_b32 m0, s58
	ds_read_b128 v[184:187], v250 offset:16384
	ds_read_b128 v[200:203], v250 offset:17408
	ds_read_b128 v[204:207], v250 offset:18432
	ds_read_b128 v[208:211], v250 offset:19456
	global_load_lds_dwordx4 v0, s[4:5]
	s_add_i32 m0, s58, 0x2000
	s_nop 0
	global_load_lds_dwordx4 v188, s[4:5]
	s_barrier
	s_waitcnt lgkmcnt(0)
	v_mfma_f32_16x16x32_bf16 v[70:73], v[184:187], v[130:133], v[70:73]
	v_mfma_f32_16x16x32_bf16 v[66:69], v[204:207], v[130:133], v[66:69]
	v_mfma_f32_16x16x32_bf16 v[62:65], v[184:187], v[146:149], v[62:65]
	v_mfma_f32_16x16x32_bf16 v[58:61], v[204:207], v[146:149], v[58:61]
	v_mfma_f32_16x16x32_bf16 v[54:57], v[184:187], v[154:157], v[54:57]
	v_mfma_f32_16x16x32_bf16 v[50:53], v[204:207], v[154:157], v[50:53]
	v_mfma_f32_16x16x32_bf16 v[46:49], v[184:187], v[170:173], v[46:49]
	v_mfma_f32_16x16x32_bf16 v[42:45], v[204:207], v[170:173], v[42:45]
	v_mfma_f32_16x16x32_bf16 v[70:73], v[200:203], v[142:145], v[70:73]
	v_mfma_f32_16x16x32_bf16 v[66:69], v[208:211], v[142:145], v[66:69]
	v_mfma_f32_16x16x32_bf16 v[62:65], v[200:203], v[150:153], v[62:65]
	v_mfma_f32_16x16x32_bf16 v[58:61], v[208:211], v[150:153], v[58:61]
	v_mfma_f32_16x16x32_bf16 v[54:57], v[200:203], v[166:169], v[54:57]
	v_mfma_f32_16x16x32_bf16 v[50:53], v[208:211], v[166:169], v[50:53]
	v_mfma_f32_16x16x32_bf16 v[46:49], v[200:203], v[174:177], v[46:49]
	v_mfma_f32_16x16x32_bf16 v[42:45], v[208:211], v[174:177], v[42:45]
	s_mov_b32 m0, s22
	s_barrier
	ds_read_b128 v[130:133], v247 offset:16384
	ds_read_b128 v[142:145], v247 offset:17408
	ds_read_b128 v[146:149], v247 offset:18432
	ds_read_b128 v[150:153], v247 offset:19456
	ds_read_b128 v[154:157], v247 offset:20480
	ds_read_b128 v[166:169], v247 offset:21504
	ds_read_b128 v[170:173], v247 offset:22528
	ds_read_b128 v[174:177], v247 offset:23552
	global_load_lds_dwordx4 v192, s[16:17]
	s_mov_b32 m0, s23
	s_nop 0
	global_load_lds_dwordx4 v190, s[16:17]
	s_barrier
	s_waitcnt lgkmcnt(0)
	v_mfma_f32_16x16x32_bf16 v[110:113], v[26:29], v[130:133], v[110:113]
	v_mfma_f32_16x16x32_bf16 v[106:109], v[98:101], v[130:133], v[106:109]
	v_mfma_f32_16x16x32_bf16 v[94:97], v[26:29], v[146:149], v[94:97]
	v_mfma_f32_16x16x32_bf16 v[90:93], v[98:101], v[146:149], v[90:93]
	v_mfma_f32_16x16x32_bf16 v[86:89], v[26:29], v[154:157], v[86:89]
	v_mfma_f32_16x16x32_bf16 v[82:85], v[98:101], v[154:157], v[82:85]
	v_mfma_f32_16x16x32_bf16 v[26:29], v[26:29], v[170:173], v[78:81]
	v_mfma_f32_16x16x32_bf16 v[110:113], v[30:33], v[142:145], v[110:113]
	v_mfma_f32_16x16x32_bf16 v[106:109], v[102:105], v[142:145], v[106:109]
	v_mfma_f32_16x16x32_bf16 v[94:97], v[30:33], v[150:153], v[94:97]
	v_mfma_f32_16x16x32_bf16 v[90:93], v[102:105], v[150:153], v[90:93]
	v_mfma_f32_16x16x32_bf16 v[86:89], v[30:33], v[166:169], v[86:89]
	v_mfma_f32_16x16x32_bf16 v[82:85], v[102:105], v[166:169], v[82:85]
	v_mfma_f32_16x16x32_bf16 v[26:29], v[30:33], v[174:177], v[26:29]
	v_mfma_f32_16x16x32_bf16 v[30:33], v[98:101], v[170:173], v[74:77]
	v_mfma_f32_16x16x32_bf16 v[30:33], v[102:105], v[174:177], v[30:33]
	s_barrier
	s_add_u32 s58, s4, 0x100000
	s_addc_u32 s59, s5, 0
	s_add_i32 s60, s60, s21
	s_mov_b32 m0, s60
	s_nop 0
	global_load_lds_dwordx4 v0, s[58:59]
	s_add_i32 m0, s60, 0x2000
	s_nop 0
	global_load_lds_dwordx4 v188, s[58:59]
	s_waitcnt vmcnt(6)
	s_barrier
	v_mfma_f32_16x16x32_bf16 v[38:41], v[184:187], v[130:133], v[38:41]
	v_mfma_f32_16x16x32_bf16 v[34:37], v[204:207], v[130:133], v[34:37]
	v_mfma_f32_16x16x32_bf16 v[22:25], v[184:187], v[146:149], v[22:25]
	v_mfma_f32_16x16x32_bf16 v[18:21], v[204:207], v[146:149], v[18:21]
	v_mfma_f32_16x16x32_bf16 v[14:17], v[184:187], v[154:157], v[14:17]
	v_mfma_f32_16x16x32_bf16 v[10:13], v[204:207], v[154:157], v[10:13]
	v_mfma_f32_16x16x32_bf16 v[6:9], v[184:187], v[170:173], v[6:9]
	v_mfma_f32_16x16x32_bf16 v[2:5], v[204:207], v[170:173], v[2:5]
	v_mfma_f32_16x16x32_bf16 v[38:41], v[200:203], v[142:145], v[38:41]
	v_mfma_f32_16x16x32_bf16 v[34:37], v[208:211], v[142:145], v[34:37]
	v_mfma_f32_16x16x32_bf16 v[22:25], v[200:203], v[150:153], v[22:25]
	v_mfma_f32_16x16x32_bf16 v[18:21], v[208:211], v[150:153], v[18:21]
	v_mfma_f32_16x16x32_bf16 v[14:17], v[200:203], v[166:169], v[14:17]
	v_mfma_f32_16x16x32_bf16 v[10:13], v[208:211], v[166:169], v[10:13]
	v_mfma_f32_16x16x32_bf16 v[6:9], v[200:203], v[174:177], v[6:9]
	v_mfma_f32_16x16x32_bf16 v[2:5], v[208:211], v[174:177], v[2:5]
	s_add_i32 s58, 0, 0x18000
	s_barrier
	ds_read_b128 v[74:77], v250 offset:32768
	ds_read_b128 v[78:81], v250 offset:33792
	ds_read_b128 v[98:101], v250 offset:34816
	ds_read_b128 v[102:105], v250 offset:35840
	s_add_u32 s16, s16, 0x1000
	s_addc_u32 s17, s17, 0
	s_mov_b32 m0, s24
	ds_read_b128 v[130:133], v247 offset:32768
	ds_read_b128 v[142:145], v247 offset:33792
	ds_read_b128 v[146:149], v247 offset:34816
	ds_read_b128 v[150:153], v247 offset:35840
	ds_read_b128 v[154:157], v247 offset:36864
	ds_read_b128 v[166:169], v247 offset:37888
	ds_read_b128 v[170:173], v247 offset:38912
	ds_read_b128 v[174:177], v247 offset:39936
	global_load_lds_dwordx4 v192, s[16:17]
	s_mov_b32 m0, s25
	s_nop 0
	global_load_lds_dwordx4 v190, s[16:17]
	s_waitcnt lgkmcnt(8)
	s_barrier
; #define PG8_STAGE(bufoff, gbase, voff) do { _Pragma("unroll") for (int _i = 0; _i < 2; ++_i) \
;         __builtin_amdgcn_global_load_lds((const unsigned*)((const char*)(gbase) + (voff)[_i]), (LAS unsigned*)(lds + (bufoff) + ldsw + _i * 8192), 16, 0, 0); } while (0)
; #define PG8_LDA(dst, b, h) do { _Pragma("unroll") for (int m = 0; m < 4; ++m) _Pragma("unroll") for (int k = 0; k < 2; ++k) dst[m][k] = *(const LAS bf16x8*)(lds + PG8_SA(b, h) + aoff + m * 2048 + k * 1024); } while (0)
; #define PG8_LDB(dst, b, h) do { _Pragma("unroll") for (int n = 0; n < 2; ++n) _Pragma("unroll") for (int k = 0; k < 2; ++k) dst[n][k] = *(const LAS bf16x8*)(lds + PG8_SB(b, h) + boff + n * 2048 + k * 1024); } while (0)
; #define PG8_MMA(ai, bj, At, Bt) do { __builtin_amdgcn_s_setprio(1); _Pragma("unroll") for (int m = 0; m < 4; ++m) _Pragma("unroll") for (int n = 0; n < 2; ++n) _Pragma("unroll") for (int k = 0; k < 2; ++k) \
;         acc[ai][bj][m][n] = __builtin_amdgcn_mfma_f32_16x16x32_bf16(Bt[n][k], At[m][k], acc[ai][bj][m][n], 0, 0, 0); __builtin_amdgcn_s_setprio(0); } while (0)
; #define PG8_WAIT_V(n) asm volatile("s_waitcnt vmcnt(" #n ")" ::: "memory")
; #define PG8_WAIT_L(n) asm volatile("s_waitcnt lgkmcnt(" #n ")" ::: "memory")
; #define PG8_BAR __builtin_amdgcn_s_barrier()
; #define PG8_SCHED __builtin_amdgcn_sched_barrier(0)
; template <class Epi>
; __device__ __forceinline__ void gemm_phase(LAS unsigned char* lds, const Gemm g, const StaticOrder& S, const Epi& E) {
;     ...
;             PG8_WAIT_L(8); PG8_BAR; PG8_WAIT_L(0); PG8_MMA(0, 0, At, B0); PG8_BAR; PG8_SCHED;
;             PG8_LDB(B1, 1, 1); PG8_STAGE(PG8_SB(1, 0), b3, voffB);
;             PG8_BAR; PG8_WAIT_L(0); PG8_MMA(0, 1, At, B1); PG8_BAR;
;             PG8_LDA(At, 1, 1); PG8_STAGE(PG8_SA(1, 0), a3, voffA);
;             PG8_BAR; PG8_WAIT_L(0); PG8_MMA(1, 0, At, B0); PG8_BAR; PG8_SCHED;
;             PG8_STAGE(PG8_SB(1, 1), b3 + hstepB, voffB);
;             PG8_WAIT_V(6); PG8_BAR; PG8_MMA(1, 1, At, B1); PG8_BAR;
	s_waitcnt lgkmcnt(0)
	v_mfma_f32_16x16x32_bf16 v[162:165], v[74:77], v[130:133], v[162:165]
	v_mfma_f32_16x16x32_bf16 v[158:161], v[98:101], v[130:133], v[158:161]
	v_mfma_f32_16x16x32_bf16 v[138:141], v[74:77], v[146:149], v[138:141]
	v_mfma_f32_16x16x32_bf16 v[134:137], v[98:101], v[146:149], v[134:137]
	v_mfma_f32_16x16x32_bf16 v[126:129], v[74:77], v[154:157], v[126:129]
	v_mfma_f32_16x16x32_bf16 v[122:125], v[98:101], v[154:157], v[122:125]
	v_mfma_f32_16x16x32_bf16 v[118:121], v[74:77], v[170:173], v[118:121]
	v_mfma_f32_16x16x32_bf16 v[114:117], v[98:101], v[170:173], v[114:117]
	v_mfma_f32_16x16x32_bf16 v[162:165], v[78:81], v[142:145], v[162:165]
	v_mfma_f32_16x16x32_bf16 v[158:161], v[102:105], v[142:145], v[158:161]
	v_mfma_f32_16x16x32_bf16 v[138:141], v[78:81], v[150:153], v[138:141]
	v_mfma_f32_16x16x32_bf16 v[134:137], v[102:105], v[150:153], v[134:137]
	v_mfma_f32_16x16x32_bf16 v[126:129], v[78:81], v[166:169], v[126:129]
	v_mfma_f32_16x16x32_bf16 v[122:125], v[102:105], v[166:169], v[122:125]
	v_mfma_f32_16x16x32_bf16 v[118:121], v[78:81], v[174:177], v[118:121]
	v_mfma_f32_16x16x32_bf16 v[114:117], v[102:105], v[174:177], v[114:117]
	s_barrier
	s_add_i32 s16, 0, 0x1c000
	s_add_i32 s17, s58, s21
	s_mov_b32 m0, s17
	ds_read_b128 v[184:187], v250 offset:49152
	ds_read_b128 v[200:203], v250 offset:50176
	ds_read_b128 v[204:207], v250 offset:51200
	ds_read_b128 v[208:211], v250 offset:52224
	global_load_lds_dwordx4 v0, s[100:101]
	s_add_i32 m0, s17, 0x2000
	s_nop 0
	global_load_lds_dwordx4 v188, s[100:101]
	s_barrier
	s_waitcnt lgkmcnt(0)
	v_mfma_f32_16x16x32_bf16 v[70:73], v[184:187], v[130:133], v[70:73]
	v_mfma_f32_16x16x32_bf16 v[66:69], v[204:207], v[130:133], v[66:69]
	v_mfma_f32_16x16x32_bf16 v[62:65], v[184:187], v[146:149], v[62:65]
	v_mfma_f32_16x16x32_bf16 v[58:61], v[204:207], v[146:149], v[58:61]
	v_mfma_f32_16x16x32_bf16 v[54:57], v[184:187], v[154:157], v[54:57]
	v_mfma_f32_16x16x32_bf16 v[50:53], v[204:207], v[154:157], v[50:53]
	v_mfma_f32_16x16x32_bf16 v[46:49], v[184:187], v[170:173], v[46:49]
	v_mfma_f32_16x16x32_bf16 v[42:45], v[204:207], v[170:173], v[42:45]
	v_mfma_f32_16x16x32_bf16 v[70:73], v[200:203], v[142:145], v[70:73]
	v_mfma_f32_16x16x32_bf16 v[66:69], v[208:211], v[142:145], v[66:69]
	v_mfma_f32_16x16x32_bf16 v[62:65], v[200:203], v[150:153], v[62:65]
	v_mfma_f32_16x16x32_bf16 v[58:61], v[208:211], v[150:153], v[58:61]
	v_mfma_f32_16x16x32_bf16 v[54:57], v[200:203], v[166:169], v[54:57]
	v_mfma_f32_16x16x32_bf16 v[50:53], v[208:211], v[166:169], v[50:53]
	v_mfma_f32_16x16x32_bf16 v[46:49], v[200:203], v[174:177], v[46:49]
	v_mfma_f32_16x16x32_bf16 v[42:45], v[208:211], v[174:177], v[42:45]
	s_mov_b32 m0, s26
	s_barrier
	ds_read_b128 v[130:133], v247 offset:49152
	ds_read_b128 v[142:145], v247 offset:50176
	ds_read_b128 v[146:149], v247 offset:51200
	ds_read_b128 v[150:153], v247 offset:52224
	ds_read_b128 v[154:157], v247 offset:53248
	ds_read_b128 v[166:169], v247 offset:54272
	ds_read_b128 v[170:173], v247 offset:55296
	ds_read_b128 v[174:177], v247 offset:56320
	global_load_lds_dwordx4 v192, s[14:15]
	s_mov_b32 m0, s27
	s_nop 0
	global_load_lds_dwordx4 v190, s[14:15]
	s_barrier
	s_waitcnt lgkmcnt(0)
	v_mfma_f32_16x16x32_bf16 v[110:113], v[74:77], v[130:133], v[110:113]
	v_mfma_f32_16x16x32_bf16 v[94:97], v[74:77], v[146:149], v[94:97]
	v_mfma_f32_16x16x32_bf16 v[86:89], v[74:77], v[154:157], v[86:89]
	v_mfma_f32_16x16x32_bf16 v[26:29], v[74:77], v[170:173], v[26:29]
	v_mfma_f32_16x16x32_bf16 v[110:113], v[78:81], v[142:145], v[110:113]
	v_mfma_f32_16x16x32_bf16 v[106:109], v[98:101], v[130:133], v[106:109]
	v_mfma_f32_16x16x32_bf16 v[94:97], v[78:81], v[150:153], v[94:97]
	v_mfma_f32_16x16x32_bf16 v[90:93], v[98:101], v[146:149], v[90:93]
	v_mfma_f32_16x16x32_bf16 v[86:89], v[78:81], v[166:169], v[86:89]
	v_mfma_f32_16x16x32_bf16 v[82:85], v[98:101], v[154:157], v[82:85]
	v_mfma_f32_16x16x32_bf16 v[78:81], v[78:81], v[174:177], v[26:29]
	v_mfma_f32_16x16x32_bf16 v[26:29], v[98:101], v[170:173], v[30:33]
	v_mfma_f32_16x16x32_bf16 v[106:109], v[102:105], v[142:145], v[106:109]
	v_mfma_f32_16x16x32_bf16 v[90:93], v[102:105], v[150:153], v[90:93]
	v_mfma_f32_16x16x32_bf16 v[82:85], v[102:105], v[166:169], v[82:85]
	v_mfma_f32_16x16x32_bf16 v[74:77], v[102:105], v[174:177], v[26:29]
	s_barrier
	s_add_u32 s4, s4, 0x100080
	s_addc_u32 s5, s5, 0
	s_add_i32 s14, s16, s21
	s_mov_b32 m0, s14
	s_nop 0
	global_load_lds_dwordx4 v0, s[4:5]
	s_add_i32 m0, s14, 0x2000
	s_nop 0
	global_load_lds_dwordx4 v188, s[4:5]
	s_waitcnt vmcnt(6)
	s_barrier
	v_mfma_f32_16x16x32_bf16 v[26:29], v[184:187], v[130:133], v[38:41]
	v_mfma_f32_16x16x32_bf16 v[38:41], v[200:203], v[142:145], v[26:29]
	v_mfma_f32_16x16x32_bf16 v[26:29], v[204:207], v[130:133], v[34:37]
	v_mfma_f32_16x16x32_bf16 v[22:25], v[184:187], v[146:149], v[22:25]
	v_mfma_f32_16x16x32_bf16 v[18:21], v[204:207], v[146:149], v[18:21]
	v_mfma_f32_16x16x32_bf16 v[14:17], v[184:187], v[154:157], v[14:17]
	v_mfma_f32_16x16x32_bf16 v[10:13], v[204:207], v[154:157], v[10:13]
	v_mfma_f32_16x16x32_bf16 v[6:9], v[184:187], v[170:173], v[6:9]
	v_mfma_f32_16x16x32_bf16 v[2:5], v[204:207], v[170:173], v[2:5]
	v_mfma_f32_16x16x32_bf16 v[34:37], v[208:211], v[142:145], v[26:29]
	v_mfma_f32_16x16x32_bf16 v[22:25], v[200:203], v[150:153], v[22:25]
	v_mfma_f32_16x16x32_bf16 v[18:21], v[208:211], v[150:153], v[18:21]
	v_mfma_f32_16x16x32_bf16 v[14:17], v[200:203], v[166:169], v[14:17]
	v_mfma_f32_16x16x32_bf16 v[10:13], v[208:211], v[166:169], v[10:13]
	v_mfma_f32_16x16x32_bf16 v[6:9], v[200:203], v[174:177], v[6:9]
	v_mfma_f32_16x16x32_bf16 v[2:5], v[208:211], v[174:177], v[2:5]
	s_add_i32 s57, s57, 2
	s_add_u32 s51, s51, 0x100
	s_addc_u32 s56, s56, 0
	s_add_u32 s8, s8, 0x208800
	s_addc_u32 s9, s9, 0
	s_cmp_gt_u32 s57, 61
	s_barrier
; __device__ __forceinline__ unsigned cvt_pk_bf16(float lo, float hi) { unsigned r; asm volatile("v_cvt_pk_bf16_f32 %0, %1, %2" : "=v"(r) : "v"(lo), "v"(hi)); return r; }
; __device__ __forceinline__ float bf_lo(unsigned w) { return __uint_as_float(w << 16); }
; __device__ __forceinline__ float bf_hi(unsigned w) { return __uint_as_float(w & 0xffff0000u); }
;     __device__ __forceinline__ void operator()(const f32x4 (&acc)[2][2][4][2], const Unit& u, int wr, int wc, int fr, int fq, const Pre&) const {
;         const int row0 = u.pm * BM + wr * 64 + fr, col0 = u.pn * BM + wc * 32 + 8 * fq;
;         f32x4 bs[2][2];
; #pragma unroll
;         for (int bj = 0; bj < 2; ++bj) { bs[bj][0] = *(const f32x4*)(bias + col0 + bj * HALF); bs[bj][1] = *(const f32x4*)(bias + col0 + bj * HALF + 4); }
; #pragma unroll
;         for (int bj = 0; bj < 2; ++bj) { const int c = col0 + bj * HALF;
; #pragma unroll
;             for (int ai = 0; ai < 2; ++ai) { u32x4 zv[4], gv[4];
; #pragma unroll
;                 for (int m = 0; m < 4; ++m) { const int r = row0 + ai * HALF + m * 16; zv[m] = *(const u32x4*)(Z + (size_t)r * DE2 + c); gv[m] = *(const u32x4*)(Gm + (size_t)(c >> 4) * GSTR + r * 16 + (c & 15)); }
; #pragma unroll
;                 for (int m = 0; m < 4; ++m) { const int r = row0 + ai * HALF + m * 16;
;                     const u32x4 zw = zv[m], gw = gv[m];
;                     const f32x4 a0 = acc[ai][bj][m][0] + bs[bj][0], a1 = acc[ai][bj][m][1] + bs[bj][1];
;                     u32x4 w;
;                     w.x = cvt_pk_bf16(glu_gate_f(bf_lo(gw.x), a0[0], bf_lo(zw.x)), glu_gate_f(bf_hi(gw.x), a0[1], bf_hi(zw.x)));
;                     w.y = cvt_pk_bf16(glu_gate_f(bf_lo(gw.y), a0[2], bf_lo(zw.y)), glu_gate_f(bf_hi(gw.y), a0[3], bf_hi(zw.y)));
;                     w.z = cvt_pk_bf16(glu_gate_f(bf_lo(gw.z), a1[0], bf_lo(zw.z)), glu_gate_f(bf_hi(gw.z), a1[1], bf_hi(zw.z)));
;                     w.w = cvt_pk_bf16(glu_gate_f(bf_lo(gw.w), a1[2], bf_lo(zw.w)), glu_gate_f(bf_hi(gw.w), a1[3], bf_hi(zw.w)));
	s_cbranch_scc0 .LBB0_796
	v_lshl_or_b32 v200, s36, 8, v246
	v_ashrrev_i32_e32 v201, 31, v200
	v_lshl_add_u32 v224, s35, 8, v244
	v_lshlrev_b64 v[204:205], 1, v[200:201]
	v_ashrrev_i32_e32 v225, 31, v224
	v_ashrrev_i32_e32 v130, 4, v200
	v_lshl_add_u64 v[222:223], s[46:47], 0, v[204:205]
	v_lshlrev_b64 v[202:203], 14, v[224:225]
	v_lshl_add_u64 v[30:31], v[200:201], 2, s[10:11]
	v_mad_i64_i32 v[220:221], s[4:5], v130, s94, v[194:195]
	v_lshl_add_u64 v[130:131], v[222:223], 0, v[202:203]
	global_load_dwordx4 v[98:101], v[30:31], off offset:16
	global_load_dwordx4 v[102:105], v[30:31], off
	global_load_dwordx4 v[26:29], v[30:31], off offset:528
	s_nop 0
	global_load_dwordx4 v[30:33], v[30:31], off offset:512
	v_or_b32_e32 v226, 48, v224
	global_load_dwordx4 v[170:173], v[130:131], off
	v_lshlrev_b32_e32 v142, 4, v226
	v_ashrrev_i32_e32 v143, 31, v142
	v_lshlrev_b64 v[218:219], 1, v[142:143]
	v_lshl_add_u64 v[142:143], v[220:221], 0, v[218:219]
	global_load_dwordx4 v[142:145], v[142:143], off
	v_lshlrev_b32_e32 v130, 4, v224
	v_ashrrev_i32_e32 v131, 31, v130
	v_lshlrev_b64 v[206:207], 1, v[130:131]
	v_lshl_add_u64 v[130:131], v[220:221], 0, v[206:207]
	global_load_dwordx4 v[174:177], v[130:131], off
	v_or_b32_e32 v230, 16, v224
	v_ashrrev_i32_e32 v231, 31, v230
	v_lshlrev_b64 v[210:211], 14, v[230:231]
	v_lshl_add_u64 v[130:131], v[222:223], 0, v[210:211]
	global_load_dwordx4 v[154:157], v[130:131], off
	v_lshlrev_b32_e32 v130, 4, v230
	v_ashrrev_i32_e32 v131, 31, v130
	v_or_b32_e32 v228, 32, v224
	v_lshlrev_b64 v[208:209], 1, v[130:131]
	v_ashrrev_i32_e32 v229, 31, v228
	v_lshl_add_u64 v[130:131], v[220:221], 0, v[208:209]
	v_lshlrev_b64 v[214:215], 14, v[228:229]
	global_load_dwordx4 v[166:169], v[130:131], off
	v_lshl_add_u64 v[130:131], v[222:223], 0, v[214:215]
	global_load_dwordx4 v[146:149], v[130:131], off
	v_lshlrev_b32_e32 v130, 4, v228
	v_ashrrev_i32_e32 v131, 31, v130
	v_lshlrev_b64 v[212:213], 1, v[130:131]
	v_ashrrev_i32_e32 v227, 31, v226
	v_lshl_add_u64 v[130:131], v[220:221], 0, v[212:213]
	v_lshlrev_b64 v[216:217], 14, v[226:227]
	global_load_dwordx4 v[150:153], v[130:131], off
	v_lshl_add_u64 v[130:131], v[222:223], 0, v[216:217]
	global_load_dwordx4 v[130:133], v[130:131], off
	s_and_b64 vcc, exec, s[40:41]
	s_mov_b32 s35, s50
	s_mov_b32 s36, s48
	s_mov_b64 s[8:9], s[54:55]
	s_mov_b64 s[14:15], s[52:53]
	s_waitcnt vmcnt(0)
	v_pk_add_f32 v[134:135], v[134:135], v[98:99]
	v_pk_add_f32 v[184:185], v[162:163], v[102:103]
	v_pk_add_f32 v[162:163], v[160:161], v[100:101]
	v_pk_add_f32 v[160:161], v[158:159], v[98:99]
	v_mul_f32_e32 v158, 0xbfb8aa3b, v184
	v_lshlrev_b32_e32 v186, 16, v170
	v_mul_f32_e32 v159, 0xbfb8aa3b, v186
	v_exp_f32_e32 v158, v158
	v_exp_f32_e32 v159, v159
	v_and_b32_e32 v170, 0xffff0000, v170
	v_pk_add_f32 v[164:165], v[164:165], v[104:105]
	v_mul_f32_e32 v160, 0xbfb8aa3b, v160
	v_pk_add_f32 v[158:159], v[158:159], 1.0 op_sel_hi:[1,0]
	v_mul_f32_e32 v164, 0xbfb8aa3b, v164
	v_mul_f32_e32 v158, v158, v159
	v_rcp_f32_e32 v158, v158
	v_lshlrev_b32_e32 v187, 16, v174
	v_mul_f32_e32 v184, v187, v186
	v_mul_f32_e32 v159, 0xbfb8aa3b, v170
	v_mul_f32_e32 v184, v184, v158
	v_mul_f32_e32 v158, 0xbfb8aa3b, v185
	v_exp_f32_e32 v158, v158
	v_exp_f32_e32 v159, v159
	v_and_b32_e32 v174, 0xffff0000, v174
	v_mul_f32_e32 v170, v174, v170
	v_mul_f32_e32 v162, 0xbfb8aa3b, v162
	v_pk_add_f32 v[158:159], v[158:159], 1.0 op_sel_hi:[1,0]
	v_pk_add_f32 v[138:139], v[138:139], v[102:103]
	v_mul_f32_e32 v158, v158, v159
	v_rcp_f32_e32 v158, v158
	v_lshlrev_b32_e32 v159, 16, v171
	v_and_b32_e32 v171, 0xffff0000, v171
	v_mul_f32_e32 v138, 0xbfb8aa3b, v138
	v_mul_f32_e32 v158, v170, v158
	v_cvt_pk_bf16_f32 v158, v184, v158
	v_exp_f32_e32 v184, v164
	v_mul_f32_e32 v164, 0xbfb8aa3b, v159
	v_exp_f32_e32 v185, v164
	v_lshlrev_b32_e32 v170, 16, v175
	v_mul_f32_e32 v159, v170, v159
	v_and_b32_e32 v170, 0xffff0000, v175
	v_pk_add_f32 v[184:185], v[184:185], 1.0 op_sel_hi:[1,0]
	v_mul_f32_e32 v170, v170, v171
	v_mul_f32_e32 v164, v184, v185
	v_rcp_f32_e32 v164, v164
	v_pk_add_f32 v[140:141], v[140:141], v[104:105]
	v_mul_f32_e32 v134, 0xbfb8aa3b, v134
	v_mul_f32_e32 v140, 0xbfb8aa3b, v140
	v_mul_f32_e32 v159, v159, v164
	v_mul_f32_e32 v164, 0xbfb8aa3b, v165
	v_mul_f32_e32 v165, 0xbfb8aa3b, v171
	v_exp_f32_e32 v164, v164
	v_exp_f32_e32 v165, v165
	v_lshlrev_b32_e32 v171, 16, v176
	v_pk_add_f32 v[136:137], v[136:137], v[100:101]
	v_pk_add_f32 v[126:127], v[126:127], v[102:103]
	v_pk_add_f32 v[164:165], v[164:165], 1.0 op_sel_hi:[1,0]
	v_mul_f32_e32 v126, 0xbfb8aa3b, v126
	v_mul_f32_e32 v164, v164, v165
	v_rcp_f32_e32 v164, v164
	v_pk_add_f32 v[128:129], v[128:129], v[104:105]
	v_pk_add_f32 v[122:123], v[122:123], v[98:99]
	v_mul_f32_e32 v128, 0xbfb8aa3b, v128
	v_mul_f32_e32 v164, v170, v164
	v_lshlrev_b32_e32 v170, 16, v172
	v_cvt_pk_bf16_f32 v159, v159, v164
	v_exp_f32_e32 v164, v160
	v_mul_f32_e32 v160, 0xbfb8aa3b, v170
	v_exp_f32_e32 v165, v160
	v_mul_f32_e32 v160, v171, v170
	v_and_b32_e32 v170, 0xffff0000, v172
	v_mul_f32_e32 v122, 0xbfb8aa3b, v122
	v_pk_add_f32 v[164:165], v[164:165], 1.0 op_sel_hi:[1,0]
	v_pk_add_f32 v[124:125], v[124:125], v[100:101]
	v_mul_f32_e32 v164, v164, v165
	v_rcp_f32_e32 v164, v164
	v_and_b32_e32 v165, 0xffff0000, v176
	v_mul_f32_e32 v165, v165, v170
	v_pk_add_f32 v[118:119], v[118:119], v[102:103]
	v_mul_f32_e32 v164, v160, v164
	v_mul_f32_e32 v160, 0xbfb8aa3b, v161
	v_mul_f32_e32 v161, 0xbfb8aa3b, v170
	v_exp_f32_e32 v160, v160
	v_exp_f32_e32 v161, v161
	v_lshlrev_b32_e32 v170, 16, v177
	v_mul_f32_e32 v118, 0xbfb8aa3b, v118
	v_pk_add_f32 v[120:121], v[120:121], v[104:105]
	v_pk_add_f32 v[160:161], v[160:161], 1.0 op_sel_hi:[1,0]
; __device__ __forceinline__ unsigned cvt_pk_bf16(float lo, float hi) { unsigned r; asm volatile("v_cvt_pk_bf16_f32 %0, %1, %2" : "=v"(r) : "v"(lo), "v"(hi)); return r; }
; __device__ __forceinline__ float bf_lo(unsigned w) { return __uint_as_float(w << 16); }
; __device__ __forceinline__ float bf_hi(unsigned w) { return __uint_as_float(w & 0xffff0000u); }
;     __device__ __forceinline__ void operator()(const f32x4 (&acc)[2][2][4][2], const Unit& u, int wr, int wc, int fr, int fq, const Pre&) const {
;     ...
;                 for (int m = 0; m < 4; ++m) { const int r = row0 + ai * HALF + m * 16; zv[m] = *(const u32x4*)(Z + (size_t)r * DE2 + c); gv[m] = *(const u32x4*)(Gm + (size_t)(c >> 4) * GSTR + r * 16 + (c & 15)); }
; #pragma unroll
;                 for (int m = 0; m < 4; ++m) { const int r = row0 + ai * HALF + m * 16;
;                     const u32x4 zw = zv[m], gw = gv[m];
;                     const f32x4 a0 = acc[ai][bj][m][0] + bs[bj][0], a1 = acc[ai][bj][m][1] + bs[bj][1];
;                     u32x4 w;
;                     w.x = cvt_pk_bf16(glu_gate_f(bf_lo(gw.x), a0[0], bf_lo(zw.x)), glu_gate_f(bf_hi(gw.x), a0[1], bf_hi(zw.x)));
;                     w.y = cvt_pk_bf16(glu_gate_f(bf_lo(gw.y), a0[2], bf_lo(zw.y)), glu_gate_f(bf_hi(gw.y), a0[3], bf_hi(zw.y)));
;                     w.z = cvt_pk_bf16(glu_gate_f(bf_lo(gw.z), a1[0], bf_lo(zw.z)), glu_gate_f(bf_hi(gw.z), a1[1], bf_hi(zw.z)));
;                     w.w = cvt_pk_bf16(glu_gate_f(bf_lo(gw.w), a1[2], bf_lo(zw.w)), glu_gate_f(bf_hi(gw.w), a1[3], bf_hi(zw.w)));
;                     *(u32x4*)(O + (size_t)r * DE + c) = w; } } }
	v_mul_f32_e32 v120, 0xbfb8aa3b, v120
	v_mul_f32_e32 v160, v160, v161
	v_rcp_f32_e32 v160, v160
	v_lshlrev_b32_e32 v161, 16, v173
	v_pk_add_f32 v[114:115], v[114:115], v[98:99]
	v_pk_add_f32 v[116:117], v[116:117], v[100:101]
	v_mul_f32_e32 v160, v165, v160
	v_cvt_pk_bf16_f32 v160, v164, v160
	v_exp_f32_e32 v164, v162
	v_mul_f32_e32 v162, 0xbfb8aa3b, v161
	v_exp_f32_e32 v165, v162
	v_mul_f32_e32 v161, v170, v161
	v_mul_f32_e32 v114, 0xbfb8aa3b, v114
	v_add_u32_e32 v176, 0x80, v224
	v_pk_add_f32 v[164:165], v[164:165], 1.0 op_sel_hi:[1,0]
	v_add_u32_e32 v170, 0xb0, v224
	v_mul_f32_e32 v162, v164, v165
	v_rcp_f32_e32 v162, v162
	v_and_b32_e32 v165, 0xffff0000, v173
	v_and_b32_e32 v164, 0xffff0000, v177
	v_mul_f32_e32 v164, v164, v165
	v_mul_f32_e32 v161, v161, v162
	v_mul_f32_e32 v162, 0xbfb8aa3b, v163
	v_mul_f32_e32 v163, 0xbfb8aa3b, v165
	v_exp_f32_e32 v162, v162
	v_exp_f32_e32 v163, v163
	v_ashrrev_i32_e32 v177, 31, v176
	v_pk_add_f32 v[110:111], v[110:111], v[102:103]
	v_add_u32_e32 v174, 0x90, v224
	v_pk_add_f32 v[162:163], v[162:163], 1.0 op_sel_hi:[1,0]
	v_mul_f32_e32 v110, 0xbfb8aa3b, v110
	v_mul_f32_e32 v162, v162, v163
	v_rcp_f32_e32 v162, v162
	v_exp_f32_e32 v184, v110
	v_ashrrev_i32_e32 v175, 31, v174
	v_add_u32_e32 v172, 0xa0, v224
	v_mul_f32_e32 v162, v164, v162
	v_cvt_pk_bf16_f32 v161, v161, v162
	v_lshlrev_b64 v[162:163], 13, v[224:225]
	v_lshl_add_u64 v[162:163], s[44:45], 0, v[162:163]
	v_lshl_add_u64 v[162:163], v[162:163], 0, v[204:205]
	global_store_dwordx4 v[162:163], v[158:161], off
	v_ashrrev_i32_e32 v173, 31, v172
	v_ashrrev_i32_e32 v171, 31, v170
	v_lshlrev_b32_e32 v160, 16, v154
	v_exp_f32_e32 v158, v138
	v_mul_f32_e32 v138, 0xbfb8aa3b, v160
	v_exp_f32_e32 v159, v138
	v_lshlrev_b32_e32 v161, 16, v166
	v_mul_f32_e32 v138, v161, v160
	v_and_b32_e32 v154, 0xffff0000, v154
	v_pk_add_f32 v[158:159], v[158:159], 1.0 op_sel_hi:[1,0]
	v_lshlrev_b64 v[160:161], 14, v[172:173]
	v_mul_f32_e32 v158, v158, v159
	v_rcp_f32_e32 v158, v158
	v_and_b32_e32 v159, 0xffff0000, v166
	v_pk_add_f32 v[112:113], v[112:113], v[104:105]
	v_pk_add_f32 v[106:107], v[106:107], v[98:99]
	v_mul_f32_e32 v158, v138, v158
	v_mul_f32_e32 v138, 0xbfb8aa3b, v139
	v_mul_f32_e32 v139, 0xbfb8aa3b, v154
	v_exp_f32_e32 v138, v138
	v_exp_f32_e32 v139, v139
	v_mul_f32_e32 v154, v159, v154
	v_mul_f32_e32 v112, 0xbfb8aa3b, v112
	v_mul_f32_e32 v106, 0xbfb8aa3b, v106
	v_pk_add_f32 v[138:139], v[138:139], 1.0 op_sel_hi:[1,0]
	v_pk_add_f32 v[108:109], v[108:109], v[100:101]
	v_mul_f32_e32 v138, v138, v139
	v_rcp_f32_e32 v138, v138
	v_lshlrev_b32_e32 v139, 16, v155
	v_and_b32_e32 v155, 0xffff0000, v155
	v_pk_add_f32 v[94:95], v[94:95], v[102:103]
	v_mul_f32_e32 v138, v154, v138
	v_cvt_pk_bf16_f32 v138, v158, v138
	v_exp_f32_e32 v158, v140
	v_mul_f32_e32 v140, 0xbfb8aa3b, v139
	v_exp_f32_e32 v159, v140
	v_lshlrev_b32_e32 v154, 16, v167
	v_mul_f32_e32 v139, v154, v139
	v_and_b32_e32 v154, 0xffff0000, v167
	v_pk_add_f32 v[158:159], v[158:159], 1.0 op_sel_hi:[1,0]
	v_mul_f32_e32 v154, v154, v155
	v_mul_f32_e32 v140, v158, v159
	v_rcp_f32_e32 v140, v140
	v_lshlrev_b64 v[166:167], 14, v[170:171]
	v_mul_f32_e32 v94, 0xbfb8aa3b, v94
	v_pk_add_f32 v[96:97], v[96:97], v[104:105]
	v_mul_f32_e32 v139, v139, v140
	v_mul_f32_e32 v140, 0xbfb8aa3b, v141
	v_mul_f32_e32 v141, 0xbfb8aa3b, v155
	v_exp_f32_e32 v140, v140
	v_exp_f32_e32 v141, v141
	v_lshlrev_b32_e32 v155, 16, v168
	v_mul_f32_e32 v96, 0xbfb8aa3b, v96
	v_pk_add_f32 v[90:91], v[90:91], v[98:99]
	v_pk_add_f32 v[140:141], v[140:141], 1.0 op_sel_hi:[1,0]
	v_mul_f32_e32 v90, 0xbfb8aa3b, v90
	v_mul_f32_e32 v140, v140, v141
	v_rcp_f32_e32 v140, v140
	v_pk_add_f32 v[92:93], v[92:93], v[100:101]
	v_pk_add_f32 v[86:87], v[86:87], v[102:103]
	v_pk_add_f32 v[88:89], v[88:89], v[104:105]
	v_mul_f32_e32 v140, v154, v140
	v_lshlrev_b32_e32 v154, 16, v156
	v_cvt_pk_bf16_f32 v139, v139, v140
	v_exp_f32_e32 v140, v134
	v_mul_f32_e32 v134, 0xbfb8aa3b, v154
	v_exp_f32_e32 v141, v134
	v_mul_f32_e32 v134, v155, v154
	v_and_b32_e32 v154, 0xffff0000, v156
	v_mul_f32_e32 v86, 0xbfb8aa3b, v86
	v_pk_add_f32 v[140:141], v[140:141], 1.0 op_sel_hi:[1,0]
	v_mul_f32_e32 v88, 0xbfb8aa3b, v88
	v_mul_f32_e32 v140, v140, v141
	v_rcp_f32_e32 v140, v140
	v_and_b32_e32 v141, 0xffff0000, v168
	v_mul_f32_e32 v141, v141, v154
	v_pk_add_f32 v[82:83], v[82:83], v[98:99]
	v_mul_f32_e32 v140, v134, v140
	v_mul_f32_e32 v134, 0xbfb8aa3b, v135
	v_mul_f32_e32 v135, 0xbfb8aa3b, v154
	v_exp_f32_e32 v134, v134
	v_exp_f32_e32 v135, v135
	v_lshlrev_b32_e32 v154, 16, v169
	v_mul_f32_e32 v82, 0xbfb8aa3b, v82
	v_pk_add_f32 v[84:85], v[84:85], v[100:101]
	v_pk_add_f32 v[134:135], v[134:135], 1.0 op_sel_hi:[1,0]
	v_pk_add_f32 v[78:79], v[78:79], v[102:103]
	v_mul_f32_e32 v134, v134, v135
	v_rcp_f32_e32 v134, v134
	v_mul_f32_e32 v78, 0xbfb8aa3b, v78
	v_pk_add_f32 v[80:81], v[80:81], v[104:105]
	v_pk_add_f32 v[74:75], v[74:75], v[98:99]
	v_mul_f32_e32 v134, v141, v134
	v_lshlrev_b32_e32 v141, 16, v157
	v_cvt_pk_bf16_f32 v140, v140, v134
	v_mul_f32_e32 v134, 0xbfb8aa3b, v136
	v_mul_f32_e32 v135, 0xbfb8aa3b, v141
	v_exp_f32_e32 v134, v134
	v_exp_f32_e32 v135, v135
	v_mul_f32_e32 v136, v154, v141
	v_and_b32_e32 v154, 0xffff0000, v157
	v_and_b32_e32 v141, 0xffff0000, v169
	v_pk_add_f32 v[134:135], v[134:135], 1.0 op_sel_hi:[1,0]
	v_lshlrev_b64 v[156:157], 14, v[174:175]
	v_mul_f32_e32 v134, v134, v135
	v_rcp_f32_e32 v134, v134
	v_mul_f32_e32 v135, 0xbfb8aa3b, v154
	v_exp_f32_e32 v135, v135
	v_mul_f32_e32 v80, 0xbfb8aa3b, v80
	v_mul_f32_e32 v136, v136, v134
	v_mul_f32_e32 v134, 0xbfb8aa3b, v137
	v_exp_f32_e32 v134, v134
	v_mul_f32_e32 v137, v141, v154
	v_mul_f32_e32 v74, 0xbfb8aa3b, v74
; __device__ __forceinline__ unsigned cvt_pk_bf16(float lo, float hi) { unsigned r; asm volatile("v_cvt_pk_bf16_f32 %0, %1, %2" : "=v"(r) : "v"(lo), "v"(hi)); return r; }
; __device__ __forceinline__ float bf_lo(unsigned w) { return __uint_as_float(w << 16); }
; __device__ __forceinline__ float bf_hi(unsigned w) { return __uint_as_float(w & 0xffff0000u); }
;     __device__ __forceinline__ void operator()(const f32x4 (&acc)[2][2][4][2], const Unit& u, int wr, int wc, int fr, int fq, const Pre&) const {
;     ...
;                 for (int m = 0; m < 4; ++m) { const int r = row0 + ai * HALF + m * 16; zv[m] = *(const u32x4*)(Z + (size_t)r * DE2 + c); gv[m] = *(const u32x4*)(Gm + (size_t)(c >> 4) * GSTR + r * 16 + (c & 15)); }
; #pragma unroll
;                 for (int m = 0; m < 4; ++m) { const int r = row0 + ai * HALF + m * 16;
;                     const u32x4 zw = zv[m], gw = gv[m];
;                     const f32x4 a0 = acc[ai][bj][m][0] + bs[bj][0], a1 = acc[ai][bj][m][1] + bs[bj][1];
;                     u32x4 w;
;                     w.x = cvt_pk_bf16(glu_gate_f(bf_lo(gw.x), a0[0], bf_lo(zw.x)), glu_gate_f(bf_hi(gw.x), a0[1], bf_hi(zw.x)));
;                     w.y = cvt_pk_bf16(glu_gate_f(bf_lo(gw.y), a0[2], bf_lo(zw.y)), glu_gate_f(bf_hi(gw.y), a0[3], bf_hi(zw.y)));
;                     w.z = cvt_pk_bf16(glu_gate_f(bf_lo(gw.z), a1[0], bf_lo(zw.z)), glu_gate_f(bf_hi(gw.z), a1[1], bf_hi(zw.z)));
;                     w.w = cvt_pk_bf16(glu_gate_f(bf_lo(gw.w), a1[2], bf_lo(zw.w)), glu_gate_f(bf_hi(gw.w), a1[3], bf_hi(zw.w)));
;                     *(u32x4*)(O + (size_t)r * DE + c) = w; } } }
	v_pk_add_f32 v[76:77], v[76:77], v[100:101]
	v_pk_add_f32 v[134:135], v[134:135], 1.0 op_sel_hi:[1,0]
	v_pk_add_f32 v[70:71], v[70:71], v[30:31]
	v_mul_f32_e32 v134, v134, v135
	v_rcp_f32_e32 v134, v134
	v_mul_f32_e32 v70, 0xbfb8aa3b, v70
	v_pk_add_f32 v[72:73], v[72:73], v[32:33]
	v_pk_add_f32 v[66:67], v[66:67], v[26:27]
	v_mul_f32_e32 v134, v137, v134
	v_cvt_pk_bf16_f32 v141, v136, v134
	v_lshlrev_b64 v[134:135], 13, v[230:231]
	v_lshl_add_u64 v[134:135], s[44:45], 0, v[134:135]
	v_lshlrev_b32_e32 v136, 16, v146
	v_lshl_add_u64 v[154:155], v[134:135], 0, v[204:205]
	v_exp_f32_e32 v134, v126
	v_mul_f32_e32 v126, 0xbfb8aa3b, v136
	v_exp_f32_e32 v135, v126
	v_lshlrev_b32_e32 v137, 16, v150
	v_mul_f32_e32 v126, v137, v136
	v_and_b32_e32 v136, 0xffff0000, v146
	v_pk_add_f32 v[134:135], v[134:135], 1.0 op_sel_hi:[1,0]
	global_store_dwordx4 v[154:155], v[138:141], off
	v_mul_f32_e32 v134, v134, v135
	v_rcp_f32_e32 v134, v134
	v_and_b32_e32 v135, 0xffff0000, v150
	v_mul_f32_e32 v135, v135, v136
	v_mul_f32_e32 v72, 0xbfb8aa3b, v72
	v_mul_f32_e32 v134, v126, v134
	v_mul_f32_e32 v126, 0xbfb8aa3b, v127
	v_mul_f32_e32 v127, 0xbfb8aa3b, v136
	v_exp_f32_e32 v126, v126
	v_exp_f32_e32 v127, v127
	v_lshlrev_b32_e32 v136, 16, v151
	v_mul_f32_e32 v66, 0xbfb8aa3b, v66
	v_pk_add_f32 v[68:69], v[68:69], v[28:29]
	v_pk_add_f32 v[126:127], v[126:127], 1.0 op_sel_hi:[1,0]
	v_pk_add_f32 v[62:63], v[62:63], v[30:31]
	v_mul_f32_e32 v126, v126, v127
	v_rcp_f32_e32 v126, v126
	v_lshlrev_b32_e32 v127, 16, v147
	v_mul_f32_e32 v62, 0xbfb8aa3b, v62
	v_pk_add_f32 v[64:65], v[64:65], v[32:33]
	v_mul_f32_e32 v126, v135, v126
	v_cvt_pk_bf16_f32 v126, v134, v126
	v_exp_f32_e32 v134, v128
	v_mul_f32_e32 v128, 0xbfb8aa3b, v127
	v_exp_f32_e32 v135, v128
	v_mul_f32_e32 v127, v136, v127
	v_mul_f32_e32 v64, 0xbfb8aa3b, v64
	v_pk_add_f32 v[58:59], v[58:59], v[26:27]
	v_pk_add_f32 v[134:135], v[134:135], 1.0 op_sel_hi:[1,0]
	v_mul_f32_e32 v58, 0xbfb8aa3b, v58
	v_mul_f32_e32 v128, v134, v135
	v_rcp_f32_e32 v128, v128
	v_and_b32_e32 v135, 0xffff0000, v147
	v_and_b32_e32 v134, 0xffff0000, v151
	v_mul_f32_e32 v134, v134, v135
	v_mul_f32_e32 v127, v127, v128
	v_mul_f32_e32 v128, 0xbfb8aa3b, v129
	v_mul_f32_e32 v129, 0xbfb8aa3b, v135
	v_exp_f32_e32 v128, v128
	v_exp_f32_e32 v129, v129
	v_lshlrev_b32_e32 v135, 16, v152
	v_lshlrev_b64 v[150:151], 14, v[176:177]
	v_pk_add_f32 v[60:61], v[60:61], v[28:29]
	v_pk_add_f32 v[128:129], v[128:129], 1.0 op_sel_hi:[1,0]
	v_pk_add_f32 v[54:55], v[54:55], v[30:31]
	v_mul_f32_e32 v128, v128, v129
	v_rcp_f32_e32 v128, v128
	v_mul_f32_e32 v54, 0xbfb8aa3b, v54
	v_pk_add_f32 v[56:57], v[56:57], v[32:33]
	v_pk_add_f32 v[50:51], v[50:51], v[26:27]
	v_mul_f32_e32 v128, v134, v128
	v_lshlrev_b32_e32 v134, 16, v148
	v_cvt_pk_bf16_f32 v127, v127, v128
	v_exp_f32_e32 v128, v122
	v_mul_f32_e32 v122, 0xbfb8aa3b, v134
	v_exp_f32_e32 v129, v122
	v_mul_f32_e32 v122, v135, v134
	v_and_b32_e32 v134, 0xffff0000, v148
	v_mul_f32_e32 v56, 0xbfb8aa3b, v56
	v_pk_add_f32 v[128:129], v[128:129], 1.0 op_sel_hi:[1,0]
	v_mul_f32_e32 v50, 0xbfb8aa3b, v50
	v_mul_f32_e32 v128, v128, v129
	v_rcp_f32_e32 v128, v128
	v_and_b32_e32 v129, 0xffff0000, v152
	v_mul_f32_e32 v129, v129, v134
	v_pk_add_f32 v[52:53], v[52:53], v[28:29]
	v_mul_f32_e32 v128, v122, v128
	v_mul_f32_e32 v122, 0xbfb8aa3b, v123
	v_mul_f32_e32 v123, 0xbfb8aa3b, v134
	v_exp_f32_e32 v122, v122
	v_exp_f32_e32 v123, v123
	v_lshlrev_b32_e32 v134, 16, v153
	v_pk_add_f32 v[46:47], v[46:47], v[30:31]
	v_pk_add_f32 v[48:49], v[48:49], v[32:33]
	v_pk_add_f32 v[122:123], v[122:123], 1.0 op_sel_hi:[1,0]
	v_mul_f32_e32 v46, 0xbfb8aa3b, v46
	v_mul_f32_e32 v122, v122, v123
	v_rcp_f32_e32 v122, v122
	v_mul_f32_e32 v48, 0xbfb8aa3b, v48
	v_pk_add_f32 v[42:43], v[42:43], v[26:27]
	v_pk_add_f32 v[44:45], v[44:45], v[28:29]
	v_mul_f32_e32 v122, v129, v122
	v_lshlrev_b32_e32 v129, 16, v149
	v_cvt_pk_bf16_f32 v128, v128, v122
	v_mul_f32_e32 v122, 0xbfb8aa3b, v124
	v_mul_f32_e32 v123, 0xbfb8aa3b, v129
	v_exp_f32_e32 v122, v122
	v_exp_f32_e32 v123, v123
	v_mul_f32_e32 v124, v134, v129
	v_and_b32_e32 v134, 0xffff0000, v149
	v_and_b32_e32 v129, 0xffff0000, v153
	v_pk_add_f32 v[122:123], v[122:123], 1.0 op_sel_hi:[1,0]
	v_mul_f32_e32 v42, 0xbfb8aa3b, v42
	v_mul_f32_e32 v122, v122, v123
	v_rcp_f32_e32 v122, v122
	v_mul_f32_e32 v123, 0xbfb8aa3b, v134
	v_exp_f32_e32 v123, v123
	v_pk_add_f32 v[38:39], v[38:39], v[30:31]
	v_mul_f32_e32 v124, v124, v122
	v_mul_f32_e32 v122, 0xbfb8aa3b, v125
	v_exp_f32_e32 v122, v122
	v_mul_f32_e32 v125, v129, v134
	v_mul_f32_e32 v38, 0xbfb8aa3b, v38
	v_pk_add_f32 v[40:41], v[40:41], v[32:33]
	v_pk_add_f32 v[122:123], v[122:123], 1.0 op_sel_hi:[1,0]
	v_mul_f32_e32 v40, 0xbfb8aa3b, v40
	v_mul_f32_e32 v122, v122, v123
	v_rcp_f32_e32 v122, v122
	v_pk_add_f32 v[34:35], v[34:35], v[26:27]
	v_pk_add_f32 v[36:37], v[36:37], v[28:29]
	v_mul_f32_e32 v34, 0xbfb8aa3b, v34
	v_mul_f32_e32 v122, v125, v122
	v_cvt_pk_bf16_f32 v129, v124, v122
	v_lshlrev_b64 v[122:123], 13, v[228:229]
	v_lshl_add_u64 v[122:123], s[44:45], 0, v[122:123]
	v_lshlrev_b32_e32 v124, 16, v130
	v_lshl_add_u64 v[146:147], v[122:123], 0, v[204:205]
	v_exp_f32_e32 v122, v118
	v_mul_f32_e32 v118, 0xbfb8aa3b, v124
	v_exp_f32_e32 v123, v118
	v_lshlrev_b32_e32 v125, 16, v142
	v_mul_f32_e32 v118, v125, v124
	v_and_b32_e32 v124, 0xffff0000, v130
	v_pk_add_f32 v[122:123], v[122:123], 1.0 op_sel_hi:[1,0]
	global_store_dwordx4 v[146:147], v[126:129], off
	v_mul_f32_e32 v122, v122, v123
	v_rcp_f32_e32 v122, v122
	v_and_b32_e32 v123, 0xffff0000, v142
	v_mul_f32_e32 v123, v123, v124
	v_pk_add_f32 v[22:23], v[22:23], v[30:31]
	v_mul_f32_e32 v122, v118, v122
; __device__ __forceinline__ unsigned cvt_pk_bf16(float lo, float hi) { unsigned r; asm volatile("v_cvt_pk_bf16_f32 %0, %1, %2" : "=v"(r) : "v"(lo), "v"(hi)); return r; }
; __device__ __forceinline__ float bf_lo(unsigned w) { return __uint_as_float(w << 16); }
; __device__ __forceinline__ float bf_hi(unsigned w) { return __uint_as_float(w & 0xffff0000u); }
;     __device__ __forceinline__ void operator()(const f32x4 (&acc)[2][2][4][2], const Unit& u, int wr, int wc, int fr, int fq, const Pre&) const {
;     ...
;             for (int ai = 0; ai < 2; ++ai) { u32x4 zv[4], gv[4];
; #pragma unroll
;                 for (int m = 0; m < 4; ++m) { const int r = row0 + ai * HALF + m * 16; zv[m] = *(const u32x4*)(Z + (size_t)r * DE2 + c); gv[m] = *(const u32x4*)(Gm + (size_t)(c >> 4) * GSTR + r * 16 + (c & 15)); }
; #pragma unroll
;                 for (int m = 0; m < 4; ++m) { const int r = row0 + ai * HALF + m * 16;
;                     const u32x4 zw = zv[m], gw = gv[m];
;                     const f32x4 a0 = acc[ai][bj][m][0] + bs[bj][0], a1 = acc[ai][bj][m][1] + bs[bj][1];
;                     u32x4 w;
;                     w.x = cvt_pk_bf16(glu_gate_f(bf_lo(gw.x), a0[0], bf_lo(zw.x)), glu_gate_f(bf_hi(gw.x), a0[1], bf_hi(zw.x)));
;                     w.y = cvt_pk_bf16(glu_gate_f(bf_lo(gw.y), a0[2], bf_lo(zw.y)), glu_gate_f(bf_hi(gw.y), a0[3], bf_hi(zw.y)));
;                     w.z = cvt_pk_bf16(glu_gate_f(bf_lo(gw.z), a1[0], bf_lo(zw.z)), glu_gate_f(bf_hi(gw.z), a1[1], bf_hi(zw.z)));
;                     w.w = cvt_pk_bf16(glu_gate_f(bf_lo(gw.w), a1[2], bf_lo(zw.w)), glu_gate_f(bf_hi(gw.w), a1[3], bf_hi(zw.w)));
;                     *(u32x4*)(O + (size_t)r * DE + c) = w; } } }
	v_mul_f32_e32 v118, 0xbfb8aa3b, v119
	v_mul_f32_e32 v119, 0xbfb8aa3b, v124
	v_exp_f32_e32 v118, v118
	v_exp_f32_e32 v119, v119
	v_lshlrev_b32_e32 v124, 16, v143
	v_mul_f32_e32 v22, 0xbfb8aa3b, v22
	v_pk_add_f32 v[24:25], v[24:25], v[32:33]
	v_pk_add_f32 v[118:119], v[118:119], 1.0 op_sel_hi:[1,0]
	v_mul_f32_e32 v24, 0xbfb8aa3b, v24
	v_mul_f32_e32 v118, v118, v119
	v_rcp_f32_e32 v118, v118
	v_lshlrev_b32_e32 v119, 16, v131
	v_pk_add_f32 v[18:19], v[18:19], v[26:27]
	v_pk_add_f32 v[20:21], v[20:21], v[28:29]
	v_mul_f32_e32 v118, v123, v118
	v_cvt_pk_bf16_f32 v118, v122, v118
	v_exp_f32_e32 v122, v120
	v_mul_f32_e32 v120, 0xbfb8aa3b, v119
	v_exp_f32_e32 v123, v120
	v_mul_f32_e32 v119, v124, v119
	v_mul_f32_e32 v18, 0xbfb8aa3b, v18
	v_pk_add_f32 v[14:15], v[14:15], v[30:31]
	v_pk_add_f32 v[122:123], v[122:123], 1.0 op_sel_hi:[1,0]
	v_mul_f32_e32 v14, 0xbfb8aa3b, v14
	v_mul_f32_e32 v120, v122, v123
	v_rcp_f32_e32 v120, v120
	v_and_b32_e32 v123, 0xffff0000, v131
	v_and_b32_e32 v122, 0xffff0000, v143
	v_mul_f32_e32 v122, v122, v123
	v_mul_f32_e32 v119, v119, v120
	v_mul_f32_e32 v120, 0xbfb8aa3b, v121
	v_mul_f32_e32 v121, 0xbfb8aa3b, v123
	v_exp_f32_e32 v120, v120
	v_exp_f32_e32 v121, v121
	v_lshlrev_b32_e32 v123, 16, v144
	v_pk_add_f32 v[16:17], v[16:17], v[32:33]
	v_pk_add_f32 v[10:11], v[10:11], v[26:27]
	v_pk_add_f32 v[120:121], v[120:121], 1.0 op_sel_hi:[1,0]
	v_mul_f32_e32 v16, 0xbfb8aa3b, v16
	v_mul_f32_e32 v120, v120, v121
	v_rcp_f32_e32 v120, v120
	v_mul_f32_e32 v10, 0xbfb8aa3b, v10
	v_pk_add_f32 v[12:13], v[12:13], v[28:29]
	v_pk_add_f32 v[6:7], v[6:7], v[30:31]
	v_mul_f32_e32 v120, v122, v120
	v_lshlrev_b32_e32 v122, 16, v132
	v_cvt_pk_bf16_f32 v119, v119, v120
	v_exp_f32_e32 v120, v114
	v_mul_f32_e32 v114, 0xbfb8aa3b, v122
	v_exp_f32_e32 v121, v114
	v_mul_f32_e32 v114, v123, v122
	v_and_b32_e32 v122, 0xffff0000, v132
	v_mul_f32_e32 v6, 0xbfb8aa3b, v6
	v_pk_add_f32 v[120:121], v[120:121], 1.0 op_sel_hi:[1,0]
	v_pk_add_f32 v[8:9], v[8:9], v[32:33]
	v_mul_f32_e32 v120, v120, v121
	v_rcp_f32_e32 v120, v120
	v_and_b32_e32 v121, 0xffff0000, v144
	v_mul_f32_e32 v121, v121, v122
	v_mul_f32_e32 v8, 0xbfb8aa3b, v8
	v_mul_f32_e32 v120, v114, v120
	v_mul_f32_e32 v114, 0xbfb8aa3b, v115
	v_mul_f32_e32 v115, 0xbfb8aa3b, v122
	v_exp_f32_e32 v114, v114
	v_exp_f32_e32 v115, v115
	v_lshlrev_b32_e32 v122, 16, v145
	v_pk_add_f32 v[2:3], v[2:3], v[26:27]
	v_pk_add_f32 v[4:5], v[4:5], v[28:29]
	v_pk_add_f32 v[114:115], v[114:115], 1.0 op_sel_hi:[1,0]
	v_mul_f32_e32 v2, 0xbfb8aa3b, v2
	v_mul_f32_e32 v114, v114, v115
	v_rcp_f32_e32 v114, v114
	s_nop 0
	v_mul_f32_e32 v114, v121, v114
	v_lshlrev_b32_e32 v121, 16, v133
	v_cvt_pk_bf16_f32 v120, v120, v114
	v_mul_f32_e32 v114, 0xbfb8aa3b, v116
	v_mul_f32_e32 v115, 0xbfb8aa3b, v121
	v_exp_f32_e32 v114, v114
	v_exp_f32_e32 v115, v115
	v_mul_f32_e32 v116, v122, v121
	v_and_b32_e32 v122, 0xffff0000, v133
	v_and_b32_e32 v121, 0xffff0000, v145
	v_pk_add_f32 v[114:115], v[114:115], 1.0 op_sel_hi:[1,0]
	s_nop 0
	v_mul_f32_e32 v114, v114, v115
	v_rcp_f32_e32 v114, v114
	v_mul_f32_e32 v115, 0xbfb8aa3b, v122
	v_exp_f32_e32 v115, v115
	v_mul_f32_e32 v116, v116, v114
	v_mul_f32_e32 v114, 0xbfb8aa3b, v117
	v_exp_f32_e32 v114, v114
	v_mul_f32_e32 v117, v121, v122
	v_pk_add_f32 v[114:115], v[114:115], 1.0 op_sel_hi:[1,0]
	s_nop 0
	v_mul_f32_e32 v114, v114, v115
	v_rcp_f32_e32 v114, v114
	s_nop 0
	v_mul_f32_e32 v114, v117, v114
	v_cvt_pk_bf16_f32 v121, v116, v114
	v_lshlrev_b64 v[114:115], 13, v[226:227]
	v_lshl_add_u64 v[114:115], s[44:45], 0, v[114:115]
	v_lshl_add_u64 v[148:149], v[114:115], 0, v[204:205]
	global_store_dwordx4 v[148:149], v[118:121], off
	v_lshl_add_u64 v[114:115], v[222:223], 0, v[150:151]
	global_load_dwordx4 v[138:141], v[114:115], off
	v_lshlrev_b32_e32 v118, 4, v170
	v_ashrrev_i32_e32 v119, 31, v118
	v_lshlrev_b64 v[168:169], 1, v[118:119]
	v_lshl_add_u64 v[118:119], v[220:221], 0, v[168:169]
	global_load_dwordx4 v[118:121], v[118:119], off
	v_lshlrev_b32_e32 v114, 4, v176
	v_ashrrev_i32_e32 v115, 31, v114
	v_lshlrev_b64 v[152:153], 1, v[114:115]
	v_lshl_add_u64 v[114:115], v[220:221], 0, v[152:153]
	global_load_dwordx4 v[142:145], v[114:115], off
	v_lshl_add_u64 v[114:115], v[222:223], 0, v[156:157]
	global_load_dwordx4 v[130:133], v[114:115], off
	v_lshlrev_b32_e32 v114, 4, v174
	v_ashrrev_i32_e32 v115, 31, v114
	v_lshlrev_b64 v[158:159], 1, v[114:115]
	v_lshl_add_u64 v[114:115], v[220:221], 0, v[158:159]
	global_load_dwordx4 v[134:137], v[114:115], off
	v_lshl_add_u64 v[114:115], v[222:223], 0, v[160:161]
	global_load_dwordx4 v[122:125], v[114:115], off
	v_lshlrev_b32_e32 v114, 4, v172
	v_ashrrev_i32_e32 v115, 31, v114
	v_lshlrev_b64 v[164:165], 1, v[114:115]
	v_lshl_add_u64 v[114:115], v[220:221], 0, v[164:165]
	global_load_dwordx4 v[126:129], v[114:115], off
	v_lshl_add_u64 v[114:115], v[222:223], 0, v[166:167]
	global_load_dwordx4 v[114:117], v[114:115], off
	s_waitcnt vmcnt(0)
; __device__ __forceinline__ unsigned cvt_pk_bf16(float lo, float hi) { unsigned r; asm volatile("v_cvt_pk_bf16_f32 %0, %1, %2" : "=v"(r) : "v"(lo), "v"(hi)); return r; }
; __device__ __forceinline__ float bf_lo(unsigned w) { return __uint_as_float(w << 16); }
; __device__ __forceinline__ float bf_hi(unsigned w) { return __uint_as_float(w & 0xffff0000u); }
;     __device__ __forceinline__ void operator()(const f32x4 (&acc)[2][2][4][2], const Unit& u, int wr, int wc, int fr, int fq, const Pre&) const {
;     ...
;                 for (int m = 0; m < 4; ++m) { const int r = row0 + ai * HALF + m * 16;
;                     const u32x4 zw = zv[m], gw = gv[m];
;                     const f32x4 a0 = acc[ai][bj][m][0] + bs[bj][0], a1 = acc[ai][bj][m][1] + bs[bj][1];
;                     u32x4 w;
;                     w.x = cvt_pk_bf16(glu_gate_f(bf_lo(gw.x), a0[0], bf_lo(zw.x)), glu_gate_f(bf_hi(gw.x), a0[1], bf_hi(zw.x)));
;                     w.y = cvt_pk_bf16(glu_gate_f(bf_lo(gw.y), a0[2], bf_lo(zw.y)), glu_gate_f(bf_hi(gw.y), a0[3], bf_hi(zw.y)));
;                     w.z = cvt_pk_bf16(glu_gate_f(bf_lo(gw.z), a1[0], bf_lo(zw.z)), glu_gate_f(bf_hi(gw.z), a1[1], bf_hi(zw.z)));
;                     w.w = cvt_pk_bf16(glu_gate_f(bf_lo(gw.w), a1[2], bf_lo(zw.w)), glu_gate_f(bf_hi(gw.w), a1[3], bf_hi(zw.w)));
;                     *(u32x4*)(O + (size_t)r * DE + c) = w; } } }
	v_lshlrev_b32_e32 v186, 16, v138
	v_mul_f32_e32 v110, 0xbfb8aa3b, v186
	v_exp_f32_e32 v185, v110
	v_and_b32_e32 v138, 0xffff0000, v138
	v_pk_add_f32 v[184:185], v[184:185], 1.0 op_sel_hi:[1,0]
	s_nop 0
	v_mul_f32_e32 v184, v184, v185
	v_rcp_f32_e32 v184, v184
	v_lshlrev_b32_e32 v187, 16, v142
	v_mul_f32_e32 v110, v187, v186
	v_mul_f32_e32 v184, v110, v184
	v_mul_f32_e32 v110, 0xbfb8aa3b, v111
	v_mul_f32_e32 v111, 0xbfb8aa3b, v138
	v_exp_f32_e32 v110, v110
	v_exp_f32_e32 v111, v111
	v_and_b32_e32 v142, 0xffff0000, v142
	v_mul_f32_e32 v138, v142, v138
	v_pk_add_f32 v[110:111], v[110:111], 1.0 op_sel_hi:[1,0]
	s_nop 0
	v_mul_f32_e32 v110, v110, v111
	v_rcp_f32_e32 v110, v110
	v_lshlrev_b32_e32 v111, 16, v139
	v_and_b32_e32 v139, 0xffff0000, v139
	v_mul_f32_e32 v110, v138, v110
	v_cvt_pk_bf16_f32 v110, v184, v110
	v_exp_f32_e32 v184, v112
	v_mul_f32_e32 v112, 0xbfb8aa3b, v111
	v_exp_f32_e32 v185, v112
	v_lshlrev_b32_e32 v138, 16, v143
	v_mul_f32_e32 v111, v138, v111
	v_and_b32_e32 v138, 0xffff0000, v143
	v_pk_add_f32 v[184:185], v[184:185], 1.0 op_sel_hi:[1,0]
	v_mul_f32_e32 v138, v138, v139
	v_mul_f32_e32 v112, v184, v185
	v_rcp_f32_e32 v112, v112
	s_nop 0
	v_mul_f32_e32 v111, v111, v112
	v_mul_f32_e32 v112, 0xbfb8aa3b, v113
	v_mul_f32_e32 v113, 0xbfb8aa3b, v139
	v_exp_f32_e32 v112, v112
	v_exp_f32_e32 v113, v113
	v_lshlrev_b32_e32 v139, 16, v144
	v_pk_add_f32 v[112:113], v[112:113], 1.0 op_sel_hi:[1,0]
	s_nop 0
	v_mul_f32_e32 v112, v112, v113
	v_rcp_f32_e32 v112, v112
	s_nop 0
	v_mul_f32_e32 v112, v138, v112
	v_lshlrev_b32_e32 v138, 16, v140
	v_cvt_pk_bf16_f32 v111, v111, v112
	v_exp_f32_e32 v112, v106
	v_mul_f32_e32 v106, 0xbfb8aa3b, v138
	v_exp_f32_e32 v113, v106
	v_mul_f32_e32 v106, v139, v138
	v_and_b32_e32 v138, 0xffff0000, v140
	v_pk_add_f32 v[112:113], v[112:113], 1.0 op_sel_hi:[1,0]
	s_nop 0
	v_mul_f32_e32 v112, v112, v113
	v_rcp_f32_e32 v112, v112
	v_and_b32_e32 v113, 0xffff0000, v144
	v_mul_f32_e32 v113, v113, v138
	v_mul_f32_e32 v112, v106, v112
	v_mul_f32_e32 v106, 0xbfb8aa3b, v107
	v_mul_f32_e32 v107, 0xbfb8aa3b, v138
	v_exp_f32_e32 v106, v106
	v_exp_f32_e32 v107, v107
	v_lshlrev_b32_e32 v138, 16, v145
	v_pk_add_f32 v[106:107], v[106:107], 1.0 op_sel_hi:[1,0]
	s_nop 0
	v_mul_f32_e32 v106, v106, v107
	v_rcp_f32_e32 v106, v106
	s_nop 0
	v_mul_f32_e32 v106, v113, v106
	v_lshlrev_b32_e32 v113, 16, v141
	v_cvt_pk_bf16_f32 v112, v112, v106
	v_mul_f32_e32 v106, 0xbfb8aa3b, v108
	v_mul_f32_e32 v107, 0xbfb8aa3b, v113
	v_exp_f32_e32 v106, v106
	v_exp_f32_e32 v107, v107
	v_mul_f32_e32 v108, v138, v113
	v_and_b32_e32 v138, 0xffff0000, v141
	v_and_b32_e32 v113, 0xffff0000, v145
	v_pk_add_f32 v[106:107], v[106:107], 1.0 op_sel_hi:[1,0]
	s_nop 0
	v_mul_f32_e32 v106, v106, v107
	v_rcp_f32_e32 v106, v106
	v_mul_f32_e32 v107, 0xbfb8aa3b, v138
	v_exp_f32_e32 v107, v107
	v_mul_f32_e32 v108, v108, v106
	v_mul_f32_e32 v106, 0xbfb8aa3b, v109
	v_exp_f32_e32 v106, v106
	v_mul_f32_e32 v109, v113, v138
	v_pk_add_f32 v[106:107], v[106:107], 1.0 op_sel_hi:[1,0]
	s_nop 0
	v_mul_f32_e32 v106, v106, v107
	v_rcp_f32_e32 v106, v106
	s_nop 0
	v_mul_f32_e32 v106, v109, v106
	v_cvt_pk_bf16_f32 v113, v108, v106
	v_lshlrev_b64 v[106:107], 13, v[176:177]
	v_lshl_add_u64 v[106:107], s[44:45], 0, v[106:107]
	v_lshl_add_u64 v[106:107], v[106:107], 0, v[204:205]
	global_store_dwordx4 v[106:107], v[110:113], off
	v_exp_f32_e32 v108, v94
	s_nop 0
	v_lshlrev_b32_e32 v110, 16, v130
	v_mul_f32_e32 v94, 0xbfb8aa3b, v110
	v_exp_f32_e32 v109, v94
	v_lshlrev_b32_e32 v111, 16, v134
	v_mul_f32_e32 v94, v111, v110
	v_and_b32_e32 v110, 0xffff0000, v130
	v_pk_add_f32 v[108:109], v[108:109], 1.0 op_sel_hi:[1,0]
	s_nop 0
	v_mul_f32_e32 v108, v108, v109
	v_rcp_f32_e32 v108, v108
	v_and_b32_e32 v109, 0xffff0000, v134
	v_mul_f32_e32 v109, v109, v110
	v_mul_f32_e32 v108, v94, v108
	v_mul_f32_e32 v94, 0xbfb8aa3b, v95
	v_mul_f32_e32 v95, 0xbfb8aa3b, v110
	v_exp_f32_e32 v94, v94
	v_exp_f32_e32 v95, v95
	v_lshlrev_b32_e32 v110, 16, v135
	v_pk_add_f32 v[94:95], v[94:95], 1.0 op_sel_hi:[1,0]
	s_nop 0
	v_mul_f32_e32 v94, v94, v95
	v_rcp_f32_e32 v94, v94
	v_lshlrev_b32_e32 v95, 16, v131
	v_mul_f32_e32 v94, v109, v94
	v_cvt_pk_bf16_f32 v94, v108, v94
	v_exp_f32_e32 v108, v96
	v_mul_f32_e32 v96, 0xbfb8aa3b, v95
	v_exp_f32_e32 v109, v96
	v_mul_f32_e32 v95, v110, v95
	v_pk_add_f32 v[108:109], v[108:109], 1.0 op_sel_hi:[1,0]
	s_nop 0
	v_mul_f32_e32 v96, v108, v109
	v_rcp_f32_e32 v96, v96
	v_and_b32_e32 v109, 0xffff0000, v131
	v_and_b32_e32 v108, 0xffff0000, v135
	v_mul_f32_e32 v108, v108, v109
	v_mul_f32_e32 v95, v95, v96
	v_mul_f32_e32 v96, 0xbfb8aa3b, v97
	v_mul_f32_e32 v97, 0xbfb8aa3b, v109
	v_exp_f32_e32 v96, v96
	v_exp_f32_e32 v97, v97
	v_lshlrev_b32_e32 v109, 16, v136
	v_pk_add_f32 v[96:97], v[96:97], 1.0 op_sel_hi:[1,0]
	s_nop 0
	v_mul_f32_e32 v96, v96, v97
	v_rcp_f32_e32 v96, v96
	s_nop 0
	v_mul_f32_e32 v96, v108, v96
	v_lshlrev_b32_e32 v108, 16, v132
	v_cvt_pk_bf16_f32 v95, v95, v96
	v_exp_f32_e32 v96, v90
	v_mul_f32_e32 v90, 0xbfb8aa3b, v108
	v_exp_f32_e32 v97, v90
	v_mul_f32_e32 v90, v109, v108
	v_and_b32_e32 v108, 0xffff0000, v132
	v_pk_add_f32 v[96:97], v[96:97], 1.0 op_sel_hi:[1,0]
	s_nop 0
	v_mul_f32_e32 v96, v96, v97
	v_rcp_f32_e32 v96, v96
	v_and_b32_e32 v97, 0xffff0000, v136
	v_mul_f32_e32 v97, v97, v108
	v_mul_f32_e32 v96, v90, v96
	v_mul_f32_e32 v90, 0xbfb8aa3b, v91
	v_mul_f32_e32 v91, 0xbfb8aa3b, v108
	v_exp_f32_e32 v90, v90
	v_exp_f32_e32 v91, v91
	v_lshlrev_b32_e32 v108, 16, v137
	v_pk_add_f32 v[90:91], v[90:91], 1.0 op_sel_hi:[1,0]
	s_nop 0
	v_mul_f32_e32 v90, v90, v91
	v_rcp_f32_e32 v90, v90
	s_nop 0
	v_mul_f32_e32 v90, v97, v90
	v_lshlrev_b32_e32 v97, 16, v133
; __device__ __forceinline__ unsigned cvt_pk_bf16(float lo, float hi) { unsigned r; asm volatile("v_cvt_pk_bf16_f32 %0, %1, %2" : "=v"(r) : "v"(lo), "v"(hi)); return r; }
; __device__ __forceinline__ float bf_lo(unsigned w) { return __uint_as_float(w << 16); }
; __device__ __forceinline__ float bf_hi(unsigned w) { return __uint_as_float(w & 0xffff0000u); }
;     __device__ __forceinline__ void operator()(const f32x4 (&acc)[2][2][4][2], const Unit& u, int wr, int wc, int fr, int fq, const Pre&) const {
;     ...
;                 for (int m = 0; m < 4; ++m) { const int r = row0 + ai * HALF + m * 16;
;                     const u32x4 zw = zv[m], gw = gv[m];
;                     const f32x4 a0 = acc[ai][bj][m][0] + bs[bj][0], a1 = acc[ai][bj][m][1] + bs[bj][1];
;                     u32x4 w;
;                     w.x = cvt_pk_bf16(glu_gate_f(bf_lo(gw.x), a0[0], bf_lo(zw.x)), glu_gate_f(bf_hi(gw.x), a0[1], bf_hi(zw.x)));
;                     w.y = cvt_pk_bf16(glu_gate_f(bf_lo(gw.y), a0[2], bf_lo(zw.y)), glu_gate_f(bf_hi(gw.y), a0[3], bf_hi(zw.y)));
;                     w.z = cvt_pk_bf16(glu_gate_f(bf_lo(gw.z), a1[0], bf_lo(zw.z)), glu_gate_f(bf_hi(gw.z), a1[1], bf_hi(zw.z)));
;                     w.w = cvt_pk_bf16(glu_gate_f(bf_lo(gw.w), a1[2], bf_lo(zw.w)), glu_gate_f(bf_hi(gw.w), a1[3], bf_hi(zw.w)));
;                     *(u32x4*)(O + (size_t)r * DE + c) = w; } } }
	v_cvt_pk_bf16_f32 v96, v96, v90
	v_mul_f32_e32 v90, 0xbfb8aa3b, v92
	v_mul_f32_e32 v91, 0xbfb8aa3b, v97
	v_exp_f32_e32 v90, v90
	v_exp_f32_e32 v91, v91
	v_mul_f32_e32 v92, v108, v97
	v_and_b32_e32 v108, 0xffff0000, v133
	v_and_b32_e32 v97, 0xffff0000, v137
	v_pk_add_f32 v[90:91], v[90:91], 1.0 op_sel_hi:[1,0]
	s_nop 0
	v_mul_f32_e32 v90, v90, v91
	v_rcp_f32_e32 v90, v90
	v_mul_f32_e32 v91, 0xbfb8aa3b, v108
	v_exp_f32_e32 v91, v91
	v_mul_f32_e32 v92, v92, v90
	v_mul_f32_e32 v90, 0xbfb8aa3b, v93
	v_exp_f32_e32 v90, v90
	v_mul_f32_e32 v93, v97, v108
	v_pk_add_f32 v[90:91], v[90:91], 1.0 op_sel_hi:[1,0]
	s_nop 0
	v_mul_f32_e32 v90, v90, v91
	v_rcp_f32_e32 v90, v90
	s_nop 0
	v_mul_f32_e32 v90, v93, v90
	v_cvt_pk_bf16_f32 v97, v92, v90
	v_lshlrev_b64 v[90:91], 13, v[174:175]
	v_lshl_add_u64 v[90:91], s[44:45], 0, v[90:91]
	v_lshlrev_b32_e32 v92, 16, v122
	v_lshl_add_u64 v[108:109], v[90:91], 0, v[204:205]
	v_exp_f32_e32 v90, v86
	v_mul_f32_e32 v86, 0xbfb8aa3b, v92
	v_exp_f32_e32 v91, v86
	v_lshlrev_b32_e32 v93, 16, v126
	v_mul_f32_e32 v86, v93, v92
	v_and_b32_e32 v92, 0xffff0000, v122
	v_pk_add_f32 v[90:91], v[90:91], 1.0 op_sel_hi:[1,0]
	global_store_dwordx4 v[108:109], v[94:97], off
	v_mul_f32_e32 v90, v90, v91
	v_rcp_f32_e32 v90, v90
	v_and_b32_e32 v91, 0xffff0000, v126
	v_mul_f32_e32 v91, v91, v92
	v_mul_f32_e32 v90, v86, v90
	v_mul_f32_e32 v86, 0xbfb8aa3b, v87
	v_mul_f32_e32 v87, 0xbfb8aa3b, v92
	v_exp_f32_e32 v86, v86
	v_exp_f32_e32 v87, v87
	v_lshlrev_b32_e32 v92, 16, v127
	v_pk_add_f32 v[86:87], v[86:87], 1.0 op_sel_hi:[1,0]
	s_nop 0
	v_mul_f32_e32 v86, v86, v87
	v_rcp_f32_e32 v86, v86
	v_lshlrev_b32_e32 v87, 16, v123
	v_mul_f32_e32 v86, v91, v86
	v_cvt_pk_bf16_f32 v86, v90, v86
	v_exp_f32_e32 v90, v88
	v_mul_f32_e32 v88, 0xbfb8aa3b, v87
	v_exp_f32_e32 v91, v88
	v_mul_f32_e32 v87, v92, v87
	v_pk_add_f32 v[90:91], v[90:91], 1.0 op_sel_hi:[1,0]
	s_nop 0
	v_mul_f32_e32 v88, v90, v91
	v_rcp_f32_e32 v88, v88
	v_and_b32_e32 v91, 0xffff0000, v123
	v_and_b32_e32 v90, 0xffff0000, v127
	v_mul_f32_e32 v90, v90, v91
	v_mul_f32_e32 v87, v87, v88
	v_mul_f32_e32 v88, 0xbfb8aa3b, v89
	v_mul_f32_e32 v89, 0xbfb8aa3b, v91
	v_exp_f32_e32 v88, v88
	v_exp_f32_e32 v89, v89
	v_lshlrev_b32_e32 v91, 16, v128
	v_pk_add_f32 v[88:89], v[88:89], 1.0 op_sel_hi:[1,0]
	s_nop 0
	v_mul_f32_e32 v88, v88, v89
	v_rcp_f32_e32 v88, v88
	s_nop 0
	v_mul_f32_e32 v88, v90, v88
	v_lshlrev_b32_e32 v90, 16, v124
	v_cvt_pk_bf16_f32 v87, v87, v88
	v_exp_f32_e32 v88, v82
	v_mul_f32_e32 v82, 0xbfb8aa3b, v90
	v_exp_f32_e32 v89, v82
	v_mul_f32_e32 v82, v91, v90
	v_and_b32_e32 v90, 0xffff0000, v124
	v_pk_add_f32 v[88:89], v[88:89], 1.0 op_sel_hi:[1,0]
	s_nop 0
	v_mul_f32_e32 v88, v88, v89
	v_rcp_f32_e32 v88, v88
	v_and_b32_e32 v89, 0xffff0000, v128
	v_mul_f32_e32 v89, v89, v90
	v_mul_f32_e32 v88, v82, v88
	v_mul_f32_e32 v82, 0xbfb8aa3b, v83
	v_mul_f32_e32 v83, 0xbfb8aa3b, v90
	v_exp_f32_e32 v82, v82
	v_exp_f32_e32 v83, v83
	v_lshlrev_b32_e32 v90, 16, v129
	v_pk_add_f32 v[82:83], v[82:83], 1.0 op_sel_hi:[1,0]
	s_nop 0
	v_mul_f32_e32 v82, v82, v83
	v_rcp_f32_e32 v82, v82
	s_nop 0
	v_mul_f32_e32 v82, v89, v82
	v_lshlrev_b32_e32 v89, 16, v125
	v_cvt_pk_bf16_f32 v88, v88, v82
	v_mul_f32_e32 v82, 0xbfb8aa3b, v84
	v_mul_f32_e32 v83, 0xbfb8aa3b, v89
	v_exp_f32_e32 v82, v82
	v_exp_f32_e32 v83, v83
	v_mul_f32_e32 v84, v90, v89
	v_and_b32_e32 v90, 0xffff0000, v125
	v_and_b32_e32 v89, 0xffff0000, v129
	v_pk_add_f32 v[82:83], v[82:83], 1.0 op_sel_hi:[1,0]
	s_nop 0
	v_mul_f32_e32 v82, v82, v83
	v_rcp_f32_e32 v82, v82
	v_mul_f32_e32 v83, 0xbfb8aa3b, v90
	v_exp_f32_e32 v83, v83
	v_mul_f32_e32 v84, v84, v82
	v_mul_f32_e32 v82, 0xbfb8aa3b, v85
	v_exp_f32_e32 v82, v82
	v_mul_f32_e32 v85, v89, v90
	v_pk_add_f32 v[82:83], v[82:83], 1.0 op_sel_hi:[1,0]
	s_nop 0
	v_mul_f32_e32 v82, v82, v83
	v_rcp_f32_e32 v82, v82
	s_nop 0
	v_mul_f32_e32 v82, v85, v82
	v_cvt_pk_bf16_f32 v89, v84, v82
	v_lshlrev_b64 v[82:83], 13, v[172:173]
	v_lshl_add_u64 v[82:83], s[44:45], 0, v[82:83]
	v_lshlrev_b32_e32 v84, 16, v114
	v_lshl_add_u64 v[110:111], v[82:83], 0, v[204:205]
	v_exp_f32_e32 v82, v78
	v_mul_f32_e32 v78, 0xbfb8aa3b, v84
	v_exp_f32_e32 v83, v78
	v_lshlrev_b32_e32 v85, 16, v118
	v_mul_f32_e32 v78, v85, v84
	v_and_b32_e32 v84, 0xffff0000, v114
	v_pk_add_f32 v[82:83], v[82:83], 1.0 op_sel_hi:[1,0]
	global_store_dwordx4 v[110:111], v[86:89], off
	v_mul_f32_e32 v82, v82, v83
	v_rcp_f32_e32 v82, v82
	v_and_b32_e32 v83, 0xffff0000, v118
	v_mul_f32_e32 v83, v83, v84
	v_exp_f32_e32 v118, v70
	v_mul_f32_e32 v82, v78, v82
	v_mul_f32_e32 v78, 0xbfb8aa3b, v79
	v_mul_f32_e32 v79, 0xbfb8aa3b, v84
	v_exp_f32_e32 v78, v78
	v_exp_f32_e32 v79, v79
	v_lshlrev_b32_e32 v84, 16, v119
	v_pk_add_f32 v[78:79], v[78:79], 1.0 op_sel_hi:[1,0]
	s_nop 0
	v_mul_f32_e32 v78, v78, v79
	v_rcp_f32_e32 v78, v78
	v_lshlrev_b32_e32 v79, 16, v115
	v_mul_f32_e32 v78, v83, v78
	v_cvt_pk_bf16_f32 v78, v82, v78
	v_exp_f32_e32 v82, v80
	v_mul_f32_e32 v80, 0xbfb8aa3b, v79
	v_exp_f32_e32 v83, v80
	v_mul_f32_e32 v79, v84, v79
	v_pk_add_f32 v[82:83], v[82:83], 1.0 op_sel_hi:[1,0]
	s_nop 0
	v_mul_f32_e32 v80, v82, v83
	v_rcp_f32_e32 v80, v80
	v_and_b32_e32 v83, 0xffff0000, v115
	v_and_b32_e32 v82, 0xffff0000, v119
	v_mul_f32_e32 v82, v82, v83
	v_mul_f32_e32 v79, v79, v80
	v_mul_f32_e32 v80, 0xbfb8aa3b, v81
	v_mul_f32_e32 v81, 0xbfb8aa3b, v83
	v_exp_f32_e32 v80, v80
	v_exp_f32_e32 v81, v81
	v_lshlrev_b32_e32 v83, 16, v120
	v_pk_add_f32 v[80:81], v[80:81], 1.0 op_sel_hi:[1,0]
	s_nop 0
	v_mul_f32_e32 v80, v80, v81
	v_rcp_f32_e32 v80, v80
	s_nop 0
	v_mul_f32_e32 v80, v82, v80
	v_lshlrev_b32_e32 v82, 16, v116
	v_cvt_pk_bf16_f32 v79, v79, v80
	v_exp_f32_e32 v80, v74
; __device__ __forceinline__ unsigned cvt_pk_bf16(float lo, float hi) { unsigned r; asm volatile("v_cvt_pk_bf16_f32 %0, %1, %2" : "=v"(r) : "v"(lo), "v"(hi)); return r; }
; __device__ __forceinline__ float bf_lo(unsigned w) { return __uint_as_float(w << 16); }
; __device__ __forceinline__ float bf_hi(unsigned w) { return __uint_as_float(w & 0xffff0000u); }
;     __device__ __forceinline__ void operator()(const f32x4 (&acc)[2][2][4][2], const Unit& u, int wr, int wc, int fr, int fq, const Pre&) const {
;     ...
;         for (int bj = 0; bj < 2; ++bj) { const int c = col0 + bj * HALF;
; #pragma unroll
;             for (int ai = 0; ai < 2; ++ai) { u32x4 zv[4], gv[4];
; #pragma unroll
;                 for (int m = 0; m < 4; ++m) { const int r = row0 + ai * HALF + m * 16; zv[m] = *(const u32x4*)(Z + (size_t)r * DE2 + c); gv[m] = *(const u32x4*)(Gm + (size_t)(c >> 4) * GSTR + r * 16 + (c & 15)); }
; #pragma unroll
;                 for (int m = 0; m < 4; ++m) { const int r = row0 + ai * HALF + m * 16;
;                     const u32x4 zw = zv[m], gw = gv[m];
;                     const f32x4 a0 = acc[ai][bj][m][0] + bs[bj][0], a1 = acc[ai][bj][m][1] + bs[bj][1];
;                     u32x4 w;
;                     w.x = cvt_pk_bf16(glu_gate_f(bf_lo(gw.x), a0[0], bf_lo(zw.x)), glu_gate_f(bf_hi(gw.x), a0[1], bf_hi(zw.x)));
;                     w.y = cvt_pk_bf16(glu_gate_f(bf_lo(gw.y), a0[2], bf_lo(zw.y)), glu_gate_f(bf_hi(gw.y), a0[3], bf_hi(zw.y)));
;                     w.z = cvt_pk_bf16(glu_gate_f(bf_lo(gw.z), a1[0], bf_lo(zw.z)), glu_gate_f(bf_hi(gw.z), a1[1], bf_hi(zw.z)));
;                     w.w = cvt_pk_bf16(glu_gate_f(bf_lo(gw.w), a1[2], bf_lo(zw.w)), glu_gate_f(bf_hi(gw.w), a1[3], bf_hi(zw.w)));
	v_mul_f32_e32 v74, 0xbfb8aa3b, v82
	v_exp_f32_e32 v81, v74
	v_mul_f32_e32 v74, v83, v82
	v_and_b32_e32 v82, 0xffff0000, v116
	v_pk_add_f32 v[80:81], v[80:81], 1.0 op_sel_hi:[1,0]
	s_nop 0
	v_mul_f32_e32 v80, v80, v81
	v_rcp_f32_e32 v80, v80
	v_and_b32_e32 v81, 0xffff0000, v120
	v_mul_f32_e32 v81, v81, v82
	v_mul_f32_e32 v80, v74, v80
	v_mul_f32_e32 v74, 0xbfb8aa3b, v75
	v_mul_f32_e32 v75, 0xbfb8aa3b, v82
	v_exp_f32_e32 v74, v74
	v_exp_f32_e32 v75, v75
	v_lshlrev_b32_e32 v82, 16, v121
	v_pk_add_f32 v[74:75], v[74:75], 1.0 op_sel_hi:[1,0]
	s_nop 0
	v_mul_f32_e32 v74, v74, v75
	v_rcp_f32_e32 v74, v74
	s_nop 0
	v_mul_f32_e32 v74, v81, v74
	v_lshlrev_b32_e32 v81, 16, v117
	v_cvt_pk_bf16_f32 v80, v80, v74
	v_mul_f32_e32 v74, 0xbfb8aa3b, v76
	v_mul_f32_e32 v75, 0xbfb8aa3b, v81
	v_exp_f32_e32 v74, v74
	v_exp_f32_e32 v75, v75
	v_mul_f32_e32 v76, v82, v81
	v_and_b32_e32 v82, 0xffff0000, v117
	v_and_b32_e32 v81, 0xffff0000, v121
	v_pk_add_f32 v[74:75], v[74:75], 1.0 op_sel_hi:[1,0]
	s_nop 0
	v_mul_f32_e32 v74, v74, v75
	v_rcp_f32_e32 v74, v74
	v_mul_f32_e32 v75, 0xbfb8aa3b, v82
	v_exp_f32_e32 v75, v75
	v_mul_f32_e32 v76, v76, v74
	v_mul_f32_e32 v74, 0xbfb8aa3b, v77
	v_exp_f32_e32 v74, v74
	v_mul_f32_e32 v77, v81, v82
	v_pk_add_f32 v[74:75], v[74:75], 1.0 op_sel_hi:[1,0]
	s_nop 0
	v_mul_f32_e32 v74, v74, v75
	v_rcp_f32_e32 v74, v74
	s_nop 0
	v_mul_f32_e32 v74, v77, v74
	v_cvt_pk_bf16_f32 v81, v76, v74
	v_lshlrev_b64 v[74:75], 13, v[170:171]
	v_lshl_add_u64 v[74:75], s[44:45], 0, v[74:75]
	v_lshl_add_u64 v[112:113], v[74:75], 0, v[204:205]
	v_or_b32_e32 v74, 0x80, v200
	v_ashrrev_i32_e32 v75, 31, v74
	v_ashrrev_i32_e32 v76, 4, v74
	v_mad_i64_i32 v[114:115], s[4:5], v76, s94, v[194:195]
	v_lshl_add_u64 v[76:77], s[46:47], 0, v[202:203]
	v_lshlrev_b64 v[116:117], 1, v[74:75]
	v_lshl_add_u64 v[74:75], v[76:77], 0, v[116:117]
	global_load_dwordx4 v[98:101], v[74:75], off
	s_nop 0
	global_store_dwordx4 v[112:113], v[78:81], off
	s_nop 1
	v_lshl_add_u64 v[78:79], v[114:115], 0, v[218:219]
	global_load_dwordx4 v[78:81], v[78:79], off
	v_lshl_add_u64 v[74:75], v[114:115], 0, v[206:207]
	global_load_dwordx4 v[102:105], v[74:75], off
	v_lshl_add_u64 v[74:75], s[46:47], 0, v[210:211]
	v_lshl_add_u64 v[74:75], v[74:75], 0, v[116:117]
	global_load_dwordx4 v[90:93], v[74:75], off
	v_lshl_add_u64 v[74:75], v[114:115], 0, v[208:209]
	global_load_dwordx4 v[94:97], v[74:75], off
	v_lshl_add_u64 v[74:75], s[46:47], 0, v[214:215]
	v_lshl_add_u64 v[74:75], v[74:75], 0, v[116:117]
	global_load_dwordx4 v[82:85], v[74:75], off
	v_lshl_add_u64 v[74:75], v[114:115], 0, v[212:213]
	global_load_dwordx4 v[86:89], v[74:75], off
	v_lshl_add_u64 v[74:75], s[46:47], 0, v[216:217]
	v_lshl_add_u64 v[74:75], v[74:75], 0, v[116:117]
	global_load_dwordx4 v[74:77], v[74:75], off
	s_waitcnt vmcnt(0)
	v_lshlrev_b32_e32 v120, 16, v98
	v_mul_f32_e32 v70, 0xbfb8aa3b, v120
	v_exp_f32_e32 v119, v70
	v_and_b32_e32 v98, 0xffff0000, v98
	v_pk_add_f32 v[118:119], v[118:119], 1.0 op_sel_hi:[1,0]
	s_nop 0
	v_mul_f32_e32 v118, v118, v119
	v_rcp_f32_e32 v118, v118
	v_lshlrev_b32_e32 v121, 16, v102
	v_mul_f32_e32 v70, v121, v120
	v_and_b32_e32 v102, 0xffff0000, v102
	v_mul_f32_e32 v118, v70, v118
	v_mul_f32_e32 v70, 0xbfb8aa3b, v71
	v_mul_f32_e32 v71, 0xbfb8aa3b, v98
	v_exp_f32_e32 v70, v70
	v_exp_f32_e32 v71, v71
	v_mul_f32_e32 v98, v102, v98
	v_pk_add_f32 v[70:71], v[70:71], 1.0 op_sel_hi:[1,0]
	s_nop 0
	v_mul_f32_e32 v70, v70, v71
	v_rcp_f32_e32 v70, v70
	v_lshlrev_b32_e32 v71, 16, v99
	v_and_b32_e32 v99, 0xffff0000, v99
	v_mul_f32_e32 v70, v98, v70
	v_cvt_pk_bf16_f32 v70, v118, v70
	v_exp_f32_e32 v118, v72
	v_mul_f32_e32 v72, 0xbfb8aa3b, v71
	v_exp_f32_e32 v119, v72
	v_lshlrev_b32_e32 v98, 16, v103
	v_mul_f32_e32 v71, v98, v71
	v_and_b32_e32 v98, 0xffff0000, v103
	v_pk_add_f32 v[118:119], v[118:119], 1.0 op_sel_hi:[1,0]
	v_mul_f32_e32 v98, v98, v99
	v_mul_f32_e32 v72, v118, v119
	v_rcp_f32_e32 v72, v72
	s_nop 0
	v_mul_f32_e32 v71, v71, v72
	v_mul_f32_e32 v72, 0xbfb8aa3b, v73
	v_mul_f32_e32 v73, 0xbfb8aa3b, v99
	v_exp_f32_e32 v72, v72
	v_exp_f32_e32 v73, v73
	v_lshlrev_b32_e32 v99, 16, v104
	v_pk_add_f32 v[72:73], v[72:73], 1.0 op_sel_hi:[1,0]
	s_nop 0
	v_mul_f32_e32 v72, v72, v73
	v_rcp_f32_e32 v72, v72
	s_nop 0
	v_mul_f32_e32 v72, v98, v72
	v_lshlrev_b32_e32 v98, 16, v100
	v_cvt_pk_bf16_f32 v71, v71, v72
	v_exp_f32_e32 v72, v66
	v_mul_f32_e32 v66, 0xbfb8aa3b, v98
	v_exp_f32_e32 v73, v66
	v_mul_f32_e32 v66, v99, v98
	v_and_b32_e32 v98, 0xffff0000, v100
	v_pk_add_f32 v[72:73], v[72:73], 1.0 op_sel_hi:[1,0]
	s_nop 0
	v_mul_f32_e32 v72, v72, v73
	v_rcp_f32_e32 v72, v72
	v_and_b32_e32 v73, 0xffff0000, v104
	v_mul_f32_e32 v73, v73, v98
	v_mul_f32_e32 v72, v66, v72
	v_mul_f32_e32 v66, 0xbfb8aa3b, v67
	v_mul_f32_e32 v67, 0xbfb8aa3b, v98
	v_exp_f32_e32 v66, v66
	v_exp_f32_e32 v67, v67
	v_lshlrev_b32_e32 v98, 16, v105
	v_pk_add_f32 v[66:67], v[66:67], 1.0 op_sel_hi:[1,0]
	s_nop 0
	v_mul_f32_e32 v66, v66, v67
	v_rcp_f32_e32 v66, v66
	s_nop 0
	v_mul_f32_e32 v66, v73, v66
	v_lshlrev_b32_e32 v73, 16, v101
	v_cvt_pk_bf16_f32 v72, v72, v66
	v_mul_f32_e32 v66, 0xbfb8aa3b, v68
	v_mul_f32_e32 v67, 0xbfb8aa3b, v73
	v_exp_f32_e32 v66, v66
	v_exp_f32_e32 v67, v67
	v_mul_f32_e32 v68, v98, v73
	v_and_b32_e32 v98, 0xffff0000, v101
	v_and_b32_e32 v73, 0xffff0000, v105
	v_pk_add_f32 v[66:67], v[66:67], 1.0 op_sel_hi:[1,0]
	s_nop 0
	v_mul_f32_e32 v66, v66, v67
	v_rcp_f32_e32 v66, v66
	v_mul_f32_e32 v67, 0xbfb8aa3b, v98
	v_exp_f32_e32 v67, v67
	v_mul_f32_e32 v68, v68, v66
	v_mul_f32_e32 v66, 0xbfb8aa3b, v69
	v_exp_f32_e32 v66, v66
	v_mul_f32_e32 v69, v73, v98
	v_pk_add_f32 v[66:67], v[66:67], 1.0 op_sel_hi:[1,0]
	s_nop 0
; __device__ __forceinline__ unsigned cvt_pk_bf16(float lo, float hi) { unsigned r; asm volatile("v_cvt_pk_bf16_f32 %0, %1, %2" : "=v"(r) : "v"(lo), "v"(hi)); return r; }
; __device__ __forceinline__ float bf_lo(unsigned w) { return __uint_as_float(w << 16); }
; __device__ __forceinline__ float bf_hi(unsigned w) { return __uint_as_float(w & 0xffff0000u); }
; __device__ __forceinline__ float fast_rcp(float x) { return __builtin_amdgcn_rcpf(x); }
; __device__ __forceinline__ float glu_gate_f(float g, float v, float z) {
;     const float ev = __builtin_amdgcn_exp2f(v * -1.44269504f), ez = __builtin_amdgcn_exp2f(z * -1.44269504f);
;     return g * z * fast_rcp((1.0f + ev) * (1.0f + ez));
;     __device__ __forceinline__ void operator()(const f32x4 (&acc)[2][2][4][2], const Unit& u, int wr, int wc, int fr, int fq, const Pre&) const {
;     ...
;                 for (int m = 0; m < 4; ++m) { const int r = row0 + ai * HALF + m * 16;
;                     const u32x4 zw = zv[m], gw = gv[m];
;                     const f32x4 a0 = acc[ai][bj][m][0] + bs[bj][0], a1 = acc[ai][bj][m][1] + bs[bj][1];
;                     u32x4 w;
;                     w.x = cvt_pk_bf16(glu_gate_f(bf_lo(gw.x), a0[0], bf_lo(zw.x)), glu_gate_f(bf_hi(gw.x), a0[1], bf_hi(zw.x)));
;                     w.y = cvt_pk_bf16(glu_gate_f(bf_lo(gw.y), a0[2], bf_lo(zw.y)), glu_gate_f(bf_hi(gw.y), a0[3], bf_hi(zw.y)));
;                     w.z = cvt_pk_bf16(glu_gate_f(bf_lo(gw.z), a1[0], bf_lo(zw.z)), glu_gate_f(bf_hi(gw.z), a1[1], bf_hi(zw.z)));
;                     w.w = cvt_pk_bf16(glu_gate_f(bf_lo(gw.w), a1[2], bf_lo(zw.w)), glu_gate_f(bf_hi(gw.w), a1[3], bf_hi(zw.w)));
;                     *(u32x4*)(O + (size_t)r * DE + c) = w; } } }
	v_mul_f32_e32 v66, v66, v67
	v_rcp_f32_e32 v66, v66
	s_nop 0
	v_mul_f32_e32 v66, v69, v66
	v_cvt_pk_bf16_f32 v73, v68, v66
	v_lshlrev_b32_e32 v68, 16, v90
	v_exp_f32_e32 v66, v62
	v_mul_f32_e32 v62, 0xbfb8aa3b, v68
	v_exp_f32_e32 v67, v62
	v_lshlrev_b32_e32 v69, 16, v94
	v_mul_f32_e32 v62, v69, v68
	v_and_b32_e32 v68, 0xffff0000, v90
	v_pk_add_f32 v[66:67], v[66:67], 1.0 op_sel_hi:[1,0]
	global_store_dwordx4 v[162:163], v[70:73], off offset:256
	v_mul_f32_e32 v66, v66, v67
	v_rcp_f32_e32 v66, v66
	v_and_b32_e32 v67, 0xffff0000, v94
	v_mul_f32_e32 v67, v67, v68
	v_mul_f32_e32 v66, v62, v66
	v_mul_f32_e32 v62, 0xbfb8aa3b, v63
	v_mul_f32_e32 v63, 0xbfb8aa3b, v68
	v_exp_f32_e32 v62, v62
	v_exp_f32_e32 v63, v63
	v_lshlrev_b32_e32 v68, 16, v95
	v_pk_add_f32 v[62:63], v[62:63], 1.0 op_sel_hi:[1,0]
	s_nop 0
	v_mul_f32_e32 v62, v62, v63
	v_rcp_f32_e32 v62, v62
	v_lshlrev_b32_e32 v63, 16, v91
	v_mul_f32_e32 v62, v67, v62
	v_cvt_pk_bf16_f32 v62, v66, v62
	v_exp_f32_e32 v66, v64
	v_mul_f32_e32 v64, 0xbfb8aa3b, v63
	v_exp_f32_e32 v67, v64
	v_mul_f32_e32 v63, v68, v63
	v_pk_add_f32 v[66:67], v[66:67], 1.0 op_sel_hi:[1,0]
	s_nop 0
	v_mul_f32_e32 v64, v66, v67
	v_rcp_f32_e32 v64, v64
	v_and_b32_e32 v67, 0xffff0000, v91
	v_and_b32_e32 v66, 0xffff0000, v95
	v_mul_f32_e32 v66, v66, v67
	v_mul_f32_e32 v63, v63, v64
	v_mul_f32_e32 v64, 0xbfb8aa3b, v65
	v_mul_f32_e32 v65, 0xbfb8aa3b, v67
	v_exp_f32_e32 v64, v64
	v_exp_f32_e32 v65, v65
	v_lshlrev_b32_e32 v67, 16, v96
	v_pk_add_f32 v[64:65], v[64:65], 1.0 op_sel_hi:[1,0]
	s_nop 0
	v_mul_f32_e32 v64, v64, v65
	v_rcp_f32_e32 v64, v64
	s_nop 0
	v_mul_f32_e32 v64, v66, v64
	v_lshlrev_b32_e32 v66, 16, v92
	v_cvt_pk_bf16_f32 v63, v63, v64
	v_exp_f32_e32 v64, v58
	v_mul_f32_e32 v58, 0xbfb8aa3b, v66
	v_exp_f32_e32 v65, v58
	v_mul_f32_e32 v58, v67, v66
	v_and_b32_e32 v66, 0xffff0000, v92
	v_pk_add_f32 v[64:65], v[64:65], 1.0 op_sel_hi:[1,0]
	s_nop 0
	v_mul_f32_e32 v64, v64, v65
	v_rcp_f32_e32 v64, v64
	v_and_b32_e32 v65, 0xffff0000, v96
	v_mul_f32_e32 v65, v65, v66
	v_mul_f32_e32 v64, v58, v64
	v_mul_f32_e32 v58, 0xbfb8aa3b, v59
	v_mul_f32_e32 v59, 0xbfb8aa3b, v66
	v_exp_f32_e32 v58, v58
	v_exp_f32_e32 v59, v59
	v_lshlrev_b32_e32 v66, 16, v97
	v_pk_add_f32 v[58:59], v[58:59], 1.0 op_sel_hi:[1,0]
	s_nop 0
	v_mul_f32_e32 v58, v58, v59
	v_rcp_f32_e32 v58, v58
	s_nop 0
	v_mul_f32_e32 v58, v65, v58
	v_lshlrev_b32_e32 v65, 16, v93
	v_cvt_pk_bf16_f32 v64, v64, v58
	v_mul_f32_e32 v58, 0xbfb8aa3b, v60
	v_mul_f32_e32 v59, 0xbfb8aa3b, v65
	v_exp_f32_e32 v58, v58
	v_exp_f32_e32 v59, v59
	v_mul_f32_e32 v60, v66, v65
	v_and_b32_e32 v66, 0xffff0000, v93
	v_and_b32_e32 v65, 0xffff0000, v97
	v_pk_add_f32 v[58:59], v[58:59], 1.0 op_sel_hi:[1,0]
	s_nop 0
	v_mul_f32_e32 v58, v58, v59
	v_rcp_f32_e32 v58, v58
	v_mul_f32_e32 v59, 0xbfb8aa3b, v66
	v_exp_f32_e32 v59, v59
	v_mul_f32_e32 v60, v60, v58
	v_mul_f32_e32 v58, 0xbfb8aa3b, v61
	v_exp_f32_e32 v58, v58
	v_mul_f32_e32 v61, v65, v66
	v_pk_add_f32 v[58:59], v[58:59], 1.0 op_sel_hi:[1,0]
	s_nop 0
	v_mul_f32_e32 v58, v58, v59
	v_rcp_f32_e32 v58, v58
	s_nop 0
	v_mul_f32_e32 v58, v61, v58
	v_cvt_pk_bf16_f32 v65, v60, v58
	v_lshlrev_b32_e32 v60, 16, v82
	v_exp_f32_e32 v58, v54
	v_mul_f32_e32 v54, 0xbfb8aa3b, v60
	v_exp_f32_e32 v59, v54
	v_lshlrev_b32_e32 v61, 16, v86
	v_mul_f32_e32 v54, v61, v60
	v_and_b32_e32 v60, 0xffff0000, v82
	v_pk_add_f32 v[58:59], v[58:59], 1.0 op_sel_hi:[1,0]
	global_store_dwordx4 v[154:155], v[62:65], off offset:256
	v_mul_f32_e32 v58, v58, v59
	v_rcp_f32_e32 v58, v58
	v_and_b32_e32 v59, 0xffff0000, v86
	v_mul_f32_e32 v59, v59, v60
	v_mul_f32_e32 v58, v54, v58
	v_mul_f32_e32 v54, 0xbfb8aa3b, v55
	v_mul_f32_e32 v55, 0xbfb8aa3b, v60
	v_exp_f32_e32 v54, v54
	v_exp_f32_e32 v55, v55
	v_lshlrev_b32_e32 v60, 16, v87
	v_pk_add_f32 v[54:55], v[54:55], 1.0 op_sel_hi:[1,0]
	s_nop 0
	v_mul_f32_e32 v54, v54, v55
	v_rcp_f32_e32 v54, v54
	v_lshlrev_b32_e32 v55, 16, v83
	v_mul_f32_e32 v54, v59, v54
	v_cvt_pk_bf16_f32 v54, v58, v54
	v_exp_f32_e32 v58, v56
	v_mul_f32_e32 v56, 0xbfb8aa3b, v55
	v_exp_f32_e32 v59, v56
	v_mul_f32_e32 v55, v60, v55
	v_pk_add_f32 v[58:59], v[58:59], 1.0 op_sel_hi:[1,0]
	s_nop 0
	v_mul_f32_e32 v56, v58, v59
	v_rcp_f32_e32 v56, v56
	v_and_b32_e32 v59, 0xffff0000, v83
	v_and_b32_e32 v58, 0xffff0000, v87
	v_mul_f32_e32 v58, v58, v59
	v_mul_f32_e32 v55, v55, v56
	v_mul_f32_e32 v56, 0xbfb8aa3b, v57
	v_mul_f32_e32 v57, 0xbfb8aa3b, v59
	v_exp_f32_e32 v56, v56
	v_exp_f32_e32 v57, v57
	v_lshlrev_b32_e32 v59, 16, v88
	v_pk_add_f32 v[56:57], v[56:57], 1.0 op_sel_hi:[1,0]
	s_nop 0
	v_mul_f32_e32 v56, v56, v57
	v_rcp_f32_e32 v56, v56
	s_nop 0
	v_mul_f32_e32 v56, v58, v56
	v_lshlrev_b32_e32 v58, 16, v84
	v_cvt_pk_bf16_f32 v55, v55, v56
	v_exp_f32_e32 v56, v50
	v_mul_f32_e32 v50, 0xbfb8aa3b, v58
	v_exp_f32_e32 v57, v50
	v_mul_f32_e32 v50, v59, v58
	v_and_b32_e32 v58, 0xffff0000, v84
	v_pk_add_f32 v[56:57], v[56:57], 1.0 op_sel_hi:[1,0]
	s_nop 0
	v_mul_f32_e32 v56, v56, v57
	v_rcp_f32_e32 v56, v56
	v_and_b32_e32 v57, 0xffff0000, v88
	v_mul_f32_e32 v57, v57, v58
	v_mul_f32_e32 v56, v50, v56
	v_mul_f32_e32 v50, 0xbfb8aa3b, v51
	v_mul_f32_e32 v51, 0xbfb8aa3b, v58
	v_exp_f32_e32 v50, v50
	v_exp_f32_e32 v51, v51
	v_lshlrev_b32_e32 v58, 16, v89
	v_pk_add_f32 v[50:51], v[50:51], 1.0 op_sel_hi:[1,0]
	s_nop 0
	v_mul_f32_e32 v50, v50, v51
	v_rcp_f32_e32 v50, v50
	s_nop 0
	v_mul_f32_e32 v50, v57, v50
	v_lshlrev_b32_e32 v57, 16, v85
	v_cvt_pk_bf16_f32 v56, v56, v50
	v_mul_f32_e32 v50, 0xbfb8aa3b, v52
	v_mul_f32_e32 v51, 0xbfb8aa3b, v57
	v_exp_f32_e32 v50, v50
	v_exp_f32_e32 v51, v51
	v_mul_f32_e32 v52, v58, v57
	v_and_b32_e32 v58, 0xffff0000, v85
	v_and_b32_e32 v57, 0xffff0000, v89
; __device__ __forceinline__ unsigned cvt_pk_bf16(float lo, float hi) { unsigned r; asm volatile("v_cvt_pk_bf16_f32 %0, %1, %2" : "=v"(r) : "v"(lo), "v"(hi)); return r; }
; __device__ __forceinline__ float bf_lo(unsigned w) { return __uint_as_float(w << 16); }
; __device__ __forceinline__ float bf_hi(unsigned w) { return __uint_as_float(w & 0xffff0000u); }
; __device__ __forceinline__ float fast_rcp(float x) { return __builtin_amdgcn_rcpf(x); }
; __device__ __forceinline__ float glu_gate_f(float g, float v, float z) {
;     const float ev = __builtin_amdgcn_exp2f(v * -1.44269504f), ez = __builtin_amdgcn_exp2f(z * -1.44269504f);
;     return g * z * fast_rcp((1.0f + ev) * (1.0f + ez));
;     __device__ __forceinline__ void operator()(const f32x4 (&acc)[2][2][4][2], const Unit& u, int wr, int wc, int fr, int fq, const Pre&) const {
;     ...
;             for (int ai = 0; ai < 2; ++ai) { u32x4 zv[4], gv[4];
; #pragma unroll
;                 for (int m = 0; m < 4; ++m) { const int r = row0 + ai * HALF + m * 16; zv[m] = *(const u32x4*)(Z + (size_t)r * DE2 + c); gv[m] = *(const u32x4*)(Gm + (size_t)(c >> 4) * GSTR + r * 16 + (c & 15)); }
; #pragma unroll
;                 for (int m = 0; m < 4; ++m) { const int r = row0 + ai * HALF + m * 16;
;                     const u32x4 zw = zv[m], gw = gv[m];
;                     const f32x4 a0 = acc[ai][bj][m][0] + bs[bj][0], a1 = acc[ai][bj][m][1] + bs[bj][1];
;                     u32x4 w;
;                     w.x = cvt_pk_bf16(glu_gate_f(bf_lo(gw.x), a0[0], bf_lo(zw.x)), glu_gate_f(bf_hi(gw.x), a0[1], bf_hi(zw.x)));
;                     w.y = cvt_pk_bf16(glu_gate_f(bf_lo(gw.y), a0[2], bf_lo(zw.y)), glu_gate_f(bf_hi(gw.y), a0[3], bf_hi(zw.y)));
;                     w.z = cvt_pk_bf16(glu_gate_f(bf_lo(gw.z), a1[0], bf_lo(zw.z)), glu_gate_f(bf_hi(gw.z), a1[1], bf_hi(zw.z)));
;                     w.w = cvt_pk_bf16(glu_gate_f(bf_lo(gw.w), a1[2], bf_lo(zw.w)), glu_gate_f(bf_hi(gw.w), a1[3], bf_hi(zw.w)));
;                     *(u32x4*)(O + (size_t)r * DE + c) = w; } } }
	v_pk_add_f32 v[50:51], v[50:51], 1.0 op_sel_hi:[1,0]
	s_nop 0
	v_mul_f32_e32 v50, v50, v51
	v_rcp_f32_e32 v50, v50
	v_mul_f32_e32 v51, 0xbfb8aa3b, v58
	v_exp_f32_e32 v51, v51
	v_mul_f32_e32 v52, v52, v50
	v_mul_f32_e32 v50, 0xbfb8aa3b, v53
	v_exp_f32_e32 v50, v50
	v_mul_f32_e32 v53, v57, v58
	v_pk_add_f32 v[50:51], v[50:51], 1.0 op_sel_hi:[1,0]
	s_nop 0
	v_mul_f32_e32 v50, v50, v51
	v_rcp_f32_e32 v50, v50
	s_nop 0
	v_mul_f32_e32 v50, v53, v50
	v_cvt_pk_bf16_f32 v57, v52, v50
	v_lshlrev_b32_e32 v52, 16, v74
	v_exp_f32_e32 v50, v46
	v_mul_f32_e32 v46, 0xbfb8aa3b, v52
	v_exp_f32_e32 v51, v46
	v_lshlrev_b32_e32 v53, 16, v78
	v_mul_f32_e32 v46, v53, v52
	v_and_b32_e32 v52, 0xffff0000, v74
	v_pk_add_f32 v[50:51], v[50:51], 1.0 op_sel_hi:[1,0]
	global_store_dwordx4 v[146:147], v[54:57], off offset:256
	v_mul_f32_e32 v50, v50, v51
	v_rcp_f32_e32 v50, v50
	v_and_b32_e32 v51, 0xffff0000, v78
	v_mul_f32_e32 v51, v51, v52
	v_exp_f32_e32 v74, v38
	v_mul_f32_e32 v50, v46, v50
	v_mul_f32_e32 v46, 0xbfb8aa3b, v47
	v_mul_f32_e32 v47, 0xbfb8aa3b, v52
	v_exp_f32_e32 v46, v46
	v_exp_f32_e32 v47, v47
	v_lshlrev_b32_e32 v52, 16, v79
	v_pk_add_f32 v[46:47], v[46:47], 1.0 op_sel_hi:[1,0]
	s_nop 0
	v_mul_f32_e32 v46, v46, v47
	v_rcp_f32_e32 v46, v46
	v_lshlrev_b32_e32 v47, 16, v75
	v_mul_f32_e32 v46, v51, v46
	v_cvt_pk_bf16_f32 v46, v50, v46
	v_exp_f32_e32 v50, v48
	v_mul_f32_e32 v48, 0xbfb8aa3b, v47
	v_exp_f32_e32 v51, v48
	v_mul_f32_e32 v47, v52, v47
	v_pk_add_f32 v[50:51], v[50:51], 1.0 op_sel_hi:[1,0]
	s_nop 0
	v_mul_f32_e32 v48, v50, v51
	v_rcp_f32_e32 v48, v48
	v_and_b32_e32 v51, 0xffff0000, v75
	v_and_b32_e32 v50, 0xffff0000, v79
	v_mul_f32_e32 v50, v50, v51
	v_mul_f32_e32 v47, v47, v48
	v_mul_f32_e32 v48, 0xbfb8aa3b, v49
	v_mul_f32_e32 v49, 0xbfb8aa3b, v51
	v_exp_f32_e32 v48, v48
	v_exp_f32_e32 v49, v49
	v_lshlrev_b32_e32 v51, 16, v80
	v_pk_add_f32 v[48:49], v[48:49], 1.0 op_sel_hi:[1,0]
	s_nop 0
	v_mul_f32_e32 v48, v48, v49
	v_rcp_f32_e32 v48, v48
	s_nop 0
	v_mul_f32_e32 v48, v50, v48
	v_lshlrev_b32_e32 v50, 16, v76
	v_cvt_pk_bf16_f32 v47, v47, v48
	v_exp_f32_e32 v48, v42
	v_mul_f32_e32 v42, 0xbfb8aa3b, v50
	v_exp_f32_e32 v49, v42
	v_mul_f32_e32 v42, v51, v50
	v_and_b32_e32 v50, 0xffff0000, v76
	v_pk_add_f32 v[48:49], v[48:49], 1.0 op_sel_hi:[1,0]
	s_nop 0
	v_mul_f32_e32 v48, v48, v49
	v_rcp_f32_e32 v48, v48
	v_and_b32_e32 v49, 0xffff0000, v80
	v_mul_f32_e32 v49, v49, v50
	v_mul_f32_e32 v48, v42, v48
	v_mul_f32_e32 v42, 0xbfb8aa3b, v43
	v_mul_f32_e32 v43, 0xbfb8aa3b, v50
	v_exp_f32_e32 v42, v42
	v_exp_f32_e32 v43, v43
	v_lshlrev_b32_e32 v50, 16, v81
	v_pk_add_f32 v[42:43], v[42:43], 1.0 op_sel_hi:[1,0]
	s_nop 0
	v_mul_f32_e32 v42, v42, v43
	v_rcp_f32_e32 v42, v42
	s_nop 0
	v_mul_f32_e32 v42, v49, v42
	v_lshlrev_b32_e32 v49, 16, v77
	v_cvt_pk_bf16_f32 v48, v48, v42
	v_mul_f32_e32 v42, 0xbfb8aa3b, v44
	v_mul_f32_e32 v43, 0xbfb8aa3b, v49
	v_exp_f32_e32 v42, v42
	v_exp_f32_e32 v43, v43
	v_mul_f32_e32 v44, v50, v49
	v_and_b32_e32 v50, 0xffff0000, v77
	v_and_b32_e32 v49, 0xffff0000, v81
	v_pk_add_f32 v[42:43], v[42:43], 1.0 op_sel_hi:[1,0]
	s_nop 0
	v_mul_f32_e32 v42, v42, v43
	v_rcp_f32_e32 v42, v42
	v_mul_f32_e32 v43, 0xbfb8aa3b, v50
	v_exp_f32_e32 v43, v43
	v_mul_f32_e32 v44, v44, v42
	v_mul_f32_e32 v42, 0xbfb8aa3b, v45
	v_exp_f32_e32 v42, v42
	v_mul_f32_e32 v45, v49, v50
	v_pk_add_f32 v[42:43], v[42:43], 1.0 op_sel_hi:[1,0]
	s_nop 0
	v_mul_f32_e32 v42, v42, v43
	v_rcp_f32_e32 v42, v42
	s_nop 0
	v_mul_f32_e32 v42, v45, v42
	v_cvt_pk_bf16_f32 v49, v44, v42
	v_lshl_add_u64 v[42:43], s[46:47], 0, v[150:151]
	global_store_dwordx4 v[148:149], v[46:49], off offset:256
	v_lshl_add_u64 v[42:43], v[42:43], 0, v[116:117]
	global_load_dwordx4 v[66:69], v[42:43], off
	v_lshl_add_u64 v[46:47], v[114:115], 0, v[168:169]
	global_load_dwordx4 v[46:49], v[46:47], off
	v_lshl_add_u64 v[42:43], v[114:115], 0, v[152:153]
	global_load_dwordx4 v[70:73], v[42:43], off
	v_lshl_add_u64 v[42:43], s[46:47], 0, v[156:157]
	v_lshl_add_u64 v[42:43], v[42:43], 0, v[116:117]
	global_load_dwordx4 v[58:61], v[42:43], off
	v_lshl_add_u64 v[42:43], v[114:115], 0, v[158:159]
	global_load_dwordx4 v[62:65], v[42:43], off
	v_lshl_add_u64 v[42:43], s[46:47], 0, v[160:161]
	v_lshl_add_u64 v[42:43], v[42:43], 0, v[116:117]
	global_load_dwordx4 v[50:53], v[42:43], off
	v_lshl_add_u64 v[42:43], v[114:115], 0, v[164:165]
	global_load_dwordx4 v[54:57], v[42:43], off
	v_lshl_add_u64 v[42:43], s[46:47], 0, v[166:167]
	v_lshl_add_u64 v[42:43], v[42:43], 0, v[116:117]
	global_load_dwordx4 v[42:45], v[42:43], off
	s_waitcnt vmcnt(0)
; __device__ __forceinline__ unsigned cvt_pk_bf16(float lo, float hi) { unsigned r; asm volatile("v_cvt_pk_bf16_f32 %0, %1, %2" : "=v"(r) : "v"(lo), "v"(hi)); return r; }
; __device__ __forceinline__ float bf_lo(unsigned w) { return __uint_as_float(w << 16); }
; __device__ __forceinline__ float bf_hi(unsigned w) { return __uint_as_float(w & 0xffff0000u); }
; __device__ __forceinline__ float fast_rcp(float x) { return __builtin_amdgcn_rcpf(x); }
; __device__ __forceinline__ float glu_gate_f(float g, float v, float z) {
;     const float ev = __builtin_amdgcn_exp2f(v * -1.44269504f), ez = __builtin_amdgcn_exp2f(z * -1.44269504f);
;     return g * z * fast_rcp((1.0f + ev) * (1.0f + ez));
;     __device__ __forceinline__ void operator()(const f32x4 (&acc)[2][2][4][2], const Unit& u, int wr, int wc, int fr, int fq, const Pre&) const {
;     ...
;                 for (int m = 0; m < 4; ++m) { const int r = row0 + ai * HALF + m * 16;
;                     const u32x4 zw = zv[m], gw = gv[m];
;                     const f32x4 a0 = acc[ai][bj][m][0] + bs[bj][0], a1 = acc[ai][bj][m][1] + bs[bj][1];
;                     u32x4 w;
;                     w.x = cvt_pk_bf16(glu_gate_f(bf_lo(gw.x), a0[0], bf_lo(zw.x)), glu_gate_f(bf_hi(gw.x), a0[1], bf_hi(zw.x)));
;                     w.y = cvt_pk_bf16(glu_gate_f(bf_lo(gw.y), a0[2], bf_lo(zw.y)), glu_gate_f(bf_hi(gw.y), a0[3], bf_hi(zw.y)));
;                     w.z = cvt_pk_bf16(glu_gate_f(bf_lo(gw.z), a1[0], bf_lo(zw.z)), glu_gate_f(bf_hi(gw.z), a1[1], bf_hi(zw.z)));
;                     w.w = cvt_pk_bf16(glu_gate_f(bf_lo(gw.w), a1[2], bf_lo(zw.w)), glu_gate_f(bf_hi(gw.w), a1[3], bf_hi(zw.w)));
;                     *(u32x4*)(O + (size_t)r * DE + c) = w; } } }
	v_lshlrev_b32_e32 v76, 16, v66
	v_mul_f32_e32 v38, 0xbfb8aa3b, v76
	v_exp_f32_e32 v75, v38
	v_and_b32_e32 v66, 0xffff0000, v66
	v_lshlrev_b32_e32 v77, 16, v70
	v_mul_f32_e32 v38, v77, v76
	v_pk_add_f32 v[74:75], v[74:75], 1.0 op_sel_hi:[1,0]
	v_and_b32_e32 v70, 0xffff0000, v70
	v_mul_f32_e32 v74, v74, v75
	v_rcp_f32_e32 v74, v74
	s_nop 0
	v_mul_f32_e32 v74, v38, v74
	v_mul_f32_e32 v38, 0xbfb8aa3b, v39
	v_mul_f32_e32 v39, 0xbfb8aa3b, v66
	v_exp_f32_e32 v38, v38
	v_exp_f32_e32 v39, v39
	v_mul_f32_e32 v66, v70, v66
	v_pk_add_f32 v[38:39], v[38:39], 1.0 op_sel_hi:[1,0]
	s_nop 0
	v_mul_f32_e32 v38, v38, v39
	v_rcp_f32_e32 v38, v38
	v_lshlrev_b32_e32 v39, 16, v67
	v_and_b32_e32 v67, 0xffff0000, v67
	v_mul_f32_e32 v38, v66, v38
	v_cvt_pk_bf16_f32 v38, v74, v38
	v_exp_f32_e32 v74, v40
	v_mul_f32_e32 v40, 0xbfb8aa3b, v39
	v_exp_f32_e32 v75, v40
	v_lshlrev_b32_e32 v66, 16, v71
	v_mul_f32_e32 v39, v66, v39
	v_and_b32_e32 v66, 0xffff0000, v71
	v_pk_add_f32 v[74:75], v[74:75], 1.0 op_sel_hi:[1,0]
	v_mul_f32_e32 v66, v66, v67
	v_mul_f32_e32 v40, v74, v75
	v_rcp_f32_e32 v40, v40
	s_nop 0
	v_mul_f32_e32 v39, v39, v40
	v_mul_f32_e32 v40, 0xbfb8aa3b, v41
	v_mul_f32_e32 v41, 0xbfb8aa3b, v67
	v_exp_f32_e32 v40, v40
	v_exp_f32_e32 v41, v41
	v_lshlrev_b32_e32 v67, 16, v72
	v_pk_add_f32 v[40:41], v[40:41], 1.0 op_sel_hi:[1,0]
	s_nop 0
	v_mul_f32_e32 v40, v40, v41
	v_rcp_f32_e32 v40, v40
	s_nop 0
	v_mul_f32_e32 v40, v66, v40
	v_lshlrev_b32_e32 v66, 16, v68
	v_cvt_pk_bf16_f32 v39, v39, v40
	v_exp_f32_e32 v40, v34
	v_mul_f32_e32 v34, 0xbfb8aa3b, v66
	v_exp_f32_e32 v41, v34
	v_mul_f32_e32 v34, v67, v66
	v_and_b32_e32 v66, 0xffff0000, v68
	v_pk_add_f32 v[40:41], v[40:41], 1.0 op_sel_hi:[1,0]
	s_nop 0
	v_mul_f32_e32 v40, v40, v41
	v_rcp_f32_e32 v40, v40
	v_and_b32_e32 v41, 0xffff0000, v72
	v_mul_f32_e32 v41, v41, v66
	v_mul_f32_e32 v40, v34, v40
	v_mul_f32_e32 v34, 0xbfb8aa3b, v35
	v_mul_f32_e32 v35, 0xbfb8aa3b, v66
	v_exp_f32_e32 v34, v34
	v_exp_f32_e32 v35, v35
	v_lshlrev_b32_e32 v66, 16, v73
	v_pk_add_f32 v[34:35], v[34:35], 1.0 op_sel_hi:[1,0]
	s_nop 0
	v_mul_f32_e32 v34, v34, v35
	v_rcp_f32_e32 v34, v34
	s_nop 0
	v_mul_f32_e32 v34, v41, v34
	v_lshlrev_b32_e32 v41, 16, v69
	v_cvt_pk_bf16_f32 v40, v40, v34
	v_mul_f32_e32 v34, 0xbfb8aa3b, v36
	v_mul_f32_e32 v35, 0xbfb8aa3b, v41
	v_exp_f32_e32 v34, v34
	v_exp_f32_e32 v35, v35
	v_mul_f32_e32 v36, v66, v41
	v_and_b32_e32 v66, 0xffff0000, v69
	v_and_b32_e32 v41, 0xffff0000, v73
	v_pk_add_f32 v[34:35], v[34:35], 1.0 op_sel_hi:[1,0]
	s_nop 0
	v_mul_f32_e32 v34, v34, v35
	v_rcp_f32_e32 v34, v34
	v_mul_f32_e32 v35, 0xbfb8aa3b, v66
	v_exp_f32_e32 v35, v35
	v_mul_f32_e32 v36, v36, v34
	v_mul_f32_e32 v34, 0xbfb8aa3b, v37
	v_exp_f32_e32 v34, v34
	v_mul_f32_e32 v37, v41, v66
	v_pk_add_f32 v[34:35], v[34:35], 1.0 op_sel_hi:[1,0]
	s_nop 0
	v_mul_f32_e32 v34, v34, v35
	v_rcp_f32_e32 v34, v34
	s_nop 0
	v_mul_f32_e32 v34, v37, v34
	v_cvt_pk_bf16_f32 v41, v36, v34
	v_lshlrev_b32_e32 v36, 16, v58
	v_exp_f32_e32 v34, v22
	v_mul_f32_e32 v22, 0xbfb8aa3b, v36
	v_exp_f32_e32 v35, v22
	v_lshlrev_b32_e32 v37, 16, v62
	v_mul_f32_e32 v22, v37, v36
	v_and_b32_e32 v36, 0xffff0000, v58
	v_pk_add_f32 v[34:35], v[34:35], 1.0 op_sel_hi:[1,0]
	global_store_dwordx4 v[106:107], v[38:41], off offset:256
	v_mul_f32_e32 v34, v34, v35
	v_rcp_f32_e32 v34, v34
	v_and_b32_e32 v35, 0xffff0000, v62
	v_mul_f32_e32 v35, v35, v36
	v_mul_f32_e32 v34, v22, v34
	v_mul_f32_e32 v22, 0xbfb8aa3b, v23
	v_mul_f32_e32 v23, 0xbfb8aa3b, v36
	v_exp_f32_e32 v22, v22
	v_exp_f32_e32 v23, v23
	v_lshlrev_b32_e32 v36, 16, v63
	v_pk_add_f32 v[22:23], v[22:23], 1.0 op_sel_hi:[1,0]
	s_nop 0
	v_mul_f32_e32 v22, v22, v23
	v_rcp_f32_e32 v22, v22
	v_lshlrev_b32_e32 v23, 16, v59
	v_mul_f32_e32 v22, v35, v22
	v_cvt_pk_bf16_f32 v22, v34, v22
	v_exp_f32_e32 v34, v24
	v_mul_f32_e32 v24, 0xbfb8aa3b, v23
	v_exp_f32_e32 v35, v24
	v_mul_f32_e32 v23, v36, v23
	v_pk_add_f32 v[34:35], v[34:35], 1.0 op_sel_hi:[1,0]
	s_nop 0
	v_mul_f32_e32 v24, v34, v35
	v_rcp_f32_e32 v24, v24
	v_and_b32_e32 v35, 0xffff0000, v59
	v_and_b32_e32 v34, 0xffff0000, v63
	v_mul_f32_e32 v34, v34, v35
	v_mul_f32_e32 v23, v23, v24
	v_mul_f32_e32 v24, 0xbfb8aa3b, v25
	v_mul_f32_e32 v25, 0xbfb8aa3b, v35
	v_exp_f32_e32 v24, v24
	v_exp_f32_e32 v25, v25
	v_lshlrev_b32_e32 v35, 16, v64
	v_pk_add_f32 v[24:25], v[24:25], 1.0 op_sel_hi:[1,0]
	s_nop 0
	v_mul_f32_e32 v24, v24, v25
	v_rcp_f32_e32 v24, v24
	s_nop 0
	v_mul_f32_e32 v24, v34, v24
	v_lshlrev_b32_e32 v34, 16, v60
	v_cvt_pk_bf16_f32 v23, v23, v24
	v_exp_f32_e32 v24, v18
	v_mul_f32_e32 v18, 0xbfb8aa3b, v34
	v_exp_f32_e32 v25, v18
	v_mul_f32_e32 v18, v35, v34
	v_and_b32_e32 v34, 0xffff0000, v60
	v_pk_add_f32 v[24:25], v[24:25], 1.0 op_sel_hi:[1,0]
	s_nop 0
	v_mul_f32_e32 v24, v24, v25
	v_rcp_f32_e32 v24, v24
	v_and_b32_e32 v25, 0xffff0000, v64
	v_mul_f32_e32 v25, v25, v34
	v_mul_f32_e32 v24, v18, v24
	v_mul_f32_e32 v18, 0xbfb8aa3b, v19
	v_mul_f32_e32 v19, 0xbfb8aa3b, v34
	v_exp_f32_e32 v18, v18
	v_exp_f32_e32 v19, v19
	v_lshlrev_b32_e32 v34, 16, v65
	v_pk_add_f32 v[18:19], v[18:19], 1.0 op_sel_hi:[1,0]
	s_nop 0
	v_mul_f32_e32 v18, v18, v19
	v_rcp_f32_e32 v18, v18
	s_nop 0
	v_mul_f32_e32 v18, v25, v18
	v_lshlrev_b32_e32 v25, 16, v61
	v_cvt_pk_bf16_f32 v24, v24, v18
	v_mul_f32_e32 v18, 0xbfb8aa3b, v20
	v_mul_f32_e32 v19, 0xbfb8aa3b, v25
	v_exp_f32_e32 v18, v18
	v_exp_f32_e32 v19, v19
	v_mul_f32_e32 v20, v34, v25
	v_and_b32_e32 v34, 0xffff0000, v61
	v_and_b32_e32 v25, 0xffff0000, v65
	v_pk_add_f32 v[18:19], v[18:19], 1.0 op_sel_hi:[1,0]
	s_nop 0
	v_mul_f32_e32 v18, v18, v19
	v_rcp_f32_e32 v18, v18
	v_mul_f32_e32 v19, 0xbfb8aa3b, v34
	v_exp_f32_e32 v19, v19
	v_mul_f32_e32 v20, v20, v18
; __device__ __forceinline__ unsigned cvt_pk_bf16(float lo, float hi) { unsigned r; asm volatile("v_cvt_pk_bf16_f32 %0, %1, %2" : "=v"(r) : "v"(lo), "v"(hi)); return r; }
; __device__ __forceinline__ float bf_lo(unsigned w) { return __uint_as_float(w << 16); }
; __device__ __forceinline__ float bf_hi(unsigned w) { return __uint_as_float(w & 0xffff0000u); }
; #define PG8_WAIT_V(n) asm volatile("s_waitcnt vmcnt(" #n ")" ::: "memory")
; #define PG8_BAR __builtin_amdgcn_s_barrier()
; template <class Epi>
; __device__ __forceinline__ void gemm_phase(LAS unsigned char* lds, const Gemm g, const StaticOrder& S, const Epi& E) {
;     ...
;     PG8_WAIT_V(0);
;     if (wr == 0) PG8_BAR;
;     __device__ __forceinline__ void operator()(const f32x4 (&acc)[2][2][4][2], const Unit& u, int wr, int wc, int fr, int fq, const Pre&) const {
;     ...
;                 for (int m = 0; m < 4; ++m) { const int r = row0 + ai * HALF + m * 16;
;                     const u32x4 zw = zv[m], gw = gv[m];
;                     const f32x4 a0 = acc[ai][bj][m][0] + bs[bj][0], a1 = acc[ai][bj][m][1] + bs[bj][1];
;                     u32x4 w;
;                     w.x = cvt_pk_bf16(glu_gate_f(bf_lo(gw.x), a0[0], bf_lo(zw.x)), glu_gate_f(bf_hi(gw.x), a0[1], bf_hi(zw.x)));
;                     w.y = cvt_pk_bf16(glu_gate_f(bf_lo(gw.y), a0[2], bf_lo(zw.y)), glu_gate_f(bf_hi(gw.y), a0[3], bf_hi(zw.y)));
;                     w.z = cvt_pk_bf16(glu_gate_f(bf_lo(gw.z), a1[0], bf_lo(zw.z)), glu_gate_f(bf_hi(gw.z), a1[1], bf_hi(zw.z)));
;                     w.w = cvt_pk_bf16(glu_gate_f(bf_lo(gw.w), a1[2], bf_lo(zw.w)), glu_gate_f(bf_hi(gw.w), a1[3], bf_hi(zw.w)));
;                     *(u32x4*)(O + (size_t)r * DE + c) = w; } } }
	v_mul_f32_e32 v18, 0xbfb8aa3b, v21
	v_exp_f32_e32 v18, v18
	v_mul_f32_e32 v21, v25, v34
	v_pk_add_f32 v[18:19], v[18:19], 1.0 op_sel_hi:[1,0]
	s_nop 0
	v_mul_f32_e32 v18, v18, v19
	v_rcp_f32_e32 v18, v18
	s_nop 0
	v_mul_f32_e32 v18, v21, v18
	v_cvt_pk_bf16_f32 v25, v20, v18
	v_lshlrev_b32_e32 v20, 16, v50
	v_exp_f32_e32 v18, v14
	v_mul_f32_e32 v14, 0xbfb8aa3b, v20
	v_exp_f32_e32 v19, v14
	v_lshlrev_b32_e32 v21, 16, v54
	v_mul_f32_e32 v14, v21, v20
	v_and_b32_e32 v20, 0xffff0000, v50
	v_pk_add_f32 v[18:19], v[18:19], 1.0 op_sel_hi:[1,0]
	global_store_dwordx4 v[108:109], v[22:25], off offset:256
	v_mul_f32_e32 v18, v18, v19
	v_rcp_f32_e32 v18, v18
	v_and_b32_e32 v19, 0xffff0000, v54
	v_mul_f32_e32 v19, v19, v20
	v_mul_f32_e32 v18, v14, v18
	v_mul_f32_e32 v14, 0xbfb8aa3b, v15
	v_mul_f32_e32 v15, 0xbfb8aa3b, v20
	v_exp_f32_e32 v14, v14
	v_exp_f32_e32 v15, v15
	v_lshlrev_b32_e32 v20, 16, v55
	v_pk_add_f32 v[14:15], v[14:15], 1.0 op_sel_hi:[1,0]
	s_nop 0
	v_mul_f32_e32 v14, v14, v15
	v_rcp_f32_e32 v14, v14
	v_lshlrev_b32_e32 v15, 16, v51
	v_mul_f32_e32 v14, v19, v14
	v_cvt_pk_bf16_f32 v14, v18, v14
	v_exp_f32_e32 v18, v16
	v_mul_f32_e32 v16, 0xbfb8aa3b, v15
	v_exp_f32_e32 v19, v16
	v_mul_f32_e32 v15, v20, v15
	v_pk_add_f32 v[18:19], v[18:19], 1.0 op_sel_hi:[1,0]
	s_nop 0
	v_mul_f32_e32 v16, v18, v19
	v_rcp_f32_e32 v16, v16
	v_and_b32_e32 v19, 0xffff0000, v51
	v_and_b32_e32 v18, 0xffff0000, v55
	v_mul_f32_e32 v18, v18, v19
	v_mul_f32_e32 v15, v15, v16
	v_mul_f32_e32 v16, 0xbfb8aa3b, v17
	v_mul_f32_e32 v17, 0xbfb8aa3b, v19
	v_exp_f32_e32 v16, v16
	v_exp_f32_e32 v17, v17
	v_lshlrev_b32_e32 v19, 16, v56
	v_pk_add_f32 v[16:17], v[16:17], 1.0 op_sel_hi:[1,0]
	s_nop 0
	v_mul_f32_e32 v16, v16, v17
	v_rcp_f32_e32 v16, v16
	s_nop 0
	v_mul_f32_e32 v16, v18, v16
	v_lshlrev_b32_e32 v18, 16, v52
	v_cvt_pk_bf16_f32 v15, v15, v16
	v_exp_f32_e32 v16, v10
	v_mul_f32_e32 v10, 0xbfb8aa3b, v18
	v_exp_f32_e32 v17, v10
	v_mul_f32_e32 v10, v19, v18
	v_and_b32_e32 v18, 0xffff0000, v52
	v_pk_add_f32 v[16:17], v[16:17], 1.0 op_sel_hi:[1,0]
	s_nop 0
	v_mul_f32_e32 v16, v16, v17
	v_rcp_f32_e32 v16, v16
	v_and_b32_e32 v17, 0xffff0000, v56
	v_mul_f32_e32 v17, v17, v18
	v_mul_f32_e32 v16, v10, v16
	v_mul_f32_e32 v10, 0xbfb8aa3b, v11
	v_mul_f32_e32 v11, 0xbfb8aa3b, v18
	v_exp_f32_e32 v10, v10
	v_exp_f32_e32 v11, v11
	v_lshlrev_b32_e32 v18, 16, v57
	v_pk_add_f32 v[10:11], v[10:11], 1.0 op_sel_hi:[1,0]
	s_nop 0
	v_mul_f32_e32 v10, v10, v11
	v_rcp_f32_e32 v10, v10
	s_nop 0
	v_mul_f32_e32 v10, v17, v10
	v_lshlrev_b32_e32 v17, 16, v53
	v_cvt_pk_bf16_f32 v16, v16, v10
	v_mul_f32_e32 v10, 0xbfb8aa3b, v12
	v_mul_f32_e32 v11, 0xbfb8aa3b, v17
	v_exp_f32_e32 v10, v10
	v_exp_f32_e32 v11, v11
	v_mul_f32_e32 v12, v18, v17
	v_and_b32_e32 v18, 0xffff0000, v53
	v_and_b32_e32 v17, 0xffff0000, v57
	v_pk_add_f32 v[10:11], v[10:11], 1.0 op_sel_hi:[1,0]
	s_nop 0
	v_mul_f32_e32 v10, v10, v11
	v_rcp_f32_e32 v10, v10
	v_mul_f32_e32 v11, 0xbfb8aa3b, v18
	v_exp_f32_e32 v11, v11
	v_mul_f32_e32 v12, v12, v10
	v_mul_f32_e32 v10, 0xbfb8aa3b, v13
	v_exp_f32_e32 v10, v10
	v_mul_f32_e32 v13, v17, v18
	v_pk_add_f32 v[10:11], v[10:11], 1.0 op_sel_hi:[1,0]
	s_nop 0
	v_mul_f32_e32 v10, v10, v11
	v_rcp_f32_e32 v10, v10
	s_nop 0
	v_mul_f32_e32 v10, v13, v10
	v_cvt_pk_bf16_f32 v17, v12, v10
	v_lshlrev_b32_e32 v12, 16, v42
	v_exp_f32_e32 v10, v6
	v_mul_f32_e32 v6, 0xbfb8aa3b, v12
	v_exp_f32_e32 v11, v6
	v_lshlrev_b32_e32 v13, 16, v46
	v_mul_f32_e32 v6, v13, v12
	v_and_b32_e32 v12, 0xffff0000, v42
	v_pk_add_f32 v[10:11], v[10:11], 1.0 op_sel_hi:[1,0]
	global_store_dwordx4 v[110:111], v[14:17], off offset:256
	v_mul_f32_e32 v10, v10, v11
	v_rcp_f32_e32 v10, v10
	v_and_b32_e32 v11, 0xffff0000, v46
	v_mul_f32_e32 v11, v11, v12
	v_mul_f32_e32 v10, v6, v10
	v_mul_f32_e32 v6, 0xbfb8aa3b, v7
	v_mul_f32_e32 v7, 0xbfb8aa3b, v12
	v_exp_f32_e32 v6, v6
	v_exp_f32_e32 v7, v7
	v_lshlrev_b32_e32 v12, 16, v47
	v_pk_add_f32 v[6:7], v[6:7], 1.0 op_sel_hi:[1,0]
	s_nop 0
	v_mul_f32_e32 v6, v6, v7
	v_rcp_f32_e32 v6, v6
	v_lshlrev_b32_e32 v7, 16, v43
	v_mul_f32_e32 v6, v11, v6
	v_cvt_pk_bf16_f32 v6, v10, v6
	v_exp_f32_e32 v10, v8
	v_mul_f32_e32 v8, 0xbfb8aa3b, v7
	v_exp_f32_e32 v11, v8
	v_mul_f32_e32 v7, v12, v7
	v_pk_add_f32 v[10:11], v[10:11], 1.0 op_sel_hi:[1,0]
	s_nop 0
	v_mul_f32_e32 v8, v10, v11
	v_rcp_f32_e32 v8, v8
	v_and_b32_e32 v11, 0xffff0000, v43
	v_and_b32_e32 v10, 0xffff0000, v47
	v_mul_f32_e32 v10, v10, v11
	v_mul_f32_e32 v7, v7, v8
	v_mul_f32_e32 v8, 0xbfb8aa3b, v9
	v_mul_f32_e32 v9, 0xbfb8aa3b, v11
	v_exp_f32_e32 v8, v8
	v_exp_f32_e32 v9, v9
	v_lshlrev_b32_e32 v11, 16, v48
	v_pk_add_f32 v[8:9], v[8:9], 1.0 op_sel_hi:[1,0]
	s_nop 0
	v_mul_f32_e32 v8, v8, v9
	v_rcp_f32_e32 v8, v8
	s_nop 0
	v_mul_f32_e32 v8, v10, v8
	v_lshlrev_b32_e32 v10, 16, v44
	v_cvt_pk_bf16_f32 v7, v7, v8
	v_exp_f32_e32 v8, v2
	v_mul_f32_e32 v2, 0xbfb8aa3b, v10
	v_exp_f32_e32 v9, v2
	v_mul_f32_e32 v2, v11, v10
	v_and_b32_e32 v10, 0xffff0000, v44
	v_pk_add_f32 v[8:9], v[8:9], 1.0 op_sel_hi:[1,0]
	s_nop 0
	v_mul_f32_e32 v8, v8, v9
	v_rcp_f32_e32 v8, v8
	v_and_b32_e32 v9, 0xffff0000, v48
	v_mul_f32_e32 v9, v9, v10
	v_mul_f32_e32 v8, v2, v8
	v_mul_f32_e32 v2, 0xbfb8aa3b, v3
	v_mul_f32_e32 v3, 0xbfb8aa3b, v10
	v_exp_f32_e32 v2, v2
	v_exp_f32_e32 v3, v3
	v_lshlrev_b32_e32 v10, 16, v49
	v_pk_add_f32 v[2:3], v[2:3], 1.0 op_sel_hi:[1,0]
	s_nop 0
	v_mul_f32_e32 v2, v2, v3
	v_rcp_f32_e32 v2, v2
	s_nop 0
	v_mul_f32_e32 v2, v9, v2
	v_lshlrev_b32_e32 v9, 16, v45
	v_cvt_pk_bf16_f32 v8, v8, v2
	v_mul_f32_e32 v2, 0xbfb8aa3b, v4
	v_mul_f32_e32 v3, 0xbfb8aa3b, v9
	v_exp_f32_e32 v2, v2
	v_exp_f32_e32 v3, v3
	v_mul_f32_e32 v4, v10, v9
	v_and_b32_e32 v10, 0xffff0000, v45
	v_and_b32_e32 v9, 0xffff0000, v49
	v_pk_add_f32 v[2:3], v[2:3], 1.0 op_sel_hi:[1,0]
	s_nop 0
	v_mul_f32_e32 v2, v2, v3
	v_rcp_f32_e32 v2, v2
	v_mul_f32_e32 v3, 0xbfb8aa3b, v10
	v_exp_f32_e32 v3, v3
	v_mul_f32_e32 v4, v4, v2
	v_mul_f32_e32 v2, 0xbfb8aa3b, v5
	v_exp_f32_e32 v2, v2
	v_mul_f32_e32 v5, v9, v10
	v_pk_add_f32 v[2:3], v[2:3], 1.0 op_sel_hi:[1,0]
	s_nop 0
	v_mul_f32_e32 v2, v2, v3
	v_rcp_f32_e32 v2, v2
	s_nop 0
	v_mul_f32_e32 v2, v5, v2
	v_cvt_pk_bf16_f32 v9, v4, v2
	global_store_dwordx4 v[112:113], v[6:9], off offset:256
	s_cbranch_vccz .LBB0_789
	s_waitcnt vmcnt(0)
	v_readlane_b32 s36, v254, 56
	s_cmpk_gt_u32 s18, 0xff
	v_readlane_b32 s37, v254, 57
	s_cbranch_scc1 .LBB0_800
	s_barrier
